# v42
# speedup vs baseline: 1.0024x; 1.0009x over previous
.LBB0_189:
	s_add_u32 s36, s34, 0xfffc0080
	s_addc_u32 s37, s35, -1
	s_add_i32 s75, 0, 0x10000
	v_add_u32_e32 v140, s75, v161
	ds_read_b128 v[164:167], v140
	ds_read_b128 v[168:171], v140 offset:1024
	ds_read_b128 v[172:175], v140 offset:2048
	ds_read_b128 v[176:179], v140 offset:3072
	s_cmp_eq_u32 s74, 12
	s_cselect_b32 s39, s25, s37
	s_cselect_b32 s38, s69, s36
	s_cselect_b32 s37, s23, s73
	s_cselect_b32 s36, s70, s71
	s_add_i32 m0, s31, 0xc000
	ds_read_b128 v[180:183], v163
	ds_read_b128 v[184:187], v163 offset:1024
	ds_read_b128 v[188:191], v163 offset:2048
	ds_read_b128 v[192:195], v163 offset:3072
	ds_read_b128 v[196:199], v163 offset:4096
	ds_read_b128 v[200:203], v163 offset:5120
	ds_read_b128 v[204:207], v163 offset:6144
	global_load_lds_dwordx4 v136, s[34:35]
	s_add_i32 m0, s31, 0xe000
	ds_read_b128 v[208:211], v163 offset:7168
	global_load_lds_dwordx4 v138, s[34:35]
	s_waitcnt lgkmcnt(8)
	s_barrier
	s_waitcnt lgkmcnt(0)
	v_mfma_f32_16x16x32_bf16 v[124:127], v[164:167], v[180:183], v[124:127]
	v_mfma_f32_16x16x32_bf16 v[120:123], v[172:175], v[180:183], v[120:123]
	v_mfma_f32_16x16x32_bf16 v[116:119], v[164:167], v[188:191], v[116:119]
	v_mfma_f32_16x16x32_bf16 v[108:111], v[172:175], v[188:191], v[108:111]
	v_mfma_f32_16x16x32_bf16 v[100:103], v[164:167], v[196:199], v[100:103]
	v_mfma_f32_16x16x32_bf16 v[92:95], v[172:175], v[196:199], v[92:95]
	v_mfma_f32_16x16x32_bf16 v[84:87], v[164:167], v[204:207], v[84:87]
	v_mfma_f32_16x16x32_bf16 v[76:79], v[172:175], v[204:207], v[76:79]
	v_mfma_f32_16x16x32_bf16 v[124:127], v[168:171], v[184:187], v[124:127]
	v_mfma_f32_16x16x32_bf16 v[120:123], v[176:179], v[184:187], v[120:123]
	v_mfma_f32_16x16x32_bf16 v[116:119], v[168:171], v[192:195], v[116:119]
	v_mfma_f32_16x16x32_bf16 v[108:111], v[176:179], v[192:195], v[108:111]
	v_mfma_f32_16x16x32_bf16 v[100:103], v[168:171], v[200:203], v[100:103]
	v_mfma_f32_16x16x32_bf16 v[92:95], v[176:179], v[200:203], v[92:95]
	v_mfma_f32_16x16x32_bf16 v[84:87], v[168:171], v[208:211], v[84:87]
	v_mfma_f32_16x16x32_bf16 v[76:79], v[176:179], v[208:211], v[76:79]
	s_barrier
	s_add_i32 s78, 0, 0x14000
	v_add_u32_e32 v140, s78, v161
	s_add_i32 s75, s75, s57
	ds_read_b128 v[212:215], v140
	ds_read_b128 v[216:219], v140 offset:1024
	ds_read_b128 v[220:223], v140 offset:2048
	ds_read_b128 v[224:227], v140 offset:3072
	s_add_u32 s98, s36, s14
	s_addc_u32 s99, s37, s15
	s_mov_b32 m0, s75
	s_nop 0
	global_load_lds_dwordx4 v128, s[36:37]
	s_add_i32 m0, s75, 0x2000
	s_nop 0
	global_load_lds_dwordx4 v130, s[36:37]
	s_barrier
	s_waitcnt lgkmcnt(0)
	v_mfma_f32_16x16x32_bf16 v[112:115], v[212:215], v[180:183], v[112:115]
	v_mfma_f32_16x16x32_bf16 v[104:107], v[220:223], v[180:183], v[104:107]
	v_mfma_f32_16x16x32_bf16 v[96:99], v[212:215], v[188:191], v[96:99]
	v_mfma_f32_16x16x32_bf16 v[88:91], v[220:223], v[188:191], v[88:91]
	v_mfma_f32_16x16x32_bf16 v[80:83], v[212:215], v[196:199], v[80:83]
	v_mfma_f32_16x16x32_bf16 v[72:75], v[220:223], v[196:199], v[72:75]
	v_mfma_f32_16x16x32_bf16 v[68:71], v[212:215], v[204:207], v[68:71]
	v_mfma_f32_16x16x32_bf16 v[64:67], v[220:223], v[204:207], v[64:67]
	v_mfma_f32_16x16x32_bf16 v[112:115], v[216:219], v[184:187], v[112:115]
	v_mfma_f32_16x16x32_bf16 v[104:107], v[224:227], v[184:187], v[104:107]
	v_mfma_f32_16x16x32_bf16 v[96:99], v[216:219], v[192:195], v[96:99]
	v_mfma_f32_16x16x32_bf16 v[88:91], v[224:227], v[192:195], v[88:91]
	v_mfma_f32_16x16x32_bf16 v[80:83], v[216:219], v[200:203], v[80:83]
	v_mfma_f32_16x16x32_bf16 v[72:75], v[224:227], v[200:203], v[72:75]
	v_mfma_f32_16x16x32_bf16 v[68:71], v[216:219], v[208:211], v[68:71]
	v_mfma_f32_16x16x32_bf16 v[64:67], v[224:227], v[208:211], v[64:67]
	s_mov_b32 m0, s31
	s_add_u32 s100, s38, s14
	s_addc_u32 s101, s39, s15
	s_barrier
	ds_read_b128 v[180:183], v163 offset:16384
	ds_read_b128 v[184:187], v163 offset:17408
	ds_read_b128 v[188:191], v163 offset:18432
	ds_read_b128 v[192:195], v163 offset:19456
	ds_read_b128 v[196:199], v163 offset:20480
	ds_read_b128 v[200:203], v163 offset:21504
	ds_read_b128 v[204:207], v163 offset:22528
	global_load_lds_dwordx4 v134, s[38:39]
	s_mov_b32 m0, s60
	ds_read_b128 v[208:211], v163 offset:23552
	global_load_lds_dwordx4 v132, s[38:39]
	s_barrier
	s_waitcnt lgkmcnt(0)
	v_mfma_f32_16x16x32_bf16 v[60:63], v[164:167], v[180:183], v[60:63]
	v_mfma_f32_16x16x32_bf16 v[56:59], v[172:175], v[180:183], v[56:59]
	v_mfma_f32_16x16x32_bf16 v[52:55], v[164:167], v[188:191], v[52:55]
	v_mfma_f32_16x16x32_bf16 v[44:47], v[172:175], v[188:191], v[44:47]
	v_mfma_f32_16x16x32_bf16 v[36:39], v[164:167], v[196:199], v[36:39]
	v_mfma_f32_16x16x32_bf16 v[28:31], v[172:175], v[196:199], v[28:31]
	v_mfma_f32_16x16x32_bf16 v[20:23], v[164:167], v[204:207], v[20:23]
	v_mfma_f32_16x16x32_bf16 v[12:15], v[172:175], v[204:207], v[12:15]
	v_mfma_f32_16x16x32_bf16 v[60:63], v[168:171], v[184:187], v[60:63]
	v_mfma_f32_16x16x32_bf16 v[56:59], v[176:179], v[184:187], v[56:59]
	v_mfma_f32_16x16x32_bf16 v[52:55], v[168:171], v[192:195], v[52:55]
	v_mfma_f32_16x16x32_bf16 v[44:47], v[176:179], v[192:195], v[44:47]
	v_mfma_f32_16x16x32_bf16 v[36:39], v[168:171], v[200:203], v[36:39]
	v_mfma_f32_16x16x32_bf16 v[28:31], v[176:179], v[200:203], v[28:31]
	v_mfma_f32_16x16x32_bf16 v[20:23], v[168:171], v[208:211], v[20:23]
	v_mfma_f32_16x16x32_bf16 v[12:15], v[176:179], v[208:211], v[12:15]
	s_barrier
	s_add_u32 s76, s36, 0x40000
	s_addc_u32 s77, s37, 0
	s_add_i32 s75, s78, s57
	s_mov_b32 m0, s75
	s_nop 0
	global_load_lds_dwordx4 v128, s[76:77]
	s_add_i32 m0, s75, 0x2000
	s_nop 0
	global_load_lds_dwordx4 v130, s[76:77]
	s_waitcnt vmcnt(6)
	s_barrier
	v_mfma_f32_16x16x32_bf16 v[48:51], v[212:215], v[180:183], v[48:51]
	v_mfma_f32_16x16x32_bf16 v[40:43], v[220:223], v[180:183], v[40:43]
	v_mfma_f32_16x16x32_bf16 v[32:35], v[212:215], v[188:191], v[32:35]
	v_mfma_f32_16x16x32_bf16 v[24:27], v[220:223], v[188:191], v[24:27]
	v_mfma_f32_16x16x32_bf16 v[16:19], v[212:215], v[196:199], v[16:19]
	v_mfma_f32_16x16x32_bf16 v[8:11], v[220:223], v[196:199], v[8:11]
	v_mfma_f32_16x16x32_bf16 v[4:7], v[212:215], v[204:207], v[4:7]
	v_mfma_f32_16x16x32_bf16 v[0:3], v[220:223], v[204:207], v[0:3]
	v_mfma_f32_16x16x32_bf16 v[48:51], v[216:219], v[184:187], v[48:51]
	v_mfma_f32_16x16x32_bf16 v[40:43], v[224:227], v[184:187], v[40:43]
	v_mfma_f32_16x16x32_bf16 v[32:35], v[216:219], v[192:195], v[32:35]
	v_mfma_f32_16x16x32_bf16 v[24:27], v[224:227], v[192:195], v[24:27]
	v_mfma_f32_16x16x32_bf16 v[16:19], v[216:219], v[200:203], v[16:19]
	v_mfma_f32_16x16x32_bf16 v[8:11], v[224:227], v[200:203], v[8:11]
	v_mfma_f32_16x16x32_bf16 v[4:7], v[216:219], v[208:211], v[4:7]
	v_mfma_f32_16x16x32_bf16 v[0:3], v[224:227], v[208:211], v[0:3]
	s_add_i32 s75, 0, 0x18000
	v_add_u32_e32 v176, s75, v161
	s_barrier
	ds_read_b128 v[164:167], v176
	ds_read_b128 v[168:171], v176 offset:1024
	ds_read_b128 v[172:175], v176 offset:2048
	ds_read_b128 v[176:179], v176 offset:3072
	s_add_u32 s38, s38, 0x40000
	s_addc_u32 s39, s39, 0
	s_mov_b32 m0, s61
	ds_read_b128 v[180:183], v163 offset:32768
	ds_read_b128 v[184:187], v163 offset:33792
	ds_read_b128 v[188:191], v163 offset:34816
	ds_read_b128 v[192:195], v163 offset:35840
	ds_read_b128 v[196:199], v163 offset:36864
	ds_read_b128 v[200:203], v163 offset:37888
	ds_read_b128 v[204:207], v163 offset:38912
	global_load_lds_dwordx4 v134, s[38:39]
	s_mov_b32 m0, s62
	ds_read_b128 v[208:211], v163 offset:39936
	global_load_lds_dwordx4 v132, s[38:39]
	s_waitcnt lgkmcnt(8)
	s_barrier
	s_waitcnt lgkmcnt(0)
	v_mfma_f32_16x16x32_bf16 v[124:127], v[164:167], v[180:183], v[124:127]
	v_mfma_f32_16x16x32_bf16 v[120:123], v[172:175], v[180:183], v[120:123]
	v_mfma_f32_16x16x32_bf16 v[116:119], v[164:167], v[188:191], v[116:119]
	v_mfma_f32_16x16x32_bf16 v[108:111], v[172:175], v[188:191], v[108:111]
	v_mfma_f32_16x16x32_bf16 v[100:103], v[164:167], v[196:199], v[100:103]
	v_mfma_f32_16x16x32_bf16 v[92:95], v[172:175], v[196:199], v[92:95]
	v_mfma_f32_16x16x32_bf16 v[84:87], v[164:167], v[204:207], v[84:87]
	v_mfma_f32_16x16x32_bf16 v[76:79], v[172:175], v[204:207], v[76:79]
	v_mfma_f32_16x16x32_bf16 v[124:127], v[168:171], v[184:187], v[124:127]
	v_mfma_f32_16x16x32_bf16 v[120:123], v[176:179], v[184:187], v[120:123]
	v_mfma_f32_16x16x32_bf16 v[116:119], v[168:171], v[192:195], v[116:119]
	v_mfma_f32_16x16x32_bf16 v[108:111], v[176:179], v[192:195], v[108:111]
	v_mfma_f32_16x16x32_bf16 v[100:103], v[168:171], v[200:203], v[100:103]
	v_mfma_f32_16x16x32_bf16 v[92:95], v[176:179], v[200:203], v[92:95]
	v_mfma_f32_16x16x32_bf16 v[84:87], v[168:171], v[208:211], v[84:87]
	v_mfma_f32_16x16x32_bf16 v[76:79], v[176:179], v[208:211], v[76:79]
	s_barrier
	s_add_i32 s38, 0, 0x1c000
	s_add_i32 s39, s75, s57
	v_add_u32_e32 v224, s38, v161
	s_mov_b32 m0, s39
	ds_read_b128 v[212:215], v224
	ds_read_b128 v[216:219], v224 offset:1024
	ds_read_b128 v[220:223], v224 offset:2048
	global_load_lds_dwordx4 v128, s[98:99]
	s_add_i32 m0, s39, 0x2000
	ds_read_b128 v[224:227], v224 offset:3072
	global_load_lds_dwordx4 v130, s[98:99]
	s_barrier
	s_waitcnt lgkmcnt(0)
	v_mfma_f32_16x16x32_bf16 v[112:115], v[212:215], v[180:183], v[112:115]
	v_mfma_f32_16x16x32_bf16 v[104:107], v[220:223], v[180:183], v[104:107]
	v_mfma_f32_16x16x32_bf16 v[96:99], v[212:215], v[188:191], v[96:99]
	v_mfma_f32_16x16x32_bf16 v[88:91], v[220:223], v[188:191], v[88:91]
	v_mfma_f32_16x16x32_bf16 v[80:83], v[212:215], v[196:199], v[80:83]
	v_mfma_f32_16x16x32_bf16 v[72:75], v[220:223], v[196:199], v[72:75]
	v_mfma_f32_16x16x32_bf16 v[68:71], v[212:215], v[204:207], v[68:71]
	v_mfma_f32_16x16x32_bf16 v[64:67], v[220:223], v[204:207], v[64:67]
	v_mfma_f32_16x16x32_bf16 v[112:115], v[216:219], v[184:187], v[112:115]
	v_mfma_f32_16x16x32_bf16 v[104:107], v[224:227], v[184:187], v[104:107]
	v_mfma_f32_16x16x32_bf16 v[96:99], v[216:219], v[192:195], v[96:99]
	v_mfma_f32_16x16x32_bf16 v[88:91], v[224:227], v[192:195], v[88:91]
	v_mfma_f32_16x16x32_bf16 v[80:83], v[216:219], v[200:203], v[80:83]
	v_mfma_f32_16x16x32_bf16 v[72:75], v[224:227], v[200:203], v[72:75]
	v_mfma_f32_16x16x32_bf16 v[68:71], v[216:219], v[208:211], v[68:71]
	v_mfma_f32_16x16x32_bf16 v[64:67], v[224:227], v[208:211], v[64:67]
	s_mov_b32 m0, s63
	s_barrier
	ds_read_b128 v[180:183], v163 offset:49152
	ds_read_b128 v[184:187], v163 offset:50176
	ds_read_b128 v[188:191], v163 offset:51200
	ds_read_b128 v[192:195], v163 offset:52224
	ds_read_b128 v[196:199], v163 offset:53248
	ds_read_b128 v[200:203], v163 offset:54272
	ds_read_b128 v[204:207], v163 offset:55296
	global_load_lds_dwordx4 v134, s[100:101]
	s_mov_b32 m0, s64
	ds_read_b128 v[208:211], v163 offset:56320
	global_load_lds_dwordx4 v132, s[100:101]
	s_barrier
	s_waitcnt lgkmcnt(0)
	v_mfma_f32_16x16x32_bf16 v[60:63], v[164:167], v[180:183], v[60:63]
	v_mfma_f32_16x16x32_bf16 v[56:59], v[172:175], v[180:183], v[56:59]
	v_mfma_f32_16x16x32_bf16 v[52:55], v[164:167], v[188:191], v[52:55]
	v_mfma_f32_16x16x32_bf16 v[44:47], v[172:175], v[188:191], v[44:47]
	v_mfma_f32_16x16x32_bf16 v[36:39], v[164:167], v[196:199], v[36:39]
	v_mfma_f32_16x16x32_bf16 v[28:31], v[172:175], v[196:199], v[28:31]
	v_mfma_f32_16x16x32_bf16 v[20:23], v[164:167], v[204:207], v[20:23]
	v_mfma_f32_16x16x32_bf16 v[12:15], v[172:175], v[204:207], v[12:15]
	v_mfma_f32_16x16x32_bf16 v[60:63], v[168:171], v[184:187], v[60:63]
	v_mfma_f32_16x16x32_bf16 v[56:59], v[176:179], v[184:187], v[56:59]
	v_mfma_f32_16x16x32_bf16 v[52:55], v[168:171], v[192:195], v[52:55]
	v_mfma_f32_16x16x32_bf16 v[44:47], v[176:179], v[192:195], v[44:47]
	v_mfma_f32_16x16x32_bf16 v[36:39], v[168:171], v[200:203], v[36:39]
	v_mfma_f32_16x16x32_bf16 v[28:31], v[176:179], v[200:203], v[28:31]
	v_mfma_f32_16x16x32_bf16 v[20:23], v[168:171], v[208:211], v[20:23]
	v_mfma_f32_16x16x32_bf16 v[12:15], v[176:179], v[208:211], v[12:15]
	s_barrier
	s_add_u32 s36, s36, 0x40080
	s_addc_u32 s37, s37, 0
	s_add_i32 s38, s38, s57
	s_mov_b32 m0, s38
	s_add_i32 s74, s74, 2
	global_load_lds_dwordx4 v128, s[36:37]
	s_add_i32 m0, s38, 0x2000
	s_add_u32 s34, s34, 0x100
	s_addc_u32 s35, s35, 0
	global_load_lds_dwordx4 v130, s[36:37]
	s_add_u32 s71, s71, 0x100
	s_addc_u32 s73, s73, 0
	s_waitcnt vmcnt(6)
	s_barrier
	v_mfma_f32_16x16x32_bf16 v[48:51], v[212:215], v[180:183], v[48:51]
	v_mfma_f32_16x16x32_bf16 v[40:43], v[220:223], v[180:183], v[40:43]
	v_mfma_f32_16x16x32_bf16 v[32:35], v[212:215], v[188:191], v[32:35]
	v_mfma_f32_16x16x32_bf16 v[24:27], v[220:223], v[188:191], v[24:27]
	v_mfma_f32_16x16x32_bf16 v[16:19], v[212:215], v[196:199], v[16:19]
	v_mfma_f32_16x16x32_bf16 v[8:11], v[220:223], v[196:199], v[8:11]
	v_mfma_f32_16x16x32_bf16 v[4:7], v[212:215], v[204:207], v[4:7]
	v_mfma_f32_16x16x32_bf16 v[0:3], v[220:223], v[204:207], v[0:3]
	v_mfma_f32_16x16x32_bf16 v[48:51], v[216:219], v[184:187], v[48:51]
	v_mfma_f32_16x16x32_bf16 v[40:43], v[224:227], v[184:187], v[40:43]
	v_mfma_f32_16x16x32_bf16 v[32:35], v[216:219], v[192:195], v[32:35]
	v_mfma_f32_16x16x32_bf16 v[24:27], v[224:227], v[192:195], v[24:27]
	v_mfma_f32_16x16x32_bf16 v[16:19], v[216:219], v[200:203], v[16:19]
	v_mfma_f32_16x16x32_bf16 v[8:11], v[224:227], v[200:203], v[8:11]
	v_mfma_f32_16x16x32_bf16 v[4:7], v[216:219], v[208:211], v[4:7]
	v_mfma_f32_16x16x32_bf16 v[0:3], v[224:227], v[208:211], v[0:3]
	s_cmp_gt_u32 s74, 13
	s_barrier
	s_cbranch_scc0 .LBB0_189
	v_lshl_or_b32 v140, s68, 8, v162
	v_lshl_add_u32 v166, s30, 8, v159
	v_ashrrev_i32_e32 v141, 31, v140
	v_lshl_add_u64 v[140:141], v[140:141], 1, s[20:21]
	v_mad_i64_i32 v[164:165], s[34:35], v166, s52, 0
	v_lshl_add_u64 v[164:165], v[164:165], 1, v[140:141]
	v_cvt_pk_bf16_f32 v124, v124, v125
	v_cvt_pk_bf16_f32 v125, v126, v127
	v_cvt_pk_bf16_f32 v126, v120, v121
	v_cvt_pk_bf16_f32 v127, v122, v123
	global_store_dwordx4 v[164:165], v[124:127], off
	v_cvt_pk_bf16_f32 v112, v112, v113
	v_cvt_pk_bf16_f32 v113, v114, v115
	v_cvt_pk_bf16_f32 v114, v104, v105
	v_or_b32_e32 v104, 16, v166
	v_mad_i64_i32 v[104:105], s[34:35], v104, s52, 0
	v_cvt_pk_bf16_f32 v115, v106, v107
	global_store_dwordx4 v[164:165], v[112:115], off offset:256
	s_and_b64 vcc, exec, s[4:5]
	s_mov_b32 s68, s22
	v_lshl_add_u64 v[112:113], v[104:105], 1, v[140:141]
	v_cvt_pk_bf16_f32 v104, v116, v117
	v_cvt_pk_bf16_f32 v105, v118, v119
	v_cvt_pk_bf16_f32 v106, v108, v109
	v_cvt_pk_bf16_f32 v107, v110, v111
	global_store_dwordx4 v[112:113], v[104:107], off
	v_cvt_pk_bf16_f32 v96, v96, v97
	v_cvt_pk_bf16_f32 v97, v98, v99
	v_cvt_pk_bf16_f32 v98, v88, v89
	v_or_b32_e32 v88, 32, v166
	v_mad_i64_i32 v[88:89], s[34:35], v88, s52, 0
	v_cvt_pk_bf16_f32 v99, v90, v91
	global_store_dwordx4 v[112:113], v[96:99], off offset:256
	s_mov_b32 s30, s24
	s_mov_b64 s[36:37], s[28:29]
	v_lshl_add_u64 v[96:97], v[88:89], 1, v[140:141]
	v_cvt_pk_bf16_f32 v88, v100, v101
	v_cvt_pk_bf16_f32 v89, v102, v103
	v_cvt_pk_bf16_f32 v90, v92, v93
	v_cvt_pk_bf16_f32 v91, v94, v95
	global_store_dwordx4 v[96:97], v[88:91], off
	v_cvt_pk_bf16_f32 v80, v80, v81
	v_cvt_pk_bf16_f32 v81, v82, v83
	v_cvt_pk_bf16_f32 v82, v72, v73
	v_or_b32_e32 v72, 48, v166
	v_mad_i64_i32 v[72:73], s[34:35], v72, s52, 0
	v_cvt_pk_bf16_f32 v83, v74, v75
	global_store_dwordx4 v[96:97], v[80:83], off offset:256
	s_nop 1
	v_lshl_add_u64 v[80:81], v[72:73], 1, v[140:141]
	v_cvt_pk_bf16_f32 v72, v84, v85
	v_cvt_pk_bf16_f32 v73, v86, v87
	v_cvt_pk_bf16_f32 v74, v76, v77
	v_cvt_pk_bf16_f32 v75, v78, v79
	global_store_dwordx4 v[80:81], v[72:75], off
	v_cvt_pk_bf16_f32 v68, v68, v69
	v_cvt_pk_bf16_f32 v69, v70, v71
	v_cvt_pk_bf16_f32 v70, v64, v65
	v_add_u32_e32 v64, 0x80, v166
	v_mad_i64_i32 v[64:65], s[34:35], v64, s52, 0
	v_lshl_add_u64 v[64:65], v[64:65], 1, v[140:141]
	v_cvt_pk_bf16_f32 v71, v66, v67
	global_store_dwordx4 v[80:81], v[68:71], off offset:256
	v_cvt_pk_bf16_f32 v60, v60, v61
	v_cvt_pk_bf16_f32 v61, v62, v63
	v_cvt_pk_bf16_f32 v62, v56, v57
	v_cvt_pk_bf16_f32 v63, v58, v59
	global_store_dwordx4 v[64:65], v[60:63], off
	v_cvt_pk_bf16_f32 v48, v48, v49
	v_cvt_pk_bf16_f32 v49, v50, v51
	v_cvt_pk_bf16_f32 v50, v40, v41
	v_add_u32_e32 v40, 0x90, v166
	v_mad_i64_i32 v[40:41], s[34:35], v40, s52, 0
	v_cvt_pk_bf16_f32 v51, v42, v43
	global_store_dwordx4 v[64:65], v[48:51], off offset:256
	s_nop 1
	v_lshl_add_u64 v[48:49], v[40:41], 1, v[140:141]
	v_cvt_pk_bf16_f32 v40, v52, v53
	v_cvt_pk_bf16_f32 v41, v54, v55
	v_cvt_pk_bf16_f32 v42, v44, v45
	v_cvt_pk_bf16_f32 v43, v46, v47
	global_store_dwordx4 v[48:49], v[40:43], off
	v_cvt_pk_bf16_f32 v32, v32, v33
	v_cvt_pk_bf16_f32 v33, v34, v35
	v_cvt_pk_bf16_f32 v34, v24, v25
	v_add_u32_e32 v24, 0xa0, v166
	v_mad_i64_i32 v[24:25], s[34:35], v24, s52, 0
	v_cvt_pk_bf16_f32 v35, v26, v27
	global_store_dwordx4 v[48:49], v[32:35], off offset:256
	s_nop 1
	v_lshl_add_u64 v[32:33], v[24:25], 1, v[140:141]
	v_cvt_pk_bf16_f32 v24, v36, v37
	v_cvt_pk_bf16_f32 v25, v38, v39
	v_cvt_pk_bf16_f32 v26, v28, v29
	v_cvt_pk_bf16_f32 v27, v30, v31
	global_store_dwordx4 v[32:33], v[24:27], off
	v_cvt_pk_bf16_f32 v16, v16, v17
	v_cvt_pk_bf16_f32 v17, v18, v19
	v_cvt_pk_bf16_f32 v18, v8, v9
	v_add_u32_e32 v8, 0xb0, v166
	v_mad_i64_i32 v[8:9], s[34:35], v8, s52, 0
	v_cvt_pk_bf16_f32 v19, v10, v11
	global_store_dwordx4 v[32:33], v[16:19], off offset:256
	s_mov_b64 s[34:35], s[26:27]
	s_nop 0
	v_lshl_add_u64 v[16:17], v[8:9], 1, v[140:141]
	v_cvt_pk_bf16_f32 v8, v20, v21
	v_cvt_pk_bf16_f32 v9, v22, v23
	v_cvt_pk_bf16_f32 v10, v12, v13
	v_cvt_pk_bf16_f32 v11, v14, v15
	global_store_dwordx4 v[16:17], v[8:11], off
	v_cvt_pk_bf16_f32 v4, v4, v5
	v_cvt_pk_bf16_f32 v5, v6, v7
	v_cvt_pk_bf16_f32 v6, v0, v1
	v_cvt_pk_bf16_f32 v7, v2, v3
	global_store_dwordx4 v[16:17], v[4:7], off offset:256
	s_cbranch_vccz .LBB0_186
	s_waitcnt vmcnt(0)
	s_cmpk_gt_u32 s56, 0xff
	s_cbranch_scc1 .LBB0_174
	s_barrier
	s_branch .LBB0_174

.LBB0_203:
	ds_read_b128 v[144:147], v153
	ds_read_b128 v[156:159], v153 offset:1024
	ds_read_b128 v[162:165], v153 offset:2048
	ds_read_b128 v[166:169], v153 offset:3072
	s_add_u32 s26, s24, 0xfffc0080
	s_addc_u32 s27, s25, -1
	s_cmp_eq_u32 s54, 12
	s_cselect_b32 s29, s5, s27
	s_cselect_b32 s28, s17, s26
	s_cselect_b32 s27, s15, s53
	s_cselect_b32 s26, s23, s52
	s_add_i32 m0, s36, 0xc000
	ds_read_b128 v[170:173], v154
	ds_read_b128 v[174:177], v154 offset:1024
	ds_read_b128 v[178:181], v154 offset:2048
	ds_read_b128 v[182:185], v154 offset:3072
	ds_read_b128 v[186:189], v154 offset:4096
	ds_read_b128 v[190:193], v154 offset:5120
	ds_read_b128 v[194:197], v154 offset:6144
	global_load_lds_dwordx4 v136, s[24:25]
	s_add_i32 m0, s36, 0xe000
	ds_read_b128 v[198:201], v154 offset:7168
	global_load_lds_dwordx4 v138, s[24:25]
	s_waitcnt lgkmcnt(8)
	s_barrier
	s_waitcnt lgkmcnt(0)
	v_mfma_f32_16x16x32_bf16 v[124:127], v[144:147], v[170:173], v[124:127]
	v_mfma_f32_16x16x32_bf16 v[120:123], v[162:165], v[170:173], v[120:123]
	v_mfma_f32_16x16x32_bf16 v[108:111], v[144:147], v[178:181], v[108:111]
	v_mfma_f32_16x16x32_bf16 v[104:107], v[162:165], v[178:181], v[104:107]
	v_mfma_f32_16x16x32_bf16 v[92:95], v[144:147], v[186:189], v[92:95]
	v_mfma_f32_16x16x32_bf16 v[88:91], v[162:165], v[186:189], v[88:91]
	v_mfma_f32_16x16x32_bf16 v[76:79], v[144:147], v[194:197], v[76:79]
	v_mfma_f32_16x16x32_bf16 v[72:75], v[162:165], v[194:197], v[72:75]
	v_mfma_f32_16x16x32_bf16 v[124:127], v[156:159], v[174:177], v[124:127]
	v_mfma_f32_16x16x32_bf16 v[120:123], v[166:169], v[174:177], v[120:123]
	v_mfma_f32_16x16x32_bf16 v[108:111], v[156:159], v[182:185], v[108:111]
	v_mfma_f32_16x16x32_bf16 v[104:107], v[166:169], v[182:185], v[104:107]
	v_mfma_f32_16x16x32_bf16 v[92:95], v[156:159], v[190:193], v[92:95]
	v_mfma_f32_16x16x32_bf16 v[88:91], v[166:169], v[190:193], v[88:91]
	v_mfma_f32_16x16x32_bf16 v[76:79], v[156:159], v[198:201], v[76:79]
	v_mfma_f32_16x16x32_bf16 v[72:75], v[166:169], v[198:201], v[72:75]
	s_barrier
	s_add_i32 s55, s48, s35
	s_add_u32 s98, s26, s12
	s_addc_u32 s99, s27, s13
	s_mov_b32 m0, s55
	ds_read_b128 v[202:205], v155
	ds_read_b128 v[206:209], v155 offset:1024
	ds_read_b128 v[210:213], v155 offset:2048
	global_load_lds_dwordx4 v130, s[26:27]
	s_add_i32 m0, s55, 0x2000
	ds_read_b128 v[214:217], v155 offset:3072
	global_load_lds_dwordx4 v134, s[26:27]
	s_barrier
	s_waitcnt lgkmcnt(0)
	v_mfma_f32_16x16x32_bf16 v[116:119], v[202:205], v[170:173], v[116:119]
	v_mfma_f32_16x16x32_bf16 v[112:115], v[210:213], v[170:173], v[112:115]
	v_mfma_f32_16x16x32_bf16 v[100:103], v[202:205], v[178:181], v[100:103]
	v_mfma_f32_16x16x32_bf16 v[96:99], v[210:213], v[178:181], v[96:99]
	v_mfma_f32_16x16x32_bf16 v[84:87], v[202:205], v[186:189], v[84:87]
	v_mfma_f32_16x16x32_bf16 v[80:83], v[210:213], v[186:189], v[80:83]
	v_mfma_f32_16x16x32_bf16 v[68:71], v[202:205], v[194:197], v[68:71]
	v_mfma_f32_16x16x32_bf16 v[64:67], v[210:213], v[194:197], v[64:67]
	v_mfma_f32_16x16x32_bf16 v[116:119], v[206:209], v[174:177], v[116:119]
	v_mfma_f32_16x16x32_bf16 v[112:115], v[214:217], v[174:177], v[112:115]
	v_mfma_f32_16x16x32_bf16 v[100:103], v[206:209], v[182:185], v[100:103]
	v_mfma_f32_16x16x32_bf16 v[96:99], v[214:217], v[182:185], v[96:99]
	v_mfma_f32_16x16x32_bf16 v[84:87], v[206:209], v[190:193], v[84:87]
	v_mfma_f32_16x16x32_bf16 v[80:83], v[214:217], v[190:193], v[80:83]
	v_mfma_f32_16x16x32_bf16 v[68:71], v[206:209], v[198:201], v[68:71]
	v_mfma_f32_16x16x32_bf16 v[64:67], v[214:217], v[198:201], v[64:67]
	s_mov_b32 m0, s36
	s_add_u32 s100, s28, s12
	s_addc_u32 s101, s29, s13
	s_barrier
	ds_read_b128 v[170:173], v154 offset:16384
	ds_read_b128 v[174:177], v154 offset:17408
	ds_read_b128 v[178:181], v154 offset:18432
	ds_read_b128 v[182:185], v154 offset:19456
	ds_read_b128 v[186:189], v154 offset:20480
	ds_read_b128 v[190:193], v154 offset:21504
	ds_read_b128 v[194:197], v154 offset:22528
	global_load_lds_dwordx4 v128, s[28:29]
	s_mov_b32 m0, s37
	ds_read_b128 v[198:201], v154 offset:23552
	global_load_lds_dwordx4 v132, s[28:29]
	s_barrier
	s_waitcnt lgkmcnt(0)
	v_mfma_f32_16x16x32_bf16 v[60:63], v[144:147], v[170:173], v[60:63]
	v_mfma_f32_16x16x32_bf16 v[56:59], v[162:165], v[170:173], v[56:59]
	v_mfma_f32_16x16x32_bf16 v[44:47], v[144:147], v[178:181], v[44:47]
	v_mfma_f32_16x16x32_bf16 v[40:43], v[162:165], v[178:181], v[40:43]
	v_mfma_f32_16x16x32_bf16 v[28:31], v[144:147], v[186:189], v[28:31]
	v_mfma_f32_16x16x32_bf16 v[24:27], v[162:165], v[186:189], v[24:27]
	v_mfma_f32_16x16x32_bf16 v[12:15], v[144:147], v[194:197], v[12:15]
	v_mfma_f32_16x16x32_bf16 v[8:11], v[162:165], v[194:197], v[8:11]
	v_mfma_f32_16x16x32_bf16 v[60:63], v[156:159], v[174:177], v[60:63]
	v_mfma_f32_16x16x32_bf16 v[56:59], v[166:169], v[174:177], v[56:59]
	v_mfma_f32_16x16x32_bf16 v[44:47], v[156:159], v[182:185], v[44:47]
	v_mfma_f32_16x16x32_bf16 v[40:43], v[166:169], v[182:185], v[40:43]
	v_mfma_f32_16x16x32_bf16 v[28:31], v[156:159], v[190:193], v[28:31]
	v_mfma_f32_16x16x32_bf16 v[24:27], v[166:169], v[190:193], v[24:27]
	v_mfma_f32_16x16x32_bf16 v[12:15], v[156:159], v[198:201], v[12:15]
	v_mfma_f32_16x16x32_bf16 v[8:11], v[166:169], v[198:201], v[8:11]
	s_barrier
	s_add_u32 s56, s26, 0x40000
	s_addc_u32 s57, s27, 0
	s_add_i32 s55, s49, s35
	s_mov_b32 m0, s55
	s_nop 0
	global_load_lds_dwordx4 v130, s[56:57]
	s_add_i32 m0, s55, 0x2000
	s_nop 0
	global_load_lds_dwordx4 v134, s[56:57]
	s_waitcnt vmcnt(6)
	s_barrier
	v_mfma_f32_16x16x32_bf16 v[52:55], v[202:205], v[170:173], v[52:55]
	v_mfma_f32_16x16x32_bf16 v[48:51], v[210:213], v[170:173], v[48:51]
	v_mfma_f32_16x16x32_bf16 v[36:39], v[202:205], v[178:181], v[36:39]
	v_mfma_f32_16x16x32_bf16 v[32:35], v[210:213], v[178:181], v[32:35]
	v_mfma_f32_16x16x32_bf16 v[20:23], v[202:205], v[186:189], v[20:23]
	v_mfma_f32_16x16x32_bf16 v[16:19], v[210:213], v[186:189], v[16:19]
	v_mfma_f32_16x16x32_bf16 v[4:7], v[202:205], v[194:197], v[4:7]
	v_mfma_f32_16x16x32_bf16 v[0:3], v[210:213], v[194:197], v[0:3]
	v_mfma_f32_16x16x32_bf16 v[52:55], v[206:209], v[174:177], v[52:55]
	v_mfma_f32_16x16x32_bf16 v[48:51], v[214:217], v[174:177], v[48:51]
	v_mfma_f32_16x16x32_bf16 v[36:39], v[206:209], v[182:185], v[36:39]
	v_mfma_f32_16x16x32_bf16 v[32:35], v[214:217], v[182:185], v[32:35]
	v_mfma_f32_16x16x32_bf16 v[20:23], v[206:209], v[190:193], v[20:23]
	v_mfma_f32_16x16x32_bf16 v[16:19], v[214:217], v[190:193], v[16:19]
	v_mfma_f32_16x16x32_bf16 v[4:7], v[206:209], v[198:201], v[4:7]
	v_mfma_f32_16x16x32_bf16 v[0:3], v[214:217], v[198:201], v[0:3]
	s_add_i32 s55, 0, 0x18000
	v_add_u32_e32 v161, s55, v151
	s_barrier
	ds_read_b128 v[144:147], v161
	ds_read_b128 v[156:159], v161 offset:1024
	ds_read_b128 v[162:165], v161 offset:2048
	ds_read_b128 v[166:169], v161 offset:3072
	s_add_u32 s28, s28, 0x40000
	s_addc_u32 s29, s29, 0
	s_mov_b32 m0, s38
	ds_read_b128 v[170:173], v154 offset:32768
	ds_read_b128 v[174:177], v154 offset:33792
	ds_read_b128 v[178:181], v154 offset:34816
	ds_read_b128 v[182:185], v154 offset:35840
	ds_read_b128 v[186:189], v154 offset:36864
	ds_read_b128 v[190:193], v154 offset:37888
	ds_read_b128 v[194:197], v154 offset:38912
	global_load_lds_dwordx4 v128, s[28:29]
	s_mov_b32 m0, s39
	ds_read_b128 v[198:201], v154 offset:39936
	global_load_lds_dwordx4 v132, s[28:29]
	s_waitcnt lgkmcnt(8)
	s_barrier
	s_waitcnt lgkmcnt(0)
	v_mfma_f32_16x16x32_bf16 v[124:127], v[144:147], v[170:173], v[124:127]
	v_mfma_f32_16x16x32_bf16 v[120:123], v[162:165], v[170:173], v[120:123]
	v_mfma_f32_16x16x32_bf16 v[108:111], v[144:147], v[178:181], v[108:111]
	v_mfma_f32_16x16x32_bf16 v[104:107], v[162:165], v[178:181], v[104:107]
	v_mfma_f32_16x16x32_bf16 v[92:95], v[144:147], v[186:189], v[92:95]
	v_mfma_f32_16x16x32_bf16 v[88:91], v[162:165], v[186:189], v[88:91]
	v_mfma_f32_16x16x32_bf16 v[76:79], v[144:147], v[194:197], v[76:79]
	v_mfma_f32_16x16x32_bf16 v[72:75], v[162:165], v[194:197], v[72:75]
	v_mfma_f32_16x16x32_bf16 v[124:127], v[156:159], v[174:177], v[124:127]
	v_mfma_f32_16x16x32_bf16 v[120:123], v[166:169], v[174:177], v[120:123]
	v_mfma_f32_16x16x32_bf16 v[108:111], v[156:159], v[182:185], v[108:111]
	v_mfma_f32_16x16x32_bf16 v[104:107], v[166:169], v[182:185], v[104:107]
	v_mfma_f32_16x16x32_bf16 v[92:95], v[156:159], v[190:193], v[92:95]
	v_mfma_f32_16x16x32_bf16 v[88:91], v[166:169], v[190:193], v[88:91]
	v_mfma_f32_16x16x32_bf16 v[76:79], v[156:159], v[198:201], v[76:79]
	v_mfma_f32_16x16x32_bf16 v[72:75], v[166:169], v[198:201], v[72:75]
	s_barrier
	s_add_i32 s28, 0, 0x1c000
	s_add_i32 s29, s55, s35
	v_add_u32_e32 v161, s28, v151
	s_mov_b32 m0, s29
	ds_read_b128 v[202:205], v161
	ds_read_b128 v[206:209], v161 offset:1024
	ds_read_b128 v[210:213], v161 offset:2048
	global_load_lds_dwordx4 v130, s[98:99]
	s_add_i32 m0, s29, 0x2000
	ds_read_b128 v[214:217], v161 offset:3072
	global_load_lds_dwordx4 v134, s[98:99]
	s_barrier
	s_waitcnt lgkmcnt(0)
	v_mfma_f32_16x16x32_bf16 v[116:119], v[202:205], v[170:173], v[116:119]
	v_mfma_f32_16x16x32_bf16 v[112:115], v[210:213], v[170:173], v[112:115]
	v_mfma_f32_16x16x32_bf16 v[100:103], v[202:205], v[178:181], v[100:103]
	v_mfma_f32_16x16x32_bf16 v[96:99], v[210:213], v[178:181], v[96:99]
	v_mfma_f32_16x16x32_bf16 v[84:87], v[202:205], v[186:189], v[84:87]
	v_mfma_f32_16x16x32_bf16 v[80:83], v[210:213], v[186:189], v[80:83]
	v_mfma_f32_16x16x32_bf16 v[68:71], v[202:205], v[194:197], v[68:71]
	v_mfma_f32_16x16x32_bf16 v[64:67], v[210:213], v[194:197], v[64:67]
	v_mfma_f32_16x16x32_bf16 v[116:119], v[206:209], v[174:177], v[116:119]
	v_mfma_f32_16x16x32_bf16 v[112:115], v[214:217], v[174:177], v[112:115]
	v_mfma_f32_16x16x32_bf16 v[100:103], v[206:209], v[182:185], v[100:103]
	v_mfma_f32_16x16x32_bf16 v[96:99], v[214:217], v[182:185], v[96:99]
	v_mfma_f32_16x16x32_bf16 v[84:87], v[206:209], v[190:193], v[84:87]
	v_mfma_f32_16x16x32_bf16 v[80:83], v[214:217], v[190:193], v[80:83]
	v_mfma_f32_16x16x32_bf16 v[68:71], v[206:209], v[198:201], v[68:71]
	v_mfma_f32_16x16x32_bf16 v[64:67], v[214:217], v[198:201], v[64:67]
	s_mov_b32 m0, s44
	s_barrier
	ds_read_b128 v[170:173], v154 offset:49152
	ds_read_b128 v[174:177], v154 offset:50176
	ds_read_b128 v[178:181], v154 offset:51200
	ds_read_b128 v[182:185], v154 offset:52224
	ds_read_b128 v[186:189], v154 offset:53248
	ds_read_b128 v[190:193], v154 offset:54272
	ds_read_b128 v[194:197], v154 offset:55296
	global_load_lds_dwordx4 v128, s[100:101]
	s_mov_b32 m0, s46
	ds_read_b128 v[198:201], v154 offset:56320
	global_load_lds_dwordx4 v132, s[100:101]
	s_barrier
	s_waitcnt lgkmcnt(0)
	v_mfma_f32_16x16x32_bf16 v[60:63], v[144:147], v[170:173], v[60:63]
	v_mfma_f32_16x16x32_bf16 v[56:59], v[162:165], v[170:173], v[56:59]
	v_mfma_f32_16x16x32_bf16 v[44:47], v[144:147], v[178:181], v[44:47]
	v_mfma_f32_16x16x32_bf16 v[40:43], v[162:165], v[178:181], v[40:43]
	v_mfma_f32_16x16x32_bf16 v[28:31], v[144:147], v[186:189], v[28:31]
	v_mfma_f32_16x16x32_bf16 v[24:27], v[162:165], v[186:189], v[24:27]
	v_mfma_f32_16x16x32_bf16 v[12:15], v[144:147], v[194:197], v[12:15]
	v_mfma_f32_16x16x32_bf16 v[8:11], v[162:165], v[194:197], v[8:11]
	v_mfma_f32_16x16x32_bf16 v[60:63], v[156:159], v[174:177], v[60:63]
	v_mfma_f32_16x16x32_bf16 v[56:59], v[166:169], v[174:177], v[56:59]
	v_mfma_f32_16x16x32_bf16 v[44:47], v[156:159], v[182:185], v[44:47]
	v_mfma_f32_16x16x32_bf16 v[40:43], v[166:169], v[182:185], v[40:43]
	v_mfma_f32_16x16x32_bf16 v[28:31], v[156:159], v[190:193], v[28:31]
	v_mfma_f32_16x16x32_bf16 v[24:27], v[166:169], v[190:193], v[24:27]
	v_mfma_f32_16x16x32_bf16 v[12:15], v[156:159], v[198:201], v[12:15]
	v_mfma_f32_16x16x32_bf16 v[8:11], v[166:169], v[198:201], v[8:11]
	s_barrier
	s_add_u32 s26, s26, 0x40080
	s_addc_u32 s27, s27, 0
	s_add_i32 s28, s28, s35
	s_mov_b32 m0, s28
	s_add_i32 s54, s54, 2
	global_load_lds_dwordx4 v130, s[26:27]
	s_add_i32 m0, s28, 0x2000
	s_add_u32 s24, s24, 0x100
	s_addc_u32 s25, s25, 0
	global_load_lds_dwordx4 v134, s[26:27]
	s_add_u32 s52, s52, 0x100
	s_addc_u32 s53, s53, 0
	s_waitcnt vmcnt(6)
	s_barrier
	v_mfma_f32_16x16x32_bf16 v[52:55], v[202:205], v[170:173], v[52:55]
	v_mfma_f32_16x16x32_bf16 v[48:51], v[210:213], v[170:173], v[48:51]
	v_mfma_f32_16x16x32_bf16 v[36:39], v[202:205], v[178:181], v[36:39]
	v_mfma_f32_16x16x32_bf16 v[32:35], v[210:213], v[178:181], v[32:35]
	v_mfma_f32_16x16x32_bf16 v[20:23], v[202:205], v[186:189], v[20:23]
	v_mfma_f32_16x16x32_bf16 v[16:19], v[210:213], v[186:189], v[16:19]
	v_mfma_f32_16x16x32_bf16 v[4:7], v[202:205], v[194:197], v[4:7]
	v_mfma_f32_16x16x32_bf16 v[0:3], v[210:213], v[194:197], v[0:3]
	v_mfma_f32_16x16x32_bf16 v[52:55], v[206:209], v[174:177], v[52:55]
	v_mfma_f32_16x16x32_bf16 v[48:51], v[214:217], v[174:177], v[48:51]
	v_mfma_f32_16x16x32_bf16 v[36:39], v[206:209], v[182:185], v[36:39]
	v_mfma_f32_16x16x32_bf16 v[32:35], v[214:217], v[182:185], v[32:35]
	v_mfma_f32_16x16x32_bf16 v[20:23], v[206:209], v[190:193], v[20:23]
	v_mfma_f32_16x16x32_bf16 v[16:19], v[214:217], v[190:193], v[16:19]
	v_mfma_f32_16x16x32_bf16 v[4:7], v[206:209], v[198:201], v[4:7]
	v_mfma_f32_16x16x32_bf16 v[0:3], v[214:217], v[198:201], v[0:3]
	s_cmp_gt_u32 s54, 13
	s_barrier
	s_cbranch_scc0 .LBB0_203
	v_lshl_or_b32 v148, s22, 8, v152
	v_cmp_lt_i32_e32 vcc, s50, v148
	s_and_saveexec_b64 s[22:23], vcc
	s_cbranch_execz .LBB0_206
	v_mul_f32_e32 v149, 0x3d372713, v126
	v_mul_f32_e32 v145, 0x3d372713, v120
	v_mul_f32_e32 v149, v126, v149
	v_mul_f32_e32 v156, 0x3d372713, v122
	v_mul_f32_e32 v145, v120, v145
	v_mul_f32_e32 v146, 0x3d372713, v125
	v_fma_f32 v149, v126, v149, v126
	v_mul_f32_e32 v156, v122, v156
	v_fma_f32 v145, v120, v145, v120
	v_mul_f32_e32 v146, v125, v146
	v_mul_f32_e32 v149, 0xc0135761, v149
	v_fma_f32 v156, v122, v156, v122
	v_mul_f32_e32 v145, 0xc0135761, v145
	v_fma_f32 v146, v125, v146, v125
	v_exp_f32_e32 v149, v149
	v_mul_f32_e32 v156, 0xc0135761, v156
	v_exp_f32_e32 v145, v145
	v_mul_f32_e32 v146, 0xc0135761, v146
	v_exp_f32_e32 v157, v156
	v_exp_f32_e32 v147, v146
	v_add_f32_e32 v149, 1.0, v149
	v_add_f32_e32 v145, 1.0, v145
	v_rcp_f32_e32 v156, v149
	v_add_f32_e32 v149, 1.0, v157
	v_mul_f32_e32 v157, 0x3d372713, v127
	v_mul_f32_e32 v144, 0x3d372713, v124
	v_rcp_f32_e32 v146, v145
	v_add_f32_e32 v145, 1.0, v147
	v_mul_f32_e32 v147, 0x3d372713, v121
	v_mul_f32_e32 v157, v127, v157
	v_mul_f32_e32 v158, 0x3d372713, v123
	v_mul_f32_e32 v144, v124, v144
	v_mul_f32_e32 v147, v121, v147
	v_fma_f32 v157, v127, v157, v127
	v_mul_f32_e32 v158, v123, v158
	v_fma_f32 v144, v124, v144, v124
	v_fma_f32 v147, v121, v147, v121
	v_mul_f32_e32 v157, 0xc0135761, v157
	v_fma_f32 v158, v123, v158, v123
	v_mul_f32_e32 v144, 0xc0135761, v144
	v_mul_f32_e32 v147, 0xc0135761, v147
	v_exp_f32_e32 v157, v157
	v_mul_f32_e32 v158, 0xc0135761, v158
	v_exp_f32_e32 v144, v144
	v_exp_f32_e32 v147, v147
	v_exp_f32_e32 v159, v158
	v_rcp_f32_e32 v158, v149
	v_add_f32_e32 v149, 1.0, v157
	v_add_f32_e32 v144, 1.0, v144
	v_add_f32_e32 v147, 1.0, v147
	v_rcp_f32_e32 v157, v149
	v_add_f32_e32 v149, 1.0, v159
	v_rcp_f32_e32 v144, v144
	v_rcp_f32_e32 v145, v145
	v_rcp_f32_e32 v159, v149
	v_rcp_f32_e32 v147, v147
	v_pk_mul_f32 v[126:127], v[126:127], v[156:157]
	v_pk_mul_f32 v[124:125], v[124:125], v[144:145]
	v_pk_mul_f32 v[122:123], v[122:123], v[158:159]
	v_pk_mul_f32 v[120:121], v[120:121], v[146:147]

.LBB0_321:
	ds_read_b128 v[144:147], v157
	ds_read_b128 v[148:151], v157 offset:1024
	ds_read_b128 v[164:167], v157 offset:2048
	ds_read_b128 v[168:171], v157 offset:3072
	s_add_u32 s4, s8, 0x100
	s_addc_u32 s5, s9, 0
	s_cmp_eq_u32 s60, 2
	s_cselect_b32 s11, s29, s5
	s_cselect_b32 s10, s28, s4
	s_cselect_b32 s7, s31, s37
	s_cselect_b32 s6, s30, s35
	s_add_i32 m0, s46, 0xc000
	ds_read_b128 v[172:175], v158
	ds_read_b128 v[176:179], v158 offset:1024
	ds_read_b128 v[180:183], v158 offset:2048
	ds_read_b128 v[184:187], v158 offset:3072
	ds_read_b128 v[188:191], v158 offset:4096
	ds_read_b128 v[192:195], v158 offset:5120
	ds_read_b128 v[196:199], v158 offset:6144
	global_load_lds_dwordx4 v136, s[8:9]
	s_add_i32 m0, s46, 0xe000
	ds_read_b128 v[200:203], v158 offset:7168
	global_load_lds_dwordx4 v138, s[8:9]
	s_waitcnt lgkmcnt(8)
	s_barrier
	s_waitcnt lgkmcnt(0)
	v_mfma_f32_16x16x32_bf16 v[124:127], v[144:147], v[172:175], v[124:127]
	v_mfma_f32_16x16x32_bf16 v[120:123], v[164:167], v[172:175], v[120:123]
	v_mfma_f32_16x16x32_bf16 v[116:119], v[144:147], v[180:183], v[116:119]
	v_mfma_f32_16x16x32_bf16 v[112:115], v[164:167], v[180:183], v[112:115]
	v_mfma_f32_16x16x32_bf16 v[108:111], v[144:147], v[188:191], v[108:111]
	v_mfma_f32_16x16x32_bf16 v[104:107], v[164:167], v[188:191], v[104:107]
	v_mfma_f32_16x16x32_bf16 v[100:103], v[144:147], v[196:199], v[100:103]
	v_mfma_f32_16x16x32_bf16 v[96:99], v[164:167], v[196:199], v[96:99]
	v_mfma_f32_16x16x32_bf16 v[124:127], v[148:151], v[176:179], v[124:127]
	v_mfma_f32_16x16x32_bf16 v[120:123], v[168:171], v[176:179], v[120:123]
	v_mfma_f32_16x16x32_bf16 v[116:119], v[148:151], v[184:187], v[116:119]
	v_mfma_f32_16x16x32_bf16 v[112:115], v[168:171], v[184:187], v[112:115]
	v_mfma_f32_16x16x32_bf16 v[108:111], v[148:151], v[192:195], v[108:111]
	v_mfma_f32_16x16x32_bf16 v[104:107], v[168:171], v[192:195], v[104:107]
	v_mfma_f32_16x16x32_bf16 v[100:103], v[148:151], v[200:203], v[100:103]
	v_mfma_f32_16x16x32_bf16 v[96:99], v[168:171], v[200:203], v[96:99]
	s_barrier
	s_add_i32 s8, s54, s44
	s_add_u32 s98, s6, s26
	s_addc_u32 s99, s7, s27
	s_mov_b32 m0, s8
	ds_read_b128 v[204:207], v159
	ds_read_b128 v[208:211], v159 offset:1024
	ds_read_b128 v[212:215], v159 offset:2048
	global_load_lds_dwordx4 v130, s[6:7]
	s_add_i32 m0, s8, 0x2000
	ds_read_b128 v[216:219], v159 offset:3072
	global_load_lds_dwordx4 v134, s[6:7]
	s_barrier
	s_waitcnt lgkmcnt(0)
	v_mfma_f32_16x16x32_bf16 v[60:63], v[204:207], v[172:175], v[60:63]
	v_mfma_f32_16x16x32_bf16 v[56:59], v[212:215], v[172:175], v[56:59]
	v_mfma_f32_16x16x32_bf16 v[52:55], v[204:207], v[180:183], v[52:55]
	v_mfma_f32_16x16x32_bf16 v[48:51], v[212:215], v[180:183], v[48:51]
	v_mfma_f32_16x16x32_bf16 v[44:47], v[204:207], v[188:191], v[44:47]
	v_mfma_f32_16x16x32_bf16 v[40:43], v[212:215], v[188:191], v[40:43]
	v_mfma_f32_16x16x32_bf16 v[36:39], v[204:207], v[196:199], v[36:39]
	v_mfma_f32_16x16x32_bf16 v[32:35], v[212:215], v[196:199], v[32:35]
	v_mfma_f32_16x16x32_bf16 v[60:63], v[208:211], v[176:179], v[60:63]
	v_mfma_f32_16x16x32_bf16 v[56:59], v[216:219], v[176:179], v[56:59]
	v_mfma_f32_16x16x32_bf16 v[52:55], v[208:211], v[184:187], v[52:55]
	v_mfma_f32_16x16x32_bf16 v[48:51], v[216:219], v[184:187], v[48:51]
	v_mfma_f32_16x16x32_bf16 v[44:47], v[208:211], v[192:195], v[44:47]
	v_mfma_f32_16x16x32_bf16 v[40:43], v[216:219], v[192:195], v[40:43]
	v_mfma_f32_16x16x32_bf16 v[36:39], v[208:211], v[200:203], v[36:39]
	v_mfma_f32_16x16x32_bf16 v[32:35], v[216:219], v[200:203], v[32:35]
	s_mov_b32 m0, s46
	s_add_u32 s100, s10, s26
	s_addc_u32 s101, s11, s27
	s_barrier
	ds_read_b128 v[172:175], v158 offset:16384
	ds_read_b128 v[176:179], v158 offset:17408
	ds_read_b128 v[180:183], v158 offset:18432
	ds_read_b128 v[184:187], v158 offset:19456
	ds_read_b128 v[188:191], v158 offset:20480
	ds_read_b128 v[192:195], v158 offset:21504
	ds_read_b128 v[196:199], v158 offset:22528
	global_load_lds_dwordx4 v128, s[10:11]
	s_mov_b32 m0, s47
	ds_read_b128 v[200:203], v158 offset:23552
	global_load_lds_dwordx4 v132, s[10:11]
	s_barrier
	s_waitcnt lgkmcnt(0)
	v_mfma_f32_16x16x32_bf16 v[92:95], v[144:147], v[172:175], v[92:95]
	v_mfma_f32_16x16x32_bf16 v[88:91], v[164:167], v[172:175], v[88:91]
	v_mfma_f32_16x16x32_bf16 v[84:87], v[144:147], v[180:183], v[84:87]
	v_mfma_f32_16x16x32_bf16 v[80:83], v[164:167], v[180:183], v[80:83]
	v_mfma_f32_16x16x32_bf16 v[76:79], v[144:147], v[188:191], v[76:79]
	v_mfma_f32_16x16x32_bf16 v[72:75], v[164:167], v[188:191], v[72:75]
	v_mfma_f32_16x16x32_bf16 v[68:71], v[144:147], v[196:199], v[68:71]
	v_mfma_f32_16x16x32_bf16 v[64:67], v[164:167], v[196:199], v[64:67]
	v_mfma_f32_16x16x32_bf16 v[92:95], v[148:151], v[176:179], v[92:95]
	v_mfma_f32_16x16x32_bf16 v[88:91], v[168:171], v[176:179], v[88:91]
	v_mfma_f32_16x16x32_bf16 v[84:87], v[148:151], v[184:187], v[84:87]
	v_mfma_f32_16x16x32_bf16 v[80:83], v[168:171], v[184:187], v[80:83]
	v_mfma_f32_16x16x32_bf16 v[76:79], v[148:151], v[192:195], v[76:79]
	v_mfma_f32_16x16x32_bf16 v[72:75], v[168:171], v[192:195], v[72:75]
	v_mfma_f32_16x16x32_bf16 v[68:71], v[148:151], v[200:203], v[68:71]
	v_mfma_f32_16x16x32_bf16 v[64:67], v[168:171], v[200:203], v[64:67]
	s_barrier
	s_add_u32 s8, s6, 0x18000
	s_addc_u32 s9, s7, 0
	s_add_i32 s61, s55, s44
	s_mov_b32 m0, s61
	s_nop 0
	global_load_lds_dwordx4 v130, s[8:9]
	s_add_i32 m0, s61, 0x2000
	s_nop 0
	global_load_lds_dwordx4 v134, s[8:9]
	s_waitcnt vmcnt(6)
	s_barrier
	v_mfma_f32_16x16x32_bf16 v[28:31], v[204:207], v[172:175], v[28:31]
	v_mfma_f32_16x16x32_bf16 v[24:27], v[212:215], v[172:175], v[24:27]
	v_mfma_f32_16x16x32_bf16 v[20:23], v[204:207], v[180:183], v[20:23]
	v_mfma_f32_16x16x32_bf16 v[16:19], v[212:215], v[180:183], v[16:19]
	v_mfma_f32_16x16x32_bf16 v[12:15], v[204:207], v[188:191], v[12:15]
	v_mfma_f32_16x16x32_bf16 v[8:11], v[212:215], v[188:191], v[8:11]
	v_mfma_f32_16x16x32_bf16 v[4:7], v[204:207], v[196:199], v[4:7]
	v_mfma_f32_16x16x32_bf16 v[0:3], v[212:215], v[196:199], v[0:3]
	v_mfma_f32_16x16x32_bf16 v[28:31], v[208:211], v[176:179], v[28:31]
	v_mfma_f32_16x16x32_bf16 v[24:27], v[216:219], v[176:179], v[24:27]
	v_mfma_f32_16x16x32_bf16 v[20:23], v[208:211], v[184:187], v[20:23]
	v_mfma_f32_16x16x32_bf16 v[16:19], v[216:219], v[184:187], v[16:19]
	v_mfma_f32_16x16x32_bf16 v[12:15], v[208:211], v[192:195], v[12:15]
	v_mfma_f32_16x16x32_bf16 v[8:11], v[216:219], v[192:195], v[8:11]
	v_mfma_f32_16x16x32_bf16 v[4:7], v[208:211], v[200:203], v[4:7]
	v_mfma_f32_16x16x32_bf16 v[0:3], v[216:219], v[200:203], v[0:3]
	s_add_i32 s61, 0, 0x18000
	v_add_u32_e32 v163, s61, v155
	s_barrier
	ds_read_b128 v[144:147], v163
	ds_read_b128 v[148:151], v163 offset:1024
	ds_read_b128 v[164:167], v163 offset:2048
	ds_read_b128 v[168:171], v163 offset:3072
	s_add_u32 s8, s10, 0x18000
	s_addc_u32 s9, s11, 0
	s_mov_b32 m0, s48
	ds_read_b128 v[172:175], v158 offset:32768
	ds_read_b128 v[176:179], v158 offset:33792
	ds_read_b128 v[180:183], v158 offset:34816
	ds_read_b128 v[184:187], v158 offset:35840
	ds_read_b128 v[188:191], v158 offset:36864
	ds_read_b128 v[192:195], v158 offset:37888
	ds_read_b128 v[196:199], v158 offset:38912
	global_load_lds_dwordx4 v128, s[8:9]
	s_mov_b32 m0, s49
	ds_read_b128 v[200:203], v158 offset:39936
	global_load_lds_dwordx4 v132, s[8:9]
	s_waitcnt lgkmcnt(8)
	s_barrier
	s_waitcnt lgkmcnt(0)
	v_mfma_f32_16x16x32_bf16 v[124:127], v[144:147], v[172:175], v[124:127]
	v_mfma_f32_16x16x32_bf16 v[120:123], v[164:167], v[172:175], v[120:123]
	v_mfma_f32_16x16x32_bf16 v[116:119], v[144:147], v[180:183], v[116:119]
	v_mfma_f32_16x16x32_bf16 v[112:115], v[164:167], v[180:183], v[112:115]
	v_mfma_f32_16x16x32_bf16 v[108:111], v[144:147], v[188:191], v[108:111]
	v_mfma_f32_16x16x32_bf16 v[104:107], v[164:167], v[188:191], v[104:107]
	v_mfma_f32_16x16x32_bf16 v[100:103], v[144:147], v[196:199], v[100:103]
	v_mfma_f32_16x16x32_bf16 v[96:99], v[164:167], v[196:199], v[96:99]
	v_mfma_f32_16x16x32_bf16 v[124:127], v[148:151], v[176:179], v[124:127]
	v_mfma_f32_16x16x32_bf16 v[120:123], v[168:171], v[176:179], v[120:123]
	v_mfma_f32_16x16x32_bf16 v[116:119], v[148:151], v[184:187], v[116:119]
	v_mfma_f32_16x16x32_bf16 v[112:115], v[168:171], v[184:187], v[112:115]
	v_mfma_f32_16x16x32_bf16 v[108:111], v[148:151], v[192:195], v[108:111]
	v_mfma_f32_16x16x32_bf16 v[104:107], v[168:171], v[192:195], v[104:107]
	v_mfma_f32_16x16x32_bf16 v[100:103], v[148:151], v[200:203], v[100:103]
	v_mfma_f32_16x16x32_bf16 v[96:99], v[168:171], v[200:203], v[96:99]
	s_barrier
	s_add_i32 s8, 0, 0x1c000
	s_add_i32 s9, s61, s44
	v_add_u32_e32 v163, s8, v155
	s_mov_b32 m0, s9
	ds_read_b128 v[204:207], v163
	ds_read_b128 v[208:211], v163 offset:1024
	ds_read_b128 v[212:215], v163 offset:2048
	global_load_lds_dwordx4 v130, s[98:99]
	s_add_i32 m0, s9, 0x2000
	ds_read_b128 v[216:219], v163 offset:3072
	global_load_lds_dwordx4 v134, s[98:99]
	s_barrier
	s_waitcnt lgkmcnt(0)
	v_mfma_f32_16x16x32_bf16 v[60:63], v[204:207], v[172:175], v[60:63]
	v_mfma_f32_16x16x32_bf16 v[56:59], v[212:215], v[172:175], v[56:59]
	v_mfma_f32_16x16x32_bf16 v[52:55], v[204:207], v[180:183], v[52:55]
	v_mfma_f32_16x16x32_bf16 v[48:51], v[212:215], v[180:183], v[48:51]
	v_mfma_f32_16x16x32_bf16 v[44:47], v[204:207], v[188:191], v[44:47]
	v_mfma_f32_16x16x32_bf16 v[40:43], v[212:215], v[188:191], v[40:43]
	v_mfma_f32_16x16x32_bf16 v[36:39], v[204:207], v[196:199], v[36:39]
	v_mfma_f32_16x16x32_bf16 v[32:35], v[212:215], v[196:199], v[32:35]
	v_mfma_f32_16x16x32_bf16 v[60:63], v[208:211], v[176:179], v[60:63]
	v_mfma_f32_16x16x32_bf16 v[56:59], v[216:219], v[176:179], v[56:59]
	v_mfma_f32_16x16x32_bf16 v[52:55], v[208:211], v[184:187], v[52:55]
	v_mfma_f32_16x16x32_bf16 v[48:51], v[216:219], v[184:187], v[48:51]
	v_mfma_f32_16x16x32_bf16 v[44:47], v[208:211], v[192:195], v[44:47]
	v_mfma_f32_16x16x32_bf16 v[40:43], v[216:219], v[192:195], v[40:43]
	v_mfma_f32_16x16x32_bf16 v[36:39], v[208:211], v[200:203], v[36:39]
	v_mfma_f32_16x16x32_bf16 v[32:35], v[216:219], v[200:203], v[32:35]
	s_mov_b32 m0, s51
	s_barrier
	ds_read_b128 v[172:175], v158 offset:49152
	ds_read_b128 v[176:179], v158 offset:50176
	ds_read_b128 v[180:183], v158 offset:51200
	ds_read_b128 v[184:187], v158 offset:52224
	ds_read_b128 v[188:191], v158 offset:53248
	ds_read_b128 v[192:195], v158 offset:54272
	ds_read_b128 v[196:199], v158 offset:55296
	global_load_lds_dwordx4 v128, s[100:101]
	s_mov_b32 m0, s52
	ds_read_b128 v[200:203], v158 offset:56320
	global_load_lds_dwordx4 v132, s[100:101]
	s_barrier
	s_waitcnt lgkmcnt(0)
	v_mfma_f32_16x16x32_bf16 v[92:95], v[144:147], v[172:175], v[92:95]
	v_mfma_f32_16x16x32_bf16 v[88:91], v[164:167], v[172:175], v[88:91]
	v_mfma_f32_16x16x32_bf16 v[84:87], v[144:147], v[180:183], v[84:87]
	v_mfma_f32_16x16x32_bf16 v[80:83], v[164:167], v[180:183], v[80:83]
	v_mfma_f32_16x16x32_bf16 v[76:79], v[144:147], v[188:191], v[76:79]
	v_mfma_f32_16x16x32_bf16 v[72:75], v[164:167], v[188:191], v[72:75]
	v_mfma_f32_16x16x32_bf16 v[68:71], v[144:147], v[196:199], v[68:71]
	v_mfma_f32_16x16x32_bf16 v[64:67], v[164:167], v[196:199], v[64:67]
	v_mfma_f32_16x16x32_bf16 v[92:95], v[148:151], v[176:179], v[92:95]
	v_mfma_f32_16x16x32_bf16 v[88:91], v[168:171], v[176:179], v[88:91]
	v_mfma_f32_16x16x32_bf16 v[84:87], v[148:151], v[184:187], v[84:87]
	v_mfma_f32_16x16x32_bf16 v[80:83], v[168:171], v[184:187], v[80:83]
	v_mfma_f32_16x16x32_bf16 v[76:79], v[148:151], v[192:195], v[76:79]
	v_mfma_f32_16x16x32_bf16 v[72:75], v[168:171], v[192:195], v[72:75]
	v_mfma_f32_16x16x32_bf16 v[68:71], v[148:151], v[200:203], v[68:71]
	v_mfma_f32_16x16x32_bf16 v[64:67], v[168:171], v[200:203], v[64:67]
	s_barrier
	s_add_u32 s6, s6, 0x18080
	s_addc_u32 s7, s7, 0
	s_add_i32 s8, s8, s44
	s_mov_b32 m0, s8
	s_add_i32 s60, s60, 2
	global_load_lds_dwordx4 v130, s[6:7]
	s_add_i32 m0, s8, 0x2000
	s_add_u32 s35, s35, 0x100
	s_addc_u32 s37, s37, 0
	global_load_lds_dwordx4 v134, s[6:7]
	s_mov_b64 s[8:9], s[4:5]
	s_waitcnt vmcnt(6)
	s_barrier
	v_mfma_f32_16x16x32_bf16 v[28:31], v[204:207], v[172:175], v[28:31]
	v_mfma_f32_16x16x32_bf16 v[24:27], v[212:215], v[172:175], v[24:27]
	v_mfma_f32_16x16x32_bf16 v[20:23], v[204:207], v[180:183], v[20:23]
	v_mfma_f32_16x16x32_bf16 v[16:19], v[212:215], v[180:183], v[16:19]
	v_mfma_f32_16x16x32_bf16 v[12:15], v[204:207], v[188:191], v[12:15]
	v_mfma_f32_16x16x32_bf16 v[8:11], v[212:215], v[188:191], v[8:11]
	v_mfma_f32_16x16x32_bf16 v[4:7], v[204:207], v[196:199], v[4:7]
	v_mfma_f32_16x16x32_bf16 v[0:3], v[212:215], v[196:199], v[0:3]
	v_mfma_f32_16x16x32_bf16 v[28:31], v[208:211], v[176:179], v[28:31]
	v_mfma_f32_16x16x32_bf16 v[24:27], v[216:219], v[176:179], v[24:27]
	v_mfma_f32_16x16x32_bf16 v[20:23], v[208:211], v[184:187], v[20:23]
	v_mfma_f32_16x16x32_bf16 v[16:19], v[216:219], v[184:187], v[16:19]
	v_mfma_f32_16x16x32_bf16 v[12:15], v[208:211], v[192:195], v[12:15]
	v_mfma_f32_16x16x32_bf16 v[8:11], v[216:219], v[192:195], v[8:11]
	v_mfma_f32_16x16x32_bf16 v[4:7], v[208:211], v[200:203], v[4:7]
	v_mfma_f32_16x16x32_bf16 v[0:3], v[216:219], v[200:203], v[0:3]
	s_cmp_gt_u32 s60, 3
	s_barrier
	s_cbranch_scc0 .LBB0_321
	s_lshl_b32 s37, s34, 8
	s_ashr_i32 s6, s34, 1
	s_cmp_lt_i32 s6, 2
	s_cselect_b64 s[8:9], -1, 0
	s_cmp_gt_i32 s6, 1
	s_cselect_b64 s[34:35], -1, 0
	s_lshl_b32 s60, s6, 9
	s_add_i32 s61, s60, 0xfffffc00
	v_bitop3_b32 v144, s37, v161, v156 bitop3:0xc8
	v_or_b32_e32 v146, s61, v144
	v_or_b32_e32 v144, s60, v144
	v_mov_b32_e32 v145, 0
	s_cmp_lt_i32 s6, 4
	v_cndmask_b32_e64 v152, v146, v144, s[8:9]
	s_cselect_b64 s[4:5], -1, 0
	s_cmp_gt_i32 s6, 3
	v_ashrrev_i32_e32 v153, 31, v152
	v_mov_b32_e32 v144, v145
	s_cbranch_scc1 .LBB0_330
	s_and_b64 s[10:11], s[8:9], exec
	s_cselect_b32 s7, s21, s23
	s_cselect_b32 s10, s20, s22
	v_mov_b32_e32 v146, s10
	v_mov_b32_e32 v147, s7
	v_lshl_add_u64 v[146:147], v[152:153], 2, v[146:147]
	global_load_dword v144, v[146:147], off
	v_cndmask_b32_e64 v146, 0, 1, s[4:5]
	v_cmp_ne_u32_e64 s[10:11], 1, v146
	s_andn2_b64 vcc, exec, s[4:5]
	s_cbranch_vccz .LBB0_331

.LBB0_583:
	ds_read_b128 v[128:131], v164
	ds_read_b128 v[132:135], v164 offset:1024
	ds_read_b128 v[152:155], v164 offset:2048
	ds_read_b128 v[156:159], v164 offset:3072
	s_add_u32 s38, s36, 0xfffc0080
	s_addc_u32 s39, s37, -1
	s_cmp_eq_u32 s63, 12
	s_cselect_b32 s41, s9, s39
	s_cselect_b32 s40, s29, s38
	s_cselect_b32 s39, s27, s62
	s_cselect_b32 s38, s60, s61
	s_add_i32 m0, s50, 0xc000
	ds_read_b128 v[168:171], v165
	ds_read_b128 v[172:175], v165 offset:1024
	ds_read_b128 v[176:179], v165 offset:2048
	ds_read_b128 v[180:183], v165 offset:3072
	ds_read_b128 v[184:187], v165 offset:4096
	ds_read_b128 v[188:191], v165 offset:5120
	ds_read_b128 v[192:195], v165 offset:6144
	global_load_lds_dwordx4 v144, s[36:37]
	s_add_i32 m0, s50, 0xe000
	ds_read_b128 v[196:199], v165 offset:7168
	global_load_lds_dwordx4 v146, s[36:37]
	s_waitcnt lgkmcnt(8)
	s_barrier
	s_waitcnt lgkmcnt(0)
	v_mfma_f32_16x16x32_bf16 v[120:123], v[128:131], v[168:171], v[120:123]
	v_mfma_f32_16x16x32_bf16 v[124:127], v[152:155], v[168:171], v[124:127]
	v_mfma_f32_16x16x32_bf16 v[104:107], v[128:131], v[176:179], v[104:107]
	v_mfma_f32_16x16x32_bf16 v[108:111], v[152:155], v[176:179], v[108:111]
	v_mfma_f32_16x16x32_bf16 v[88:91], v[128:131], v[184:187], v[88:91]
	v_mfma_f32_16x16x32_bf16 v[92:95], v[152:155], v[184:187], v[92:95]
	v_mfma_f32_16x16x32_bf16 v[72:75], v[128:131], v[192:195], v[72:75]
	v_mfma_f32_16x16x32_bf16 v[76:79], v[152:155], v[192:195], v[76:79]
	v_mfma_f32_16x16x32_bf16 v[120:123], v[132:135], v[172:175], v[120:123]
	v_mfma_f32_16x16x32_bf16 v[124:127], v[156:159], v[172:175], v[124:127]
	v_mfma_f32_16x16x32_bf16 v[104:107], v[132:135], v[180:183], v[104:107]
	v_mfma_f32_16x16x32_bf16 v[108:111], v[156:159], v[180:183], v[108:111]
	v_mfma_f32_16x16x32_bf16 v[88:91], v[132:135], v[188:191], v[88:91]
	v_mfma_f32_16x16x32_bf16 v[92:95], v[156:159], v[188:191], v[92:95]
	v_mfma_f32_16x16x32_bf16 v[72:75], v[132:135], v[196:199], v[72:75]
	v_mfma_f32_16x16x32_bf16 v[76:79], v[156:159], v[196:199], v[76:79]
	s_barrier
	s_add_i32 s64, s57, s49
	s_add_u32 s98, s38, s22
	s_addc_u32 s99, s39, s23
	s_mov_b32 m0, s64
	ds_read_b128 v[200:203], v166
	ds_read_b128 v[204:207], v166 offset:1024
	ds_read_b128 v[208:211], v166 offset:2048
	global_load_lds_dwordx4 v138, s[38:39]
	s_add_i32 m0, s64, 0x2000
	ds_read_b128 v[212:215], v166 offset:3072
	global_load_lds_dwordx4 v142, s[38:39]
	s_barrier
	s_waitcnt lgkmcnt(0)
	v_mfma_f32_16x16x32_bf16 v[112:115], v[200:203], v[168:171], v[112:115]
	v_mfma_f32_16x16x32_bf16 v[116:119], v[208:211], v[168:171], v[116:119]
	v_mfma_f32_16x16x32_bf16 v[96:99], v[200:203], v[176:179], v[96:99]
	v_mfma_f32_16x16x32_bf16 v[100:103], v[208:211], v[176:179], v[100:103]
	v_mfma_f32_16x16x32_bf16 v[80:83], v[200:203], v[184:187], v[80:83]
	v_mfma_f32_16x16x32_bf16 v[84:87], v[208:211], v[184:187], v[84:87]
	v_mfma_f32_16x16x32_bf16 v[64:67], v[200:203], v[192:195], v[64:67]
	v_mfma_f32_16x16x32_bf16 v[68:71], v[208:211], v[192:195], v[68:71]
	v_mfma_f32_16x16x32_bf16 v[112:115], v[204:207], v[172:175], v[112:115]
	v_mfma_f32_16x16x32_bf16 v[116:119], v[212:215], v[172:175], v[116:119]
	v_mfma_f32_16x16x32_bf16 v[96:99], v[204:207], v[180:183], v[96:99]
	v_mfma_f32_16x16x32_bf16 v[100:103], v[212:215], v[180:183], v[100:103]
	v_mfma_f32_16x16x32_bf16 v[80:83], v[204:207], v[188:191], v[80:83]
	v_mfma_f32_16x16x32_bf16 v[84:87], v[212:215], v[188:191], v[84:87]
	v_mfma_f32_16x16x32_bf16 v[64:67], v[204:207], v[196:199], v[64:67]
	v_mfma_f32_16x16x32_bf16 v[68:71], v[212:215], v[196:199], v[68:71]
	s_mov_b32 m0, s50
	s_add_u32 s100, s40, s22
	s_addc_u32 s101, s41, s23
	s_barrier
	ds_read_b128 v[168:171], v165 offset:16384
	ds_read_b128 v[172:175], v165 offset:17408
	ds_read_b128 v[176:179], v165 offset:18432
	ds_read_b128 v[180:183], v165 offset:19456
	ds_read_b128 v[184:187], v165 offset:20480
	ds_read_b128 v[188:191], v165 offset:21504
	ds_read_b128 v[192:195], v165 offset:22528
	global_load_lds_dwordx4 v136, s[40:41]
	s_mov_b32 m0, s51
	ds_read_b128 v[196:199], v165 offset:23552
	global_load_lds_dwordx4 v140, s[40:41]
	s_barrier
	s_waitcnt lgkmcnt(0)
	v_mfma_f32_16x16x32_bf16 v[56:59], v[128:131], v[168:171], v[56:59]
	v_mfma_f32_16x16x32_bf16 v[60:63], v[152:155], v[168:171], v[60:63]
	v_mfma_f32_16x16x32_bf16 v[40:43], v[128:131], v[176:179], v[40:43]
	v_mfma_f32_16x16x32_bf16 v[44:47], v[152:155], v[176:179], v[44:47]
	v_mfma_f32_16x16x32_bf16 v[24:27], v[128:131], v[184:187], v[24:27]
	v_mfma_f32_16x16x32_bf16 v[28:31], v[152:155], v[184:187], v[28:31]
	v_mfma_f32_16x16x32_bf16 v[8:11], v[128:131], v[192:195], v[8:11]
	v_mfma_f32_16x16x32_bf16 v[12:15], v[152:155], v[192:195], v[12:15]
	v_mfma_f32_16x16x32_bf16 v[56:59], v[132:135], v[172:175], v[56:59]
	v_mfma_f32_16x16x32_bf16 v[60:63], v[156:159], v[172:175], v[60:63]
	v_mfma_f32_16x16x32_bf16 v[40:43], v[132:135], v[180:183], v[40:43]
	v_mfma_f32_16x16x32_bf16 v[44:47], v[156:159], v[180:183], v[44:47]
	v_mfma_f32_16x16x32_bf16 v[24:27], v[132:135], v[188:191], v[24:27]
	v_mfma_f32_16x16x32_bf16 v[28:31], v[156:159], v[188:191], v[28:31]
	v_mfma_f32_16x16x32_bf16 v[8:11], v[132:135], v[196:199], v[8:11]
	v_mfma_f32_16x16x32_bf16 v[12:15], v[156:159], v[196:199], v[12:15]
	s_barrier
	s_add_u32 s64, s38, 0x40000
	s_addc_u32 s65, s39, 0
	s_add_i32 s66, s58, s49
	s_mov_b32 m0, s66
	s_nop 0
	global_load_lds_dwordx4 v138, s[64:65]
	s_add_i32 m0, s66, 0x2000
	s_nop 0
	global_load_lds_dwordx4 v142, s[64:65]
	s_waitcnt vmcnt(6)
	s_barrier
	v_mfma_f32_16x16x32_bf16 v[48:51], v[200:203], v[168:171], v[48:51]
	v_mfma_f32_16x16x32_bf16 v[52:55], v[208:211], v[168:171], v[52:55]
	v_mfma_f32_16x16x32_bf16 v[32:35], v[200:203], v[176:179], v[32:35]
	v_mfma_f32_16x16x32_bf16 v[36:39], v[208:211], v[176:179], v[36:39]
	v_mfma_f32_16x16x32_bf16 v[16:19], v[200:203], v[184:187], v[16:19]
	v_mfma_f32_16x16x32_bf16 v[20:23], v[208:211], v[184:187], v[20:23]
	v_mfma_f32_16x16x32_bf16 v[4:7], v[200:203], v[192:195], v[4:7]
	v_mfma_f32_16x16x32_bf16 v[0:3], v[208:211], v[192:195], v[0:3]
	v_mfma_f32_16x16x32_bf16 v[48:51], v[204:207], v[172:175], v[48:51]
	v_mfma_f32_16x16x32_bf16 v[52:55], v[212:215], v[172:175], v[52:55]
	v_mfma_f32_16x16x32_bf16 v[32:35], v[204:207], v[180:183], v[32:35]
	v_mfma_f32_16x16x32_bf16 v[36:39], v[212:215], v[180:183], v[36:39]
	v_mfma_f32_16x16x32_bf16 v[16:19], v[204:207], v[188:191], v[16:19]
	v_mfma_f32_16x16x32_bf16 v[20:23], v[212:215], v[188:191], v[20:23]
	v_mfma_f32_16x16x32_bf16 v[4:7], v[204:207], v[196:199], v[4:7]
	v_mfma_f32_16x16x32_bf16 v[0:3], v[212:215], v[196:199], v[0:3]
	s_add_i32 s64, 0, 0x18000
	v_add_u32_e32 v156, s64, v162
	s_barrier
	ds_read_b128 v[128:131], v156
	ds_read_b128 v[132:135], v156 offset:1024
	ds_read_b128 v[152:155], v156 offset:2048
	ds_read_b128 v[156:159], v156 offset:3072
	s_add_u32 s40, s40, 0x40000
	s_addc_u32 s41, s41, 0
	s_mov_b32 m0, s52
	ds_read_b128 v[168:171], v165 offset:32768
	ds_read_b128 v[172:175], v165 offset:33792
	ds_read_b128 v[176:179], v165 offset:34816
	ds_read_b128 v[180:183], v165 offset:35840
	ds_read_b128 v[184:187], v165 offset:36864
	ds_read_b128 v[188:191], v165 offset:37888
	ds_read_b128 v[192:195], v165 offset:38912
	global_load_lds_dwordx4 v136, s[40:41]
	s_mov_b32 m0, s53
	ds_read_b128 v[196:199], v165 offset:39936
	global_load_lds_dwordx4 v140, s[40:41]
	s_waitcnt lgkmcnt(8)
	s_barrier
	s_waitcnt lgkmcnt(0)
	v_mfma_f32_16x16x32_bf16 v[120:123], v[128:131], v[168:171], v[120:123]
	v_mfma_f32_16x16x32_bf16 v[124:127], v[152:155], v[168:171], v[124:127]
	v_mfma_f32_16x16x32_bf16 v[104:107], v[128:131], v[176:179], v[104:107]
	v_mfma_f32_16x16x32_bf16 v[108:111], v[152:155], v[176:179], v[108:111]
	v_mfma_f32_16x16x32_bf16 v[88:91], v[128:131], v[184:187], v[88:91]
	v_mfma_f32_16x16x32_bf16 v[92:95], v[152:155], v[184:187], v[92:95]
	v_mfma_f32_16x16x32_bf16 v[72:75], v[128:131], v[192:195], v[72:75]
	v_mfma_f32_16x16x32_bf16 v[76:79], v[152:155], v[192:195], v[76:79]
	v_mfma_f32_16x16x32_bf16 v[120:123], v[132:135], v[172:175], v[120:123]
	v_mfma_f32_16x16x32_bf16 v[124:127], v[156:159], v[172:175], v[124:127]
	v_mfma_f32_16x16x32_bf16 v[104:107], v[132:135], v[180:183], v[104:107]
	v_mfma_f32_16x16x32_bf16 v[108:111], v[156:159], v[180:183], v[108:111]
	v_mfma_f32_16x16x32_bf16 v[88:91], v[132:135], v[188:191], v[88:91]
	v_mfma_f32_16x16x32_bf16 v[92:95], v[156:159], v[188:191], v[92:95]
	v_mfma_f32_16x16x32_bf16 v[72:75], v[132:135], v[196:199], v[72:75]
	v_mfma_f32_16x16x32_bf16 v[76:79], v[156:159], v[196:199], v[76:79]
	s_barrier
	s_add_i32 s40, 0, 0x1c000
	s_add_i32 s41, s64, s49
	v_add_u32_e32 v212, s40, v162
	s_mov_b32 m0, s41
	ds_read_b128 v[200:203], v212
	ds_read_b128 v[204:207], v212 offset:1024
	ds_read_b128 v[208:211], v212 offset:2048
	global_load_lds_dwordx4 v138, s[98:99]
	s_add_i32 m0, s41, 0x2000
	ds_read_b128 v[212:215], v212 offset:3072
	global_load_lds_dwordx4 v142, s[98:99]
	s_barrier
	s_waitcnt lgkmcnt(0)
	v_mfma_f32_16x16x32_bf16 v[112:115], v[200:203], v[168:171], v[112:115]
	v_mfma_f32_16x16x32_bf16 v[116:119], v[208:211], v[168:171], v[116:119]
	v_mfma_f32_16x16x32_bf16 v[96:99], v[200:203], v[176:179], v[96:99]
	v_mfma_f32_16x16x32_bf16 v[100:103], v[208:211], v[176:179], v[100:103]
	v_mfma_f32_16x16x32_bf16 v[80:83], v[200:203], v[184:187], v[80:83]
	v_mfma_f32_16x16x32_bf16 v[84:87], v[208:211], v[184:187], v[84:87]
	v_mfma_f32_16x16x32_bf16 v[64:67], v[200:203], v[192:195], v[64:67]
	v_mfma_f32_16x16x32_bf16 v[68:71], v[208:211], v[192:195], v[68:71]
	v_mfma_f32_16x16x32_bf16 v[112:115], v[204:207], v[172:175], v[112:115]
	v_mfma_f32_16x16x32_bf16 v[116:119], v[212:215], v[172:175], v[116:119]
	v_mfma_f32_16x16x32_bf16 v[96:99], v[204:207], v[180:183], v[96:99]
	v_mfma_f32_16x16x32_bf16 v[100:103], v[212:215], v[180:183], v[100:103]
	v_mfma_f32_16x16x32_bf16 v[80:83], v[204:207], v[188:191], v[80:83]
	v_mfma_f32_16x16x32_bf16 v[84:87], v[212:215], v[188:191], v[84:87]
	v_mfma_f32_16x16x32_bf16 v[64:67], v[204:207], v[196:199], v[64:67]
	v_mfma_f32_16x16x32_bf16 v[68:71], v[212:215], v[196:199], v[68:71]
	s_mov_b32 m0, s55
	s_barrier
	ds_read_b128 v[168:171], v165 offset:49152
	ds_read_b128 v[172:175], v165 offset:50176
	ds_read_b128 v[176:179], v165 offset:51200
	ds_read_b128 v[180:183], v165 offset:52224
	ds_read_b128 v[184:187], v165 offset:53248
	ds_read_b128 v[188:191], v165 offset:54272
	ds_read_b128 v[192:195], v165 offset:55296
	global_load_lds_dwordx4 v136, s[100:101]
	s_mov_b32 m0, s56
	ds_read_b128 v[196:199], v165 offset:56320
	global_load_lds_dwordx4 v140, s[100:101]
	s_barrier
	s_waitcnt lgkmcnt(0)
	v_mfma_f32_16x16x32_bf16 v[56:59], v[128:131], v[168:171], v[56:59]
	v_mfma_f32_16x16x32_bf16 v[60:63], v[152:155], v[168:171], v[60:63]
	v_mfma_f32_16x16x32_bf16 v[40:43], v[128:131], v[176:179], v[40:43]
	v_mfma_f32_16x16x32_bf16 v[44:47], v[152:155], v[176:179], v[44:47]
	v_mfma_f32_16x16x32_bf16 v[24:27], v[128:131], v[184:187], v[24:27]
	v_mfma_f32_16x16x32_bf16 v[28:31], v[152:155], v[184:187], v[28:31]
	v_mfma_f32_16x16x32_bf16 v[8:11], v[128:131], v[192:195], v[8:11]
	v_mfma_f32_16x16x32_bf16 v[12:15], v[152:155], v[192:195], v[12:15]
	v_mfma_f32_16x16x32_bf16 v[56:59], v[132:135], v[172:175], v[56:59]
	v_mfma_f32_16x16x32_bf16 v[60:63], v[156:159], v[172:175], v[60:63]
	v_mfma_f32_16x16x32_bf16 v[40:43], v[132:135], v[180:183], v[40:43]
	v_mfma_f32_16x16x32_bf16 v[44:47], v[156:159], v[180:183], v[44:47]
	v_mfma_f32_16x16x32_bf16 v[24:27], v[132:135], v[188:191], v[24:27]
	v_mfma_f32_16x16x32_bf16 v[28:31], v[156:159], v[188:191], v[28:31]
	v_mfma_f32_16x16x32_bf16 v[8:11], v[132:135], v[196:199], v[8:11]
	v_mfma_f32_16x16x32_bf16 v[12:15], v[156:159], v[196:199], v[12:15]
	s_barrier
	s_add_u32 s38, s38, 0x40080
	s_addc_u32 s39, s39, 0
	s_add_i32 s40, s40, s49
	s_mov_b32 m0, s40
	s_add_i32 s63, s63, 2
	global_load_lds_dwordx4 v138, s[38:39]
	s_add_i32 m0, s40, 0x2000
	s_add_u32 s36, s36, 0x100
	s_addc_u32 s37, s37, 0
	global_load_lds_dwordx4 v142, s[38:39]
	s_add_u32 s61, s61, 0x100
	s_addc_u32 s62, s62, 0
	s_waitcnt vmcnt(6)
	s_barrier
	v_mfma_f32_16x16x32_bf16 v[48:51], v[200:203], v[168:171], v[48:51]
	v_mfma_f32_16x16x32_bf16 v[52:55], v[208:211], v[168:171], v[52:55]
	v_mfma_f32_16x16x32_bf16 v[32:35], v[200:203], v[176:179], v[32:35]
	v_mfma_f32_16x16x32_bf16 v[36:39], v[208:211], v[176:179], v[36:39]
	v_mfma_f32_16x16x32_bf16 v[16:19], v[200:203], v[184:187], v[16:19]
	v_mfma_f32_16x16x32_bf16 v[20:23], v[208:211], v[184:187], v[20:23]
	v_mfma_f32_16x16x32_bf16 v[4:7], v[200:203], v[192:195], v[4:7]
	v_mfma_f32_16x16x32_bf16 v[0:3], v[208:211], v[192:195], v[0:3]
	v_mfma_f32_16x16x32_bf16 v[48:51], v[204:207], v[172:175], v[48:51]
	v_mfma_f32_16x16x32_bf16 v[52:55], v[212:215], v[172:175], v[52:55]
	v_mfma_f32_16x16x32_bf16 v[32:35], v[204:207], v[180:183], v[32:35]
	v_mfma_f32_16x16x32_bf16 v[36:39], v[212:215], v[180:183], v[36:39]
	v_mfma_f32_16x16x32_bf16 v[16:19], v[204:207], v[188:191], v[16:19]
	v_mfma_f32_16x16x32_bf16 v[20:23], v[212:215], v[188:191], v[20:23]
	v_mfma_f32_16x16x32_bf16 v[4:7], v[204:207], v[196:199], v[4:7]
	v_mfma_f32_16x16x32_bf16 v[0:3], v[212:215], v[196:199], v[0:3]
	s_cmp_gt_u32 s63, 13
	s_barrier
	s_cbranch_scc0 .LBB0_583
	v_lshl_add_u32 v152, s8, 8, v161
	v_lshl_or_b32 v153, s16, 8, v163
	s_lshl_b32 s36, s16, 2
	s_ashr_i32 s37, s36, 31
	s_lshl_b32 s16, s54, 2
	v_lshl_add_u32 v154, v152, 10, v153
	v_lshl_add_u32 v156, v152, 6, s16
	v_lshl_add_u32 v156, s36, 2, v156
	v_lshlrev_b32_e32 v155, 1, v154
	v_lshlrev_b32_e32 v154, 2, v154
	global_load_dwordx4 v[168:171], v154, s[14:15]
	global_load_dwordx4 v[172:175], v154, s[14:15] offset:16
	global_load_dwordx4 v[176:179], v154, s[14:15] offset:512
	global_load_dwordx4 v[180:183], v154, s[14:15] offset:528
	v_add_u32_e32 v154, 0x10000, v154
	global_load_dwordx4 v[184:187], v154, s[14:15]
	global_load_dwordx4 v[188:191], v154, s[14:15] offset:16
	global_load_dwordx4 v[192:195], v154, s[14:15] offset:512
	global_load_dwordx4 v[196:199], v154, s[14:15] offset:528
	v_add_u32_e32 v154, 0x10000, v154
	global_load_dwordx4 v[200:203], v154, s[14:15]
	global_load_dwordx4 v[204:207], v154, s[14:15] offset:16
	global_load_dwordx4 v[208:211], v154, s[14:15] offset:512
	global_load_dwordx4 v[212:215], v154, s[14:15] offset:528
	v_add_u32_e32 v154, 0x10000, v154
	global_load_dwordx4 v[216:219], v154, s[14:15]
	global_load_dwordx4 v[220:223], v154, s[14:15] offset:16
	global_load_dwordx4 v[128:131], v154, s[14:15] offset:512
	global_load_dwordx4 v[132:135], v154, s[14:15] offset:528
	v_add_u32_e32 v154, 0x50000, v154
	s_waitcnt vmcnt(12)
	v_pk_add_f32 v[120:121], v[120:121], v[168:169]
	v_pk_add_f32 v[122:123], v[122:123], v[170:171]
	v_pk_add_f32 v[124:125], v[124:125], v[172:173]
	v_pk_add_f32 v[126:127], v[126:127], v[174:175]
	v_cvt_pk_bf16_f32 v168, v120, v121
	v_cvt_pk_bf16_f32 v169, v122, v123
	v_cvt_pk_bf16_f32 v170, v124, v125
	v_cvt_pk_bf16_f32 v171, v126, v127
	v_pk_mul_f32 v[172:173], v[120:121], v[120:121]
	global_store_dwordx4 v155, v[168:171], s[18:19]
	v_pk_fma_f32 v[172:173], v[122:123], v[122:123], v[172:173]
	v_pk_fma_f32 v[172:173], v[124:125], v[124:125], v[172:173]
	v_pk_fma_f32 v[172:173], v[126:127], v[126:127], v[172:173]
	v_pk_add_f32 v[112:113], v[112:113], v[176:177]
	v_pk_add_f32 v[114:115], v[114:115], v[178:179]
	v_pk_add_f32 v[116:117], v[116:117], v[180:181]
	v_pk_add_f32 v[118:119], v[118:119], v[182:183]
	v_cvt_pk_bf16_f32 v176, v112, v113
	v_cvt_pk_bf16_f32 v177, v114, v115
	v_cvt_pk_bf16_f32 v178, v116, v117
	v_cvt_pk_bf16_f32 v179, v118, v119
	v_pk_fma_f32 v[172:173], v[112:113], v[112:113], v[172:173]
	global_store_dwordx4 v155, v[176:179], s[18:19] offset:256
	v_pk_fma_f32 v[172:173], v[114:115], v[114:115], v[172:173]
	v_pk_fma_f32 v[172:173], v[116:117], v[116:117], v[172:173]
	v_pk_fma_f32 v[172:173], v[118:119], v[118:119], v[172:173]
	v_add_f32_e32 v157, v172, v173
	v_add_u32_e32 v155, 0x8000, v155
	v_mov_b32_e32 v158, v157
	s_nop 1
	v_permlane16_swap_b32_e32 v157, v158
	s_nop 0
	v_add_f32_e32 v157, v157, v158
	v_mov_b32_e32 v158, v157
	s_nop 1
	v_permlane32_swap_b32_e32 v157, v158
	s_nop 0
	v_add_f32_e32 v157, v157, v158
	s_and_saveexec_b64 s[38:39], s[4:5]
	global_store_dword v156, v157, s[20:21]
	s_mov_b64 exec, s[38:39]
	global_load_dwordx4 v[168:171], v154, s[14:15]
	global_load_dwordx4 v[172:175], v154, s[14:15] offset:16
	global_load_dwordx4 v[176:179], v154, s[14:15] offset:512
	global_load_dwordx4 v[180:183], v154, s[14:15] offset:528
	v_add_u32_e32 v154, 0x10000, v154
	s_waitcnt vmcnt(15)
	v_pk_add_f32 v[104:105], v[104:105], v[184:185]
	v_pk_add_f32 v[106:107], v[106:107], v[186:187]
	v_pk_add_f32 v[108:109], v[108:109], v[188:189]
	v_pk_add_f32 v[110:111], v[110:111], v[190:191]
	v_cvt_pk_bf16_f32 v184, v104, v105
	v_cvt_pk_bf16_f32 v185, v106, v107
	v_cvt_pk_bf16_f32 v186, v108, v109
	v_cvt_pk_bf16_f32 v187, v110, v111
	v_pk_mul_f32 v[188:189], v[104:105], v[104:105]
	global_store_dwordx4 v155, v[184:187], s[18:19]
	v_pk_fma_f32 v[188:189], v[106:107], v[106:107], v[188:189]
	v_pk_fma_f32 v[188:189], v[108:109], v[108:109], v[188:189]
	v_pk_fma_f32 v[188:189], v[110:111], v[110:111], v[188:189]
	v_pk_add_f32 v[96:97], v[96:97], v[192:193]
	v_pk_add_f32 v[98:99], v[98:99], v[194:195]
	v_pk_add_f32 v[100:101], v[100:101], v[196:197]
	v_pk_add_f32 v[102:103], v[102:103], v[198:199]
	v_cvt_pk_bf16_f32 v192, v96, v97
	v_cvt_pk_bf16_f32 v193, v98, v99
	v_cvt_pk_bf16_f32 v194, v100, v101
	v_cvt_pk_bf16_f32 v195, v102, v103
	v_pk_fma_f32 v[188:189], v[96:97], v[96:97], v[188:189]
	global_store_dwordx4 v155, v[192:195], s[18:19] offset:256
	v_pk_fma_f32 v[188:189], v[98:99], v[98:99], v[188:189]
	v_pk_fma_f32 v[188:189], v[100:101], v[100:101], v[188:189]
	v_pk_fma_f32 v[188:189], v[102:103], v[102:103], v[188:189]
	v_add_f32_e32 v157, v188, v189
	v_add_u32_e32 v155, 0x8000, v155
	v_mov_b32_e32 v158, v157
	s_nop 1
	v_permlane16_swap_b32_e32 v157, v158
	s_nop 0
	v_add_f32_e32 v157, v157, v158
	v_mov_b32_e32 v158, v157
	s_nop 1
	v_permlane32_swap_b32_e32 v157, v158
	s_nop 0
	v_add_f32_e32 v157, v157, v158
	s_and_saveexec_b64 s[38:39], s[4:5]
	global_store_dword v156, v157, s[20:21] offset:1024
	s_mov_b64 exec, s[38:39]
	global_load_dwordx4 v[184:187], v154, s[14:15]
	global_load_dwordx4 v[188:191], v154, s[14:15] offset:16
	global_load_dwordx4 v[192:195], v154, s[14:15] offset:512
	global_load_dwordx4 v[196:199], v154, s[14:15] offset:528
	v_add_u32_e32 v154, 0x10000, v154
	s_waitcnt vmcnt(18)
	v_pk_add_f32 v[88:89], v[88:89], v[200:201]
	v_pk_add_f32 v[90:91], v[90:91], v[202:203]
	v_pk_add_f32 v[92:93], v[92:93], v[204:205]
	v_pk_add_f32 v[94:95], v[94:95], v[206:207]
	v_cvt_pk_bf16_f32 v200, v88, v89
	v_cvt_pk_bf16_f32 v201, v90, v91
	v_cvt_pk_bf16_f32 v202, v92, v93
	v_cvt_pk_bf16_f32 v203, v94, v95
	v_pk_mul_f32 v[204:205], v[88:89], v[88:89]
	global_store_dwordx4 v155, v[200:203], s[18:19]
	v_pk_fma_f32 v[204:205], v[90:91], v[90:91], v[204:205]
	v_pk_fma_f32 v[204:205], v[92:93], v[92:93], v[204:205]
	v_pk_fma_f32 v[204:205], v[94:95], v[94:95], v[204:205]
	v_pk_add_f32 v[80:81], v[80:81], v[208:209]
	v_pk_add_f32 v[82:83], v[82:83], v[210:211]
	v_pk_add_f32 v[84:85], v[84:85], v[212:213]
	v_pk_add_f32 v[86:87], v[86:87], v[214:215]
	v_cvt_pk_bf16_f32 v208, v80, v81
	v_cvt_pk_bf16_f32 v209, v82, v83
	v_cvt_pk_bf16_f32 v210, v84, v85
	v_cvt_pk_bf16_f32 v211, v86, v87
	v_pk_fma_f32 v[204:205], v[80:81], v[80:81], v[204:205]
	global_store_dwordx4 v155, v[208:211], s[18:19] offset:256
	v_pk_fma_f32 v[204:205], v[82:83], v[82:83], v[204:205]
	v_pk_fma_f32 v[204:205], v[84:85], v[84:85], v[204:205]
	v_pk_fma_f32 v[204:205], v[86:87], v[86:87], v[204:205]
	v_add_f32_e32 v157, v204, v205
	v_add_u32_e32 v155, 0x8000, v155
	v_mov_b32_e32 v158, v157
	s_nop 1
	v_permlane16_swap_b32_e32 v157, v158
	s_nop 0
	v_add_f32_e32 v157, v157, v158
	v_mov_b32_e32 v158, v157
	s_nop 1
	v_permlane32_swap_b32_e32 v157, v158
	s_nop 0
	v_add_f32_e32 v157, v157, v158
	s_and_saveexec_b64 s[38:39], s[4:5]
	global_store_dword v156, v157, s[20:21] offset:2048
	s_mov_b64 exec, s[38:39]
	global_load_dwordx4 v[200:203], v154, s[14:15]
	global_load_dwordx4 v[204:207], v154, s[14:15] offset:16
	global_load_dwordx4 v[208:211], v154, s[14:15] offset:512
	global_load_dwordx4 v[212:215], v154, s[14:15] offset:528
	v_add_u32_e32 v154, 0x10000, v154
	s_waitcnt vmcnt(21)
	v_pk_add_f32 v[72:73], v[72:73], v[216:217]
	v_pk_add_f32 v[74:75], v[74:75], v[218:219]
	v_pk_add_f32 v[76:77], v[76:77], v[220:221]
	v_pk_add_f32 v[78:79], v[78:79], v[222:223]
	v_cvt_pk_bf16_f32 v216, v72, v73
	v_cvt_pk_bf16_f32 v217, v74, v75
	v_cvt_pk_bf16_f32 v218, v76, v77
	v_cvt_pk_bf16_f32 v219, v78, v79
	v_pk_mul_f32 v[220:221], v[72:73], v[72:73]
	global_store_dwordx4 v155, v[216:219], s[18:19]
	v_pk_fma_f32 v[220:221], v[74:75], v[74:75], v[220:221]
	v_pk_fma_f32 v[220:221], v[76:77], v[76:77], v[220:221]
	v_pk_fma_f32 v[220:221], v[78:79], v[78:79], v[220:221]
	v_pk_add_f32 v[64:65], v[64:65], v[128:129]
	v_pk_add_f32 v[66:67], v[66:67], v[130:131]
	v_pk_add_f32 v[68:69], v[68:69], v[132:133]
	v_pk_add_f32 v[70:71], v[70:71], v[134:135]
	v_cvt_pk_bf16_f32 v128, v64, v65
	v_cvt_pk_bf16_f32 v129, v66, v67
	v_cvt_pk_bf16_f32 v130, v68, v69
	v_cvt_pk_bf16_f32 v131, v70, v71
	v_pk_fma_f32 v[220:221], v[64:65], v[64:65], v[220:221]
	global_store_dwordx4 v155, v[128:131], s[18:19] offset:256
	v_pk_fma_f32 v[220:221], v[66:67], v[66:67], v[220:221]
	v_pk_fma_f32 v[220:221], v[68:69], v[68:69], v[220:221]
	v_pk_fma_f32 v[220:221], v[70:71], v[70:71], v[220:221]
	v_add_f32_e32 v157, v220, v221
	v_add_u32_e32 v155, 0x28000, v155
	v_mov_b32_e32 v158, v157
	s_nop 1
	v_permlane16_swap_b32_e32 v157, v158
	s_nop 0
	v_add_f32_e32 v157, v157, v158
	v_mov_b32_e32 v158, v157
	s_nop 1
	v_permlane32_swap_b32_e32 v157, v158
	s_nop 0
	v_add_f32_e32 v157, v157, v158
	s_and_saveexec_b64 s[38:39], s[4:5]
	global_store_dword v156, v157, s[20:21] offset:3072
	s_mov_b64 exec, s[38:39]
	v_add_u32_e32 v156, 0x2000, v156
	global_load_dwordx4 v[216:219], v154, s[14:15]
	global_load_dwordx4 v[220:223], v154, s[14:15] offset:16
	global_load_dwordx4 v[128:131], v154, s[14:15] offset:512
	global_load_dwordx4 v[132:135], v154, s[14:15] offset:528
	s_waitcnt vmcnt(21)
	v_pk_add_f32 v[56:57], v[56:57], v[168:169]
	v_pk_add_f32 v[58:59], v[58:59], v[170:171]
	v_pk_add_f32 v[60:61], v[60:61], v[172:173]
	v_pk_add_f32 v[62:63], v[62:63], v[174:175]
	v_cvt_pk_bf16_f32 v168, v56, v57
	v_cvt_pk_bf16_f32 v169, v58, v59
	v_cvt_pk_bf16_f32 v170, v60, v61
	v_cvt_pk_bf16_f32 v171, v62, v63
	v_pk_mul_f32 v[172:173], v[56:57], v[56:57]
	global_store_dwordx4 v155, v[168:171], s[18:19]
	v_pk_fma_f32 v[172:173], v[58:59], v[58:59], v[172:173]
	v_pk_fma_f32 v[172:173], v[60:61], v[60:61], v[172:173]
	v_pk_fma_f32 v[172:173], v[62:63], v[62:63], v[172:173]
	v_pk_add_f32 v[48:49], v[48:49], v[176:177]
	v_pk_add_f32 v[50:51], v[50:51], v[178:179]
	v_pk_add_f32 v[52:53], v[52:53], v[180:181]
	v_pk_add_f32 v[54:55], v[54:55], v[182:183]
	v_cvt_pk_bf16_f32 v176, v48, v49
	v_cvt_pk_bf16_f32 v177, v50, v51
	v_cvt_pk_bf16_f32 v178, v52, v53
	v_cvt_pk_bf16_f32 v179, v54, v55
	v_pk_fma_f32 v[172:173], v[48:49], v[48:49], v[172:173]
	global_store_dwordx4 v155, v[176:179], s[18:19] offset:256
	v_pk_fma_f32 v[172:173], v[50:51], v[50:51], v[172:173]
	v_pk_fma_f32 v[172:173], v[52:53], v[52:53], v[172:173]
	v_pk_fma_f32 v[172:173], v[54:55], v[54:55], v[172:173]
	v_add_f32_e32 v157, v172, v173
	v_add_u32_e32 v155, 0x8000, v155
	v_mov_b32_e32 v158, v157
	s_nop 1
	v_permlane16_swap_b32_e32 v157, v158
	s_nop 0
	v_add_f32_e32 v157, v157, v158
	v_mov_b32_e32 v158, v157
	s_nop 1
	v_permlane32_swap_b32_e32 v157, v158
	s_nop 0
	v_add_f32_e32 v157, v157, v158
	s_and_saveexec_b64 s[38:39], s[4:5]
	global_store_dword v156, v157, s[20:21]
	s_mov_b64 exec, s[38:39]
	s_waitcnt vmcnt(17)
	v_pk_add_f32 v[40:41], v[40:41], v[184:185]
	v_pk_add_f32 v[42:43], v[42:43], v[186:187]
	v_pk_add_f32 v[44:45], v[44:45], v[188:189]
	v_pk_add_f32 v[46:47], v[46:47], v[190:191]
	v_cvt_pk_bf16_f32 v184, v40, v41
	v_cvt_pk_bf16_f32 v185, v42, v43
	v_cvt_pk_bf16_f32 v186, v44, v45
	v_cvt_pk_bf16_f32 v187, v46, v47
	v_pk_mul_f32 v[188:189], v[40:41], v[40:41]
	global_store_dwordx4 v155, v[184:187], s[18:19]
	v_pk_fma_f32 v[188:189], v[42:43], v[42:43], v[188:189]
	v_pk_fma_f32 v[188:189], v[44:45], v[44:45], v[188:189]
	v_pk_fma_f32 v[188:189], v[46:47], v[46:47], v[188:189]
	v_pk_add_f32 v[32:33], v[32:33], v[192:193]
	v_pk_add_f32 v[34:35], v[34:35], v[194:195]
	v_pk_add_f32 v[36:37], v[36:37], v[196:197]
	v_pk_add_f32 v[38:39], v[38:39], v[198:199]
	v_cvt_pk_bf16_f32 v192, v32, v33
	v_cvt_pk_bf16_f32 v193, v34, v35
	v_cvt_pk_bf16_f32 v194, v36, v37
	v_cvt_pk_bf16_f32 v195, v38, v39
	v_pk_fma_f32 v[188:189], v[32:33], v[32:33], v[188:189]
	global_store_dwordx4 v155, v[192:195], s[18:19] offset:256
	v_pk_fma_f32 v[188:189], v[34:35], v[34:35], v[188:189]
	v_pk_fma_f32 v[188:189], v[36:37], v[36:37], v[188:189]
	v_pk_fma_f32 v[188:189], v[38:39], v[38:39], v[188:189]
	v_add_f32_e32 v157, v188, v189
	v_add_u32_e32 v155, 0x8000, v155
	v_mov_b32_e32 v158, v157
	s_nop 1
	v_permlane16_swap_b32_e32 v157, v158
	s_nop 0
	v_add_f32_e32 v157, v157, v158
	v_mov_b32_e32 v158, v157
	s_nop 1
	v_permlane32_swap_b32_e32 v157, v158
	s_nop 0
	v_add_f32_e32 v157, v157, v158
	s_and_saveexec_b64 s[38:39], s[4:5]
	global_store_dword v156, v157, s[20:21] offset:1024
	s_mov_b64 exec, s[38:39]
	s_waitcnt vmcnt(13)
	v_pk_add_f32 v[24:25], v[24:25], v[200:201]
	v_pk_add_f32 v[26:27], v[26:27], v[202:203]
	v_pk_add_f32 v[28:29], v[28:29], v[204:205]
	v_pk_add_f32 v[30:31], v[30:31], v[206:207]
	v_cvt_pk_bf16_f32 v200, v24, v25
	v_cvt_pk_bf16_f32 v201, v26, v27
	v_cvt_pk_bf16_f32 v202, v28, v29
	v_cvt_pk_bf16_f32 v203, v30, v31
	v_pk_mul_f32 v[204:205], v[24:25], v[24:25]
	global_store_dwordx4 v155, v[200:203], s[18:19]
	v_pk_fma_f32 v[204:205], v[26:27], v[26:27], v[204:205]
	v_pk_fma_f32 v[204:205], v[28:29], v[28:29], v[204:205]
	v_pk_fma_f32 v[204:205], v[30:31], v[30:31], v[204:205]
	v_pk_add_f32 v[16:17], v[16:17], v[208:209]
	v_pk_add_f32 v[18:19], v[18:19], v[210:211]
	v_pk_add_f32 v[20:21], v[20:21], v[212:213]
	v_pk_add_f32 v[22:23], v[22:23], v[214:215]
	v_cvt_pk_bf16_f32 v208, v16, v17
	v_cvt_pk_bf16_f32 v209, v18, v19
	v_cvt_pk_bf16_f32 v210, v20, v21
	v_cvt_pk_bf16_f32 v211, v22, v23
	v_pk_fma_f32 v[204:205], v[16:17], v[16:17], v[204:205]
	global_store_dwordx4 v155, v[208:211], s[18:19] offset:256
	v_pk_fma_f32 v[204:205], v[18:19], v[18:19], v[204:205]
	v_pk_fma_f32 v[204:205], v[20:21], v[20:21], v[204:205]
	v_pk_fma_f32 v[204:205], v[22:23], v[22:23], v[204:205]
	v_add_f32_e32 v157, v204, v205
	v_add_u32_e32 v155, 0x8000, v155
	v_mov_b32_e32 v158, v157
	s_nop 1
	v_permlane16_swap_b32_e32 v157, v158
	s_nop 0
	v_add_f32_e32 v157, v157, v158
	v_mov_b32_e32 v158, v157
	s_nop 1
	v_permlane32_swap_b32_e32 v157, v158
	s_nop 0
	v_add_f32_e32 v157, v157, v158
	s_and_saveexec_b64 s[38:39], s[4:5]
	global_store_dword v156, v157, s[20:21] offset:2048
	s_mov_b64 exec, s[38:39]
	s_waitcnt vmcnt(9)
	v_pk_add_f32 v[8:9], v[8:9], v[216:217]
	v_pk_add_f32 v[10:11], v[10:11], v[218:219]
	v_pk_add_f32 v[12:13], v[12:13], v[220:221]
	v_pk_add_f32 v[14:15], v[14:15], v[222:223]
	v_cvt_pk_bf16_f32 v216, v8, v9
	v_cvt_pk_bf16_f32 v217, v10, v11
	v_cvt_pk_bf16_f32 v218, v12, v13
	v_cvt_pk_bf16_f32 v219, v14, v15
	v_pk_mul_f32 v[220:221], v[8:9], v[8:9]
	global_store_dwordx4 v155, v[216:219], s[18:19]
	v_pk_fma_f32 v[220:221], v[10:11], v[10:11], v[220:221]
	v_pk_fma_f32 v[220:221], v[12:13], v[12:13], v[220:221]
	v_pk_fma_f32 v[220:221], v[14:15], v[14:15], v[220:221]
	v_pk_add_f32 v[4:5], v[4:5], v[128:129]
	v_pk_add_f32 v[6:7], v[6:7], v[130:131]
	v_pk_add_f32 v[0:1], v[0:1], v[132:133]
	v_pk_add_f32 v[2:3], v[2:3], v[134:135]
	v_cvt_pk_bf16_f32 v128, v4, v5
	v_cvt_pk_bf16_f32 v129, v6, v7
	v_cvt_pk_bf16_f32 v130, v0, v1
	v_cvt_pk_bf16_f32 v131, v2, v3
	v_pk_fma_f32 v[220:221], v[4:5], v[4:5], v[220:221]
	global_store_dwordx4 v155, v[128:131], s[18:19] offset:256
	v_pk_fma_f32 v[220:221], v[6:7], v[6:7], v[220:221]
	v_pk_fma_f32 v[220:221], v[0:1], v[0:1], v[220:221]
	v_pk_fma_f32 v[220:221], v[2:3], v[2:3], v[220:221]
	v_add_f32_e32 v157, v220, v221
	v_add_u32_e32 v155, 0x8000, v155
	v_mov_b32_e32 v158, v157
	s_nop 1
	v_permlane16_swap_b32_e32 v157, v158
	s_nop 0
	v_add_f32_e32 v157, v157, v158
	v_mov_b32_e32 v158, v157
	s_nop 1
	v_permlane32_swap_b32_e32 v157, v158
	s_nop 0
	v_add_f32_e32 v157, v157, v158
	s_and_saveexec_b64 s[38:39], s[4:5]
	global_store_dword v156, v157, s[20:21] offset:3072
	s_mov_b64 exec, s[38:39]
	s_branch .LBB0_575

.LBB0_698:
	s_add_u32 s28, s26, 0xfffc0080
	s_addc_u32 s29, s27, -1
	s_add_i32 s68, 0, 0x10000
	v_add_u32_e32 v155, s68, v153
	ds_read_b128 v[138:141], v155
	ds_read_b128 v[142:145], v155 offset:1024
	ds_read_b128 v[146:149], v155 offset:2048
	ds_read_b128 v[156:159], v155 offset:3072
	s_cmp_eq_u32 s51, 12
	s_cselect_b32 s31, s21, s29
	s_cselect_b32 s30, s38, s28
	s_cselect_b32 s29, s7, s50
	s_cselect_b32 s28, s39, s46
	s_add_i32 m0, s58, 0xc000
	ds_read_b128 v[160:163], v154
	ds_read_b128 v[164:167], v154 offset:1024
	ds_read_b128 v[168:171], v154 offset:2048
	ds_read_b128 v[172:175], v154 offset:3072
	ds_read_b128 v[176:179], v154 offset:4096
	ds_read_b128 v[180:183], v154 offset:5120
	ds_read_b128 v[184:187], v154 offset:6144
	global_load_lds_dwordx4 v134, s[26:27]
	s_add_i32 m0, s58, 0xe000
	ds_read_b128 v[188:191], v154 offset:7168
	global_load_lds_dwordx4 v136, s[26:27]
	s_waitcnt lgkmcnt(8)
	s_barrier
	s_waitcnt lgkmcnt(0)
	v_mfma_f32_16x16x32_bf16 v[124:127], v[138:141], v[160:163], v[124:127]
	v_mfma_f32_16x16x32_bf16 v[120:123], v[146:149], v[160:163], v[120:123]
	v_mfma_f32_16x16x32_bf16 v[108:111], v[138:141], v[168:171], v[108:111]
	v_mfma_f32_16x16x32_bf16 v[104:107], v[146:149], v[168:171], v[104:107]
	v_mfma_f32_16x16x32_bf16 v[92:95], v[138:141], v[176:179], v[92:95]
	v_mfma_f32_16x16x32_bf16 v[88:91], v[146:149], v[176:179], v[88:91]
	v_mfma_f32_16x16x32_bf16 v[76:79], v[138:141], v[184:187], v[76:79]
	v_mfma_f32_16x16x32_bf16 v[72:75], v[146:149], v[184:187], v[72:75]
	v_mfma_f32_16x16x32_bf16 v[124:127], v[142:145], v[164:167], v[124:127]
	v_mfma_f32_16x16x32_bf16 v[120:123], v[156:159], v[164:167], v[120:123]
	v_mfma_f32_16x16x32_bf16 v[108:111], v[142:145], v[172:175], v[108:111]
	v_mfma_f32_16x16x32_bf16 v[104:107], v[156:159], v[172:175], v[104:107]
	v_mfma_f32_16x16x32_bf16 v[92:95], v[142:145], v[180:183], v[92:95]
	v_mfma_f32_16x16x32_bf16 v[88:91], v[156:159], v[180:183], v[88:91]
	v_mfma_f32_16x16x32_bf16 v[76:79], v[142:145], v[188:191], v[76:79]
	v_mfma_f32_16x16x32_bf16 v[72:75], v[156:159], v[188:191], v[72:75]
	s_barrier
	s_add_i32 s70, 0, 0x14000
	s_add_i32 s68, s68, s57
	v_add_u32_e32 v155, s70, v153
	s_add_u32 s98, s28, s40
	s_addc_u32 s99, s29, s41
	s_mov_b32 m0, s68
	ds_read_b128 v[192:195], v155
	ds_read_b128 v[196:199], v155 offset:1024
	ds_read_b128 v[200:203], v155 offset:2048
	global_load_lds_dwordx4 v208, s[28:29]
	s_add_i32 m0, s68, 0x2000
	ds_read_b128 v[204:207], v155 offset:3072
	global_load_lds_dwordx4 v128, s[28:29]
	s_barrier
	s_waitcnt lgkmcnt(0)
	v_mfma_f32_16x16x32_bf16 v[116:119], v[192:195], v[160:163], v[116:119]
	v_mfma_f32_16x16x32_bf16 v[112:115], v[200:203], v[160:163], v[112:115]
	v_mfma_f32_16x16x32_bf16 v[100:103], v[192:195], v[168:171], v[100:103]
	v_mfma_f32_16x16x32_bf16 v[96:99], v[200:203], v[168:171], v[96:99]
	v_mfma_f32_16x16x32_bf16 v[84:87], v[192:195], v[176:179], v[84:87]
	v_mfma_f32_16x16x32_bf16 v[80:83], v[200:203], v[176:179], v[80:83]
	v_mfma_f32_16x16x32_bf16 v[68:71], v[192:195], v[184:187], v[68:71]
	v_mfma_f32_16x16x32_bf16 v[64:67], v[200:203], v[184:187], v[64:67]
	v_mfma_f32_16x16x32_bf16 v[116:119], v[196:199], v[164:167], v[116:119]
	v_mfma_f32_16x16x32_bf16 v[112:115], v[204:207], v[164:167], v[112:115]
	v_mfma_f32_16x16x32_bf16 v[100:103], v[196:199], v[172:175], v[100:103]
	v_mfma_f32_16x16x32_bf16 v[96:99], v[204:207], v[172:175], v[96:99]
	v_mfma_f32_16x16x32_bf16 v[84:87], v[196:199], v[180:183], v[84:87]
	v_mfma_f32_16x16x32_bf16 v[80:83], v[204:207], v[180:183], v[80:83]
	v_mfma_f32_16x16x32_bf16 v[68:71], v[196:199], v[188:191], v[68:71]
	v_mfma_f32_16x16x32_bf16 v[64:67], v[204:207], v[188:191], v[64:67]
	s_mov_b32 m0, s58
	s_add_u32 s100, s30, s40
	s_addc_u32 s101, s31, s41
	s_barrier
	ds_read_b128 v[160:163], v154 offset:16384
	ds_read_b128 v[164:167], v154 offset:17408
	ds_read_b128 v[168:171], v154 offset:18432
	ds_read_b128 v[172:175], v154 offset:19456
	ds_read_b128 v[176:179], v154 offset:20480
	ds_read_b128 v[180:183], v154 offset:21504
	ds_read_b128 v[184:187], v154 offset:22528
	global_load_lds_dwordx4 v132, s[30:31]
	s_mov_b32 m0, s59
	ds_read_b128 v[188:191], v154 offset:23552
	global_load_lds_dwordx4 v130, s[30:31]
	s_barrier
	s_waitcnt lgkmcnt(0)
	v_mfma_f32_16x16x32_bf16 v[60:63], v[138:141], v[160:163], v[60:63]
	v_mfma_f32_16x16x32_bf16 v[56:59], v[146:149], v[160:163], v[56:59]
	v_mfma_f32_16x16x32_bf16 v[44:47], v[138:141], v[168:171], v[44:47]
	v_mfma_f32_16x16x32_bf16 v[40:43], v[146:149], v[168:171], v[40:43]
	v_mfma_f32_16x16x32_bf16 v[28:31], v[138:141], v[176:179], v[28:31]
	v_mfma_f32_16x16x32_bf16 v[24:27], v[146:149], v[176:179], v[24:27]
	v_mfma_f32_16x16x32_bf16 v[12:15], v[138:141], v[184:187], v[12:15]
	v_mfma_f32_16x16x32_bf16 v[8:11], v[146:149], v[184:187], v[8:11]
	v_mfma_f32_16x16x32_bf16 v[60:63], v[142:145], v[164:167], v[60:63]
	v_mfma_f32_16x16x32_bf16 v[56:59], v[156:159], v[164:167], v[56:59]
	v_mfma_f32_16x16x32_bf16 v[44:47], v[142:145], v[172:175], v[44:47]
	v_mfma_f32_16x16x32_bf16 v[40:43], v[156:159], v[172:175], v[40:43]
	v_mfma_f32_16x16x32_bf16 v[28:31], v[142:145], v[180:183], v[28:31]
	v_mfma_f32_16x16x32_bf16 v[24:27], v[156:159], v[180:183], v[24:27]
	v_mfma_f32_16x16x32_bf16 v[12:15], v[142:145], v[188:191], v[12:15]
	v_mfma_f32_16x16x32_bf16 v[8:11], v[156:159], v[188:191], v[8:11]
	s_barrier
	s_add_u32 s68, s28, 0x40000
	s_addc_u32 s69, s29, 0
	s_add_i32 s70, s70, s57
	s_mov_b32 m0, s70
	s_nop 0
	global_load_lds_dwordx4 v208, s[68:69]
	s_add_i32 m0, s70, 0x2000
	s_nop 0
	global_load_lds_dwordx4 v128, s[68:69]
	s_waitcnt vmcnt(6)
	s_barrier
	v_mfma_f32_16x16x32_bf16 v[52:55], v[192:195], v[160:163], v[52:55]
	v_mfma_f32_16x16x32_bf16 v[48:51], v[200:203], v[160:163], v[48:51]
	v_mfma_f32_16x16x32_bf16 v[36:39], v[192:195], v[168:171], v[36:39]
	v_mfma_f32_16x16x32_bf16 v[32:35], v[200:203], v[168:171], v[32:35]
	v_mfma_f32_16x16x32_bf16 v[20:23], v[192:195], v[176:179], v[20:23]
	v_mfma_f32_16x16x32_bf16 v[16:19], v[200:203], v[176:179], v[16:19]
	v_mfma_f32_16x16x32_bf16 v[4:7], v[192:195], v[184:187], v[4:7]
	v_mfma_f32_16x16x32_bf16 v[0:3], v[200:203], v[184:187], v[0:3]
	v_mfma_f32_16x16x32_bf16 v[52:55], v[196:199], v[164:167], v[52:55]
	v_mfma_f32_16x16x32_bf16 v[48:51], v[204:207], v[164:167], v[48:51]
	v_mfma_f32_16x16x32_bf16 v[36:39], v[196:199], v[172:175], v[36:39]
	v_mfma_f32_16x16x32_bf16 v[32:35], v[204:207], v[172:175], v[32:35]
	v_mfma_f32_16x16x32_bf16 v[20:23], v[196:199], v[180:183], v[20:23]
	v_mfma_f32_16x16x32_bf16 v[16:19], v[204:207], v[180:183], v[16:19]
	v_mfma_f32_16x16x32_bf16 v[4:7], v[196:199], v[188:191], v[4:7]
	v_mfma_f32_16x16x32_bf16 v[0:3], v[204:207], v[188:191], v[0:3]
	s_add_i32 s68, 0, 0x18000
	v_add_u32_e32 v155, s68, v153
	s_barrier
	ds_read_b128 v[138:141], v155
	ds_read_b128 v[142:145], v155 offset:1024
	ds_read_b128 v[146:149], v155 offset:2048
	ds_read_b128 v[156:159], v155 offset:3072
	s_add_u32 s30, s30, 0x40000
	s_addc_u32 s31, s31, 0
	s_mov_b32 m0, s60
	ds_read_b128 v[160:163], v154 offset:32768
	ds_read_b128 v[164:167], v154 offset:33792
	ds_read_b128 v[168:171], v154 offset:34816
	ds_read_b128 v[172:175], v154 offset:35840
	ds_read_b128 v[176:179], v154 offset:36864
	ds_read_b128 v[180:183], v154 offset:37888
	ds_read_b128 v[184:187], v154 offset:38912
	global_load_lds_dwordx4 v132, s[30:31]
	s_mov_b32 m0, s61
	ds_read_b128 v[188:191], v154 offset:39936
	global_load_lds_dwordx4 v130, s[30:31]
	s_waitcnt lgkmcnt(8)
	s_barrier
	s_waitcnt lgkmcnt(0)
	v_mfma_f32_16x16x32_bf16 v[124:127], v[138:141], v[160:163], v[124:127]
	v_mfma_f32_16x16x32_bf16 v[120:123], v[146:149], v[160:163], v[120:123]
	v_mfma_f32_16x16x32_bf16 v[108:111], v[138:141], v[168:171], v[108:111]
	v_mfma_f32_16x16x32_bf16 v[104:107], v[146:149], v[168:171], v[104:107]
	v_mfma_f32_16x16x32_bf16 v[92:95], v[138:141], v[176:179], v[92:95]
	v_mfma_f32_16x16x32_bf16 v[88:91], v[146:149], v[176:179], v[88:91]
	v_mfma_f32_16x16x32_bf16 v[76:79], v[138:141], v[184:187], v[76:79]
	v_mfma_f32_16x16x32_bf16 v[72:75], v[146:149], v[184:187], v[72:75]
	v_mfma_f32_16x16x32_bf16 v[124:127], v[142:145], v[164:167], v[124:127]
	v_mfma_f32_16x16x32_bf16 v[120:123], v[156:159], v[164:167], v[120:123]
	v_mfma_f32_16x16x32_bf16 v[108:111], v[142:145], v[172:175], v[108:111]
	v_mfma_f32_16x16x32_bf16 v[104:107], v[156:159], v[172:175], v[104:107]
	v_mfma_f32_16x16x32_bf16 v[92:95], v[142:145], v[180:183], v[92:95]
	v_mfma_f32_16x16x32_bf16 v[88:91], v[156:159], v[180:183], v[88:91]
	v_mfma_f32_16x16x32_bf16 v[76:79], v[142:145], v[188:191], v[76:79]
	v_mfma_f32_16x16x32_bf16 v[72:75], v[156:159], v[188:191], v[72:75]
	s_barrier
	s_add_i32 s30, 0, 0x1c000
	s_add_i32 s31, s68, s57
	v_add_u32_e32 v155, s30, v153
	s_mov_b32 m0, s31
	ds_read_b128 v[192:195], v155
	ds_read_b128 v[196:199], v155 offset:1024
	ds_read_b128 v[200:203], v155 offset:2048
	global_load_lds_dwordx4 v208, s[98:99]
	s_add_i32 m0, s31, 0x2000
	ds_read_b128 v[204:207], v155 offset:3072
	global_load_lds_dwordx4 v128, s[98:99]
	s_barrier
	s_waitcnt lgkmcnt(0)
	v_mfma_f32_16x16x32_bf16 v[116:119], v[192:195], v[160:163], v[116:119]
	v_mfma_f32_16x16x32_bf16 v[112:115], v[200:203], v[160:163], v[112:115]
	v_mfma_f32_16x16x32_bf16 v[100:103], v[192:195], v[168:171], v[100:103]
	v_mfma_f32_16x16x32_bf16 v[96:99], v[200:203], v[168:171], v[96:99]
	v_mfma_f32_16x16x32_bf16 v[84:87], v[192:195], v[176:179], v[84:87]
	v_mfma_f32_16x16x32_bf16 v[80:83], v[200:203], v[176:179], v[80:83]
	v_mfma_f32_16x16x32_bf16 v[68:71], v[192:195], v[184:187], v[68:71]
	v_mfma_f32_16x16x32_bf16 v[64:67], v[200:203], v[184:187], v[64:67]
	v_mfma_f32_16x16x32_bf16 v[116:119], v[196:199], v[164:167], v[116:119]
	v_mfma_f32_16x16x32_bf16 v[112:115], v[204:207], v[164:167], v[112:115]
	v_mfma_f32_16x16x32_bf16 v[100:103], v[196:199], v[172:175], v[100:103]
	v_mfma_f32_16x16x32_bf16 v[96:99], v[204:207], v[172:175], v[96:99]
	v_mfma_f32_16x16x32_bf16 v[84:87], v[196:199], v[180:183], v[84:87]
	v_mfma_f32_16x16x32_bf16 v[80:83], v[204:207], v[180:183], v[80:83]
	v_mfma_f32_16x16x32_bf16 v[68:71], v[196:199], v[188:191], v[68:71]
	v_mfma_f32_16x16x32_bf16 v[64:67], v[204:207], v[188:191], v[64:67]
	s_mov_b32 m0, s64
	s_barrier
	ds_read_b128 v[160:163], v154 offset:49152
	ds_read_b128 v[164:167], v154 offset:50176
	ds_read_b128 v[168:171], v154 offset:51200
	ds_read_b128 v[172:175], v154 offset:52224
	ds_read_b128 v[176:179], v154 offset:53248
	ds_read_b128 v[180:183], v154 offset:54272
	ds_read_b128 v[184:187], v154 offset:55296
	global_load_lds_dwordx4 v132, s[100:101]
	s_mov_b32 m0, s65
	ds_read_b128 v[188:191], v154 offset:56320
	global_load_lds_dwordx4 v130, s[100:101]
	s_barrier
	s_waitcnt lgkmcnt(0)
	v_mfma_f32_16x16x32_bf16 v[60:63], v[138:141], v[160:163], v[60:63]
	v_mfma_f32_16x16x32_bf16 v[56:59], v[146:149], v[160:163], v[56:59]
	v_mfma_f32_16x16x32_bf16 v[44:47], v[138:141], v[168:171], v[44:47]
	v_mfma_f32_16x16x32_bf16 v[40:43], v[146:149], v[168:171], v[40:43]
	v_mfma_f32_16x16x32_bf16 v[28:31], v[138:141], v[176:179], v[28:31]
	v_mfma_f32_16x16x32_bf16 v[24:27], v[146:149], v[176:179], v[24:27]
	v_mfma_f32_16x16x32_bf16 v[12:15], v[138:141], v[184:187], v[12:15]
	v_mfma_f32_16x16x32_bf16 v[8:11], v[146:149], v[184:187], v[8:11]
	v_mfma_f32_16x16x32_bf16 v[60:63], v[142:145], v[164:167], v[60:63]
	v_mfma_f32_16x16x32_bf16 v[56:59], v[156:159], v[164:167], v[56:59]
	v_mfma_f32_16x16x32_bf16 v[44:47], v[142:145], v[172:175], v[44:47]
	v_mfma_f32_16x16x32_bf16 v[40:43], v[156:159], v[172:175], v[40:43]
	v_mfma_f32_16x16x32_bf16 v[28:31], v[142:145], v[180:183], v[28:31]
	v_mfma_f32_16x16x32_bf16 v[24:27], v[156:159], v[180:183], v[24:27]
	v_mfma_f32_16x16x32_bf16 v[12:15], v[142:145], v[188:191], v[12:15]
	v_mfma_f32_16x16x32_bf16 v[8:11], v[156:159], v[188:191], v[8:11]
	s_barrier
	s_add_u32 s28, s28, 0x40080
	s_addc_u32 s29, s29, 0
	s_add_i32 s30, s30, s57
	s_mov_b32 m0, s30
	s_add_i32 s51, s51, 2
	global_load_lds_dwordx4 v208, s[28:29]
	s_add_i32 m0, s30, 0x2000
	s_add_u32 s26, s26, 0x100
	s_addc_u32 s27, s27, 0
	global_load_lds_dwordx4 v128, s[28:29]
	s_add_u32 s46, s46, 0x100
	s_addc_u32 s50, s50, 0
	s_waitcnt vmcnt(6)
	s_barrier
	v_mfma_f32_16x16x32_bf16 v[52:55], v[192:195], v[160:163], v[52:55]
	v_mfma_f32_16x16x32_bf16 v[48:51], v[200:203], v[160:163], v[48:51]
	v_mfma_f32_16x16x32_bf16 v[36:39], v[192:195], v[168:171], v[36:39]
	v_mfma_f32_16x16x32_bf16 v[32:35], v[200:203], v[168:171], v[32:35]
	v_mfma_f32_16x16x32_bf16 v[20:23], v[192:195], v[176:179], v[20:23]
	v_mfma_f32_16x16x32_bf16 v[16:19], v[200:203], v[176:179], v[16:19]
	v_mfma_f32_16x16x32_bf16 v[4:7], v[192:195], v[184:187], v[4:7]
	v_mfma_f32_16x16x32_bf16 v[0:3], v[200:203], v[184:187], v[0:3]
	v_mfma_f32_16x16x32_bf16 v[52:55], v[196:199], v[164:167], v[52:55]
	v_mfma_f32_16x16x32_bf16 v[48:51], v[204:207], v[164:167], v[48:51]
	v_mfma_f32_16x16x32_bf16 v[36:39], v[196:199], v[172:175], v[36:39]
	v_mfma_f32_16x16x32_bf16 v[32:35], v[204:207], v[172:175], v[32:35]
	v_mfma_f32_16x16x32_bf16 v[20:23], v[196:199], v[180:183], v[20:23]
	v_mfma_f32_16x16x32_bf16 v[16:19], v[204:207], v[180:183], v[16:19]
	v_mfma_f32_16x16x32_bf16 v[4:7], v[196:199], v[188:191], v[4:7]
	v_mfma_f32_16x16x32_bf16 v[0:3], v[204:207], v[188:191], v[0:3]
	s_cmp_gt_u32 s51, 13
	s_barrier
	s_cbranch_scc0 .LBB0_698
	s_cmp_lt_i32 s34, 4
	s_cselect_b64 vcc, -1, 0
	v_mov_b32_e32 v138, 0x3e38aa3b
	s_nop 0
	v_cndmask_b32_e32 v155, 1.0, v138, vcc
	s_and_b64 s[26:27], vcc, exec
	v_lshl_add_u32 v140, s35, 8, v152
	s_cselect_b32 s7, s9, s11
	s_cselect_b32 s21, s8, s10
	v_mov_b32_e32 v138, s21
	v_mov_b32_e32 v139, s7
	v_lshlrev_b32_e32 v142, 3, v151
	v_mov_b32_e32 v143, 0
	v_lshl_add_u64 v[138:139], v[142:143], 2, v[138:139]
	global_load_dwordx4 v[188:191], v[138:139], off
	global_load_dwordx4 v[192:195], v[138:139], off offset:16
	global_load_dwordx4 v[196:199], v[138:139], off offset:128
	global_load_dwordx4 v[200:203], v[138:139], off offset:144
	s_lshl_b32 s7, s34, 8
	s_or_b32 s26, s7, s66
	s_ashr_i32 s27, s26, 31
	s_lshl_b64 s[26:27], s[26:27], 1
	s_add_u32 s26, s62, s26
	s_addc_u32 s27, s63, s27
	s_mov_b32 s34, s6
	s_mov_b32 s35, s20
	s_mov_b64 s[28:29], s[24:25]
	v_mbcnt_lo_u32_b32 v210, -1, 0
	v_mbcnt_hi_u32_b32 v210, -1, v210
	v_and_b32_e32 v210, 48, v210
	v_lshl_add_u32 v210, v140, 6, v210
	v_lshlrev_b32_e32 v211, 12, v140
	v_lshl_add_u32 v211, v151, 4, v211
	global_load_dwordx4 v[156:159], v210, s[18:19]
	global_load_dwordx4 v[160:163], v210, s[18:19] offset:1024
	global_load_dwordx4 v[164:167], v210, s[18:19] offset:2048
	global_load_dwordx4 v[168:171], v210, s[18:19] offset:3072
	v_add_u32_e32 v210, 0x2000, v210
	global_load_dwordx4 v[172:175], v210, s[18:19]
	global_load_dwordx4 v[176:179], v210, s[18:19] offset:1024
	global_load_dwordx4 v[180:183], v210, s[18:19] offset:2048
	global_load_dwordx4 v[184:187], v210, s[18:19] offset:3072
	s_waitcnt vmcnt(7)
	v_pk_add_f32 v[156:157], v[156:157], v[158:159]
	s_nop 0
	v_add_f32_e32 v214, v156, v157
	v_mov_b32_e32 v215, v214
	s_nop 1
	v_permlane16_swap_b32_e32 v214, v215
	s_nop 0
	v_add_f32_e32 v214, v214, v215
	v_mov_b32_e32 v215, v214
	s_nop 1
	v_permlane32_swap_b32_e32 v214, v215
	s_nop 0
	v_add_f32_e32 v214, v214, v215
	v_fmamk_f32 v214, v214, 0x3a800000, v248
	v_rsq_f32_e32 v216, v214
	s_nop 0
	v_pk_mul_f32 v[124:125], v[124:125], v[216:217] op_sel_hi:[1,0]
	v_pk_mul_f32 v[126:127], v[126:127], v[216:217] op_sel_hi:[1,0]
	v_pk_mul_f32 v[120:121], v[120:121], v[216:217] op_sel_hi:[1,0]
	v_pk_mul_f32 v[122:123], v[122:123], v[216:217] op_sel_hi:[1,0]
	v_pk_mul_f32 v[116:117], v[116:117], v[216:217] op_sel_hi:[1,0]
	v_pk_mul_f32 v[118:119], v[118:119], v[216:217] op_sel_hi:[1,0]
	v_pk_mul_f32 v[112:113], v[112:113], v[216:217] op_sel_hi:[1,0]
	v_pk_mul_f32 v[114:115], v[114:115], v[216:217] op_sel_hi:[1,0]
	v_pk_mul_f32 v[148:149], v[124:125], v[124:125]
	v_pk_fma_f32 v[148:149], v[126:127], v[126:127], v[148:149]
	v_pk_fma_f32 v[148:149], v[120:121], v[120:121], v[148:149]
	v_pk_fma_f32 v[148:149], v[122:123], v[122:123], v[148:149]
	v_pk_fma_f32 v[148:149], v[116:117], v[116:117], v[148:149]
	v_pk_fma_f32 v[148:149], v[118:119], v[118:119], v[148:149]
	v_pk_fma_f32 v[148:149], v[112:113], v[112:113], v[148:149]
	v_pk_fma_f32 v[148:149], v[114:115], v[114:115], v[148:149]
	v_add_f32_e32 v214, v148, v149
	v_mov_b32_e32 v215, v214
	s_nop 1
	v_permlane16_swap_b32_e32 v214, v215
	s_nop 0
	v_add_f32_e32 v214, v214, v215
	v_mov_b32_e32 v215, v214
	s_nop 1
	v_permlane32_swap_b32_e32 v214, v215
	s_nop 0
	v_add_f32_e32 v214, v214, v215
	v_fmamk_f32 v214, v214, 0x3c800000, v248
	v_rsq_f32_e32 v214, v214
	s_nop 0
	v_mul_f32_e32 v218, v155, v214
	v_pk_mul_f32 v[156:157], v[188:189], v[218:219] op_sel_hi:[1,0]
	v_pk_mul_f32 v[124:125], v[124:125], v[156:157]
	v_pk_mul_f32 v[156:157], v[190:191], v[218:219] op_sel_hi:[1,0]
	v_pk_mul_f32 v[126:127], v[126:127], v[156:157]
	v_pk_mul_f32 v[156:157], v[192:193], v[218:219] op_sel_hi:[1,0]
	v_pk_mul_f32 v[120:121], v[120:121], v[156:157]
	v_pk_mul_f32 v[156:157], v[194:195], v[218:219] op_sel_hi:[1,0]
	v_pk_mul_f32 v[122:123], v[122:123], v[156:157]
	v_cvt_pk_bf16_f32 v204, v124, v125
	v_cvt_pk_bf16_f32 v205, v126, v127
	v_cvt_pk_bf16_f32 v206, v120, v121
	v_cvt_pk_bf16_f32 v207, v122, v123
	global_store_dwordx4 v211, v[204:207], s[26:27]
	v_pk_mul_f32 v[156:157], v[196:197], v[218:219] op_sel_hi:[1,0]
	v_pk_mul_f32 v[116:117], v[116:117], v[156:157]
	v_pk_mul_f32 v[156:157], v[198:199], v[218:219] op_sel_hi:[1,0]
	v_pk_mul_f32 v[118:119], v[118:119], v[156:157]
	v_pk_mul_f32 v[156:157], v[200:201], v[218:219] op_sel_hi:[1,0]
	v_pk_mul_f32 v[112:113], v[112:113], v[156:157]
	v_pk_mul_f32 v[156:157], v[202:203], v[218:219] op_sel_hi:[1,0]
	v_pk_mul_f32 v[114:115], v[114:115], v[156:157]
	v_cvt_pk_bf16_f32 v144, v116, v117
	v_cvt_pk_bf16_f32 v145, v118, v119
	v_cvt_pk_bf16_f32 v146, v112, v113
	v_cvt_pk_bf16_f32 v147, v114, v115
	global_store_dwordx4 v211, v[144:147], s[26:27] offset:64
	v_add_u32_e32 v211, 0x10000, v211
	s_waitcnt vmcnt(8)
	v_pk_add_f32 v[160:161], v[160:161], v[162:163]
	s_nop 0
	v_add_f32_e32 v214, v160, v161
	v_mov_b32_e32 v215, v214
	s_nop 1
	v_permlane16_swap_b32_e32 v214, v215
	s_nop 0
	v_add_f32_e32 v214, v214, v215
	v_mov_b32_e32 v215, v214
	s_nop 1
	v_permlane32_swap_b32_e32 v214, v215
	s_nop 0
	v_add_f32_e32 v214, v214, v215
	v_fmamk_f32 v214, v214, 0x3a800000, v248
	v_rsq_f32_e32 v216, v214
	s_nop 0
	v_pk_mul_f32 v[108:109], v[108:109], v[216:217] op_sel_hi:[1,0]
	v_pk_mul_f32 v[110:111], v[110:111], v[216:217] op_sel_hi:[1,0]
	v_pk_mul_f32 v[104:105], v[104:105], v[216:217] op_sel_hi:[1,0]
	v_pk_mul_f32 v[106:107], v[106:107], v[216:217] op_sel_hi:[1,0]
	v_pk_mul_f32 v[100:101], v[100:101], v[216:217] op_sel_hi:[1,0]
	v_pk_mul_f32 v[102:103], v[102:103], v[216:217] op_sel_hi:[1,0]
	v_pk_mul_f32 v[96:97], v[96:97], v[216:217] op_sel_hi:[1,0]
	v_pk_mul_f32 v[98:99], v[98:99], v[216:217] op_sel_hi:[1,0]
	v_pk_mul_f32 v[148:149], v[108:109], v[108:109]
	v_pk_fma_f32 v[148:149], v[110:111], v[110:111], v[148:149]
	v_pk_fma_f32 v[148:149], v[104:105], v[104:105], v[148:149]
	v_pk_fma_f32 v[148:149], v[106:107], v[106:107], v[148:149]
	v_pk_fma_f32 v[148:149], v[100:101], v[100:101], v[148:149]
	v_pk_fma_f32 v[148:149], v[102:103], v[102:103], v[148:149]
	v_pk_fma_f32 v[148:149], v[96:97], v[96:97], v[148:149]
	v_pk_fma_f32 v[148:149], v[98:99], v[98:99], v[148:149]
	v_add_f32_e32 v214, v148, v149
	v_mov_b32_e32 v215, v214
	s_nop 1
	v_permlane16_swap_b32_e32 v214, v215
	s_nop 0
	v_add_f32_e32 v214, v214, v215
	v_mov_b32_e32 v215, v214
	s_nop 1
	v_permlane32_swap_b32_e32 v214, v215
	s_nop 0
	v_add_f32_e32 v214, v214, v215
	v_fmamk_f32 v214, v214, 0x3c800000, v248
	v_rsq_f32_e32 v214, v214
	s_nop 0
	v_mul_f32_e32 v218, v155, v214
	v_pk_mul_f32 v[160:161], v[188:189], v[218:219] op_sel_hi:[1,0]
	v_pk_mul_f32 v[108:109], v[108:109], v[160:161]
	v_pk_mul_f32 v[160:161], v[190:191], v[218:219] op_sel_hi:[1,0]
	v_pk_mul_f32 v[110:111], v[110:111], v[160:161]
	v_pk_mul_f32 v[160:161], v[192:193], v[218:219] op_sel_hi:[1,0]
	v_pk_mul_f32 v[104:105], v[104:105], v[160:161]
	v_pk_mul_f32 v[160:161], v[194:195], v[218:219] op_sel_hi:[1,0]
	v_pk_mul_f32 v[106:107], v[106:107], v[160:161]
	v_cvt_pk_bf16_f32 v204, v108, v109
	v_cvt_pk_bf16_f32 v205, v110, v111
	v_cvt_pk_bf16_f32 v206, v104, v105
	v_cvt_pk_bf16_f32 v207, v106, v107
	global_store_dwordx4 v211, v[204:207], s[26:27]
	v_pk_mul_f32 v[160:161], v[196:197], v[218:219] op_sel_hi:[1,0]
	v_pk_mul_f32 v[100:101], v[100:101], v[160:161]
	v_pk_mul_f32 v[160:161], v[198:199], v[218:219] op_sel_hi:[1,0]
	v_pk_mul_f32 v[102:103], v[102:103], v[160:161]
	v_pk_mul_f32 v[160:161], v[200:201], v[218:219] op_sel_hi:[1,0]
	v_pk_mul_f32 v[96:97], v[96:97], v[160:161]
	v_pk_mul_f32 v[160:161], v[202:203], v[218:219] op_sel_hi:[1,0]
	v_pk_mul_f32 v[98:99], v[98:99], v[160:161]
	v_cvt_pk_bf16_f32 v144, v100, v101
	v_cvt_pk_bf16_f32 v145, v102, v103
	v_cvt_pk_bf16_f32 v146, v96, v97
	v_cvt_pk_bf16_f32 v147, v98, v99
	global_store_dwordx4 v211, v[144:147], s[26:27] offset:64
	v_add_u32_e32 v211, 0x10000, v211
	s_waitcnt vmcnt(9)
	v_pk_add_f32 v[164:165], v[164:165], v[166:167]
	s_nop 0
	v_add_f32_e32 v214, v164, v165
	v_mov_b32_e32 v215, v214
	s_nop 1
	v_permlane16_swap_b32_e32 v214, v215
	s_nop 0
	v_add_f32_e32 v214, v214, v215
	v_mov_b32_e32 v215, v214
	s_nop 1
	v_permlane32_swap_b32_e32 v214, v215
	s_nop 0
	v_add_f32_e32 v214, v214, v215
	v_fmamk_f32 v214, v214, 0x3a800000, v248
	v_rsq_f32_e32 v216, v214
	s_nop 0
	v_pk_mul_f32 v[92:93], v[92:93], v[216:217] op_sel_hi:[1,0]
	v_pk_mul_f32 v[94:95], v[94:95], v[216:217] op_sel_hi:[1,0]
	v_pk_mul_f32 v[88:89], v[88:89], v[216:217] op_sel_hi:[1,0]
	v_pk_mul_f32 v[90:91], v[90:91], v[216:217] op_sel_hi:[1,0]
	v_pk_mul_f32 v[84:85], v[84:85], v[216:217] op_sel_hi:[1,0]
	v_pk_mul_f32 v[86:87], v[86:87], v[216:217] op_sel_hi:[1,0]
	v_pk_mul_f32 v[80:81], v[80:81], v[216:217] op_sel_hi:[1,0]
	v_pk_mul_f32 v[82:83], v[82:83], v[216:217] op_sel_hi:[1,0]
	v_pk_mul_f32 v[148:149], v[92:93], v[92:93]
	v_pk_fma_f32 v[148:149], v[94:95], v[94:95], v[148:149]
	v_pk_fma_f32 v[148:149], v[88:89], v[88:89], v[148:149]
	v_pk_fma_f32 v[148:149], v[90:91], v[90:91], v[148:149]
	v_pk_fma_f32 v[148:149], v[84:85], v[84:85], v[148:149]
	v_pk_fma_f32 v[148:149], v[86:87], v[86:87], v[148:149]
	v_pk_fma_f32 v[148:149], v[80:81], v[80:81], v[148:149]
	v_pk_fma_f32 v[148:149], v[82:83], v[82:83], v[148:149]
	v_add_f32_e32 v214, v148, v149
	v_mov_b32_e32 v215, v214
	s_nop 1
	v_permlane16_swap_b32_e32 v214, v215
	s_nop 0
	v_add_f32_e32 v214, v214, v215
	v_mov_b32_e32 v215, v214
	s_nop 1
	v_permlane32_swap_b32_e32 v214, v215
	s_nop 0
	v_add_f32_e32 v214, v214, v215
	v_fmamk_f32 v214, v214, 0x3c800000, v248
	v_rsq_f32_e32 v214, v214
	s_nop 0
	v_mul_f32_e32 v218, v155, v214
	v_pk_mul_f32 v[164:165], v[188:189], v[218:219] op_sel_hi:[1,0]
	v_pk_mul_f32 v[92:93], v[92:93], v[164:165]
	v_pk_mul_f32 v[164:165], v[190:191], v[218:219] op_sel_hi:[1,0]
	v_pk_mul_f32 v[94:95], v[94:95], v[164:165]
	v_pk_mul_f32 v[164:165], v[192:193], v[218:219] op_sel_hi:[1,0]
	v_pk_mul_f32 v[88:89], v[88:89], v[164:165]
	v_pk_mul_f32 v[164:165], v[194:195], v[218:219] op_sel_hi:[1,0]
	v_pk_mul_f32 v[90:91], v[90:91], v[164:165]
	v_cvt_pk_bf16_f32 v204, v92, v93
	v_cvt_pk_bf16_f32 v205, v94, v95
	v_cvt_pk_bf16_f32 v206, v88, v89
	v_cvt_pk_bf16_f32 v207, v90, v91
	global_store_dwordx4 v211, v[204:207], s[26:27]
	v_pk_mul_f32 v[164:165], v[196:197], v[218:219] op_sel_hi:[1,0]
	v_pk_mul_f32 v[84:85], v[84:85], v[164:165]
	v_pk_mul_f32 v[164:165], v[198:199], v[218:219] op_sel_hi:[1,0]
	v_pk_mul_f32 v[86:87], v[86:87], v[164:165]
	v_pk_mul_f32 v[164:165], v[200:201], v[218:219] op_sel_hi:[1,0]
	v_pk_mul_f32 v[80:81], v[80:81], v[164:165]
	v_pk_mul_f32 v[164:165], v[202:203], v[218:219] op_sel_hi:[1,0]
	v_pk_mul_f32 v[82:83], v[82:83], v[164:165]
	v_cvt_pk_bf16_f32 v144, v84, v85
	v_cvt_pk_bf16_f32 v145, v86, v87
	v_cvt_pk_bf16_f32 v146, v80, v81
	v_cvt_pk_bf16_f32 v147, v82, v83
	global_store_dwordx4 v211, v[144:147], s[26:27] offset:64
	v_add_u32_e32 v211, 0x10000, v211
	s_waitcnt vmcnt(10)
	v_pk_add_f32 v[168:169], v[168:169], v[170:171]
	s_nop 0
	v_add_f32_e32 v214, v168, v169
	v_mov_b32_e32 v215, v214
	s_nop 1
	v_permlane16_swap_b32_e32 v214, v215
	s_nop 0
	v_add_f32_e32 v214, v214, v215
	v_mov_b32_e32 v215, v214
	s_nop 1
	v_permlane32_swap_b32_e32 v214, v215
	s_nop 0
	v_add_f32_e32 v214, v214, v215
	v_fmamk_f32 v214, v214, 0x3a800000, v248
	v_rsq_f32_e32 v216, v214
	s_nop 0
	v_pk_mul_f32 v[76:77], v[76:77], v[216:217] op_sel_hi:[1,0]
	v_pk_mul_f32 v[78:79], v[78:79], v[216:217] op_sel_hi:[1,0]
	v_pk_mul_f32 v[72:73], v[72:73], v[216:217] op_sel_hi:[1,0]
	v_pk_mul_f32 v[74:75], v[74:75], v[216:217] op_sel_hi:[1,0]
	v_pk_mul_f32 v[68:69], v[68:69], v[216:217] op_sel_hi:[1,0]
	v_pk_mul_f32 v[70:71], v[70:71], v[216:217] op_sel_hi:[1,0]
	v_pk_mul_f32 v[64:65], v[64:65], v[216:217] op_sel_hi:[1,0]
	v_pk_mul_f32 v[66:67], v[66:67], v[216:217] op_sel_hi:[1,0]
	v_pk_mul_f32 v[148:149], v[76:77], v[76:77]
	v_pk_fma_f32 v[148:149], v[78:79], v[78:79], v[148:149]
	v_pk_fma_f32 v[148:149], v[72:73], v[72:73], v[148:149]
	v_pk_fma_f32 v[148:149], v[74:75], v[74:75], v[148:149]
	v_pk_fma_f32 v[148:149], v[68:69], v[68:69], v[148:149]
	v_pk_fma_f32 v[148:149], v[70:71], v[70:71], v[148:149]
	v_pk_fma_f32 v[148:149], v[64:65], v[64:65], v[148:149]
	v_pk_fma_f32 v[148:149], v[66:67], v[66:67], v[148:149]
	v_add_f32_e32 v214, v148, v149
	v_mov_b32_e32 v215, v214
	s_nop 1
	v_permlane16_swap_b32_e32 v214, v215
	s_nop 0
	v_add_f32_e32 v214, v214, v215
	v_mov_b32_e32 v215, v214
	s_nop 1
	v_permlane32_swap_b32_e32 v214, v215
	s_nop 0
	v_add_f32_e32 v214, v214, v215
	v_fmamk_f32 v214, v214, 0x3c800000, v248
	v_rsq_f32_e32 v214, v214
	s_nop 0
	v_mul_f32_e32 v218, v155, v214
	v_pk_mul_f32 v[168:169], v[188:189], v[218:219] op_sel_hi:[1,0]
	v_pk_mul_f32 v[76:77], v[76:77], v[168:169]
	v_pk_mul_f32 v[168:169], v[190:191], v[218:219] op_sel_hi:[1,0]
	v_pk_mul_f32 v[78:79], v[78:79], v[168:169]
	v_pk_mul_f32 v[168:169], v[192:193], v[218:219] op_sel_hi:[1,0]
	v_pk_mul_f32 v[72:73], v[72:73], v[168:169]
	v_pk_mul_f32 v[168:169], v[194:195], v[218:219] op_sel_hi:[1,0]
	v_pk_mul_f32 v[74:75], v[74:75], v[168:169]
	v_cvt_pk_bf16_f32 v204, v76, v77
	v_cvt_pk_bf16_f32 v205, v78, v79
	v_cvt_pk_bf16_f32 v206, v72, v73
	v_cvt_pk_bf16_f32 v207, v74, v75
	global_store_dwordx4 v211, v[204:207], s[26:27]
	v_pk_mul_f32 v[168:169], v[196:197], v[218:219] op_sel_hi:[1,0]
	v_pk_mul_f32 v[68:69], v[68:69], v[168:169]
	v_pk_mul_f32 v[168:169], v[198:199], v[218:219] op_sel_hi:[1,0]
	v_pk_mul_f32 v[70:71], v[70:71], v[168:169]
	v_pk_mul_f32 v[168:169], v[200:201], v[218:219] op_sel_hi:[1,0]
	v_pk_mul_f32 v[64:65], v[64:65], v[168:169]
	v_pk_mul_f32 v[168:169], v[202:203], v[218:219] op_sel_hi:[1,0]
	v_pk_mul_f32 v[66:67], v[66:67], v[168:169]
	v_cvt_pk_bf16_f32 v144, v68, v69
	v_cvt_pk_bf16_f32 v145, v70, v71
	v_cvt_pk_bf16_f32 v146, v64, v65
	v_cvt_pk_bf16_f32 v147, v66, v67
	global_store_dwordx4 v211, v[144:147], s[26:27] offset:64
	v_add_u32_e32 v211, 0x50000, v211
	s_waitcnt vmcnt(11)
	v_pk_add_f32 v[172:173], v[172:173], v[174:175]
	s_nop 0
	v_add_f32_e32 v214, v172, v173
	v_mov_b32_e32 v215, v214
	s_nop 1
	v_permlane16_swap_b32_e32 v214, v215
	s_nop 0
	v_add_f32_e32 v214, v214, v215
	v_mov_b32_e32 v215, v214
	s_nop 1
	v_permlane32_swap_b32_e32 v214, v215
	s_nop 0
	v_add_f32_e32 v214, v214, v215
	v_fmamk_f32 v214, v214, 0x3a800000, v248
	v_rsq_f32_e32 v216, v214
	s_nop 0
	v_pk_mul_f32 v[60:61], v[60:61], v[216:217] op_sel_hi:[1,0]
	v_pk_mul_f32 v[62:63], v[62:63], v[216:217] op_sel_hi:[1,0]
	v_pk_mul_f32 v[56:57], v[56:57], v[216:217] op_sel_hi:[1,0]
	v_pk_mul_f32 v[58:59], v[58:59], v[216:217] op_sel_hi:[1,0]
	v_pk_mul_f32 v[52:53], v[52:53], v[216:217] op_sel_hi:[1,0]
	v_pk_mul_f32 v[54:55], v[54:55], v[216:217] op_sel_hi:[1,0]
	v_pk_mul_f32 v[48:49], v[48:49], v[216:217] op_sel_hi:[1,0]
	v_pk_mul_f32 v[50:51], v[50:51], v[216:217] op_sel_hi:[1,0]
	v_pk_mul_f32 v[148:149], v[60:61], v[60:61]
	v_pk_fma_f32 v[148:149], v[62:63], v[62:63], v[148:149]
	v_pk_fma_f32 v[148:149], v[56:57], v[56:57], v[148:149]
	v_pk_fma_f32 v[148:149], v[58:59], v[58:59], v[148:149]
	v_pk_fma_f32 v[148:149], v[52:53], v[52:53], v[148:149]
	v_pk_fma_f32 v[148:149], v[54:55], v[54:55], v[148:149]
	v_pk_fma_f32 v[148:149], v[48:49], v[48:49], v[148:149]
	v_pk_fma_f32 v[148:149], v[50:51], v[50:51], v[148:149]
	v_add_f32_e32 v214, v148, v149
	v_mov_b32_e32 v215, v214
	s_nop 1
	v_permlane16_swap_b32_e32 v214, v215
	s_nop 0
	v_add_f32_e32 v214, v214, v215
	v_mov_b32_e32 v215, v214
	s_nop 1
	v_permlane32_swap_b32_e32 v214, v215
	s_nop 0
	v_add_f32_e32 v214, v214, v215
	v_fmamk_f32 v214, v214, 0x3c800000, v248
	v_rsq_f32_e32 v214, v214
	s_nop 0
	v_mul_f32_e32 v218, v155, v214
	v_pk_mul_f32 v[172:173], v[188:189], v[218:219] op_sel_hi:[1,0]
	v_pk_mul_f32 v[60:61], v[60:61], v[172:173]
	v_pk_mul_f32 v[172:173], v[190:191], v[218:219] op_sel_hi:[1,0]
	v_pk_mul_f32 v[62:63], v[62:63], v[172:173]
	v_pk_mul_f32 v[172:173], v[192:193], v[218:219] op_sel_hi:[1,0]
	v_pk_mul_f32 v[56:57], v[56:57], v[172:173]
	v_pk_mul_f32 v[172:173], v[194:195], v[218:219] op_sel_hi:[1,0]
	v_pk_mul_f32 v[58:59], v[58:59], v[172:173]
	v_cvt_pk_bf16_f32 v204, v60, v61
	v_cvt_pk_bf16_f32 v205, v62, v63
	v_cvt_pk_bf16_f32 v206, v56, v57
	v_cvt_pk_bf16_f32 v207, v58, v59
	global_store_dwordx4 v211, v[204:207], s[26:27]
	v_pk_mul_f32 v[172:173], v[196:197], v[218:219] op_sel_hi:[1,0]
	v_pk_mul_f32 v[52:53], v[52:53], v[172:173]
	v_pk_mul_f32 v[172:173], v[198:199], v[218:219] op_sel_hi:[1,0]
	v_pk_mul_f32 v[54:55], v[54:55], v[172:173]
	v_pk_mul_f32 v[172:173], v[200:201], v[218:219] op_sel_hi:[1,0]
	v_pk_mul_f32 v[48:49], v[48:49], v[172:173]
	v_pk_mul_f32 v[172:173], v[202:203], v[218:219] op_sel_hi:[1,0]
	v_pk_mul_f32 v[50:51], v[50:51], v[172:173]
	v_cvt_pk_bf16_f32 v144, v52, v53
	v_cvt_pk_bf16_f32 v145, v54, v55
	v_cvt_pk_bf16_f32 v146, v48, v49
	v_cvt_pk_bf16_f32 v147, v50, v51
	global_store_dwordx4 v211, v[144:147], s[26:27] offset:64
	v_add_u32_e32 v211, 0x10000, v211
	s_waitcnt vmcnt(12)
	v_pk_add_f32 v[176:177], v[176:177], v[178:179]
	s_nop 0
	v_add_f32_e32 v214, v176, v177
	v_mov_b32_e32 v215, v214
	s_nop 1
	v_permlane16_swap_b32_e32 v214, v215
	s_nop 0
	v_add_f32_e32 v214, v214, v215
	v_mov_b32_e32 v215, v214
	s_nop 1
	v_permlane32_swap_b32_e32 v214, v215
	s_nop 0
	v_add_f32_e32 v214, v214, v215
	v_fmamk_f32 v214, v214, 0x3a800000, v248
	v_rsq_f32_e32 v216, v214
	s_nop 0
	v_pk_mul_f32 v[44:45], v[44:45], v[216:217] op_sel_hi:[1,0]
	v_pk_mul_f32 v[46:47], v[46:47], v[216:217] op_sel_hi:[1,0]
	v_pk_mul_f32 v[40:41], v[40:41], v[216:217] op_sel_hi:[1,0]
	v_pk_mul_f32 v[42:43], v[42:43], v[216:217] op_sel_hi:[1,0]
	v_pk_mul_f32 v[36:37], v[36:37], v[216:217] op_sel_hi:[1,0]
	v_pk_mul_f32 v[38:39], v[38:39], v[216:217] op_sel_hi:[1,0]
	v_pk_mul_f32 v[32:33], v[32:33], v[216:217] op_sel_hi:[1,0]
	v_pk_mul_f32 v[34:35], v[34:35], v[216:217] op_sel_hi:[1,0]
	v_pk_mul_f32 v[148:149], v[44:45], v[44:45]
	v_pk_fma_f32 v[148:149], v[46:47], v[46:47], v[148:149]
	v_pk_fma_f32 v[148:149], v[40:41], v[40:41], v[148:149]
	v_pk_fma_f32 v[148:149], v[42:43], v[42:43], v[148:149]
	v_pk_fma_f32 v[148:149], v[36:37], v[36:37], v[148:149]
	v_pk_fma_f32 v[148:149], v[38:39], v[38:39], v[148:149]
	v_pk_fma_f32 v[148:149], v[32:33], v[32:33], v[148:149]
	v_pk_fma_f32 v[148:149], v[34:35], v[34:35], v[148:149]
	v_add_f32_e32 v214, v148, v149
	v_mov_b32_e32 v215, v214
	s_nop 1
	v_permlane16_swap_b32_e32 v214, v215
	s_nop 0
	v_add_f32_e32 v214, v214, v215
	v_mov_b32_e32 v215, v214
	s_nop 1
	v_permlane32_swap_b32_e32 v214, v215
	s_nop 0
	v_add_f32_e32 v214, v214, v215
	v_fmamk_f32 v214, v214, 0x3c800000, v248
	v_rsq_f32_e32 v214, v214
	s_nop 0
	v_mul_f32_e32 v218, v155, v214
	v_pk_mul_f32 v[176:177], v[188:189], v[218:219] op_sel_hi:[1,0]
	v_pk_mul_f32 v[44:45], v[44:45], v[176:177]
	v_pk_mul_f32 v[176:177], v[190:191], v[218:219] op_sel_hi:[1,0]
	v_pk_mul_f32 v[46:47], v[46:47], v[176:177]
	v_pk_mul_f32 v[176:177], v[192:193], v[218:219] op_sel_hi:[1,0]
	v_pk_mul_f32 v[40:41], v[40:41], v[176:177]
	v_pk_mul_f32 v[176:177], v[194:195], v[218:219] op_sel_hi:[1,0]
	v_pk_mul_f32 v[42:43], v[42:43], v[176:177]
	v_cvt_pk_bf16_f32 v204, v44, v45
	v_cvt_pk_bf16_f32 v205, v46, v47
	v_cvt_pk_bf16_f32 v206, v40, v41
	v_cvt_pk_bf16_f32 v207, v42, v43
	global_store_dwordx4 v211, v[204:207], s[26:27]
	v_pk_mul_f32 v[176:177], v[196:197], v[218:219] op_sel_hi:[1,0]
	v_pk_mul_f32 v[36:37], v[36:37], v[176:177]
	v_pk_mul_f32 v[176:177], v[198:199], v[218:219] op_sel_hi:[1,0]
	v_pk_mul_f32 v[38:39], v[38:39], v[176:177]
	v_pk_mul_f32 v[176:177], v[200:201], v[218:219] op_sel_hi:[1,0]
	v_pk_mul_f32 v[32:33], v[32:33], v[176:177]
	v_pk_mul_f32 v[176:177], v[202:203], v[218:219] op_sel_hi:[1,0]
	v_pk_mul_f32 v[34:35], v[34:35], v[176:177]
	v_cvt_pk_bf16_f32 v144, v36, v37
	v_cvt_pk_bf16_f32 v145, v38, v39
	v_cvt_pk_bf16_f32 v146, v32, v33
	v_cvt_pk_bf16_f32 v147, v34, v35
	global_store_dwordx4 v211, v[144:147], s[26:27] offset:64
	v_add_u32_e32 v211, 0x10000, v211
	s_waitcnt vmcnt(13)
	v_pk_add_f32 v[180:181], v[180:181], v[182:183]
	s_nop 0
	v_add_f32_e32 v214, v180, v181
	v_mov_b32_e32 v215, v214
	s_nop 1
	v_permlane16_swap_b32_e32 v214, v215
	s_nop 0
	v_add_f32_e32 v214, v214, v215
	v_mov_b32_e32 v215, v214
	s_nop 1
	v_permlane32_swap_b32_e32 v214, v215
	s_nop 0
	v_add_f32_e32 v214, v214, v215
	v_fmamk_f32 v214, v214, 0x3a800000, v248
	v_rsq_f32_e32 v216, v214
	s_nop 0
	v_pk_mul_f32 v[28:29], v[28:29], v[216:217] op_sel_hi:[1,0]
	v_pk_mul_f32 v[30:31], v[30:31], v[216:217] op_sel_hi:[1,0]
	v_pk_mul_f32 v[24:25], v[24:25], v[216:217] op_sel_hi:[1,0]
	v_pk_mul_f32 v[26:27], v[26:27], v[216:217] op_sel_hi:[1,0]
	v_pk_mul_f32 v[20:21], v[20:21], v[216:217] op_sel_hi:[1,0]
	v_pk_mul_f32 v[22:23], v[22:23], v[216:217] op_sel_hi:[1,0]
	v_pk_mul_f32 v[16:17], v[16:17], v[216:217] op_sel_hi:[1,0]
	v_pk_mul_f32 v[18:19], v[18:19], v[216:217] op_sel_hi:[1,0]
	v_pk_mul_f32 v[148:149], v[28:29], v[28:29]
	v_pk_fma_f32 v[148:149], v[30:31], v[30:31], v[148:149]
	v_pk_fma_f32 v[148:149], v[24:25], v[24:25], v[148:149]
	v_pk_fma_f32 v[148:149], v[26:27], v[26:27], v[148:149]
	v_pk_fma_f32 v[148:149], v[20:21], v[20:21], v[148:149]
	v_pk_fma_f32 v[148:149], v[22:23], v[22:23], v[148:149]
	v_pk_fma_f32 v[148:149], v[16:17], v[16:17], v[148:149]
	v_pk_fma_f32 v[148:149], v[18:19], v[18:19], v[148:149]
	v_add_f32_e32 v214, v148, v149
	v_mov_b32_e32 v215, v214
	s_nop 1
	v_permlane16_swap_b32_e32 v214, v215
	s_nop 0
	v_add_f32_e32 v214, v214, v215
	v_mov_b32_e32 v215, v214
	s_nop 1
	v_permlane32_swap_b32_e32 v214, v215
	s_nop 0
	v_add_f32_e32 v214, v214, v215
	v_fmamk_f32 v214, v214, 0x3c800000, v248
	v_rsq_f32_e32 v214, v214
	s_nop 0
	v_mul_f32_e32 v218, v155, v214
	v_pk_mul_f32 v[180:181], v[188:189], v[218:219] op_sel_hi:[1,0]
	v_pk_mul_f32 v[28:29], v[28:29], v[180:181]
	v_pk_mul_f32 v[180:181], v[190:191], v[218:219] op_sel_hi:[1,0]
	v_pk_mul_f32 v[30:31], v[30:31], v[180:181]
	v_pk_mul_f32 v[180:181], v[192:193], v[218:219] op_sel_hi:[1,0]
	v_pk_mul_f32 v[24:25], v[24:25], v[180:181]
	v_pk_mul_f32 v[180:181], v[194:195], v[218:219] op_sel_hi:[1,0]
	v_pk_mul_f32 v[26:27], v[26:27], v[180:181]
	v_cvt_pk_bf16_f32 v204, v28, v29
	v_cvt_pk_bf16_f32 v205, v30, v31
	v_cvt_pk_bf16_f32 v206, v24, v25
	v_cvt_pk_bf16_f32 v207, v26, v27
	global_store_dwordx4 v211, v[204:207], s[26:27]
	v_pk_mul_f32 v[180:181], v[196:197], v[218:219] op_sel_hi:[1,0]
	v_pk_mul_f32 v[20:21], v[20:21], v[180:181]
	v_pk_mul_f32 v[180:181], v[198:199], v[218:219] op_sel_hi:[1,0]
	v_pk_mul_f32 v[22:23], v[22:23], v[180:181]
	v_pk_mul_f32 v[180:181], v[200:201], v[218:219] op_sel_hi:[1,0]
	v_pk_mul_f32 v[16:17], v[16:17], v[180:181]
	v_pk_mul_f32 v[180:181], v[202:203], v[218:219] op_sel_hi:[1,0]
	v_pk_mul_f32 v[18:19], v[18:19], v[180:181]
	v_cvt_pk_bf16_f32 v144, v20, v21
	v_cvt_pk_bf16_f32 v145, v22, v23
	v_cvt_pk_bf16_f32 v146, v16, v17
	v_cvt_pk_bf16_f32 v147, v18, v19
	global_store_dwordx4 v211, v[144:147], s[26:27] offset:64
	v_add_u32_e32 v211, 0x10000, v211
	s_waitcnt vmcnt(14)
	v_pk_add_f32 v[184:185], v[184:185], v[186:187]
	s_nop 0
	v_add_f32_e32 v214, v184, v185
	v_mov_b32_e32 v215, v214
	s_nop 1
	v_permlane16_swap_b32_e32 v214, v215
	s_nop 0
	v_add_f32_e32 v214, v214, v215
	v_mov_b32_e32 v215, v214
	s_nop 1
	v_permlane32_swap_b32_e32 v214, v215
	s_nop 0
	v_add_f32_e32 v214, v214, v215
	v_fmamk_f32 v214, v214, 0x3a800000, v248
	v_rsq_f32_e32 v216, v214
	s_nop 0
	v_pk_mul_f32 v[12:13], v[12:13], v[216:217] op_sel_hi:[1,0]
	v_pk_mul_f32 v[14:15], v[14:15], v[216:217] op_sel_hi:[1,0]
	v_pk_mul_f32 v[8:9], v[8:9], v[216:217] op_sel_hi:[1,0]
	v_pk_mul_f32 v[10:11], v[10:11], v[216:217] op_sel_hi:[1,0]
	v_pk_mul_f32 v[4:5], v[4:5], v[216:217] op_sel_hi:[1,0]
	v_pk_mul_f32 v[6:7], v[6:7], v[216:217] op_sel_hi:[1,0]
	v_pk_mul_f32 v[0:1], v[0:1], v[216:217] op_sel_hi:[1,0]
	v_pk_mul_f32 v[2:3], v[2:3], v[216:217] op_sel_hi:[1,0]
	v_pk_mul_f32 v[148:149], v[12:13], v[12:13]
	v_pk_fma_f32 v[148:149], v[14:15], v[14:15], v[148:149]
	v_pk_fma_f32 v[148:149], v[8:9], v[8:9], v[148:149]
	v_pk_fma_f32 v[148:149], v[10:11], v[10:11], v[148:149]
	v_pk_fma_f32 v[148:149], v[4:5], v[4:5], v[148:149]
	v_pk_fma_f32 v[148:149], v[6:7], v[6:7], v[148:149]
	v_pk_fma_f32 v[148:149], v[0:1], v[0:1], v[148:149]
	v_pk_fma_f32 v[148:149], v[2:3], v[2:3], v[148:149]
	v_add_f32_e32 v214, v148, v149
	v_mov_b32_e32 v215, v214
	s_nop 1
	v_permlane16_swap_b32_e32 v214, v215
	s_nop 0
	v_add_f32_e32 v214, v214, v215
	v_mov_b32_e32 v215, v214
	s_nop 1
	v_permlane32_swap_b32_e32 v214, v215
	s_nop 0
	v_add_f32_e32 v214, v214, v215
	v_fmamk_f32 v214, v214, 0x3c800000, v248
	v_rsq_f32_e32 v214, v214
	s_nop 0
	v_mul_f32_e32 v218, v155, v214
	v_pk_mul_f32 v[184:185], v[188:189], v[218:219] op_sel_hi:[1,0]
	v_pk_mul_f32 v[12:13], v[12:13], v[184:185]
	v_pk_mul_f32 v[184:185], v[190:191], v[218:219] op_sel_hi:[1,0]
	v_pk_mul_f32 v[14:15], v[14:15], v[184:185]
	v_pk_mul_f32 v[184:185], v[192:193], v[218:219] op_sel_hi:[1,0]
	v_pk_mul_f32 v[8:9], v[8:9], v[184:185]
	v_pk_mul_f32 v[184:185], v[194:195], v[218:219] op_sel_hi:[1,0]
	v_pk_mul_f32 v[10:11], v[10:11], v[184:185]
	v_cvt_pk_bf16_f32 v204, v12, v13
	v_cvt_pk_bf16_f32 v205, v14, v15
	v_cvt_pk_bf16_f32 v206, v8, v9
	v_cvt_pk_bf16_f32 v207, v10, v11
	global_store_dwordx4 v211, v[204:207], s[26:27]
	v_pk_mul_f32 v[184:185], v[196:197], v[218:219] op_sel_hi:[1,0]
	v_pk_mul_f32 v[4:5], v[4:5], v[184:185]
	v_pk_mul_f32 v[184:185], v[198:199], v[218:219] op_sel_hi:[1,0]
	v_pk_mul_f32 v[6:7], v[6:7], v[184:185]
	v_pk_mul_f32 v[184:185], v[200:201], v[218:219] op_sel_hi:[1,0]
	v_pk_mul_f32 v[0:1], v[0:1], v[184:185]
	v_pk_mul_f32 v[184:185], v[202:203], v[218:219] op_sel_hi:[1,0]
	v_pk_mul_f32 v[2:3], v[2:3], v[184:185]
	v_cvt_pk_bf16_f32 v144, v4, v5
	v_cvt_pk_bf16_f32 v145, v6, v7
	v_cvt_pk_bf16_f32 v146, v0, v1
	v_cvt_pk_bf16_f32 v147, v2, v3
	global_store_dwordx4 v211, v[144:147], s[26:27] offset:64
	s_and_b64 vcc, exec, s[4:5]
	s_mov_b64 s[26:27], s[22:23]
	s_cbranch_vccz .LBB0_691
	s_waitcnt vmcnt(0)
	s_cmpk_gt_u32 s54, 0xff
	s_cbranch_scc1 .LBB0_702
	s_barrier

.LBB0_714:
	s_add_u32 s26, s6, 0xfffc0080
	s_addc_u32 s27, s7, -1
	s_add_i32 s63, 0, 0x10000
	v_add_u32_e32 v140, s63, v165
	ds_read_b128 v[128:131], v140
	ds_read_b128 v[132:135], v140 offset:1024
	ds_read_b128 v[136:139], v140 offset:2048
	ds_read_b128 v[140:143], v140 offset:3072
	s_cmp_eq_u32 s51, 12
	s_cselect_b32 s29, s21, s27
	s_cselect_b32 s28, s38, s26
	s_cselect_b32 s27, s11, s50
	s_cselect_b32 s26, s39, s46
	s_add_i32 m0, s56, 0xc000
	ds_read_b128 v[154:157], v167
	ds_read_b128 v[158:161], v167 offset:1024
	ds_read_b128 v[168:171], v167 offset:2048
	ds_read_b128 v[172:175], v167 offset:3072
	ds_read_b128 v[176:179], v167 offset:4096
	ds_read_b128 v[180:183], v167 offset:5120
	ds_read_b128 v[184:187], v167 offset:6144
	global_load_lds_dwordx4 v150, s[6:7]
	s_add_i32 m0, s56, 0xe000
	ds_read_b128 v[188:191], v167 offset:7168
	global_load_lds_dwordx4 v152, s[6:7]
	s_waitcnt lgkmcnt(8)
	s_barrier
	s_waitcnt lgkmcnt(0)
	v_mfma_f32_16x16x32_bf16 v[124:127], v[128:131], v[154:157], v[124:127]
	v_mfma_f32_16x16x32_bf16 v[120:123], v[136:139], v[154:157], v[120:123]
	v_mfma_f32_16x16x32_bf16 v[116:119], v[128:131], v[168:171], v[116:119]
	v_mfma_f32_16x16x32_bf16 v[112:115], v[136:139], v[168:171], v[112:115]
	v_mfma_f32_16x16x32_bf16 v[108:111], v[128:131], v[176:179], v[108:111]
	v_mfma_f32_16x16x32_bf16 v[104:107], v[136:139], v[176:179], v[104:107]
	v_mfma_f32_16x16x32_bf16 v[100:103], v[128:131], v[184:187], v[100:103]
	v_mfma_f32_16x16x32_bf16 v[96:99], v[136:139], v[184:187], v[96:99]
	v_mfma_f32_16x16x32_bf16 v[124:127], v[132:135], v[158:161], v[124:127]
	v_mfma_f32_16x16x32_bf16 v[120:123], v[140:143], v[158:161], v[120:123]
	v_mfma_f32_16x16x32_bf16 v[116:119], v[132:135], v[172:175], v[116:119]
	v_mfma_f32_16x16x32_bf16 v[112:115], v[140:143], v[172:175], v[112:115]
	v_mfma_f32_16x16x32_bf16 v[108:111], v[132:135], v[180:183], v[108:111]
	v_mfma_f32_16x16x32_bf16 v[104:107], v[140:143], v[180:183], v[104:107]
	v_mfma_f32_16x16x32_bf16 v[100:103], v[132:135], v[188:191], v[100:103]
	v_mfma_f32_16x16x32_bf16 v[96:99], v[140:143], v[188:191], v[96:99]
	s_barrier
	s_add_i32 s66, 0, 0x14000
	v_add_u32_e32 v162, s66, v165
	s_add_i32 s63, s63, s55
	ds_read_b128 v[192:195], v162
	ds_read_b128 v[196:199], v162 offset:1024
	ds_read_b128 v[200:203], v162 offset:2048
	ds_read_b128 v[204:207], v162 offset:3072
	s_add_u32 s98, s26, s40
	s_addc_u32 s99, s27, s41
	s_mov_b32 m0, s63
	s_nop 0
	global_load_lds_dwordx4 v208, s[26:27]
	s_add_i32 m0, s63, 0x2000
	s_nop 0
	global_load_lds_dwordx4 v144, s[26:27]
	s_barrier
	s_waitcnt lgkmcnt(0)
	v_mfma_f32_16x16x32_bf16 v[60:63], v[192:195], v[154:157], v[60:63]
	v_mfma_f32_16x16x32_bf16 v[56:59], v[200:203], v[154:157], v[56:59]
	v_mfma_f32_16x16x32_bf16 v[52:55], v[192:195], v[168:171], v[52:55]
	v_mfma_f32_16x16x32_bf16 v[48:51], v[200:203], v[168:171], v[48:51]
	v_mfma_f32_16x16x32_bf16 v[44:47], v[192:195], v[176:179], v[44:47]
	v_mfma_f32_16x16x32_bf16 v[40:43], v[200:203], v[176:179], v[40:43]
	v_mfma_f32_16x16x32_bf16 v[36:39], v[192:195], v[184:187], v[36:39]
	v_mfma_f32_16x16x32_bf16 v[32:35], v[200:203], v[184:187], v[32:35]
	v_mfma_f32_16x16x32_bf16 v[60:63], v[196:199], v[158:161], v[60:63]
	v_mfma_f32_16x16x32_bf16 v[56:59], v[204:207], v[158:161], v[56:59]
	v_mfma_f32_16x16x32_bf16 v[52:55], v[196:199], v[172:175], v[52:55]
	v_mfma_f32_16x16x32_bf16 v[48:51], v[204:207], v[172:175], v[48:51]
	v_mfma_f32_16x16x32_bf16 v[44:47], v[196:199], v[180:183], v[44:47]
	v_mfma_f32_16x16x32_bf16 v[40:43], v[204:207], v[180:183], v[40:43]
	v_mfma_f32_16x16x32_bf16 v[36:39], v[196:199], v[188:191], v[36:39]
	v_mfma_f32_16x16x32_bf16 v[32:35], v[204:207], v[188:191], v[32:35]
	s_mov_b32 m0, s56
	s_add_u32 s100, s28, s40
	s_addc_u32 s101, s29, s41
	s_barrier
	ds_read_b128 v[154:157], v167 offset:16384
	ds_read_b128 v[158:161], v167 offset:17408
	ds_read_b128 v[168:171], v167 offset:18432
	ds_read_b128 v[172:175], v167 offset:19456
	ds_read_b128 v[176:179], v167 offset:20480
	ds_read_b128 v[180:183], v167 offset:21504
	ds_read_b128 v[184:187], v167 offset:22528
	global_load_lds_dwordx4 v148, s[28:29]
	s_mov_b32 m0, s57
	ds_read_b128 v[188:191], v167 offset:23552
	global_load_lds_dwordx4 v146, s[28:29]
	s_barrier
	s_waitcnt lgkmcnt(0)
	v_mfma_f32_16x16x32_bf16 v[92:95], v[128:131], v[154:157], v[92:95]
	v_mfma_f32_16x16x32_bf16 v[88:91], v[136:139], v[154:157], v[88:91]
	v_mfma_f32_16x16x32_bf16 v[84:87], v[128:131], v[168:171], v[84:87]
	v_mfma_f32_16x16x32_bf16 v[80:83], v[136:139], v[168:171], v[80:83]
	v_mfma_f32_16x16x32_bf16 v[76:79], v[128:131], v[176:179], v[76:79]
	v_mfma_f32_16x16x32_bf16 v[72:75], v[136:139], v[176:179], v[72:75]
	v_mfma_f32_16x16x32_bf16 v[68:71], v[128:131], v[184:187], v[68:71]
	v_mfma_f32_16x16x32_bf16 v[64:67], v[136:139], v[184:187], v[64:67]
	v_mfma_f32_16x16x32_bf16 v[92:95], v[132:135], v[158:161], v[92:95]
	v_mfma_f32_16x16x32_bf16 v[88:91], v[140:143], v[158:161], v[88:91]
	v_mfma_f32_16x16x32_bf16 v[84:87], v[132:135], v[172:175], v[84:87]
	v_mfma_f32_16x16x32_bf16 v[80:83], v[140:143], v[172:175], v[80:83]
	v_mfma_f32_16x16x32_bf16 v[76:79], v[132:135], v[180:183], v[76:79]
	v_mfma_f32_16x16x32_bf16 v[72:75], v[140:143], v[180:183], v[72:75]
	v_mfma_f32_16x16x32_bf16 v[68:71], v[132:135], v[188:191], v[68:71]
	v_mfma_f32_16x16x32_bf16 v[64:67], v[140:143], v[188:191], v[64:67]
	s_barrier
	s_add_u32 s64, s26, 0x40000
	s_addc_u32 s65, s27, 0
	s_add_i32 s63, s66, s55
	s_mov_b32 m0, s63
	s_nop 0
	global_load_lds_dwordx4 v208, s[64:65]
	s_add_i32 m0, s63, 0x2000
	s_nop 0
	global_load_lds_dwordx4 v144, s[64:65]
	s_waitcnt vmcnt(6)
	s_barrier
	v_mfma_f32_16x16x32_bf16 v[28:31], v[192:195], v[154:157], v[28:31]
	v_mfma_f32_16x16x32_bf16 v[24:27], v[200:203], v[154:157], v[24:27]
	v_mfma_f32_16x16x32_bf16 v[20:23], v[192:195], v[168:171], v[20:23]
	v_mfma_f32_16x16x32_bf16 v[16:19], v[200:203], v[168:171], v[16:19]
	v_mfma_f32_16x16x32_bf16 v[12:15], v[192:195], v[176:179], v[12:15]
	v_mfma_f32_16x16x32_bf16 v[8:11], v[200:203], v[176:179], v[8:11]
	v_mfma_f32_16x16x32_bf16 v[4:7], v[192:195], v[184:187], v[4:7]
	v_mfma_f32_16x16x32_bf16 v[0:3], v[200:203], v[184:187], v[0:3]
	v_mfma_f32_16x16x32_bf16 v[28:31], v[196:199], v[158:161], v[28:31]
	v_mfma_f32_16x16x32_bf16 v[24:27], v[204:207], v[158:161], v[24:27]
	v_mfma_f32_16x16x32_bf16 v[20:23], v[196:199], v[172:175], v[20:23]
	v_mfma_f32_16x16x32_bf16 v[16:19], v[204:207], v[172:175], v[16:19]
	v_mfma_f32_16x16x32_bf16 v[12:15], v[196:199], v[180:183], v[12:15]
	v_mfma_f32_16x16x32_bf16 v[8:11], v[204:207], v[180:183], v[8:11]
	v_mfma_f32_16x16x32_bf16 v[4:7], v[196:199], v[188:191], v[4:7]
	v_mfma_f32_16x16x32_bf16 v[0:3], v[204:207], v[188:191], v[0:3]
	s_add_i32 s63, 0, 0x18000
	v_add_u32_e32 v140, s63, v165
	s_barrier
	ds_read_b128 v[128:131], v140
	ds_read_b128 v[132:135], v140 offset:1024
	ds_read_b128 v[136:139], v140 offset:2048
	ds_read_b128 v[140:143], v140 offset:3072
	s_add_u32 s28, s28, 0x40000
	s_addc_u32 s29, s29, 0
	s_mov_b32 m0, s58
	ds_read_b128 v[154:157], v167 offset:32768
	ds_read_b128 v[158:161], v167 offset:33792
	ds_read_b128 v[168:171], v167 offset:34816
	ds_read_b128 v[172:175], v167 offset:35840
	ds_read_b128 v[176:179], v167 offset:36864
	ds_read_b128 v[180:183], v167 offset:37888
	ds_read_b128 v[184:187], v167 offset:38912
	global_load_lds_dwordx4 v148, s[28:29]
	s_mov_b32 m0, s59
	ds_read_b128 v[188:191], v167 offset:39936
	global_load_lds_dwordx4 v146, s[28:29]
	s_waitcnt lgkmcnt(8)
	s_barrier
	s_waitcnt lgkmcnt(0)
	v_mfma_f32_16x16x32_bf16 v[124:127], v[128:131], v[154:157], v[124:127]
	v_mfma_f32_16x16x32_bf16 v[120:123], v[136:139], v[154:157], v[120:123]
	v_mfma_f32_16x16x32_bf16 v[116:119], v[128:131], v[168:171], v[116:119]
	v_mfma_f32_16x16x32_bf16 v[112:115], v[136:139], v[168:171], v[112:115]
	v_mfma_f32_16x16x32_bf16 v[108:111], v[128:131], v[176:179], v[108:111]
	v_mfma_f32_16x16x32_bf16 v[104:107], v[136:139], v[176:179], v[104:107]
	v_mfma_f32_16x16x32_bf16 v[100:103], v[128:131], v[184:187], v[100:103]
	v_mfma_f32_16x16x32_bf16 v[96:99], v[136:139], v[184:187], v[96:99]
	v_mfma_f32_16x16x32_bf16 v[124:127], v[132:135], v[158:161], v[124:127]
	v_mfma_f32_16x16x32_bf16 v[120:123], v[140:143], v[158:161], v[120:123]
	v_mfma_f32_16x16x32_bf16 v[116:119], v[132:135], v[172:175], v[116:119]
	v_mfma_f32_16x16x32_bf16 v[112:115], v[140:143], v[172:175], v[112:115]
	v_mfma_f32_16x16x32_bf16 v[108:111], v[132:135], v[180:183], v[108:111]
	v_mfma_f32_16x16x32_bf16 v[104:107], v[140:143], v[180:183], v[104:107]
	v_mfma_f32_16x16x32_bf16 v[100:103], v[132:135], v[188:191], v[100:103]
	v_mfma_f32_16x16x32_bf16 v[96:99], v[140:143], v[188:191], v[96:99]
	s_barrier
	s_add_i32 s28, 0, 0x1c000
	s_add_i32 s29, s63, s55
	v_add_u32_e32 v204, s28, v165
	s_mov_b32 m0, s29
	ds_read_b128 v[192:195], v204
	ds_read_b128 v[196:199], v204 offset:1024
	ds_read_b128 v[200:203], v204 offset:2048
	global_load_lds_dwordx4 v208, s[98:99]
	s_add_i32 m0, s29, 0x2000
	ds_read_b128 v[204:207], v204 offset:3072
	global_load_lds_dwordx4 v144, s[98:99]
	s_barrier
	s_waitcnt lgkmcnt(0)
	v_mfma_f32_16x16x32_bf16 v[60:63], v[192:195], v[154:157], v[60:63]
	v_mfma_f32_16x16x32_bf16 v[56:59], v[200:203], v[154:157], v[56:59]
	v_mfma_f32_16x16x32_bf16 v[52:55], v[192:195], v[168:171], v[52:55]
	v_mfma_f32_16x16x32_bf16 v[48:51], v[200:203], v[168:171], v[48:51]
	v_mfma_f32_16x16x32_bf16 v[44:47], v[192:195], v[176:179], v[44:47]
	v_mfma_f32_16x16x32_bf16 v[40:43], v[200:203], v[176:179], v[40:43]
	v_mfma_f32_16x16x32_bf16 v[36:39], v[192:195], v[184:187], v[36:39]
	v_mfma_f32_16x16x32_bf16 v[32:35], v[200:203], v[184:187], v[32:35]
	v_mfma_f32_16x16x32_bf16 v[60:63], v[196:199], v[158:161], v[60:63]
	v_mfma_f32_16x16x32_bf16 v[56:59], v[204:207], v[158:161], v[56:59]
	v_mfma_f32_16x16x32_bf16 v[52:55], v[196:199], v[172:175], v[52:55]
	v_mfma_f32_16x16x32_bf16 v[48:51], v[204:207], v[172:175], v[48:51]
	v_mfma_f32_16x16x32_bf16 v[44:47], v[196:199], v[180:183], v[44:47]
	v_mfma_f32_16x16x32_bf16 v[40:43], v[204:207], v[180:183], v[40:43]
	v_mfma_f32_16x16x32_bf16 v[36:39], v[196:199], v[188:191], v[36:39]
	v_mfma_f32_16x16x32_bf16 v[32:35], v[204:207], v[188:191], v[32:35]
	s_mov_b32 m0, s60
	s_barrier
	ds_read_b128 v[154:157], v167 offset:49152
	ds_read_b128 v[158:161], v167 offset:50176
	ds_read_b128 v[168:171], v167 offset:51200
	ds_read_b128 v[172:175], v167 offset:52224
	ds_read_b128 v[176:179], v167 offset:53248
	ds_read_b128 v[180:183], v167 offset:54272
	ds_read_b128 v[184:187], v167 offset:55296
	global_load_lds_dwordx4 v148, s[100:101]
	s_mov_b32 m0, s61
	ds_read_b128 v[188:191], v167 offset:56320
	global_load_lds_dwordx4 v146, s[100:101]
	s_barrier
	s_waitcnt lgkmcnt(0)
	v_mfma_f32_16x16x32_bf16 v[92:95], v[128:131], v[154:157], v[92:95]
	v_mfma_f32_16x16x32_bf16 v[88:91], v[136:139], v[154:157], v[88:91]
	v_mfma_f32_16x16x32_bf16 v[84:87], v[128:131], v[168:171], v[84:87]
	v_mfma_f32_16x16x32_bf16 v[80:83], v[136:139], v[168:171], v[80:83]
	v_mfma_f32_16x16x32_bf16 v[76:79], v[128:131], v[176:179], v[76:79]
	v_mfma_f32_16x16x32_bf16 v[72:75], v[136:139], v[176:179], v[72:75]
	v_mfma_f32_16x16x32_bf16 v[68:71], v[128:131], v[184:187], v[68:71]
	v_mfma_f32_16x16x32_bf16 v[64:67], v[136:139], v[184:187], v[64:67]
	v_mfma_f32_16x16x32_bf16 v[92:95], v[132:135], v[158:161], v[92:95]
	v_mfma_f32_16x16x32_bf16 v[88:91], v[140:143], v[158:161], v[88:91]
	v_mfma_f32_16x16x32_bf16 v[84:87], v[132:135], v[172:175], v[84:87]
	v_mfma_f32_16x16x32_bf16 v[80:83], v[140:143], v[172:175], v[80:83]
	v_mfma_f32_16x16x32_bf16 v[76:79], v[132:135], v[180:183], v[76:79]
	v_mfma_f32_16x16x32_bf16 v[72:75], v[140:143], v[180:183], v[72:75]
	v_mfma_f32_16x16x32_bf16 v[68:71], v[132:135], v[188:191], v[68:71]
	v_mfma_f32_16x16x32_bf16 v[64:67], v[140:143], v[188:191], v[64:67]
	s_barrier
	s_add_u32 s26, s26, 0x40080
	s_addc_u32 s27, s27, 0
	s_add_i32 s28, s28, s55
	s_mov_b32 m0, s28
	s_add_i32 s51, s51, 2
	global_load_lds_dwordx4 v208, s[26:27]
	s_add_i32 m0, s28, 0x2000
	s_add_u32 s6, s6, 0x100
	s_addc_u32 s7, s7, 0
	global_load_lds_dwordx4 v144, s[26:27]
	s_add_u32 s46, s46, 0x100
	s_addc_u32 s50, s50, 0
	s_waitcnt vmcnt(6)
	s_barrier
	v_mfma_f32_16x16x32_bf16 v[28:31], v[192:195], v[154:157], v[28:31]
	v_mfma_f32_16x16x32_bf16 v[24:27], v[200:203], v[154:157], v[24:27]
	v_mfma_f32_16x16x32_bf16 v[20:23], v[192:195], v[168:171], v[20:23]
	v_mfma_f32_16x16x32_bf16 v[16:19], v[200:203], v[168:171], v[16:19]
	v_mfma_f32_16x16x32_bf16 v[12:15], v[192:195], v[176:179], v[12:15]
	v_mfma_f32_16x16x32_bf16 v[8:11], v[200:203], v[176:179], v[8:11]
	v_mfma_f32_16x16x32_bf16 v[4:7], v[192:195], v[184:187], v[4:7]
	v_mfma_f32_16x16x32_bf16 v[0:3], v[200:203], v[184:187], v[0:3]
	v_mfma_f32_16x16x32_bf16 v[28:31], v[196:199], v[158:161], v[28:31]
	v_mfma_f32_16x16x32_bf16 v[24:27], v[204:207], v[158:161], v[24:27]
	v_mfma_f32_16x16x32_bf16 v[20:23], v[196:199], v[172:175], v[20:23]
	v_mfma_f32_16x16x32_bf16 v[16:19], v[204:207], v[172:175], v[16:19]
	v_mfma_f32_16x16x32_bf16 v[12:15], v[196:199], v[180:183], v[12:15]
	v_mfma_f32_16x16x32_bf16 v[8:11], v[204:207], v[180:183], v[8:11]
	v_mfma_f32_16x16x32_bf16 v[4:7], v[196:199], v[188:191], v[4:7]
	v_mfma_f32_16x16x32_bf16 v[0:3], v[204:207], v[188:191], v[0:3]
	s_cmp_gt_u32 s51, 13
	s_barrier
	s_cbranch_scc0 .LBB0_714
	v_lshl_or_b32 v158, s34, 8, v166
	v_lshl_add_u32 v159, s35, 8, v164
	s_mov_b32 s34, s10
	s_mov_b32 s35, s20
	s_mov_b64 s[26:27], s[24:25]
	v_mbcnt_lo_u32_b32 v160, -1, 0
	v_mbcnt_hi_u32_b32 v160, -1, v160
	v_and_b32_e32 v157, 7, v160
	v_and_b32_e32 v160, 8, v160
	v_add_u32_e32 v157, v158, v157
	v_lshlrev_b32_e32 v157, 6, v157
	v_lshl_add_u32 v157, v160, 2, v157
	v_add_u32_e32 v161, 0x2000, v157
	global_load_dwordx4 v[128:131], v157, s[18:19]
	global_load_dwordx4 v[132:135], v157, s[18:19] offset:16
	global_load_dwordx4 v[136:139], v161, s[18:19]
	global_load_dwordx4 v[140:143], v161, s[18:19] offset:16
	v_mov_b32_e32 v155, 0x358637bd
	v_lshlrev_b32_e32 v156, 17, v159
	v_lshl_add_u32 v156, v158, 1, v156
	s_waitcnt vmcnt(0)
	v_pk_add_f32 v[128:129], v[128:129], v[130:131]
	v_pk_add_f32 v[132:133], v[132:133], v[134:135]
	v_pk_add_f32 v[128:129], v[128:129], v[132:133]
	s_nop 0
	v_add_f32_e32 v154, v128, v129
	s_nop 1
	v_add_f32_dpp v154, v154, v154 row_ror:8 row_mask:0xf bank_mask:0xf
	s_nop 0
	v_fmamk_f32 v154, v154, 0x3a800000, v155
	v_rsq_f32_e32 v154, v154
	s_nop 1
	v_mov_b32_dpp v168, v154 row_newbcast:0 row_mask:0xf bank_mask:0xf
	v_mov_b32_dpp v169, v154 row_newbcast:1 row_mask:0xf bank_mask:0xf
	v_mov_b32_dpp v170, v154 row_newbcast:2 row_mask:0xf bank_mask:0xf
	v_mov_b32_dpp v171, v154 row_newbcast:3 row_mask:0xf bank_mask:0xf
	v_mov_b32_dpp v172, v154 row_newbcast:4 row_mask:0xf bank_mask:0xf
	v_mov_b32_dpp v173, v154 row_newbcast:5 row_mask:0xf bank_mask:0xf
	v_mov_b32_dpp v174, v154 row_newbcast:6 row_mask:0xf bank_mask:0xf
	v_mov_b32_dpp v175, v154 row_newbcast:7 row_mask:0xf bank_mask:0xf
	v_pk_add_f32 v[136:137], v[136:137], v[138:139]
	v_pk_add_f32 v[140:141], v[140:141], v[142:143]
	v_pk_add_f32 v[136:137], v[136:137], v[140:141]
	s_nop 0
	v_add_f32_e32 v154, v136, v137
	s_nop 1
	v_add_f32_dpp v154, v154, v154 row_ror:8 row_mask:0xf bank_mask:0xf
	s_nop 0
	v_fmamk_f32 v154, v154, 0x3a800000, v155
	v_rsq_f32_e32 v154, v154
	s_nop 1
	v_mov_b32_dpp v176, v154 row_newbcast:0 row_mask:0xf bank_mask:0xf
	v_mov_b32_dpp v177, v154 row_newbcast:1 row_mask:0xf bank_mask:0xf
	v_mov_b32_dpp v178, v154 row_newbcast:2 row_mask:0xf bank_mask:0xf
	v_mov_b32_dpp v179, v154 row_newbcast:3 row_mask:0xf bank_mask:0xf
	v_mov_b32_dpp v180, v154 row_newbcast:4 row_mask:0xf bank_mask:0xf
	v_mov_b32_dpp v181, v154 row_newbcast:5 row_mask:0xf bank_mask:0xf
	v_mov_b32_dpp v182, v154 row_newbcast:6 row_mask:0xf bank_mask:0xf
	v_mov_b32_dpp v183, v154 row_newbcast:7 row_mask:0xf bank_mask:0xf
	v_pk_mul_f32 v[124:125], v[124:125], v[168:169]
	v_pk_mul_f32 v[126:127], v[126:127], v[170:171]
	v_pk_mul_f32 v[120:121], v[120:121], v[172:173]
	v_pk_mul_f32 v[122:123], v[122:123], v[174:175]
	v_cvt_pk_bf16_f32 v184, v124, v125
	v_cvt_pk_bf16_f32 v185, v126, v127
	v_cvt_pk_bf16_f32 v186, v120, v121
	v_cvt_pk_bf16_f32 v187, v122, v123
	global_store_dwordx4 v156, v[184:187], s[8:9]
	v_pk_mul_f32 v[60:61], v[60:61], v[176:177]
	v_pk_mul_f32 v[62:63], v[62:63], v[178:179]
	v_pk_mul_f32 v[56:57], v[56:57], v[180:181]
	v_pk_mul_f32 v[58:59], v[58:59], v[182:183]
	v_cvt_pk_bf16_f32 v188, v60, v61
	v_cvt_pk_bf16_f32 v189, v62, v63
	v_cvt_pk_bf16_f32 v190, v56, v57
	v_cvt_pk_bf16_f32 v191, v58, v59
	global_store_dwordx4 v156, v[188:191], s[8:9] offset:256
	v_add_u32_e32 v156, 0x200000, v156
	v_pk_mul_f32 v[116:117], v[116:117], v[168:169]
	v_pk_mul_f32 v[118:119], v[118:119], v[170:171]
	v_pk_mul_f32 v[112:113], v[112:113], v[172:173]
	v_pk_mul_f32 v[114:115], v[114:115], v[174:175]
	v_cvt_pk_bf16_f32 v184, v116, v117
	v_cvt_pk_bf16_f32 v185, v118, v119
	v_cvt_pk_bf16_f32 v186, v112, v113
	v_cvt_pk_bf16_f32 v187, v114, v115
	global_store_dwordx4 v156, v[184:187], s[8:9]
	v_pk_mul_f32 v[52:53], v[52:53], v[176:177]
	v_pk_mul_f32 v[54:55], v[54:55], v[178:179]
	v_pk_mul_f32 v[48:49], v[48:49], v[180:181]
	v_pk_mul_f32 v[50:51], v[50:51], v[182:183]
	v_cvt_pk_bf16_f32 v188, v52, v53
	v_cvt_pk_bf16_f32 v189, v54, v55
	v_cvt_pk_bf16_f32 v190, v48, v49
	v_cvt_pk_bf16_f32 v191, v50, v51
	global_store_dwordx4 v156, v[188:191], s[8:9] offset:256
	v_add_u32_e32 v156, 0x200000, v156
	v_pk_mul_f32 v[108:109], v[108:109], v[168:169]
	v_pk_mul_f32 v[110:111], v[110:111], v[170:171]
	v_pk_mul_f32 v[104:105], v[104:105], v[172:173]
	v_pk_mul_f32 v[106:107], v[106:107], v[174:175]
	v_cvt_pk_bf16_f32 v184, v108, v109
	v_cvt_pk_bf16_f32 v185, v110, v111
	v_cvt_pk_bf16_f32 v186, v104, v105
	v_cvt_pk_bf16_f32 v187, v106, v107
	global_store_dwordx4 v156, v[184:187], s[8:9]
	v_pk_mul_f32 v[44:45], v[44:45], v[176:177]
	v_pk_mul_f32 v[46:47], v[46:47], v[178:179]
	v_pk_mul_f32 v[40:41], v[40:41], v[180:181]
	v_pk_mul_f32 v[42:43], v[42:43], v[182:183]
	v_cvt_pk_bf16_f32 v188, v44, v45
	v_cvt_pk_bf16_f32 v189, v46, v47
	v_cvt_pk_bf16_f32 v190, v40, v41
	v_cvt_pk_bf16_f32 v191, v42, v43
	global_store_dwordx4 v156, v[188:191], s[8:9] offset:256
	v_add_u32_e32 v156, 0x200000, v156
	v_pk_mul_f32 v[100:101], v[100:101], v[168:169]
	v_pk_mul_f32 v[102:103], v[102:103], v[170:171]
	v_pk_mul_f32 v[96:97], v[96:97], v[172:173]
	v_pk_mul_f32 v[98:99], v[98:99], v[174:175]
	v_cvt_pk_bf16_f32 v184, v100, v101
	v_cvt_pk_bf16_f32 v185, v102, v103
	v_cvt_pk_bf16_f32 v186, v96, v97
	v_cvt_pk_bf16_f32 v187, v98, v99
	global_store_dwordx4 v156, v[184:187], s[8:9]
	v_pk_mul_f32 v[36:37], v[36:37], v[176:177]
	v_pk_mul_f32 v[38:39], v[38:39], v[178:179]
	v_pk_mul_f32 v[32:33], v[32:33], v[180:181]
	v_pk_mul_f32 v[34:35], v[34:35], v[182:183]
	v_cvt_pk_bf16_f32 v188, v36, v37
	v_cvt_pk_bf16_f32 v189, v38, v39
	v_cvt_pk_bf16_f32 v190, v32, v33
	v_cvt_pk_bf16_f32 v191, v34, v35
	global_store_dwordx4 v156, v[188:191], s[8:9] offset:256
	v_add_u32_e32 v156, 0xa00000, v156
	v_pk_mul_f32 v[92:93], v[92:93], v[168:169]
	v_pk_mul_f32 v[94:95], v[94:95], v[170:171]
	v_pk_mul_f32 v[88:89], v[88:89], v[172:173]
	v_pk_mul_f32 v[90:91], v[90:91], v[174:175]
	v_cvt_pk_bf16_f32 v184, v92, v93
	v_cvt_pk_bf16_f32 v185, v94, v95
	v_cvt_pk_bf16_f32 v186, v88, v89
	v_cvt_pk_bf16_f32 v187, v90, v91
	global_store_dwordx4 v156, v[184:187], s[8:9]
	v_pk_mul_f32 v[28:29], v[28:29], v[176:177]
	v_pk_mul_f32 v[30:31], v[30:31], v[178:179]
	v_pk_mul_f32 v[24:25], v[24:25], v[180:181]
	v_pk_mul_f32 v[26:27], v[26:27], v[182:183]
	v_cvt_pk_bf16_f32 v188, v28, v29
	v_cvt_pk_bf16_f32 v189, v30, v31
	v_cvt_pk_bf16_f32 v190, v24, v25
	v_cvt_pk_bf16_f32 v191, v26, v27
	global_store_dwordx4 v156, v[188:191], s[8:9] offset:256
	v_add_u32_e32 v156, 0x200000, v156
	v_pk_mul_f32 v[84:85], v[84:85], v[168:169]
	v_pk_mul_f32 v[86:87], v[86:87], v[170:171]
	v_pk_mul_f32 v[80:81], v[80:81], v[172:173]
	v_pk_mul_f32 v[82:83], v[82:83], v[174:175]
	v_cvt_pk_bf16_f32 v184, v84, v85
	v_cvt_pk_bf16_f32 v185, v86, v87
	v_cvt_pk_bf16_f32 v186, v80, v81
	v_cvt_pk_bf16_f32 v187, v82, v83
	global_store_dwordx4 v156, v[184:187], s[8:9]
	v_pk_mul_f32 v[20:21], v[20:21], v[176:177]
	v_pk_mul_f32 v[22:23], v[22:23], v[178:179]
	v_pk_mul_f32 v[16:17], v[16:17], v[180:181]
	v_pk_mul_f32 v[18:19], v[18:19], v[182:183]
	v_cvt_pk_bf16_f32 v188, v20, v21
	v_cvt_pk_bf16_f32 v189, v22, v23
	v_cvt_pk_bf16_f32 v190, v16, v17
	v_cvt_pk_bf16_f32 v191, v18, v19
	global_store_dwordx4 v156, v[188:191], s[8:9] offset:256
	v_add_u32_e32 v156, 0x200000, v156
	v_pk_mul_f32 v[76:77], v[76:77], v[168:169]
	v_pk_mul_f32 v[78:79], v[78:79], v[170:171]
	v_pk_mul_f32 v[72:73], v[72:73], v[172:173]
	v_pk_mul_f32 v[74:75], v[74:75], v[174:175]
	v_cvt_pk_bf16_f32 v184, v76, v77
	v_cvt_pk_bf16_f32 v185, v78, v79
	v_cvt_pk_bf16_f32 v186, v72, v73
	v_cvt_pk_bf16_f32 v187, v74, v75
	global_store_dwordx4 v156, v[184:187], s[8:9]
	v_pk_mul_f32 v[12:13], v[12:13], v[176:177]
	v_pk_mul_f32 v[14:15], v[14:15], v[178:179]
	v_pk_mul_f32 v[8:9], v[8:9], v[180:181]
	v_pk_mul_f32 v[10:11], v[10:11], v[182:183]
	v_cvt_pk_bf16_f32 v188, v12, v13
	v_cvt_pk_bf16_f32 v189, v14, v15
	v_cvt_pk_bf16_f32 v190, v8, v9
	v_cvt_pk_bf16_f32 v191, v10, v11
	global_store_dwordx4 v156, v[188:191], s[8:9] offset:256
	v_add_u32_e32 v156, 0x200000, v156
	v_pk_mul_f32 v[68:69], v[68:69], v[168:169]
	v_pk_mul_f32 v[70:71], v[70:71], v[170:171]
	v_pk_mul_f32 v[64:65], v[64:65], v[172:173]
	v_pk_mul_f32 v[66:67], v[66:67], v[174:175]
	v_cvt_pk_bf16_f32 v184, v68, v69
	v_cvt_pk_bf16_f32 v185, v70, v71
	v_cvt_pk_bf16_f32 v186, v64, v65
	v_cvt_pk_bf16_f32 v187, v66, v67
	global_store_dwordx4 v156, v[184:187], s[8:9]
	v_pk_mul_f32 v[4:5], v[4:5], v[176:177]
	v_pk_mul_f32 v[6:7], v[6:7], v[178:179]
	v_pk_mul_f32 v[0:1], v[0:1], v[180:181]
	v_pk_mul_f32 v[2:3], v[2:3], v[182:183]
	v_cvt_pk_bf16_f32 v188, v4, v5
	v_cvt_pk_bf16_f32 v189, v6, v7
	v_cvt_pk_bf16_f32 v190, v0, v1
	v_cvt_pk_bf16_f32 v191, v2, v3
	global_store_dwordx4 v156, v[188:191], s[8:9] offset:256
	s_mov_b64 s[6:7], s[22:23]
	s_and_b64 vcc, exec, s[4:5]
	s_cbranch_vccz .LBB0_707
	s_waitcnt vmcnt(0)
	s_cmpk_gt_u32 s30, 0xff
	s_cbranch_scc1 .LBB0_718
	s_barrier

.LBB0_776:
	s_add_u32 s28, s26, 0xfffc0080
	s_addc_u32 s29, s27, -1
	s_add_i32 s66, 0, 0x10000
	v_add_u32_e32 v154, s66, v143
	ds_read_b128 v[138:141], v154
	ds_read_b128 v[146:149], v154 offset:1024
	ds_read_b128 v[150:153], v154 offset:2048
	ds_read_b128 v[154:157], v154 offset:3072
	s_cmp_eq_u32 s65, 12
	s_cselect_b32 s31, s21, s29
	s_cselect_b32 s30, s39, s28
	s_cselect_b32 s29, s19, s64
	s_cselect_b32 s28, s62, s63
	s_add_i32 m0, s54, 0xc000
	ds_read_b128 v[158:161], v145
	ds_read_b128 v[162:165], v145 offset:1024
	ds_read_b128 v[166:169], v145 offset:2048
	ds_read_b128 v[170:173], v145 offset:3072
	ds_read_b128 v[174:177], v145 offset:4096
	ds_read_b128 v[178:181], v145 offset:5120
	ds_read_b128 v[182:185], v145 offset:6144
	global_load_lds_dwordx4 v134, s[26:27]
	s_add_i32 m0, s54, 0xe000
	ds_read_b128 v[186:189], v145 offset:7168
	global_load_lds_dwordx4 v136, s[26:27]
	s_waitcnt lgkmcnt(8)
	s_barrier
	s_waitcnt lgkmcnt(0)
	v_mfma_f32_16x16x32_bf16 v[124:127], v[138:141], v[158:161], v[124:127]
	v_mfma_f32_16x16x32_bf16 v[120:123], v[150:153], v[158:161], v[120:123]
	v_mfma_f32_16x16x32_bf16 v[108:111], v[138:141], v[166:169], v[108:111]
	v_mfma_f32_16x16x32_bf16 v[104:107], v[150:153], v[166:169], v[104:107]
	v_mfma_f32_16x16x32_bf16 v[92:95], v[138:141], v[174:177], v[92:95]
	v_mfma_f32_16x16x32_bf16 v[88:91], v[150:153], v[174:177], v[88:91]
	v_mfma_f32_16x16x32_bf16 v[76:79], v[138:141], v[182:185], v[76:79]
	v_mfma_f32_16x16x32_bf16 v[72:75], v[150:153], v[182:185], v[72:75]
	v_mfma_f32_16x16x32_bf16 v[124:127], v[146:149], v[162:165], v[124:127]
	v_mfma_f32_16x16x32_bf16 v[120:123], v[154:157], v[162:165], v[120:123]
	v_mfma_f32_16x16x32_bf16 v[108:111], v[146:149], v[170:173], v[108:111]
	v_mfma_f32_16x16x32_bf16 v[104:107], v[154:157], v[170:173], v[104:107]
	v_mfma_f32_16x16x32_bf16 v[92:95], v[146:149], v[178:181], v[92:95]
	v_mfma_f32_16x16x32_bf16 v[88:91], v[154:157], v[178:181], v[88:91]
	v_mfma_f32_16x16x32_bf16 v[76:79], v[146:149], v[186:189], v[76:79]
	v_mfma_f32_16x16x32_bf16 v[72:75], v[154:157], v[186:189], v[72:75]
	s_barrier
	s_add_i32 s68, 0, 0x14000
	s_add_i32 s66, s66, s53
	v_add_u32_e32 v202, s68, v143
	s_add_u32 s98, s28, s40
	s_addc_u32 s99, s29, s41
	s_mov_b32 m0, s66
	ds_read_b128 v[190:193], v202
	ds_read_b128 v[194:197], v202 offset:1024
	ds_read_b128 v[198:201], v202 offset:2048
	global_load_lds_dwordx4 v208, s[28:29]
	s_add_i32 m0, s66, 0x2000
	ds_read_b128 v[202:205], v202 offset:3072
	global_load_lds_dwordx4 v128, s[28:29]
	s_barrier
	s_waitcnt lgkmcnt(0)
	v_mfma_f32_16x16x32_bf16 v[116:119], v[190:193], v[158:161], v[116:119]
	v_mfma_f32_16x16x32_bf16 v[112:115], v[198:201], v[158:161], v[112:115]
	v_mfma_f32_16x16x32_bf16 v[100:103], v[190:193], v[166:169], v[100:103]
	v_mfma_f32_16x16x32_bf16 v[96:99], v[198:201], v[166:169], v[96:99]
	v_mfma_f32_16x16x32_bf16 v[84:87], v[190:193], v[174:177], v[84:87]
	v_mfma_f32_16x16x32_bf16 v[80:83], v[198:201], v[174:177], v[80:83]
	v_mfma_f32_16x16x32_bf16 v[68:71], v[190:193], v[182:185], v[68:71]
	v_mfma_f32_16x16x32_bf16 v[64:67], v[198:201], v[182:185], v[64:67]
	v_mfma_f32_16x16x32_bf16 v[116:119], v[194:197], v[162:165], v[116:119]
	v_mfma_f32_16x16x32_bf16 v[112:115], v[202:205], v[162:165], v[112:115]
	v_mfma_f32_16x16x32_bf16 v[100:103], v[194:197], v[170:173], v[100:103]
	v_mfma_f32_16x16x32_bf16 v[96:99], v[202:205], v[170:173], v[96:99]
	v_mfma_f32_16x16x32_bf16 v[84:87], v[194:197], v[178:181], v[84:87]
	v_mfma_f32_16x16x32_bf16 v[80:83], v[202:205], v[178:181], v[80:83]
	v_mfma_f32_16x16x32_bf16 v[68:71], v[194:197], v[186:189], v[68:71]
	v_mfma_f32_16x16x32_bf16 v[64:67], v[202:205], v[186:189], v[64:67]
	s_mov_b32 m0, s54
	s_add_u32 s100, s30, s40
	s_addc_u32 s101, s31, s41
	s_barrier
	ds_read_b128 v[158:161], v145 offset:16384
	ds_read_b128 v[162:165], v145 offset:17408
	ds_read_b128 v[166:169], v145 offset:18432
	ds_read_b128 v[170:173], v145 offset:19456
	ds_read_b128 v[174:177], v145 offset:20480
	ds_read_b128 v[178:181], v145 offset:21504
	ds_read_b128 v[182:185], v145 offset:22528
	global_load_lds_dwordx4 v132, s[30:31]
	s_mov_b32 m0, s55
	ds_read_b128 v[186:189], v145 offset:23552
	global_load_lds_dwordx4 v130, s[30:31]
	s_barrier
	s_waitcnt lgkmcnt(0)
	v_mfma_f32_16x16x32_bf16 v[60:63], v[138:141], v[158:161], v[60:63]
	v_mfma_f32_16x16x32_bf16 v[56:59], v[150:153], v[158:161], v[56:59]
	v_mfma_f32_16x16x32_bf16 v[44:47], v[138:141], v[166:169], v[44:47]
	v_mfma_f32_16x16x32_bf16 v[40:43], v[150:153], v[166:169], v[40:43]
	v_mfma_f32_16x16x32_bf16 v[28:31], v[138:141], v[174:177], v[28:31]
	v_mfma_f32_16x16x32_bf16 v[24:27], v[150:153], v[174:177], v[24:27]
	v_mfma_f32_16x16x32_bf16 v[12:15], v[138:141], v[182:185], v[12:15]
	v_mfma_f32_16x16x32_bf16 v[8:11], v[150:153], v[182:185], v[8:11]
	v_mfma_f32_16x16x32_bf16 v[60:63], v[146:149], v[162:165], v[60:63]
	v_mfma_f32_16x16x32_bf16 v[56:59], v[154:157], v[162:165], v[56:59]
	v_mfma_f32_16x16x32_bf16 v[44:47], v[146:149], v[170:173], v[44:47]
	v_mfma_f32_16x16x32_bf16 v[40:43], v[154:157], v[170:173], v[40:43]
	v_mfma_f32_16x16x32_bf16 v[28:31], v[146:149], v[178:181], v[28:31]
	v_mfma_f32_16x16x32_bf16 v[24:27], v[154:157], v[178:181], v[24:27]
	v_mfma_f32_16x16x32_bf16 v[12:15], v[146:149], v[186:189], v[12:15]
	v_mfma_f32_16x16x32_bf16 v[8:11], v[154:157], v[186:189], v[8:11]
	s_barrier
	s_add_u32 s66, s28, 0x40000
	s_addc_u32 s67, s29, 0
	s_add_i32 s68, s68, s53
	s_mov_b32 m0, s68
	s_nop 0
	global_load_lds_dwordx4 v208, s[66:67]
	s_add_i32 m0, s68, 0x2000
	s_nop 0
	global_load_lds_dwordx4 v128, s[66:67]
	s_waitcnt vmcnt(6)
	s_barrier
	v_mfma_f32_16x16x32_bf16 v[52:55], v[190:193], v[158:161], v[52:55]
	v_mfma_f32_16x16x32_bf16 v[48:51], v[198:201], v[158:161], v[48:51]
	v_mfma_f32_16x16x32_bf16 v[36:39], v[190:193], v[166:169], v[36:39]
	v_mfma_f32_16x16x32_bf16 v[32:35], v[198:201], v[166:169], v[32:35]
	v_mfma_f32_16x16x32_bf16 v[20:23], v[190:193], v[174:177], v[20:23]
	v_mfma_f32_16x16x32_bf16 v[16:19], v[198:201], v[174:177], v[16:19]
	v_mfma_f32_16x16x32_bf16 v[4:7], v[190:193], v[182:185], v[4:7]
	v_mfma_f32_16x16x32_bf16 v[0:3], v[198:201], v[182:185], v[0:3]
	v_mfma_f32_16x16x32_bf16 v[52:55], v[194:197], v[162:165], v[52:55]
	v_mfma_f32_16x16x32_bf16 v[48:51], v[202:205], v[162:165], v[48:51]
	v_mfma_f32_16x16x32_bf16 v[36:39], v[194:197], v[170:173], v[36:39]
	v_mfma_f32_16x16x32_bf16 v[32:35], v[202:205], v[170:173], v[32:35]
	v_mfma_f32_16x16x32_bf16 v[20:23], v[194:197], v[178:181], v[20:23]
	v_mfma_f32_16x16x32_bf16 v[16:19], v[202:205], v[178:181], v[16:19]
	v_mfma_f32_16x16x32_bf16 v[4:7], v[194:197], v[186:189], v[4:7]
	v_mfma_f32_16x16x32_bf16 v[0:3], v[202:205], v[186:189], v[0:3]
	s_add_i32 s66, 0, 0x18000
	v_add_u32_e32 v154, s66, v143
	s_barrier
	ds_read_b128 v[138:141], v154
	ds_read_b128 v[146:149], v154 offset:1024
	ds_read_b128 v[150:153], v154 offset:2048
	ds_read_b128 v[154:157], v154 offset:3072
	s_add_u32 s30, s30, 0x40000
	s_addc_u32 s31, s31, 0
	s_mov_b32 m0, s56
	ds_read_b128 v[158:161], v145 offset:32768
	ds_read_b128 v[162:165], v145 offset:33792
	ds_read_b128 v[166:169], v145 offset:34816
	ds_read_b128 v[170:173], v145 offset:35840
	ds_read_b128 v[174:177], v145 offset:36864
	ds_read_b128 v[178:181], v145 offset:37888
	ds_read_b128 v[182:185], v145 offset:38912
	global_load_lds_dwordx4 v132, s[30:31]
	s_mov_b32 m0, s57
	ds_read_b128 v[186:189], v145 offset:39936
	global_load_lds_dwordx4 v130, s[30:31]
	s_waitcnt lgkmcnt(8)
	s_barrier
	s_waitcnt lgkmcnt(0)
	v_mfma_f32_16x16x32_bf16 v[124:127], v[138:141], v[158:161], v[124:127]
	v_mfma_f32_16x16x32_bf16 v[120:123], v[150:153], v[158:161], v[120:123]
	v_mfma_f32_16x16x32_bf16 v[108:111], v[138:141], v[166:169], v[108:111]
	v_mfma_f32_16x16x32_bf16 v[104:107], v[150:153], v[166:169], v[104:107]
	v_mfma_f32_16x16x32_bf16 v[92:95], v[138:141], v[174:177], v[92:95]
	v_mfma_f32_16x16x32_bf16 v[88:91], v[150:153], v[174:177], v[88:91]
	v_mfma_f32_16x16x32_bf16 v[76:79], v[138:141], v[182:185], v[76:79]
	v_mfma_f32_16x16x32_bf16 v[72:75], v[150:153], v[182:185], v[72:75]
	v_mfma_f32_16x16x32_bf16 v[124:127], v[146:149], v[162:165], v[124:127]
	v_mfma_f32_16x16x32_bf16 v[120:123], v[154:157], v[162:165], v[120:123]
	v_mfma_f32_16x16x32_bf16 v[108:111], v[146:149], v[170:173], v[108:111]
	v_mfma_f32_16x16x32_bf16 v[104:107], v[154:157], v[170:173], v[104:107]
	v_mfma_f32_16x16x32_bf16 v[92:95], v[146:149], v[178:181], v[92:95]
	v_mfma_f32_16x16x32_bf16 v[88:91], v[154:157], v[178:181], v[88:91]
	v_mfma_f32_16x16x32_bf16 v[76:79], v[146:149], v[186:189], v[76:79]
	v_mfma_f32_16x16x32_bf16 v[72:75], v[154:157], v[186:189], v[72:75]
	s_barrier
	s_add_i32 s30, 0, 0x1c000
	s_add_i32 s31, s66, s53
	v_add_u32_e32 v202, s30, v143
	s_mov_b32 m0, s31
	ds_read_b128 v[190:193], v202
	ds_read_b128 v[194:197], v202 offset:1024
	ds_read_b128 v[198:201], v202 offset:2048
	global_load_lds_dwordx4 v208, s[98:99]
	s_add_i32 m0, s31, 0x2000
	ds_read_b128 v[202:205], v202 offset:3072
	global_load_lds_dwordx4 v128, s[98:99]
	s_barrier
	s_waitcnt lgkmcnt(0)
	v_mfma_f32_16x16x32_bf16 v[116:119], v[190:193], v[158:161], v[116:119]
	v_mfma_f32_16x16x32_bf16 v[112:115], v[198:201], v[158:161], v[112:115]
	v_mfma_f32_16x16x32_bf16 v[100:103], v[190:193], v[166:169], v[100:103]
	v_mfma_f32_16x16x32_bf16 v[96:99], v[198:201], v[166:169], v[96:99]
	v_mfma_f32_16x16x32_bf16 v[84:87], v[190:193], v[174:177], v[84:87]
	v_mfma_f32_16x16x32_bf16 v[80:83], v[198:201], v[174:177], v[80:83]
	v_mfma_f32_16x16x32_bf16 v[68:71], v[190:193], v[182:185], v[68:71]
	v_mfma_f32_16x16x32_bf16 v[64:67], v[198:201], v[182:185], v[64:67]
	v_mfma_f32_16x16x32_bf16 v[116:119], v[194:197], v[162:165], v[116:119]
	v_mfma_f32_16x16x32_bf16 v[112:115], v[202:205], v[162:165], v[112:115]
	v_mfma_f32_16x16x32_bf16 v[100:103], v[194:197], v[170:173], v[100:103]
	v_mfma_f32_16x16x32_bf16 v[96:99], v[202:205], v[170:173], v[96:99]
	v_mfma_f32_16x16x32_bf16 v[84:87], v[194:197], v[178:181], v[84:87]
	v_mfma_f32_16x16x32_bf16 v[80:83], v[202:205], v[178:181], v[80:83]
	v_mfma_f32_16x16x32_bf16 v[68:71], v[194:197], v[186:189], v[68:71]
	v_mfma_f32_16x16x32_bf16 v[64:67], v[202:205], v[186:189], v[64:67]
	s_mov_b32 m0, s59
	s_barrier
	ds_read_b128 v[158:161], v145 offset:49152
	ds_read_b128 v[162:165], v145 offset:50176
	ds_read_b128 v[166:169], v145 offset:51200
	ds_read_b128 v[170:173], v145 offset:52224
	ds_read_b128 v[174:177], v145 offset:53248
	ds_read_b128 v[178:181], v145 offset:54272
	ds_read_b128 v[182:185], v145 offset:55296
	global_load_lds_dwordx4 v132, s[100:101]
	s_mov_b32 m0, s60
	ds_read_b128 v[186:189], v145 offset:56320
	global_load_lds_dwordx4 v130, s[100:101]
	s_barrier
	s_waitcnt lgkmcnt(0)
	v_mfma_f32_16x16x32_bf16 v[60:63], v[138:141], v[158:161], v[60:63]
	v_mfma_f32_16x16x32_bf16 v[56:59], v[150:153], v[158:161], v[56:59]
	v_mfma_f32_16x16x32_bf16 v[44:47], v[138:141], v[166:169], v[44:47]
	v_mfma_f32_16x16x32_bf16 v[40:43], v[150:153], v[166:169], v[40:43]
	v_mfma_f32_16x16x32_bf16 v[28:31], v[138:141], v[174:177], v[28:31]
	v_mfma_f32_16x16x32_bf16 v[24:27], v[150:153], v[174:177], v[24:27]
	v_mfma_f32_16x16x32_bf16 v[12:15], v[138:141], v[182:185], v[12:15]
	v_mfma_f32_16x16x32_bf16 v[8:11], v[150:153], v[182:185], v[8:11]
	v_mfma_f32_16x16x32_bf16 v[60:63], v[146:149], v[162:165], v[60:63]
	v_mfma_f32_16x16x32_bf16 v[56:59], v[154:157], v[162:165], v[56:59]
	v_mfma_f32_16x16x32_bf16 v[44:47], v[146:149], v[170:173], v[44:47]
	v_mfma_f32_16x16x32_bf16 v[40:43], v[154:157], v[170:173], v[40:43]
	v_mfma_f32_16x16x32_bf16 v[28:31], v[146:149], v[178:181], v[28:31]
	v_mfma_f32_16x16x32_bf16 v[24:27], v[154:157], v[178:181], v[24:27]
	v_mfma_f32_16x16x32_bf16 v[12:15], v[146:149], v[186:189], v[12:15]
	v_mfma_f32_16x16x32_bf16 v[8:11], v[154:157], v[186:189], v[8:11]
	s_barrier
	s_add_u32 s28, s28, 0x40080
	s_addc_u32 s29, s29, 0
	s_add_i32 s30, s30, s53
	s_mov_b32 m0, s30
	s_add_i32 s65, s65, 2
	global_load_lds_dwordx4 v208, s[28:29]
	s_add_i32 m0, s30, 0x2000
	s_add_u32 s26, s26, 0x100
	s_addc_u32 s27, s27, 0
	global_load_lds_dwordx4 v128, s[28:29]
	s_add_u32 s63, s63, 0x100
	s_addc_u32 s64, s64, 0
	s_waitcnt vmcnt(6)
	s_barrier
	v_mfma_f32_16x16x32_bf16 v[52:55], v[190:193], v[158:161], v[52:55]
	v_mfma_f32_16x16x32_bf16 v[48:51], v[198:201], v[158:161], v[48:51]
	v_mfma_f32_16x16x32_bf16 v[36:39], v[190:193], v[166:169], v[36:39]
	v_mfma_f32_16x16x32_bf16 v[32:35], v[198:201], v[166:169], v[32:35]
	v_mfma_f32_16x16x32_bf16 v[20:23], v[190:193], v[174:177], v[20:23]
	v_mfma_f32_16x16x32_bf16 v[16:19], v[198:201], v[174:177], v[16:19]
	v_mfma_f32_16x16x32_bf16 v[4:7], v[190:193], v[182:185], v[4:7]
	v_mfma_f32_16x16x32_bf16 v[0:3], v[198:201], v[182:185], v[0:3]
	v_mfma_f32_16x16x32_bf16 v[52:55], v[194:197], v[162:165], v[52:55]
	v_mfma_f32_16x16x32_bf16 v[48:51], v[202:205], v[162:165], v[48:51]
	v_mfma_f32_16x16x32_bf16 v[36:39], v[194:197], v[170:173], v[36:39]
	v_mfma_f32_16x16x32_bf16 v[32:35], v[202:205], v[170:173], v[32:35]
	v_mfma_f32_16x16x32_bf16 v[20:23], v[194:197], v[178:181], v[20:23]
	v_mfma_f32_16x16x32_bf16 v[16:19], v[202:205], v[178:181], v[16:19]
	v_mfma_f32_16x16x32_bf16 v[4:7], v[194:197], v[186:189], v[4:7]
	v_mfma_f32_16x16x32_bf16 v[0:3], v[202:205], v[186:189], v[0:3]
	s_cmp_gt_u32 s65, 13
	s_barrier
	s_cbranch_scc0 .LBB0_776
	v_lshl_add_u32 v140, s38, 8, v142
	v_lshl_or_b32 v141, s36, 8, v144
	s_lshl_b32 s26, s36, 2
	s_ashr_i32 s27, s26, 31
	s_lshl_b32 s36, s58, 2
	v_lshlrev_b32_e32 v206, 11, v140
	v_lshl_add_u32 v206, v141, 1, v206
	v_lshl_add_u32 v210, v140, 6, s36
	v_lshl_add_u32 v210, s26, 2, v210
	v_mov_b32_e32 v207, v206
	global_load_dwordx4 v[146:149], v206, s[10:11]
	global_load_dwordx4 v[150:153], v206, s[10:11] offset:256
	v_add_u32_e32 v206, 0x8000, v206
	global_load_dwordx4 v[154:157], v206, s[10:11]
	global_load_dwordx4 v[158:161], v206, s[10:11] offset:256
	v_add_u32_e32 v206, 0x8000, v206
	global_load_dwordx4 v[162:165], v206, s[10:11]
	global_load_dwordx4 v[166:169], v206, s[10:11] offset:256
	v_add_u32_e32 v206, 0x8000, v206
	global_load_dwordx4 v[170:173], v206, s[10:11]
	global_load_dwordx4 v[174:177], v206, s[10:11] offset:256
	v_add_u32_e32 v206, 0x28000, v206
	global_load_dwordx4 v[178:181], v206, s[10:11]
	global_load_dwordx4 v[182:185], v206, s[10:11] offset:256
	v_add_u32_e32 v206, 0x8000, v206
	global_load_dwordx4 v[186:189], v206, s[10:11]
	global_load_dwordx4 v[190:193], v206, s[10:11] offset:256
	v_add_u32_e32 v206, 0x8000, v206
	global_load_dwordx4 v[194:197], v206, s[10:11]
	global_load_dwordx4 v[198:201], v206, s[10:11] offset:256
	v_add_u32_e32 v206, 0x8000, v206
	s_waitcnt vmcnt(12)
	v_lshlrev_b32_e32 v202, 16, v146
	v_and_b32_e32 v203, 0xffff0000, v146
	v_lshlrev_b32_e32 v204, 16, v147
	v_and_b32_e32 v205, 0xffff0000, v147
	v_pk_add_f32 v[124:125], v[124:125], v[202:203]
	v_pk_add_f32 v[126:127], v[126:127], v[204:205]
	v_lshlrev_b32_e32 v202, 16, v148
	v_and_b32_e32 v203, 0xffff0000, v148
	v_lshlrev_b32_e32 v204, 16, v149
	v_and_b32_e32 v205, 0xffff0000, v149
	v_pk_add_f32 v[120:121], v[120:121], v[202:203]
	v_pk_add_f32 v[122:123], v[122:123], v[204:205]
	v_cvt_pk_bf16_f32 v146, v124, v125
	v_cvt_pk_bf16_f32 v147, v126, v127
	v_cvt_pk_bf16_f32 v148, v120, v121
	v_cvt_pk_bf16_f32 v149, v122, v123
	v_pk_mul_f32 v[138:139], v[124:125], v[124:125]
	global_store_dwordx4 v207, v[146:149], s[10:11]
	v_pk_fma_f32 v[138:139], v[126:127], v[126:127], v[138:139]
	v_pk_fma_f32 v[138:139], v[120:121], v[120:121], v[138:139]
	v_pk_fma_f32 v[138:139], v[122:123], v[122:123], v[138:139]
	v_lshlrev_b32_e32 v202, 16, v150
	v_and_b32_e32 v203, 0xffff0000, v150
	v_lshlrev_b32_e32 v204, 16, v151
	v_and_b32_e32 v205, 0xffff0000, v151
	v_pk_add_f32 v[116:117], v[116:117], v[202:203]
	v_pk_add_f32 v[118:119], v[118:119], v[204:205]
	v_lshlrev_b32_e32 v202, 16, v152
	v_and_b32_e32 v203, 0xffff0000, v152
	v_lshlrev_b32_e32 v204, 16, v153
	v_and_b32_e32 v205, 0xffff0000, v153
	v_pk_add_f32 v[112:113], v[112:113], v[202:203]
	v_pk_add_f32 v[114:115], v[114:115], v[204:205]
	v_cvt_pk_bf16_f32 v150, v116, v117
	v_cvt_pk_bf16_f32 v151, v118, v119
	v_cvt_pk_bf16_f32 v152, v112, v113
	v_cvt_pk_bf16_f32 v153, v114, v115
	v_pk_fma_f32 v[138:139], v[116:117], v[116:117], v[138:139]
	global_store_dwordx4 v207, v[150:153], s[10:11] offset:256
	v_pk_fma_f32 v[138:139], v[118:119], v[118:119], v[138:139]
	v_pk_fma_f32 v[138:139], v[112:113], v[112:113], v[138:139]
	v_pk_fma_f32 v[138:139], v[114:115], v[114:115], v[138:139]
	v_add_f32_e32 v214, v138, v139
	v_add_u32_e32 v207, 0x8000, v207
	v_mov_b32_e32 v215, v214
	s_nop 1
	v_permlane16_swap_b32_e32 v214, v215
	s_nop 0
	v_add_f32_e32 v214, v214, v215
	v_mov_b32_e32 v215, v214
	s_nop 1
	v_permlane32_swap_b32_e32 v214, v215
	s_nop 0
	v_add_f32_e32 v214, v214, v215
	s_and_saveexec_b64 s[28:29], s[4:5]
	global_store_dword v210, v214, s[16:17]
	s_mov_b64 exec, s[28:29]
	global_load_dwordx4 v[146:149], v206, s[10:11]
	global_load_dwordx4 v[150:153], v206, s[10:11] offset:256
	s_waitcnt vmcnt(15)
	v_lshlrev_b32_e32 v202, 16, v154
	v_and_b32_e32 v203, 0xffff0000, v154
	v_lshlrev_b32_e32 v204, 16, v155
	v_and_b32_e32 v205, 0xffff0000, v155
	v_pk_add_f32 v[108:109], v[108:109], v[202:203]
	v_pk_add_f32 v[110:111], v[110:111], v[204:205]
	v_lshlrev_b32_e32 v202, 16, v156
	v_and_b32_e32 v203, 0xffff0000, v156
	v_lshlrev_b32_e32 v204, 16, v157
	v_and_b32_e32 v205, 0xffff0000, v157
	v_pk_add_f32 v[104:105], v[104:105], v[202:203]
	v_pk_add_f32 v[106:107], v[106:107], v[204:205]
	v_cvt_pk_bf16_f32 v154, v108, v109
	v_cvt_pk_bf16_f32 v155, v110, v111
	v_cvt_pk_bf16_f32 v156, v104, v105
	v_cvt_pk_bf16_f32 v157, v106, v107
	v_pk_mul_f32 v[138:139], v[108:109], v[108:109]
	global_store_dwordx4 v207, v[154:157], s[10:11]
	v_pk_fma_f32 v[138:139], v[110:111], v[110:111], v[138:139]
	v_pk_fma_f32 v[138:139], v[104:105], v[104:105], v[138:139]
	v_pk_fma_f32 v[138:139], v[106:107], v[106:107], v[138:139]
	v_lshlrev_b32_e32 v202, 16, v158
	v_and_b32_e32 v203, 0xffff0000, v158
	v_lshlrev_b32_e32 v204, 16, v159
	v_and_b32_e32 v205, 0xffff0000, v159
	v_pk_add_f32 v[100:101], v[100:101], v[202:203]
	v_pk_add_f32 v[102:103], v[102:103], v[204:205]
	v_lshlrev_b32_e32 v202, 16, v160
	v_and_b32_e32 v203, 0xffff0000, v160
	v_lshlrev_b32_e32 v204, 16, v161
	v_and_b32_e32 v205, 0xffff0000, v161
	v_pk_add_f32 v[96:97], v[96:97], v[202:203]
	v_pk_add_f32 v[98:99], v[98:99], v[204:205]
	v_cvt_pk_bf16_f32 v158, v100, v101
	v_cvt_pk_bf16_f32 v159, v102, v103
	v_cvt_pk_bf16_f32 v160, v96, v97
	v_cvt_pk_bf16_f32 v161, v98, v99
	v_pk_fma_f32 v[138:139], v[100:101], v[100:101], v[138:139]
	global_store_dwordx4 v207, v[158:161], s[10:11] offset:256
	v_pk_fma_f32 v[138:139], v[102:103], v[102:103], v[138:139]
	v_pk_fma_f32 v[138:139], v[96:97], v[96:97], v[138:139]
	v_pk_fma_f32 v[138:139], v[98:99], v[98:99], v[138:139]
	v_add_f32_e32 v214, v138, v139
	v_add_u32_e32 v207, 0x8000, v207
	v_mov_b32_e32 v215, v214
	s_nop 1
	v_permlane16_swap_b32_e32 v214, v215
	s_nop 0
	v_add_f32_e32 v214, v214, v215
	v_mov_b32_e32 v215, v214
	s_nop 1
	v_permlane32_swap_b32_e32 v214, v215
	s_nop 0
	v_add_f32_e32 v214, v214, v215
	s_and_saveexec_b64 s[28:29], s[4:5]
	global_store_dword v210, v214, s[16:17] offset:1024
	s_mov_b64 exec, s[28:29]
	s_waitcnt vmcnt(16)
	v_lshlrev_b32_e32 v202, 16, v162
	v_and_b32_e32 v203, 0xffff0000, v162
	v_lshlrev_b32_e32 v204, 16, v163
	v_and_b32_e32 v205, 0xffff0000, v163
	v_pk_add_f32 v[92:93], v[92:93], v[202:203]
	v_pk_add_f32 v[94:95], v[94:95], v[204:205]
	v_lshlrev_b32_e32 v202, 16, v164
	v_and_b32_e32 v203, 0xffff0000, v164
	v_lshlrev_b32_e32 v204, 16, v165
	v_and_b32_e32 v205, 0xffff0000, v165
	v_pk_add_f32 v[88:89], v[88:89], v[202:203]
	v_pk_add_f32 v[90:91], v[90:91], v[204:205]
	v_cvt_pk_bf16_f32 v162, v92, v93
	v_cvt_pk_bf16_f32 v163, v94, v95
	v_cvt_pk_bf16_f32 v164, v88, v89
	v_cvt_pk_bf16_f32 v165, v90, v91
	v_pk_mul_f32 v[138:139], v[92:93], v[92:93]
	global_store_dwordx4 v207, v[162:165], s[10:11]
	v_pk_fma_f32 v[138:139], v[94:95], v[94:95], v[138:139]
	v_pk_fma_f32 v[138:139], v[88:89], v[88:89], v[138:139]
	v_pk_fma_f32 v[138:139], v[90:91], v[90:91], v[138:139]
	v_lshlrev_b32_e32 v202, 16, v166
	v_and_b32_e32 v203, 0xffff0000, v166
	v_lshlrev_b32_e32 v204, 16, v167
	v_and_b32_e32 v205, 0xffff0000, v167
	v_pk_add_f32 v[84:85], v[84:85], v[202:203]
	v_pk_add_f32 v[86:87], v[86:87], v[204:205]
	v_lshlrev_b32_e32 v202, 16, v168
	v_and_b32_e32 v203, 0xffff0000, v168
	v_lshlrev_b32_e32 v204, 16, v169
	v_and_b32_e32 v205, 0xffff0000, v169
	v_pk_add_f32 v[80:81], v[80:81], v[202:203]
	v_pk_add_f32 v[82:83], v[82:83], v[204:205]
	v_cvt_pk_bf16_f32 v166, v84, v85
	v_cvt_pk_bf16_f32 v167, v86, v87
	v_cvt_pk_bf16_f32 v168, v80, v81
	v_cvt_pk_bf16_f32 v169, v82, v83
	v_pk_fma_f32 v[138:139], v[84:85], v[84:85], v[138:139]
	global_store_dwordx4 v207, v[166:169], s[10:11] offset:256
	v_pk_fma_f32 v[138:139], v[86:87], v[86:87], v[138:139]
	v_pk_fma_f32 v[138:139], v[80:81], v[80:81], v[138:139]
	v_pk_fma_f32 v[138:139], v[82:83], v[82:83], v[138:139]
	v_add_f32_e32 v214, v138, v139
	v_add_u32_e32 v207, 0x8000, v207
	v_mov_b32_e32 v215, v214
	s_nop 1
	v_permlane16_swap_b32_e32 v214, v215
	s_nop 0
	v_add_f32_e32 v214, v214, v215
	v_mov_b32_e32 v215, v214
	s_nop 1
	v_permlane32_swap_b32_e32 v214, v215
	s_nop 0
	v_add_f32_e32 v214, v214, v215
	s_and_saveexec_b64 s[28:29], s[4:5]
	global_store_dword v210, v214, s[16:17] offset:2048
	s_mov_b64 exec, s[28:29]
	s_waitcnt vmcnt(17)
	v_lshlrev_b32_e32 v202, 16, v170
	v_and_b32_e32 v203, 0xffff0000, v170
	v_lshlrev_b32_e32 v204, 16, v171
	v_and_b32_e32 v205, 0xffff0000, v171
	v_pk_add_f32 v[76:77], v[76:77], v[202:203]
	v_pk_add_f32 v[78:79], v[78:79], v[204:205]
	v_lshlrev_b32_e32 v202, 16, v172
	v_and_b32_e32 v203, 0xffff0000, v172
	v_lshlrev_b32_e32 v204, 16, v173
	v_and_b32_e32 v205, 0xffff0000, v173
	v_pk_add_f32 v[72:73], v[72:73], v[202:203]
	v_pk_add_f32 v[74:75], v[74:75], v[204:205]
	v_cvt_pk_bf16_f32 v170, v76, v77
	v_cvt_pk_bf16_f32 v171, v78, v79
	v_cvt_pk_bf16_f32 v172, v72, v73
	v_cvt_pk_bf16_f32 v173, v74, v75
	v_pk_mul_f32 v[138:139], v[76:77], v[76:77]
	global_store_dwordx4 v207, v[170:173], s[10:11]
	v_pk_fma_f32 v[138:139], v[78:79], v[78:79], v[138:139]
	v_pk_fma_f32 v[138:139], v[72:73], v[72:73], v[138:139]
	v_pk_fma_f32 v[138:139], v[74:75], v[74:75], v[138:139]
	v_lshlrev_b32_e32 v202, 16, v174
	v_and_b32_e32 v203, 0xffff0000, v174
	v_lshlrev_b32_e32 v204, 16, v175
	v_and_b32_e32 v205, 0xffff0000, v175
	v_pk_add_f32 v[68:69], v[68:69], v[202:203]
	v_pk_add_f32 v[70:71], v[70:71], v[204:205]
	v_lshlrev_b32_e32 v202, 16, v176
	v_and_b32_e32 v203, 0xffff0000, v176
	v_lshlrev_b32_e32 v204, 16, v177
	v_and_b32_e32 v205, 0xffff0000, v177
	v_pk_add_f32 v[64:65], v[64:65], v[202:203]
	v_pk_add_f32 v[66:67], v[66:67], v[204:205]
	v_cvt_pk_bf16_f32 v174, v68, v69
	v_cvt_pk_bf16_f32 v175, v70, v71
	v_cvt_pk_bf16_f32 v176, v64, v65
	v_cvt_pk_bf16_f32 v177, v66, v67
	v_pk_fma_f32 v[138:139], v[68:69], v[68:69], v[138:139]
	global_store_dwordx4 v207, v[174:177], s[10:11] offset:256
	v_pk_fma_f32 v[138:139], v[70:71], v[70:71], v[138:139]
	v_pk_fma_f32 v[138:139], v[64:65], v[64:65], v[138:139]
	v_pk_fma_f32 v[138:139], v[66:67], v[66:67], v[138:139]
	v_add_f32_e32 v214, v138, v139
	v_add_u32_e32 v207, 0x28000, v207
	v_mov_b32_e32 v215, v214
	s_nop 1
	v_permlane16_swap_b32_e32 v214, v215
	s_nop 0
	v_add_f32_e32 v214, v214, v215
	v_mov_b32_e32 v215, v214
	s_nop 1
	v_permlane32_swap_b32_e32 v214, v215
	s_nop 0
	v_add_f32_e32 v214, v214, v215
	s_and_saveexec_b64 s[28:29], s[4:5]
	global_store_dword v210, v214, s[16:17] offset:3072
	s_mov_b64 exec, s[28:29]
	v_add_u32_e32 v210, 0x2000, v210
	s_waitcnt vmcnt(18)
	v_lshlrev_b32_e32 v202, 16, v178
	v_and_b32_e32 v203, 0xffff0000, v178
	v_lshlrev_b32_e32 v204, 16, v179
	v_and_b32_e32 v205, 0xffff0000, v179
	v_pk_add_f32 v[60:61], v[60:61], v[202:203]
	v_pk_add_f32 v[62:63], v[62:63], v[204:205]
	v_lshlrev_b32_e32 v202, 16, v180
	v_and_b32_e32 v203, 0xffff0000, v180
	v_lshlrev_b32_e32 v204, 16, v181
	v_and_b32_e32 v205, 0xffff0000, v181
	v_pk_add_f32 v[56:57], v[56:57], v[202:203]
	v_pk_add_f32 v[58:59], v[58:59], v[204:205]
	v_cvt_pk_bf16_f32 v178, v60, v61
	v_cvt_pk_bf16_f32 v179, v62, v63
	v_cvt_pk_bf16_f32 v180, v56, v57
	v_cvt_pk_bf16_f32 v181, v58, v59
	v_pk_mul_f32 v[138:139], v[60:61], v[60:61]
	global_store_dwordx4 v207, v[178:181], s[10:11]
	v_pk_fma_f32 v[138:139], v[62:63], v[62:63], v[138:139]
	v_pk_fma_f32 v[138:139], v[56:57], v[56:57], v[138:139]
	v_pk_fma_f32 v[138:139], v[58:59], v[58:59], v[138:139]
	v_lshlrev_b32_e32 v202, 16, v182
	v_and_b32_e32 v203, 0xffff0000, v182
	v_lshlrev_b32_e32 v204, 16, v183
	v_and_b32_e32 v205, 0xffff0000, v183
	v_pk_add_f32 v[52:53], v[52:53], v[202:203]
	v_pk_add_f32 v[54:55], v[54:55], v[204:205]
	v_lshlrev_b32_e32 v202, 16, v184
	v_and_b32_e32 v203, 0xffff0000, v184
	v_lshlrev_b32_e32 v204, 16, v185
	v_and_b32_e32 v205, 0xffff0000, v185
	v_pk_add_f32 v[48:49], v[48:49], v[202:203]
	v_pk_add_f32 v[50:51], v[50:51], v[204:205]
	v_cvt_pk_bf16_f32 v182, v52, v53
	v_cvt_pk_bf16_f32 v183, v54, v55
	v_cvt_pk_bf16_f32 v184, v48, v49
	v_cvt_pk_bf16_f32 v185, v50, v51
	v_pk_fma_f32 v[138:139], v[52:53], v[52:53], v[138:139]
	global_store_dwordx4 v207, v[182:185], s[10:11] offset:256
	v_pk_fma_f32 v[138:139], v[54:55], v[54:55], v[138:139]
	v_pk_fma_f32 v[138:139], v[48:49], v[48:49], v[138:139]
	v_pk_fma_f32 v[138:139], v[50:51], v[50:51], v[138:139]
	v_add_f32_e32 v214, v138, v139
	v_add_u32_e32 v207, 0x8000, v207
	v_mov_b32_e32 v215, v214
	s_nop 1
	v_permlane16_swap_b32_e32 v214, v215
	s_nop 0
	v_add_f32_e32 v214, v214, v215
	v_mov_b32_e32 v215, v214
	s_nop 1
	v_permlane32_swap_b32_e32 v214, v215
	s_nop 0
	v_add_f32_e32 v214, v214, v215
	s_and_saveexec_b64 s[28:29], s[4:5]
	global_store_dword v210, v214, s[16:17]
	s_mov_b64 exec, s[28:29]
	s_waitcnt vmcnt(19)
	v_lshlrev_b32_e32 v202, 16, v186
	v_and_b32_e32 v203, 0xffff0000, v186
	v_lshlrev_b32_e32 v204, 16, v187
	v_and_b32_e32 v205, 0xffff0000, v187
	v_pk_add_f32 v[44:45], v[44:45], v[202:203]
	v_pk_add_f32 v[46:47], v[46:47], v[204:205]
	v_lshlrev_b32_e32 v202, 16, v188
	v_and_b32_e32 v203, 0xffff0000, v188
	v_lshlrev_b32_e32 v204, 16, v189
	v_and_b32_e32 v205, 0xffff0000, v189
	v_pk_add_f32 v[40:41], v[40:41], v[202:203]
	v_pk_add_f32 v[42:43], v[42:43], v[204:205]
	v_cvt_pk_bf16_f32 v186, v44, v45
	v_cvt_pk_bf16_f32 v187, v46, v47
	v_cvt_pk_bf16_f32 v188, v40, v41
	v_cvt_pk_bf16_f32 v189, v42, v43
	v_pk_mul_f32 v[138:139], v[44:45], v[44:45]
	global_store_dwordx4 v207, v[186:189], s[10:11]
	v_pk_fma_f32 v[138:139], v[46:47], v[46:47], v[138:139]
	v_pk_fma_f32 v[138:139], v[40:41], v[40:41], v[138:139]
	v_pk_fma_f32 v[138:139], v[42:43], v[42:43], v[138:139]
	v_lshlrev_b32_e32 v202, 16, v190
	v_and_b32_e32 v203, 0xffff0000, v190
	v_lshlrev_b32_e32 v204, 16, v191
	v_and_b32_e32 v205, 0xffff0000, v191
	v_pk_add_f32 v[36:37], v[36:37], v[202:203]
	v_pk_add_f32 v[38:39], v[38:39], v[204:205]
	v_lshlrev_b32_e32 v202, 16, v192
	v_and_b32_e32 v203, 0xffff0000, v192
	v_lshlrev_b32_e32 v204, 16, v193
	v_and_b32_e32 v205, 0xffff0000, v193
	v_pk_add_f32 v[32:33], v[32:33], v[202:203]
	v_pk_add_f32 v[34:35], v[34:35], v[204:205]
	v_cvt_pk_bf16_f32 v190, v36, v37
	v_cvt_pk_bf16_f32 v191, v38, v39
	v_cvt_pk_bf16_f32 v192, v32, v33
	v_cvt_pk_bf16_f32 v193, v34, v35
	v_pk_fma_f32 v[138:139], v[36:37], v[36:37], v[138:139]
	global_store_dwordx4 v207, v[190:193], s[10:11] offset:256
	v_pk_fma_f32 v[138:139], v[38:39], v[38:39], v[138:139]
	v_pk_fma_f32 v[138:139], v[32:33], v[32:33], v[138:139]
	v_pk_fma_f32 v[138:139], v[34:35], v[34:35], v[138:139]
	v_add_f32_e32 v214, v138, v139
	v_add_u32_e32 v207, 0x8000, v207
	v_mov_b32_e32 v215, v214
	s_nop 1
	v_permlane16_swap_b32_e32 v214, v215
	s_nop 0
	v_add_f32_e32 v214, v214, v215
	v_mov_b32_e32 v215, v214
	s_nop 1
	v_permlane32_swap_b32_e32 v214, v215
	s_nop 0
	v_add_f32_e32 v214, v214, v215
	s_and_saveexec_b64 s[28:29], s[4:5]
	global_store_dword v210, v214, s[16:17] offset:1024
	s_mov_b64 exec, s[28:29]
	s_waitcnt vmcnt(20)
	v_lshlrev_b32_e32 v202, 16, v194
	v_and_b32_e32 v203, 0xffff0000, v194
	v_lshlrev_b32_e32 v204, 16, v195
	v_and_b32_e32 v205, 0xffff0000, v195
	v_pk_add_f32 v[28:29], v[28:29], v[202:203]
	v_pk_add_f32 v[30:31], v[30:31], v[204:205]
	v_lshlrev_b32_e32 v202, 16, v196
	v_and_b32_e32 v203, 0xffff0000, v196
	v_lshlrev_b32_e32 v204, 16, v197
	v_and_b32_e32 v205, 0xffff0000, v197
	v_pk_add_f32 v[24:25], v[24:25], v[202:203]
	v_pk_add_f32 v[26:27], v[26:27], v[204:205]
	v_cvt_pk_bf16_f32 v194, v28, v29
	v_cvt_pk_bf16_f32 v195, v30, v31
	v_cvt_pk_bf16_f32 v196, v24, v25
	v_cvt_pk_bf16_f32 v197, v26, v27
	v_pk_mul_f32 v[138:139], v[28:29], v[28:29]
	global_store_dwordx4 v207, v[194:197], s[10:11]
	v_pk_fma_f32 v[138:139], v[30:31], v[30:31], v[138:139]
	v_pk_fma_f32 v[138:139], v[24:25], v[24:25], v[138:139]
	v_pk_fma_f32 v[138:139], v[26:27], v[26:27], v[138:139]
	v_lshlrev_b32_e32 v202, 16, v198
	v_and_b32_e32 v203, 0xffff0000, v198
	v_lshlrev_b32_e32 v204, 16, v199
	v_and_b32_e32 v205, 0xffff0000, v199
	v_pk_add_f32 v[20:21], v[20:21], v[202:203]
	v_pk_add_f32 v[22:23], v[22:23], v[204:205]
	v_lshlrev_b32_e32 v202, 16, v200
	v_and_b32_e32 v203, 0xffff0000, v200
	v_lshlrev_b32_e32 v204, 16, v201
	v_and_b32_e32 v205, 0xffff0000, v201
	v_pk_add_f32 v[16:17], v[16:17], v[202:203]
	v_pk_add_f32 v[18:19], v[18:19], v[204:205]
	v_cvt_pk_bf16_f32 v198, v20, v21
	v_cvt_pk_bf16_f32 v199, v22, v23
	v_cvt_pk_bf16_f32 v200, v16, v17
	v_cvt_pk_bf16_f32 v201, v18, v19
	v_pk_fma_f32 v[138:139], v[20:21], v[20:21], v[138:139]
	global_store_dwordx4 v207, v[198:201], s[10:11] offset:256
	v_pk_fma_f32 v[138:139], v[22:23], v[22:23], v[138:139]
	v_pk_fma_f32 v[138:139], v[16:17], v[16:17], v[138:139]
	v_pk_fma_f32 v[138:139], v[18:19], v[18:19], v[138:139]
	v_add_f32_e32 v214, v138, v139
	v_add_u32_e32 v207, 0x8000, v207
	v_mov_b32_e32 v215, v214
	s_nop 1
	v_permlane16_swap_b32_e32 v214, v215
	s_nop 0
	v_add_f32_e32 v214, v214, v215
	v_mov_b32_e32 v215, v214
	s_nop 1
	v_permlane32_swap_b32_e32 v214, v215
	s_nop 0
	v_add_f32_e32 v214, v214, v215
	s_and_saveexec_b64 s[28:29], s[4:5]
	global_store_dword v210, v214, s[16:17] offset:2048
	s_mov_b64 exec, s[28:29]
	s_waitcnt vmcnt(18)
	v_lshlrev_b32_e32 v202, 16, v146
	v_and_b32_e32 v203, 0xffff0000, v146
	v_lshlrev_b32_e32 v204, 16, v147
	v_and_b32_e32 v205, 0xffff0000, v147
	v_pk_add_f32 v[12:13], v[12:13], v[202:203]
	v_pk_add_f32 v[14:15], v[14:15], v[204:205]
	v_lshlrev_b32_e32 v202, 16, v148
	v_and_b32_e32 v203, 0xffff0000, v148
	v_lshlrev_b32_e32 v204, 16, v149
	v_and_b32_e32 v205, 0xffff0000, v149
	v_pk_add_f32 v[8:9], v[8:9], v[202:203]
	v_pk_add_f32 v[10:11], v[10:11], v[204:205]
	v_cvt_pk_bf16_f32 v146, v12, v13
	v_cvt_pk_bf16_f32 v147, v14, v15
	v_cvt_pk_bf16_f32 v148, v8, v9
	v_cvt_pk_bf16_f32 v149, v10, v11
	v_pk_mul_f32 v[138:139], v[12:13], v[12:13]
	global_store_dwordx4 v207, v[146:149], s[10:11]
	v_pk_fma_f32 v[138:139], v[14:15], v[14:15], v[138:139]
	v_pk_fma_f32 v[138:139], v[8:9], v[8:9], v[138:139]
	v_pk_fma_f32 v[138:139], v[10:11], v[10:11], v[138:139]
	v_lshlrev_b32_e32 v202, 16, v150
	v_and_b32_e32 v203, 0xffff0000, v150
	v_lshlrev_b32_e32 v204, 16, v151
	v_and_b32_e32 v205, 0xffff0000, v151
	v_pk_add_f32 v[4:5], v[4:5], v[202:203]
	v_pk_add_f32 v[6:7], v[6:7], v[204:205]
	v_lshlrev_b32_e32 v202, 16, v152
	v_and_b32_e32 v203, 0xffff0000, v152
	v_lshlrev_b32_e32 v204, 16, v153
	v_and_b32_e32 v205, 0xffff0000, v153
	v_pk_add_f32 v[0:1], v[0:1], v[202:203]
	v_pk_add_f32 v[2:3], v[2:3], v[204:205]
	v_cvt_pk_bf16_f32 v150, v4, v5
	v_cvt_pk_bf16_f32 v151, v6, v7
	v_cvt_pk_bf16_f32 v152, v0, v1
	v_cvt_pk_bf16_f32 v153, v2, v3
	v_pk_fma_f32 v[138:139], v[4:5], v[4:5], v[138:139]
	global_store_dwordx4 v207, v[150:153], s[10:11] offset:256
	v_pk_fma_f32 v[138:139], v[6:7], v[6:7], v[138:139]
	v_pk_fma_f32 v[138:139], v[0:1], v[0:1], v[138:139]
	v_pk_fma_f32 v[138:139], v[2:3], v[2:3], v[138:139]
	v_add_f32_e32 v214, v138, v139
	v_add_u32_e32 v207, 0x8000, v207
	v_mov_b32_e32 v215, v214
	s_nop 1
	v_permlane16_swap_b32_e32 v214, v215
	s_nop 0
	v_add_f32_e32 v214, v214, v215
	v_mov_b32_e32 v215, v214
	s_nop 1
	v_permlane32_swap_b32_e32 v214, v215
	s_nop 0
	v_add_f32_e32 v214, v214, v215
	s_and_saveexec_b64 s[28:29], s[4:5]
	global_store_dword v210, v214, s[16:17] offset:3072
	s_mov_b64 exec, s[28:29]
	s_branch .LBB0_768

.LBB0_823:
	s_add_u32 s26, s24, 0xfffc0080
	s_addc_u32 s27, s25, -1
	s_add_i32 s65, 0, 0x10000
	v_add_u32_e32 v154, s65, v143
	ds_read_b128 v[138:141], v154
	ds_read_b128 v[146:149], v154 offset:1024
	ds_read_b128 v[150:153], v154 offset:2048
	ds_read_b128 v[154:157], v154 offset:3072
	s_cmp_eq_u32 s51, 12
	s_cselect_b32 s29, s19, s27
	s_cselect_b32 s28, s38, s26
	s_cselect_b32 s27, s17, s50
	s_cselect_b32 s26, s39, s46
	s_add_i32 m0, s58, 0xc000
	ds_read_b128 v[158:161], v145
	ds_read_b128 v[162:165], v145 offset:1024
	ds_read_b128 v[166:169], v145 offset:2048
	ds_read_b128 v[170:173], v145 offset:3072
	ds_read_b128 v[174:177], v145 offset:4096
	ds_read_b128 v[178:181], v145 offset:5120
	ds_read_b128 v[182:185], v145 offset:6144
	global_load_lds_dwordx4 v134, s[24:25]
	s_add_i32 m0, s58, 0xe000
	ds_read_b128 v[186:189], v145 offset:7168
	global_load_lds_dwordx4 v136, s[24:25]
	s_waitcnt lgkmcnt(8)
	s_barrier
	s_waitcnt lgkmcnt(0)
	v_mfma_f32_16x16x32_bf16 v[124:127], v[138:141], v[158:161], v[124:127]
	v_mfma_f32_16x16x32_bf16 v[120:123], v[150:153], v[158:161], v[120:123]
	v_mfma_f32_16x16x32_bf16 v[108:111], v[138:141], v[166:169], v[108:111]
	v_mfma_f32_16x16x32_bf16 v[104:107], v[150:153], v[166:169], v[104:107]
	v_mfma_f32_16x16x32_bf16 v[92:95], v[138:141], v[174:177], v[92:95]
	v_mfma_f32_16x16x32_bf16 v[88:91], v[150:153], v[174:177], v[88:91]
	v_mfma_f32_16x16x32_bf16 v[76:79], v[138:141], v[182:185], v[76:79]
	v_mfma_f32_16x16x32_bf16 v[72:75], v[150:153], v[182:185], v[72:75]
	v_mfma_f32_16x16x32_bf16 v[124:127], v[146:149], v[162:165], v[124:127]
	v_mfma_f32_16x16x32_bf16 v[120:123], v[154:157], v[162:165], v[120:123]
	v_mfma_f32_16x16x32_bf16 v[108:111], v[146:149], v[170:173], v[108:111]
	v_mfma_f32_16x16x32_bf16 v[104:107], v[154:157], v[170:173], v[104:107]
	v_mfma_f32_16x16x32_bf16 v[92:95], v[146:149], v[178:181], v[92:95]
	v_mfma_f32_16x16x32_bf16 v[88:91], v[154:157], v[178:181], v[88:91]
	v_mfma_f32_16x16x32_bf16 v[76:79], v[146:149], v[186:189], v[76:79]
	v_mfma_f32_16x16x32_bf16 v[72:75], v[154:157], v[186:189], v[72:75]
	s_barrier
	s_add_i32 s68, 0, 0x14000
	s_add_i32 s65, s65, s57
	v_add_u32_e32 v202, s68, v143
	s_add_u32 s98, s26, s40
	s_addc_u32 s99, s27, s41
	s_mov_b32 m0, s65
	ds_read_b128 v[190:193], v202
	ds_read_b128 v[194:197], v202 offset:1024
	ds_read_b128 v[198:201], v202 offset:2048
	global_load_lds_dwordx4 v208, s[26:27]
	s_add_i32 m0, s65, 0x2000
	ds_read_b128 v[202:205], v202 offset:3072
	global_load_lds_dwordx4 v128, s[26:27]
	s_barrier
	s_waitcnt lgkmcnt(0)
	v_mfma_f32_16x16x32_bf16 v[116:119], v[190:193], v[158:161], v[116:119]
	v_mfma_f32_16x16x32_bf16 v[112:115], v[198:201], v[158:161], v[112:115]
	v_mfma_f32_16x16x32_bf16 v[100:103], v[190:193], v[166:169], v[100:103]
	v_mfma_f32_16x16x32_bf16 v[96:99], v[198:201], v[166:169], v[96:99]
	v_mfma_f32_16x16x32_bf16 v[84:87], v[190:193], v[174:177], v[84:87]
	v_mfma_f32_16x16x32_bf16 v[80:83], v[198:201], v[174:177], v[80:83]
	v_mfma_f32_16x16x32_bf16 v[68:71], v[190:193], v[182:185], v[68:71]
	v_mfma_f32_16x16x32_bf16 v[64:67], v[198:201], v[182:185], v[64:67]
	v_mfma_f32_16x16x32_bf16 v[116:119], v[194:197], v[162:165], v[116:119]
	v_mfma_f32_16x16x32_bf16 v[112:115], v[202:205], v[162:165], v[112:115]
	v_mfma_f32_16x16x32_bf16 v[100:103], v[194:197], v[170:173], v[100:103]
	v_mfma_f32_16x16x32_bf16 v[96:99], v[202:205], v[170:173], v[96:99]
	v_mfma_f32_16x16x32_bf16 v[84:87], v[194:197], v[178:181], v[84:87]
	v_mfma_f32_16x16x32_bf16 v[80:83], v[202:205], v[178:181], v[80:83]
	v_mfma_f32_16x16x32_bf16 v[68:71], v[194:197], v[186:189], v[68:71]
	v_mfma_f32_16x16x32_bf16 v[64:67], v[202:205], v[186:189], v[64:67]
	s_mov_b32 m0, s58
	s_add_u32 s100, s28, s40
	s_addc_u32 s101, s29, s41
	s_barrier
	ds_read_b128 v[158:161], v145 offset:16384
	ds_read_b128 v[162:165], v145 offset:17408
	ds_read_b128 v[166:169], v145 offset:18432
	ds_read_b128 v[170:173], v145 offset:19456
	ds_read_b128 v[174:177], v145 offset:20480
	ds_read_b128 v[178:181], v145 offset:21504
	ds_read_b128 v[182:185], v145 offset:22528
	global_load_lds_dwordx4 v132, s[28:29]
	s_mov_b32 m0, s59
	ds_read_b128 v[186:189], v145 offset:23552
	global_load_lds_dwordx4 v130, s[28:29]
	s_barrier
	s_waitcnt lgkmcnt(0)
	v_mfma_f32_16x16x32_bf16 v[60:63], v[138:141], v[158:161], v[60:63]
	v_mfma_f32_16x16x32_bf16 v[56:59], v[150:153], v[158:161], v[56:59]
	v_mfma_f32_16x16x32_bf16 v[44:47], v[138:141], v[166:169], v[44:47]
	v_mfma_f32_16x16x32_bf16 v[40:43], v[150:153], v[166:169], v[40:43]
	v_mfma_f32_16x16x32_bf16 v[28:31], v[138:141], v[174:177], v[28:31]
	v_mfma_f32_16x16x32_bf16 v[24:27], v[150:153], v[174:177], v[24:27]
	v_mfma_f32_16x16x32_bf16 v[12:15], v[138:141], v[182:185], v[12:15]
	v_mfma_f32_16x16x32_bf16 v[8:11], v[150:153], v[182:185], v[8:11]
	v_mfma_f32_16x16x32_bf16 v[60:63], v[146:149], v[162:165], v[60:63]
	v_mfma_f32_16x16x32_bf16 v[56:59], v[154:157], v[162:165], v[56:59]
	v_mfma_f32_16x16x32_bf16 v[44:47], v[146:149], v[170:173], v[44:47]
	v_mfma_f32_16x16x32_bf16 v[40:43], v[154:157], v[170:173], v[40:43]
	v_mfma_f32_16x16x32_bf16 v[28:31], v[146:149], v[178:181], v[28:31]
	v_mfma_f32_16x16x32_bf16 v[24:27], v[154:157], v[178:181], v[24:27]
	v_mfma_f32_16x16x32_bf16 v[12:15], v[146:149], v[186:189], v[12:15]
	v_mfma_f32_16x16x32_bf16 v[8:11], v[154:157], v[186:189], v[8:11]
	s_barrier
	s_add_u32 s66, s26, 0x40000
	s_addc_u32 s67, s27, 0
	s_add_i32 s65, s68, s57
	s_mov_b32 m0, s65
	s_nop 0
	global_load_lds_dwordx4 v208, s[66:67]
	s_add_i32 m0, s65, 0x2000
	s_nop 0
	global_load_lds_dwordx4 v128, s[66:67]
	s_waitcnt vmcnt(6)
	s_barrier
	v_mfma_f32_16x16x32_bf16 v[52:55], v[190:193], v[158:161], v[52:55]
	v_mfma_f32_16x16x32_bf16 v[48:51], v[198:201], v[158:161], v[48:51]
	v_mfma_f32_16x16x32_bf16 v[36:39], v[190:193], v[166:169], v[36:39]
	v_mfma_f32_16x16x32_bf16 v[32:35], v[198:201], v[166:169], v[32:35]
	v_mfma_f32_16x16x32_bf16 v[20:23], v[190:193], v[174:177], v[20:23]
	v_mfma_f32_16x16x32_bf16 v[16:19], v[198:201], v[174:177], v[16:19]
	v_mfma_f32_16x16x32_bf16 v[4:7], v[190:193], v[182:185], v[4:7]
	v_mfma_f32_16x16x32_bf16 v[0:3], v[198:201], v[182:185], v[0:3]
	v_mfma_f32_16x16x32_bf16 v[52:55], v[194:197], v[162:165], v[52:55]
	v_mfma_f32_16x16x32_bf16 v[48:51], v[202:205], v[162:165], v[48:51]
	v_mfma_f32_16x16x32_bf16 v[36:39], v[194:197], v[170:173], v[36:39]
	v_mfma_f32_16x16x32_bf16 v[32:35], v[202:205], v[170:173], v[32:35]
	v_mfma_f32_16x16x32_bf16 v[20:23], v[194:197], v[178:181], v[20:23]
	v_mfma_f32_16x16x32_bf16 v[16:19], v[202:205], v[178:181], v[16:19]
	v_mfma_f32_16x16x32_bf16 v[4:7], v[194:197], v[186:189], v[4:7]
	v_mfma_f32_16x16x32_bf16 v[0:3], v[202:205], v[186:189], v[0:3]
	s_add_i32 s65, 0, 0x18000
	v_add_u32_e32 v154, s65, v143
	s_barrier
	ds_read_b128 v[138:141], v154
	ds_read_b128 v[146:149], v154 offset:1024
	ds_read_b128 v[150:153], v154 offset:2048
	ds_read_b128 v[154:157], v154 offset:3072
	s_add_u32 s28, s28, 0x40000
	s_addc_u32 s29, s29, 0
	s_mov_b32 m0, s60
	ds_read_b128 v[158:161], v145 offset:32768
	ds_read_b128 v[162:165], v145 offset:33792
	ds_read_b128 v[166:169], v145 offset:34816
	ds_read_b128 v[170:173], v145 offset:35840
	ds_read_b128 v[174:177], v145 offset:36864
	ds_read_b128 v[178:181], v145 offset:37888
	ds_read_b128 v[182:185], v145 offset:38912
	global_load_lds_dwordx4 v132, s[28:29]
	s_mov_b32 m0, s61
	ds_read_b128 v[186:189], v145 offset:39936
	global_load_lds_dwordx4 v130, s[28:29]
	s_waitcnt lgkmcnt(8)
	s_barrier
	s_waitcnt lgkmcnt(0)
	v_mfma_f32_16x16x32_bf16 v[124:127], v[138:141], v[158:161], v[124:127]
	v_mfma_f32_16x16x32_bf16 v[120:123], v[150:153], v[158:161], v[120:123]
	v_mfma_f32_16x16x32_bf16 v[108:111], v[138:141], v[166:169], v[108:111]
	v_mfma_f32_16x16x32_bf16 v[104:107], v[150:153], v[166:169], v[104:107]
	v_mfma_f32_16x16x32_bf16 v[92:95], v[138:141], v[174:177], v[92:95]
	v_mfma_f32_16x16x32_bf16 v[88:91], v[150:153], v[174:177], v[88:91]
	v_mfma_f32_16x16x32_bf16 v[76:79], v[138:141], v[182:185], v[76:79]
	v_mfma_f32_16x16x32_bf16 v[72:75], v[150:153], v[182:185], v[72:75]
	v_mfma_f32_16x16x32_bf16 v[124:127], v[146:149], v[162:165], v[124:127]
	v_mfma_f32_16x16x32_bf16 v[120:123], v[154:157], v[162:165], v[120:123]
	v_mfma_f32_16x16x32_bf16 v[108:111], v[146:149], v[170:173], v[108:111]
	v_mfma_f32_16x16x32_bf16 v[104:107], v[154:157], v[170:173], v[104:107]
	v_mfma_f32_16x16x32_bf16 v[92:95], v[146:149], v[178:181], v[92:95]
	v_mfma_f32_16x16x32_bf16 v[88:91], v[154:157], v[178:181], v[88:91]
	v_mfma_f32_16x16x32_bf16 v[76:79], v[146:149], v[186:189], v[76:79]
	v_mfma_f32_16x16x32_bf16 v[72:75], v[154:157], v[186:189], v[72:75]
	s_barrier
	s_add_i32 s28, 0, 0x1c000
	s_add_i32 s29, s65, s57
	v_add_u32_e32 v202, s28, v143
	s_mov_b32 m0, s29
	ds_read_b128 v[190:193], v202
	ds_read_b128 v[194:197], v202 offset:1024
	ds_read_b128 v[198:201], v202 offset:2048
	global_load_lds_dwordx4 v208, s[98:99]
	s_add_i32 m0, s29, 0x2000
	ds_read_b128 v[202:205], v202 offset:3072
	global_load_lds_dwordx4 v128, s[98:99]
	s_barrier
	s_waitcnt lgkmcnt(0)
	v_mfma_f32_16x16x32_bf16 v[116:119], v[190:193], v[158:161], v[116:119]
	v_mfma_f32_16x16x32_bf16 v[112:115], v[198:201], v[158:161], v[112:115]
	v_mfma_f32_16x16x32_bf16 v[100:103], v[190:193], v[166:169], v[100:103]
	v_mfma_f32_16x16x32_bf16 v[96:99], v[198:201], v[166:169], v[96:99]
	v_mfma_f32_16x16x32_bf16 v[84:87], v[190:193], v[174:177], v[84:87]
	v_mfma_f32_16x16x32_bf16 v[80:83], v[198:201], v[174:177], v[80:83]
	v_mfma_f32_16x16x32_bf16 v[68:71], v[190:193], v[182:185], v[68:71]
	v_mfma_f32_16x16x32_bf16 v[64:67], v[198:201], v[182:185], v[64:67]
	v_mfma_f32_16x16x32_bf16 v[116:119], v[194:197], v[162:165], v[116:119]
	v_mfma_f32_16x16x32_bf16 v[112:115], v[202:205], v[162:165], v[112:115]
	v_mfma_f32_16x16x32_bf16 v[100:103], v[194:197], v[170:173], v[100:103]
	v_mfma_f32_16x16x32_bf16 v[96:99], v[202:205], v[170:173], v[96:99]
	v_mfma_f32_16x16x32_bf16 v[84:87], v[194:197], v[178:181], v[84:87]
	v_mfma_f32_16x16x32_bf16 v[80:83], v[202:205], v[178:181], v[80:83]
	v_mfma_f32_16x16x32_bf16 v[68:71], v[194:197], v[186:189], v[68:71]
	v_mfma_f32_16x16x32_bf16 v[64:67], v[202:205], v[186:189], v[64:67]
	s_mov_b32 m0, s62
	s_barrier
	ds_read_b128 v[158:161], v145 offset:49152
	ds_read_b128 v[162:165], v145 offset:50176
	ds_read_b128 v[166:169], v145 offset:51200
	ds_read_b128 v[170:173], v145 offset:52224
	ds_read_b128 v[174:177], v145 offset:53248
	ds_read_b128 v[178:181], v145 offset:54272
	ds_read_b128 v[182:185], v145 offset:55296
	global_load_lds_dwordx4 v132, s[100:101]
	s_mov_b32 m0, s63
	ds_read_b128 v[186:189], v145 offset:56320
	global_load_lds_dwordx4 v130, s[100:101]
	s_barrier
	s_waitcnt lgkmcnt(0)
	v_mfma_f32_16x16x32_bf16 v[60:63], v[138:141], v[158:161], v[60:63]
	v_mfma_f32_16x16x32_bf16 v[56:59], v[150:153], v[158:161], v[56:59]
	v_mfma_f32_16x16x32_bf16 v[44:47], v[138:141], v[166:169], v[44:47]
	v_mfma_f32_16x16x32_bf16 v[40:43], v[150:153], v[166:169], v[40:43]
	v_mfma_f32_16x16x32_bf16 v[28:31], v[138:141], v[174:177], v[28:31]
	v_mfma_f32_16x16x32_bf16 v[24:27], v[150:153], v[174:177], v[24:27]
	v_mfma_f32_16x16x32_bf16 v[12:15], v[138:141], v[182:185], v[12:15]
	v_mfma_f32_16x16x32_bf16 v[8:11], v[150:153], v[182:185], v[8:11]
	v_mfma_f32_16x16x32_bf16 v[60:63], v[146:149], v[162:165], v[60:63]
	v_mfma_f32_16x16x32_bf16 v[56:59], v[154:157], v[162:165], v[56:59]
	v_mfma_f32_16x16x32_bf16 v[44:47], v[146:149], v[170:173], v[44:47]
	v_mfma_f32_16x16x32_bf16 v[40:43], v[154:157], v[170:173], v[40:43]
	v_mfma_f32_16x16x32_bf16 v[28:31], v[146:149], v[178:181], v[28:31]
	v_mfma_f32_16x16x32_bf16 v[24:27], v[154:157], v[178:181], v[24:27]
	v_mfma_f32_16x16x32_bf16 v[12:15], v[146:149], v[186:189], v[12:15]
	v_mfma_f32_16x16x32_bf16 v[8:11], v[154:157], v[186:189], v[8:11]
	s_barrier
	s_add_u32 s26, s26, 0x40080
	s_addc_u32 s27, s27, 0
	s_add_i32 s28, s28, s57
	s_mov_b32 m0, s28
	s_add_i32 s51, s51, 2
	global_load_lds_dwordx4 v208, s[26:27]
	s_add_i32 m0, s28, 0x2000
	s_add_u32 s24, s24, 0x100
	s_addc_u32 s25, s25, 0
	global_load_lds_dwordx4 v128, s[26:27]
	s_add_u32 s46, s46, 0x100
	s_addc_u32 s50, s50, 0
	s_waitcnt vmcnt(6)
	s_barrier
	v_mfma_f32_16x16x32_bf16 v[52:55], v[190:193], v[158:161], v[52:55]
	v_mfma_f32_16x16x32_bf16 v[48:51], v[198:201], v[158:161], v[48:51]
	v_mfma_f32_16x16x32_bf16 v[36:39], v[190:193], v[166:169], v[36:39]
	v_mfma_f32_16x16x32_bf16 v[32:35], v[198:201], v[166:169], v[32:35]
	v_mfma_f32_16x16x32_bf16 v[20:23], v[190:193], v[174:177], v[20:23]
	v_mfma_f32_16x16x32_bf16 v[16:19], v[198:201], v[174:177], v[16:19]
	v_mfma_f32_16x16x32_bf16 v[4:7], v[190:193], v[182:185], v[4:7]
	v_mfma_f32_16x16x32_bf16 v[0:3], v[198:201], v[182:185], v[0:3]
	v_mfma_f32_16x16x32_bf16 v[52:55], v[194:197], v[162:165], v[52:55]
	v_mfma_f32_16x16x32_bf16 v[48:51], v[202:205], v[162:165], v[48:51]
	v_mfma_f32_16x16x32_bf16 v[36:39], v[194:197], v[170:173], v[36:39]
	v_mfma_f32_16x16x32_bf16 v[32:35], v[202:205], v[170:173], v[32:35]
	v_mfma_f32_16x16x32_bf16 v[20:23], v[194:197], v[178:181], v[20:23]
	v_mfma_f32_16x16x32_bf16 v[16:19], v[202:205], v[178:181], v[16:19]
	v_mfma_f32_16x16x32_bf16 v[4:7], v[194:197], v[186:189], v[4:7]
	v_mfma_f32_16x16x32_bf16 v[0:3], v[202:205], v[186:189], v[0:3]
	s_cmp_gt_u32 s51, 13
	s_barrier
	s_cbranch_scc0 .LBB0_823
	v_lshl_add_u32 v140, s35, 8, v142
	v_lshl_or_b32 v141, s34, 8, v144
	s_mov_b32 s34, s16
	s_mov_b32 s35, s18
	s_mov_b64 s[26:27], s[22:23]
	s_mov_b64 s[24:25], s[20:21]
	v_mbcnt_lo_u32_b32 v206, -1, 0
	v_mbcnt_hi_u32_b32 v206, -1, v206
	v_and_b32_e32 v206, 48, v206
	v_lshl_add_u32 v206, v140, 6, v206
	v_lshlrev_b32_e32 v207, 11, v140
	v_lshl_add_u32 v207, v141, 1, v207
	global_load_dwordx4 v[146:149], v206, s[14:15]
	global_load_dwordx4 v[150:153], v206, s[14:15] offset:1024
	global_load_dwordx4 v[154:157], v206, s[14:15] offset:2048
	global_load_dwordx4 v[158:161], v206, s[14:15] offset:3072
	v_add_u32_e32 v206, 0x2000, v206
	global_load_dwordx4 v[162:165], v206, s[14:15]
	global_load_dwordx4 v[166:169], v206, s[14:15] offset:1024
	global_load_dwordx4 v[170:173], v206, s[14:15] offset:2048
	global_load_dwordx4 v[174:177], v206, s[14:15] offset:3072
	s_waitcnt vmcnt(7)
	v_pk_add_f32 v[146:147], v[146:147], v[148:149]
	s_nop 0
	v_add_f32_e32 v214, v146, v147
	v_mov_b32_e32 v215, v214
	s_nop 1
	v_permlane16_swap_b32_e32 v214, v215
	s_nop 0
	v_add_f32_e32 v214, v214, v215
	v_mov_b32_e32 v215, v214
	s_nop 1
	v_permlane32_swap_b32_e32 v214, v215
	s_nop 0
	v_add_f32_e32 v214, v214, v215
	v_fmamk_f32 v214, v214, 0x3a800000, v248
	v_rsq_f32_e32 v178, v214
	s_nop 0
	v_pk_mul_f32 v[124:125], v[124:125], v[178:179] op_sel_hi:[1,0]
	v_pk_mul_f32 v[126:127], v[126:127], v[178:179] op_sel_hi:[1,0]
	v_pk_mul_f32 v[120:121], v[120:121], v[178:179] op_sel_hi:[1,0]
	v_pk_mul_f32 v[122:123], v[122:123], v[178:179] op_sel_hi:[1,0]
	v_cvt_pk_bf16_f32 v198, v124, v125
	v_cvt_pk_bf16_f32 v199, v126, v127
	v_cvt_pk_bf16_f32 v200, v120, v121
	v_cvt_pk_bf16_f32 v201, v122, v123
	global_store_dwordx4 v207, v[198:201], s[10:11]
	v_pk_mul_f32 v[116:117], v[116:117], v[178:179] op_sel_hi:[1,0]
	v_pk_mul_f32 v[118:119], v[118:119], v[178:179] op_sel_hi:[1,0]
	v_pk_mul_f32 v[112:113], v[112:113], v[178:179] op_sel_hi:[1,0]
	v_pk_mul_f32 v[114:115], v[114:115], v[178:179] op_sel_hi:[1,0]
	v_cvt_pk_bf16_f32 v202, v116, v117
	v_cvt_pk_bf16_f32 v203, v118, v119
	v_cvt_pk_bf16_f32 v204, v112, v113
	v_cvt_pk_bf16_f32 v205, v114, v115
	global_store_dwordx4 v207, v[202:205], s[10:11] offset:256
	v_add_u32_e32 v207, 0x8000, v207
	s_waitcnt vmcnt(8)
	v_pk_add_f32 v[150:151], v[150:151], v[152:153]
	s_nop 0
	v_add_f32_e32 v214, v150, v151
	v_mov_b32_e32 v215, v214
	s_nop 1
	v_permlane16_swap_b32_e32 v214, v215
	s_nop 0
	v_add_f32_e32 v214, v214, v215
	v_mov_b32_e32 v215, v214
	s_nop 1
	v_permlane32_swap_b32_e32 v214, v215
	s_nop 0
	v_add_f32_e32 v214, v214, v215
	v_fmamk_f32 v214, v214, 0x3a800000, v248
	v_rsq_f32_e32 v180, v214
	s_nop 0
	v_pk_mul_f32 v[108:109], v[108:109], v[180:181] op_sel_hi:[1,0]
	v_pk_mul_f32 v[110:111], v[110:111], v[180:181] op_sel_hi:[1,0]
	v_pk_mul_f32 v[104:105], v[104:105], v[180:181] op_sel_hi:[1,0]
	v_pk_mul_f32 v[106:107], v[106:107], v[180:181] op_sel_hi:[1,0]
	v_cvt_pk_bf16_f32 v198, v108, v109
	v_cvt_pk_bf16_f32 v199, v110, v111
	v_cvt_pk_bf16_f32 v200, v104, v105
	v_cvt_pk_bf16_f32 v201, v106, v107
	global_store_dwordx4 v207, v[198:201], s[10:11]
	v_pk_mul_f32 v[100:101], v[100:101], v[180:181] op_sel_hi:[1,0]
	v_pk_mul_f32 v[102:103], v[102:103], v[180:181] op_sel_hi:[1,0]
	v_pk_mul_f32 v[96:97], v[96:97], v[180:181] op_sel_hi:[1,0]
	v_pk_mul_f32 v[98:99], v[98:99], v[180:181] op_sel_hi:[1,0]
	v_cvt_pk_bf16_f32 v202, v100, v101
	v_cvt_pk_bf16_f32 v203, v102, v103
	v_cvt_pk_bf16_f32 v204, v96, v97
	v_cvt_pk_bf16_f32 v205, v98, v99
	global_store_dwordx4 v207, v[202:205], s[10:11] offset:256
	v_add_u32_e32 v207, 0x8000, v207
	s_waitcnt vmcnt(9)
	v_pk_add_f32 v[154:155], v[154:155], v[156:157]
	s_nop 0
	v_add_f32_e32 v214, v154, v155
	v_mov_b32_e32 v215, v214
	s_nop 1
	v_permlane16_swap_b32_e32 v214, v215
	s_nop 0
	v_add_f32_e32 v214, v214, v215
	v_mov_b32_e32 v215, v214
	s_nop 1
	v_permlane32_swap_b32_e32 v214, v215
	s_nop 0
	v_add_f32_e32 v214, v214, v215
	v_fmamk_f32 v214, v214, 0x3a800000, v248
	v_rsq_f32_e32 v182, v214
	s_nop 0
	v_pk_mul_f32 v[92:93], v[92:93], v[182:183] op_sel_hi:[1,0]
	v_pk_mul_f32 v[94:95], v[94:95], v[182:183] op_sel_hi:[1,0]
	v_pk_mul_f32 v[88:89], v[88:89], v[182:183] op_sel_hi:[1,0]
	v_pk_mul_f32 v[90:91], v[90:91], v[182:183] op_sel_hi:[1,0]
	v_cvt_pk_bf16_f32 v198, v92, v93
	v_cvt_pk_bf16_f32 v199, v94, v95
	v_cvt_pk_bf16_f32 v200, v88, v89
	v_cvt_pk_bf16_f32 v201, v90, v91
	global_store_dwordx4 v207, v[198:201], s[10:11]
	v_pk_mul_f32 v[84:85], v[84:85], v[182:183] op_sel_hi:[1,0]
	v_pk_mul_f32 v[86:87], v[86:87], v[182:183] op_sel_hi:[1,0]
	v_pk_mul_f32 v[80:81], v[80:81], v[182:183] op_sel_hi:[1,0]
	v_pk_mul_f32 v[82:83], v[82:83], v[182:183] op_sel_hi:[1,0]
	v_cvt_pk_bf16_f32 v202, v84, v85
	v_cvt_pk_bf16_f32 v203, v86, v87
	v_cvt_pk_bf16_f32 v204, v80, v81
	v_cvt_pk_bf16_f32 v205, v82, v83
	global_store_dwordx4 v207, v[202:205], s[10:11] offset:256
	v_add_u32_e32 v207, 0x8000, v207
	s_waitcnt vmcnt(10)
	v_pk_add_f32 v[158:159], v[158:159], v[160:161]
	s_nop 0
	v_add_f32_e32 v214, v158, v159
	v_mov_b32_e32 v215, v214
	s_nop 1
	v_permlane16_swap_b32_e32 v214, v215
	s_nop 0
	v_add_f32_e32 v214, v214, v215
	v_mov_b32_e32 v215, v214
	s_nop 1
	v_permlane32_swap_b32_e32 v214, v215
	s_nop 0
	v_add_f32_e32 v214, v214, v215
	v_fmamk_f32 v214, v214, 0x3a800000, v248
	v_rsq_f32_e32 v184, v214
	s_nop 0
	v_pk_mul_f32 v[76:77], v[76:77], v[184:185] op_sel_hi:[1,0]
	v_pk_mul_f32 v[78:79], v[78:79], v[184:185] op_sel_hi:[1,0]
	v_pk_mul_f32 v[72:73], v[72:73], v[184:185] op_sel_hi:[1,0]
	v_pk_mul_f32 v[74:75], v[74:75], v[184:185] op_sel_hi:[1,0]
	v_cvt_pk_bf16_f32 v198, v76, v77
	v_cvt_pk_bf16_f32 v199, v78, v79
	v_cvt_pk_bf16_f32 v200, v72, v73
	v_cvt_pk_bf16_f32 v201, v74, v75
	global_store_dwordx4 v207, v[198:201], s[10:11]
	v_pk_mul_f32 v[68:69], v[68:69], v[184:185] op_sel_hi:[1,0]
	v_pk_mul_f32 v[70:71], v[70:71], v[184:185] op_sel_hi:[1,0]
	v_pk_mul_f32 v[64:65], v[64:65], v[184:185] op_sel_hi:[1,0]
	v_pk_mul_f32 v[66:67], v[66:67], v[184:185] op_sel_hi:[1,0]
	v_cvt_pk_bf16_f32 v202, v68, v69
	v_cvt_pk_bf16_f32 v203, v70, v71
	v_cvt_pk_bf16_f32 v204, v64, v65
	v_cvt_pk_bf16_f32 v205, v66, v67
	global_store_dwordx4 v207, v[202:205], s[10:11] offset:256
	v_add_u32_e32 v207, 0x28000, v207
	s_waitcnt vmcnt(11)
	v_pk_add_f32 v[162:163], v[162:163], v[164:165]
	s_nop 0
	v_add_f32_e32 v214, v162, v163
	v_mov_b32_e32 v215, v214
	s_nop 1
	v_permlane16_swap_b32_e32 v214, v215
	s_nop 0
	v_add_f32_e32 v214, v214, v215
	v_mov_b32_e32 v215, v214
	s_nop 1
	v_permlane32_swap_b32_e32 v214, v215
	s_nop 0
	v_add_f32_e32 v214, v214, v215
	v_fmamk_f32 v214, v214, 0x3a800000, v248
	v_rsq_f32_e32 v186, v214
	s_nop 0
	v_pk_mul_f32 v[60:61], v[60:61], v[186:187] op_sel_hi:[1,0]
	v_pk_mul_f32 v[62:63], v[62:63], v[186:187] op_sel_hi:[1,0]
	v_pk_mul_f32 v[56:57], v[56:57], v[186:187] op_sel_hi:[1,0]
	v_pk_mul_f32 v[58:59], v[58:59], v[186:187] op_sel_hi:[1,0]
	v_cvt_pk_bf16_f32 v198, v60, v61
	v_cvt_pk_bf16_f32 v199, v62, v63
	v_cvt_pk_bf16_f32 v200, v56, v57
	v_cvt_pk_bf16_f32 v201, v58, v59
	global_store_dwordx4 v207, v[198:201], s[10:11]
	v_pk_mul_f32 v[52:53], v[52:53], v[186:187] op_sel_hi:[1,0]
	v_pk_mul_f32 v[54:55], v[54:55], v[186:187] op_sel_hi:[1,0]
	v_pk_mul_f32 v[48:49], v[48:49], v[186:187] op_sel_hi:[1,0]
	v_pk_mul_f32 v[50:51], v[50:51], v[186:187] op_sel_hi:[1,0]
	v_cvt_pk_bf16_f32 v202, v52, v53
	v_cvt_pk_bf16_f32 v203, v54, v55
	v_cvt_pk_bf16_f32 v204, v48, v49
	v_cvt_pk_bf16_f32 v205, v50, v51
	global_store_dwordx4 v207, v[202:205], s[10:11] offset:256
	v_add_u32_e32 v207, 0x8000, v207
	s_waitcnt vmcnt(12)
	v_pk_add_f32 v[166:167], v[166:167], v[168:169]
	s_nop 0
	v_add_f32_e32 v214, v166, v167
	v_mov_b32_e32 v215, v214
	s_nop 1
	v_permlane16_swap_b32_e32 v214, v215
	s_nop 0
	v_add_f32_e32 v214, v214, v215
	v_mov_b32_e32 v215, v214
	s_nop 1
	v_permlane32_swap_b32_e32 v214, v215
	s_nop 0
	v_add_f32_e32 v214, v214, v215
	v_fmamk_f32 v214, v214, 0x3a800000, v248
	v_rsq_f32_e32 v188, v214
	s_nop 0
	v_pk_mul_f32 v[44:45], v[44:45], v[188:189] op_sel_hi:[1,0]
	v_pk_mul_f32 v[46:47], v[46:47], v[188:189] op_sel_hi:[1,0]
	v_pk_mul_f32 v[40:41], v[40:41], v[188:189] op_sel_hi:[1,0]
	v_pk_mul_f32 v[42:43], v[42:43], v[188:189] op_sel_hi:[1,0]
	v_cvt_pk_bf16_f32 v198, v44, v45
	v_cvt_pk_bf16_f32 v199, v46, v47
	v_cvt_pk_bf16_f32 v200, v40, v41
	v_cvt_pk_bf16_f32 v201, v42, v43
	global_store_dwordx4 v207, v[198:201], s[10:11]
	v_pk_mul_f32 v[36:37], v[36:37], v[188:189] op_sel_hi:[1,0]
	v_pk_mul_f32 v[38:39], v[38:39], v[188:189] op_sel_hi:[1,0]
	v_pk_mul_f32 v[32:33], v[32:33], v[188:189] op_sel_hi:[1,0]
	v_pk_mul_f32 v[34:35], v[34:35], v[188:189] op_sel_hi:[1,0]
	v_cvt_pk_bf16_f32 v202, v36, v37
	v_cvt_pk_bf16_f32 v203, v38, v39
	v_cvt_pk_bf16_f32 v204, v32, v33
	v_cvt_pk_bf16_f32 v205, v34, v35
	global_store_dwordx4 v207, v[202:205], s[10:11] offset:256
	v_add_u32_e32 v207, 0x8000, v207
	s_waitcnt vmcnt(13)
	v_pk_add_f32 v[170:171], v[170:171], v[172:173]
	s_nop 0
	v_add_f32_e32 v214, v170, v171
	v_mov_b32_e32 v215, v214
	s_nop 1
	v_permlane16_swap_b32_e32 v214, v215
	s_nop 0
	v_add_f32_e32 v214, v214, v215
	v_mov_b32_e32 v215, v214
	s_nop 1
	v_permlane32_swap_b32_e32 v214, v215
	s_nop 0
	v_add_f32_e32 v214, v214, v215
	v_fmamk_f32 v214, v214, 0x3a800000, v248
	v_rsq_f32_e32 v190, v214
	s_nop 0
	v_pk_mul_f32 v[28:29], v[28:29], v[190:191] op_sel_hi:[1,0]
	v_pk_mul_f32 v[30:31], v[30:31], v[190:191] op_sel_hi:[1,0]
	v_pk_mul_f32 v[24:25], v[24:25], v[190:191] op_sel_hi:[1,0]
	v_pk_mul_f32 v[26:27], v[26:27], v[190:191] op_sel_hi:[1,0]
	v_cvt_pk_bf16_f32 v198, v28, v29
	v_cvt_pk_bf16_f32 v199, v30, v31
	v_cvt_pk_bf16_f32 v200, v24, v25
	v_cvt_pk_bf16_f32 v201, v26, v27
	global_store_dwordx4 v207, v[198:201], s[10:11]
	v_pk_mul_f32 v[20:21], v[20:21], v[190:191] op_sel_hi:[1,0]
	v_pk_mul_f32 v[22:23], v[22:23], v[190:191] op_sel_hi:[1,0]
	v_pk_mul_f32 v[16:17], v[16:17], v[190:191] op_sel_hi:[1,0]
	v_pk_mul_f32 v[18:19], v[18:19], v[190:191] op_sel_hi:[1,0]
	v_cvt_pk_bf16_f32 v202, v20, v21
	v_cvt_pk_bf16_f32 v203, v22, v23
	v_cvt_pk_bf16_f32 v204, v16, v17
	v_cvt_pk_bf16_f32 v205, v18, v19
	global_store_dwordx4 v207, v[202:205], s[10:11] offset:256
	v_add_u32_e32 v207, 0x8000, v207
	s_waitcnt vmcnt(14)
	v_pk_add_f32 v[174:175], v[174:175], v[176:177]
	s_nop 0
	v_add_f32_e32 v214, v174, v175
	v_mov_b32_e32 v215, v214
	s_nop 1
	v_permlane16_swap_b32_e32 v214, v215
	s_nop 0
	v_add_f32_e32 v214, v214, v215
	v_mov_b32_e32 v215, v214
	s_nop 1
	v_permlane32_swap_b32_e32 v214, v215
	s_nop 0
	v_add_f32_e32 v214, v214, v215
	v_fmamk_f32 v214, v214, 0x3a800000, v248
	v_rsq_f32_e32 v192, v214
	s_nop 0
	v_pk_mul_f32 v[12:13], v[12:13], v[192:193] op_sel_hi:[1,0]
	v_pk_mul_f32 v[14:15], v[14:15], v[192:193] op_sel_hi:[1,0]
	v_pk_mul_f32 v[8:9], v[8:9], v[192:193] op_sel_hi:[1,0]
	v_pk_mul_f32 v[10:11], v[10:11], v[192:193] op_sel_hi:[1,0]
	v_cvt_pk_bf16_f32 v198, v12, v13
	v_cvt_pk_bf16_f32 v199, v14, v15
	v_cvt_pk_bf16_f32 v200, v8, v9
	v_cvt_pk_bf16_f32 v201, v10, v11
	global_store_dwordx4 v207, v[198:201], s[10:11]
	v_pk_mul_f32 v[4:5], v[4:5], v[192:193] op_sel_hi:[1,0]
	v_pk_mul_f32 v[6:7], v[6:7], v[192:193] op_sel_hi:[1,0]
	v_pk_mul_f32 v[0:1], v[0:1], v[192:193] op_sel_hi:[1,0]
	v_pk_mul_f32 v[2:3], v[2:3], v[192:193] op_sel_hi:[1,0]
	v_cvt_pk_bf16_f32 v202, v4, v5
	v_cvt_pk_bf16_f32 v203, v6, v7
	v_cvt_pk_bf16_f32 v204, v0, v1
	v_cvt_pk_bf16_f32 v205, v2, v3
	global_store_dwordx4 v207, v[202:205], s[10:11] offset:256
	s_and_b64 vcc, exec, s[4:5]
	s_cbranch_vccz .LBB0_816
	s_waitcnt vmcnt(0)
	s_cmpk_gt_u32 s30, 0xff
	s_cbranch_scc1 .LBB0_827
	s_barrier

.LBB0_878:
	s_add_u32 s26, s24, 0xfffc0080
	s_addc_u32 s27, s25, -1
	s_add_i32 s65, 0, 0x10000
	v_add_u32_e32 v154, s65, v143
	ds_read_b128 v[138:141], v154
	ds_read_b128 v[146:149], v154 offset:1024
	ds_read_b128 v[150:153], v154 offset:2048
	ds_read_b128 v[154:157], v154 offset:3072
	s_cmp_eq_u32 s64, 12
	s_cselect_b32 s29, s19, s27
	s_cselect_b32 s28, s39, s26
	s_cselect_b32 s27, s17, s63
	s_cselect_b32 s26, s61, s62
	s_add_i32 m0, s50, 0xc000
	ds_read_b128 v[158:161], v145
	ds_read_b128 v[162:165], v145 offset:1024
	ds_read_b128 v[166:169], v145 offset:2048
	ds_read_b128 v[170:173], v145 offset:3072
	ds_read_b128 v[174:177], v145 offset:4096
	ds_read_b128 v[178:181], v145 offset:5120
	ds_read_b128 v[182:185], v145 offset:6144
	global_load_lds_dwordx4 v134, s[24:25]
	s_add_i32 m0, s50, 0xe000
	ds_read_b128 v[186:189], v145 offset:7168
	global_load_lds_dwordx4 v136, s[24:25]
	s_waitcnt lgkmcnt(8)
	s_barrier
	s_waitcnt lgkmcnt(0)
	v_mfma_f32_16x16x32_bf16 v[124:127], v[138:141], v[158:161], v[124:127]
	v_mfma_f32_16x16x32_bf16 v[120:123], v[150:153], v[158:161], v[120:123]
	v_mfma_f32_16x16x32_bf16 v[108:111], v[138:141], v[166:169], v[108:111]
	v_mfma_f32_16x16x32_bf16 v[104:107], v[150:153], v[166:169], v[104:107]
	v_mfma_f32_16x16x32_bf16 v[92:95], v[138:141], v[174:177], v[92:95]
	v_mfma_f32_16x16x32_bf16 v[88:91], v[150:153], v[174:177], v[88:91]
	v_mfma_f32_16x16x32_bf16 v[76:79], v[138:141], v[182:185], v[76:79]
	v_mfma_f32_16x16x32_bf16 v[72:75], v[150:153], v[182:185], v[72:75]
	v_mfma_f32_16x16x32_bf16 v[124:127], v[146:149], v[162:165], v[124:127]
	v_mfma_f32_16x16x32_bf16 v[120:123], v[154:157], v[162:165], v[120:123]
	v_mfma_f32_16x16x32_bf16 v[108:111], v[146:149], v[170:173], v[108:111]
	v_mfma_f32_16x16x32_bf16 v[104:107], v[154:157], v[170:173], v[104:107]
	v_mfma_f32_16x16x32_bf16 v[92:95], v[146:149], v[178:181], v[92:95]
	v_mfma_f32_16x16x32_bf16 v[88:91], v[154:157], v[178:181], v[88:91]
	v_mfma_f32_16x16x32_bf16 v[76:79], v[146:149], v[186:189], v[76:79]
	v_mfma_f32_16x16x32_bf16 v[72:75], v[154:157], v[186:189], v[72:75]
	s_barrier
	s_add_i32 s68, 0, 0x14000
	s_add_i32 s65, s65, s47
	v_add_u32_e32 v202, s68, v143
	s_add_u32 s98, s26, s40
	s_addc_u32 s99, s27, s41
	s_mov_b32 m0, s65
	ds_read_b128 v[190:193], v202
	ds_read_b128 v[194:197], v202 offset:1024
	ds_read_b128 v[198:201], v202 offset:2048
	global_load_lds_dwordx4 v208, s[26:27]
	s_add_i32 m0, s65, 0x2000
	ds_read_b128 v[202:205], v202 offset:3072
	global_load_lds_dwordx4 v128, s[26:27]
	s_barrier
	s_waitcnt lgkmcnt(0)
	v_mfma_f32_16x16x32_bf16 v[116:119], v[190:193], v[158:161], v[116:119]
	v_mfma_f32_16x16x32_bf16 v[112:115], v[198:201], v[158:161], v[112:115]
	v_mfma_f32_16x16x32_bf16 v[100:103], v[190:193], v[166:169], v[100:103]
	v_mfma_f32_16x16x32_bf16 v[96:99], v[198:201], v[166:169], v[96:99]
	v_mfma_f32_16x16x32_bf16 v[84:87], v[190:193], v[174:177], v[84:87]
	v_mfma_f32_16x16x32_bf16 v[80:83], v[198:201], v[174:177], v[80:83]
	v_mfma_f32_16x16x32_bf16 v[68:71], v[190:193], v[182:185], v[68:71]
	v_mfma_f32_16x16x32_bf16 v[64:67], v[198:201], v[182:185], v[64:67]
	v_mfma_f32_16x16x32_bf16 v[116:119], v[194:197], v[162:165], v[116:119]
	v_mfma_f32_16x16x32_bf16 v[112:115], v[202:205], v[162:165], v[112:115]
	v_mfma_f32_16x16x32_bf16 v[100:103], v[194:197], v[170:173], v[100:103]
	v_mfma_f32_16x16x32_bf16 v[96:99], v[202:205], v[170:173], v[96:99]
	v_mfma_f32_16x16x32_bf16 v[84:87], v[194:197], v[178:181], v[84:87]
	v_mfma_f32_16x16x32_bf16 v[80:83], v[202:205], v[178:181], v[80:83]
	v_mfma_f32_16x16x32_bf16 v[68:71], v[194:197], v[186:189], v[68:71]
	v_mfma_f32_16x16x32_bf16 v[64:67], v[202:205], v[186:189], v[64:67]
	s_mov_b32 m0, s50
	s_add_u32 s100, s28, s40
	s_addc_u32 s101, s29, s41
	s_barrier
	ds_read_b128 v[158:161], v145 offset:16384
	ds_read_b128 v[162:165], v145 offset:17408
	ds_read_b128 v[166:169], v145 offset:18432
	ds_read_b128 v[170:173], v145 offset:19456
	ds_read_b128 v[174:177], v145 offset:20480
	ds_read_b128 v[178:181], v145 offset:21504
	ds_read_b128 v[182:185], v145 offset:22528
	global_load_lds_dwordx4 v132, s[28:29]
	s_mov_b32 m0, s51
	ds_read_b128 v[186:189], v145 offset:23552
	global_load_lds_dwordx4 v130, s[28:29]
	s_barrier
	s_waitcnt lgkmcnt(0)
	v_mfma_f32_16x16x32_bf16 v[60:63], v[138:141], v[158:161], v[60:63]
	v_mfma_f32_16x16x32_bf16 v[56:59], v[150:153], v[158:161], v[56:59]
	v_mfma_f32_16x16x32_bf16 v[44:47], v[138:141], v[166:169], v[44:47]
	v_mfma_f32_16x16x32_bf16 v[40:43], v[150:153], v[166:169], v[40:43]
	v_mfma_f32_16x16x32_bf16 v[28:31], v[138:141], v[174:177], v[28:31]
	v_mfma_f32_16x16x32_bf16 v[24:27], v[150:153], v[174:177], v[24:27]
	v_mfma_f32_16x16x32_bf16 v[12:15], v[138:141], v[182:185], v[12:15]
	v_mfma_f32_16x16x32_bf16 v[8:11], v[150:153], v[182:185], v[8:11]
	v_mfma_f32_16x16x32_bf16 v[60:63], v[146:149], v[162:165], v[60:63]
	v_mfma_f32_16x16x32_bf16 v[56:59], v[154:157], v[162:165], v[56:59]
	v_mfma_f32_16x16x32_bf16 v[44:47], v[146:149], v[170:173], v[44:47]
	v_mfma_f32_16x16x32_bf16 v[40:43], v[154:157], v[170:173], v[40:43]
	v_mfma_f32_16x16x32_bf16 v[28:31], v[146:149], v[178:181], v[28:31]
	v_mfma_f32_16x16x32_bf16 v[24:27], v[154:157], v[178:181], v[24:27]
	v_mfma_f32_16x16x32_bf16 v[12:15], v[146:149], v[186:189], v[12:15]
	v_mfma_f32_16x16x32_bf16 v[8:11], v[154:157], v[186:189], v[8:11]
	s_barrier
	s_add_u32 s66, s26, 0x40000
	s_addc_u32 s67, s27, 0
	s_add_i32 s65, s68, s47
	s_mov_b32 m0, s65
	s_nop 0
	global_load_lds_dwordx4 v208, s[66:67]
	s_add_i32 m0, s65, 0x2000
	s_nop 0
	global_load_lds_dwordx4 v128, s[66:67]
	s_waitcnt vmcnt(6)
	s_barrier
	v_mfma_f32_16x16x32_bf16 v[52:55], v[190:193], v[158:161], v[52:55]
	v_mfma_f32_16x16x32_bf16 v[48:51], v[198:201], v[158:161], v[48:51]
	v_mfma_f32_16x16x32_bf16 v[36:39], v[190:193], v[166:169], v[36:39]
	v_mfma_f32_16x16x32_bf16 v[32:35], v[198:201], v[166:169], v[32:35]
	v_mfma_f32_16x16x32_bf16 v[20:23], v[190:193], v[174:177], v[20:23]
	v_mfma_f32_16x16x32_bf16 v[16:19], v[198:201], v[174:177], v[16:19]
	v_mfma_f32_16x16x32_bf16 v[4:7], v[190:193], v[182:185], v[4:7]
	v_mfma_f32_16x16x32_bf16 v[0:3], v[198:201], v[182:185], v[0:3]
	v_mfma_f32_16x16x32_bf16 v[52:55], v[194:197], v[162:165], v[52:55]
	v_mfma_f32_16x16x32_bf16 v[48:51], v[202:205], v[162:165], v[48:51]
	v_mfma_f32_16x16x32_bf16 v[36:39], v[194:197], v[170:173], v[36:39]
	v_mfma_f32_16x16x32_bf16 v[32:35], v[202:205], v[170:173], v[32:35]
	v_mfma_f32_16x16x32_bf16 v[20:23], v[194:197], v[178:181], v[20:23]
	v_mfma_f32_16x16x32_bf16 v[16:19], v[202:205], v[178:181], v[16:19]
	v_mfma_f32_16x16x32_bf16 v[4:7], v[194:197], v[186:189], v[4:7]
	v_mfma_f32_16x16x32_bf16 v[0:3], v[202:205], v[186:189], v[0:3]
	s_add_i32 s65, 0, 0x18000
	v_add_u32_e32 v154, s65, v143
	s_barrier
	ds_read_b128 v[138:141], v154
	ds_read_b128 v[146:149], v154 offset:1024
	ds_read_b128 v[150:153], v154 offset:2048
	ds_read_b128 v[154:157], v154 offset:3072
	s_add_u32 s28, s28, 0x40000
	s_addc_u32 s29, s29, 0
	s_mov_b32 m0, s53
	ds_read_b128 v[158:161], v145 offset:32768
	ds_read_b128 v[162:165], v145 offset:33792
	ds_read_b128 v[166:169], v145 offset:34816
	ds_read_b128 v[170:173], v145 offset:35840
	ds_read_b128 v[174:177], v145 offset:36864
	ds_read_b128 v[178:181], v145 offset:37888
	ds_read_b128 v[182:185], v145 offset:38912
	global_load_lds_dwordx4 v132, s[28:29]
	s_mov_b32 m0, s56
	ds_read_b128 v[186:189], v145 offset:39936
	global_load_lds_dwordx4 v130, s[28:29]
	s_waitcnt lgkmcnt(8)
	s_barrier
	s_waitcnt lgkmcnt(0)
	v_mfma_f32_16x16x32_bf16 v[124:127], v[138:141], v[158:161], v[124:127]
	v_mfma_f32_16x16x32_bf16 v[120:123], v[150:153], v[158:161], v[120:123]
	v_mfma_f32_16x16x32_bf16 v[108:111], v[138:141], v[166:169], v[108:111]
	v_mfma_f32_16x16x32_bf16 v[104:107], v[150:153], v[166:169], v[104:107]
	v_mfma_f32_16x16x32_bf16 v[92:95], v[138:141], v[174:177], v[92:95]
	v_mfma_f32_16x16x32_bf16 v[88:91], v[150:153], v[174:177], v[88:91]
	v_mfma_f32_16x16x32_bf16 v[76:79], v[138:141], v[182:185], v[76:79]
	v_mfma_f32_16x16x32_bf16 v[72:75], v[150:153], v[182:185], v[72:75]
	v_mfma_f32_16x16x32_bf16 v[124:127], v[146:149], v[162:165], v[124:127]
	v_mfma_f32_16x16x32_bf16 v[120:123], v[154:157], v[162:165], v[120:123]
	v_mfma_f32_16x16x32_bf16 v[108:111], v[146:149], v[170:173], v[108:111]
	v_mfma_f32_16x16x32_bf16 v[104:107], v[154:157], v[170:173], v[104:107]
	v_mfma_f32_16x16x32_bf16 v[92:95], v[146:149], v[178:181], v[92:95]
	v_mfma_f32_16x16x32_bf16 v[88:91], v[154:157], v[178:181], v[88:91]
	v_mfma_f32_16x16x32_bf16 v[76:79], v[146:149], v[186:189], v[76:79]
	v_mfma_f32_16x16x32_bf16 v[72:75], v[154:157], v[186:189], v[72:75]
	s_barrier
	s_add_i32 s28, 0, 0x1c000
	s_add_i32 s29, s65, s47
	v_add_u32_e32 v202, s28, v143
	s_mov_b32 m0, s29
	ds_read_b128 v[190:193], v202
	ds_read_b128 v[194:197], v202 offset:1024
	ds_read_b128 v[198:201], v202 offset:2048
	global_load_lds_dwordx4 v208, s[98:99]
	s_add_i32 m0, s29, 0x2000
	ds_read_b128 v[202:205], v202 offset:3072
	global_load_lds_dwordx4 v128, s[98:99]
	s_barrier
	s_waitcnt lgkmcnt(0)
	v_mfma_f32_16x16x32_bf16 v[116:119], v[190:193], v[158:161], v[116:119]
	v_mfma_f32_16x16x32_bf16 v[112:115], v[198:201], v[158:161], v[112:115]
	v_mfma_f32_16x16x32_bf16 v[100:103], v[190:193], v[166:169], v[100:103]
	v_mfma_f32_16x16x32_bf16 v[96:99], v[198:201], v[166:169], v[96:99]
	v_mfma_f32_16x16x32_bf16 v[84:87], v[190:193], v[174:177], v[84:87]
	v_mfma_f32_16x16x32_bf16 v[80:83], v[198:201], v[174:177], v[80:83]
	v_mfma_f32_16x16x32_bf16 v[68:71], v[190:193], v[182:185], v[68:71]
	v_mfma_f32_16x16x32_bf16 v[64:67], v[198:201], v[182:185], v[64:67]
	v_mfma_f32_16x16x32_bf16 v[116:119], v[194:197], v[162:165], v[116:119]
	v_mfma_f32_16x16x32_bf16 v[112:115], v[202:205], v[162:165], v[112:115]
	v_mfma_f32_16x16x32_bf16 v[100:103], v[194:197], v[170:173], v[100:103]
	v_mfma_f32_16x16x32_bf16 v[96:99], v[202:205], v[170:173], v[96:99]
	v_mfma_f32_16x16x32_bf16 v[84:87], v[194:197], v[178:181], v[84:87]
	v_mfma_f32_16x16x32_bf16 v[80:83], v[202:205], v[178:181], v[80:83]
	v_mfma_f32_16x16x32_bf16 v[68:71], v[194:197], v[186:189], v[68:71]
	v_mfma_f32_16x16x32_bf16 v[64:67], v[202:205], v[186:189], v[64:67]
	s_mov_b32 m0, s58
	s_barrier
	ds_read_b128 v[158:161], v145 offset:49152
	ds_read_b128 v[162:165], v145 offset:50176
	ds_read_b128 v[166:169], v145 offset:51200
	ds_read_b128 v[170:173], v145 offset:52224
	ds_read_b128 v[174:177], v145 offset:53248
	ds_read_b128 v[178:181], v145 offset:54272
	ds_read_b128 v[182:185], v145 offset:55296
	global_load_lds_dwordx4 v132, s[100:101]
	s_mov_b32 m0, s59
	ds_read_b128 v[186:189], v145 offset:56320
	global_load_lds_dwordx4 v130, s[100:101]
	s_barrier
	s_waitcnt lgkmcnt(0)
	v_mfma_f32_16x16x32_bf16 v[60:63], v[138:141], v[158:161], v[60:63]
	v_mfma_f32_16x16x32_bf16 v[56:59], v[150:153], v[158:161], v[56:59]
	v_mfma_f32_16x16x32_bf16 v[44:47], v[138:141], v[166:169], v[44:47]
	v_mfma_f32_16x16x32_bf16 v[40:43], v[150:153], v[166:169], v[40:43]
	v_mfma_f32_16x16x32_bf16 v[28:31], v[138:141], v[174:177], v[28:31]
	v_mfma_f32_16x16x32_bf16 v[24:27], v[150:153], v[174:177], v[24:27]
	v_mfma_f32_16x16x32_bf16 v[12:15], v[138:141], v[182:185], v[12:15]
	v_mfma_f32_16x16x32_bf16 v[8:11], v[150:153], v[182:185], v[8:11]
	v_mfma_f32_16x16x32_bf16 v[60:63], v[146:149], v[162:165], v[60:63]
	v_mfma_f32_16x16x32_bf16 v[56:59], v[154:157], v[162:165], v[56:59]
	v_mfma_f32_16x16x32_bf16 v[44:47], v[146:149], v[170:173], v[44:47]
	v_mfma_f32_16x16x32_bf16 v[40:43], v[154:157], v[170:173], v[40:43]
	v_mfma_f32_16x16x32_bf16 v[28:31], v[146:149], v[178:181], v[28:31]
	v_mfma_f32_16x16x32_bf16 v[24:27], v[154:157], v[178:181], v[24:27]
	v_mfma_f32_16x16x32_bf16 v[12:15], v[146:149], v[186:189], v[12:15]
	v_mfma_f32_16x16x32_bf16 v[8:11], v[154:157], v[186:189], v[8:11]
	s_barrier
	s_add_u32 s26, s26, 0x40080
	s_addc_u32 s27, s27, 0
	s_add_i32 s28, s28, s47
	s_mov_b32 m0, s28
	s_add_i32 s64, s64, 2
	global_load_lds_dwordx4 v208, s[26:27]
	s_add_i32 m0, s28, 0x2000
	s_add_u32 s24, s24, 0x100
	s_addc_u32 s25, s25, 0
	global_load_lds_dwordx4 v128, s[26:27]
	s_add_u32 s62, s62, 0x100
	s_addc_u32 s63, s63, 0
	s_waitcnt vmcnt(6)
	s_barrier
	v_mfma_f32_16x16x32_bf16 v[52:55], v[190:193], v[158:161], v[52:55]
	v_mfma_f32_16x16x32_bf16 v[48:51], v[198:201], v[158:161], v[48:51]
	v_mfma_f32_16x16x32_bf16 v[36:39], v[190:193], v[166:169], v[36:39]
	v_mfma_f32_16x16x32_bf16 v[32:35], v[198:201], v[166:169], v[32:35]
	v_mfma_f32_16x16x32_bf16 v[20:23], v[190:193], v[174:177], v[20:23]
	v_mfma_f32_16x16x32_bf16 v[16:19], v[198:201], v[174:177], v[16:19]
	v_mfma_f32_16x16x32_bf16 v[4:7], v[190:193], v[182:185], v[4:7]
	v_mfma_f32_16x16x32_bf16 v[0:3], v[198:201], v[182:185], v[0:3]
	v_mfma_f32_16x16x32_bf16 v[52:55], v[194:197], v[162:165], v[52:55]
	v_mfma_f32_16x16x32_bf16 v[48:51], v[202:205], v[162:165], v[48:51]
	v_mfma_f32_16x16x32_bf16 v[36:39], v[194:197], v[170:173], v[36:39]
	v_mfma_f32_16x16x32_bf16 v[32:35], v[202:205], v[170:173], v[32:35]
	v_mfma_f32_16x16x32_bf16 v[20:23], v[194:197], v[178:181], v[20:23]
	v_mfma_f32_16x16x32_bf16 v[16:19], v[202:205], v[178:181], v[16:19]
	v_mfma_f32_16x16x32_bf16 v[4:7], v[194:197], v[186:189], v[4:7]
	v_mfma_f32_16x16x32_bf16 v[0:3], v[202:205], v[186:189], v[0:3]
	s_cmp_gt_u32 s64, 13
	s_barrier
	s_cbranch_scc0 .LBB0_878
	v_lshl_add_u32 v140, s38, 8, v142
	v_lshl_or_b32 v141, s36, 8, v144
	s_lshl_b32 s24, s36, 2
	s_ashr_i32 s25, s24, 31
	s_lshl_b32 s36, s57, 2
	v_lshlrev_b32_e32 v206, 11, v140
	v_lshl_add_u32 v206, v141, 1, v206
	v_lshl_add_u32 v210, v140, 6, s36
	v_lshl_add_u32 v210, s24, 2, v210
	v_mov_b32_e32 v207, v206
	global_load_dwordx4 v[146:149], v206, s[8:9]
	global_load_dwordx4 v[150:153], v206, s[8:9] offset:256
	v_add_u32_e32 v206, 0x8000, v206
	global_load_dwordx4 v[154:157], v206, s[8:9]
	global_load_dwordx4 v[158:161], v206, s[8:9] offset:256
	v_add_u32_e32 v206, 0x8000, v206
	global_load_dwordx4 v[162:165], v206, s[8:9]
	global_load_dwordx4 v[166:169], v206, s[8:9] offset:256
	v_add_u32_e32 v206, 0x8000, v206
	global_load_dwordx4 v[170:173], v206, s[8:9]
	global_load_dwordx4 v[174:177], v206, s[8:9] offset:256
	v_add_u32_e32 v206, 0x28000, v206
	global_load_dwordx4 v[178:181], v206, s[8:9]
	global_load_dwordx4 v[182:185], v206, s[8:9] offset:256
	v_add_u32_e32 v206, 0x8000, v206
	global_load_dwordx4 v[186:189], v206, s[8:9]
	global_load_dwordx4 v[190:193], v206, s[8:9] offset:256
	v_add_u32_e32 v206, 0x8000, v206
	global_load_dwordx4 v[194:197], v206, s[8:9]
	global_load_dwordx4 v[198:201], v206, s[8:9] offset:256
	v_add_u32_e32 v206, 0x8000, v206
	s_waitcnt vmcnt(12)
	v_lshlrev_b32_e32 v202, 16, v146
	v_and_b32_e32 v203, 0xffff0000, v146
	v_lshlrev_b32_e32 v204, 16, v147
	v_and_b32_e32 v205, 0xffff0000, v147
	v_pk_add_f32 v[124:125], v[124:125], v[202:203]
	v_pk_add_f32 v[126:127], v[126:127], v[204:205]
	v_lshlrev_b32_e32 v202, 16, v148
	v_and_b32_e32 v203, 0xffff0000, v148
	v_lshlrev_b32_e32 v204, 16, v149
	v_and_b32_e32 v205, 0xffff0000, v149
	v_pk_add_f32 v[120:121], v[120:121], v[202:203]
	v_pk_add_f32 v[122:123], v[122:123], v[204:205]
	v_cvt_pk_bf16_f32 v146, v124, v125
	v_cvt_pk_bf16_f32 v147, v126, v127
	v_cvt_pk_bf16_f32 v148, v120, v121
	v_cvt_pk_bf16_f32 v149, v122, v123
	v_pk_mul_f32 v[138:139], v[124:125], v[124:125]
	global_store_dwordx4 v207, v[146:149], s[8:9]
	v_pk_fma_f32 v[138:139], v[126:127], v[126:127], v[138:139]
	v_pk_fma_f32 v[138:139], v[120:121], v[120:121], v[138:139]
	v_pk_fma_f32 v[138:139], v[122:123], v[122:123], v[138:139]
	v_lshlrev_b32_e32 v202, 16, v150
	v_and_b32_e32 v203, 0xffff0000, v150
	v_lshlrev_b32_e32 v204, 16, v151
	v_and_b32_e32 v205, 0xffff0000, v151
	v_pk_add_f32 v[116:117], v[116:117], v[202:203]
	v_pk_add_f32 v[118:119], v[118:119], v[204:205]
	v_lshlrev_b32_e32 v202, 16, v152
	v_and_b32_e32 v203, 0xffff0000, v152
	v_lshlrev_b32_e32 v204, 16, v153
	v_and_b32_e32 v205, 0xffff0000, v153
	v_pk_add_f32 v[112:113], v[112:113], v[202:203]
	v_pk_add_f32 v[114:115], v[114:115], v[204:205]
	v_cvt_pk_bf16_f32 v150, v116, v117
	v_cvt_pk_bf16_f32 v151, v118, v119
	v_cvt_pk_bf16_f32 v152, v112, v113
	v_cvt_pk_bf16_f32 v153, v114, v115
	v_pk_fma_f32 v[138:139], v[116:117], v[116:117], v[138:139]
	global_store_dwordx4 v207, v[150:153], s[8:9] offset:256
	v_pk_fma_f32 v[138:139], v[118:119], v[118:119], v[138:139]
	v_pk_fma_f32 v[138:139], v[112:113], v[112:113], v[138:139]
	v_pk_fma_f32 v[138:139], v[114:115], v[114:115], v[138:139]
	v_add_f32_e32 v214, v138, v139
	v_add_u32_e32 v207, 0x8000, v207
	v_mov_b32_e32 v215, v214
	s_nop 1
	v_permlane16_swap_b32_e32 v214, v215
	s_nop 0
	v_add_f32_e32 v214, v214, v215
	v_mov_b32_e32 v215, v214
	s_nop 1
	v_permlane32_swap_b32_e32 v214, v215
	s_nop 0
	v_add_f32_e32 v214, v214, v215
	s_and_saveexec_b64 s[26:27], s[4:5]
	global_store_dword v210, v214, s[14:15]
	s_mov_b64 exec, s[26:27]
	global_load_dwordx4 v[146:149], v206, s[8:9]
	global_load_dwordx4 v[150:153], v206, s[8:9] offset:256
	s_waitcnt vmcnt(15)
	v_lshlrev_b32_e32 v202, 16, v154
	v_and_b32_e32 v203, 0xffff0000, v154
	v_lshlrev_b32_e32 v204, 16, v155
	v_and_b32_e32 v205, 0xffff0000, v155
	v_pk_add_f32 v[108:109], v[108:109], v[202:203]
	v_pk_add_f32 v[110:111], v[110:111], v[204:205]
	v_lshlrev_b32_e32 v202, 16, v156
	v_and_b32_e32 v203, 0xffff0000, v156
	v_lshlrev_b32_e32 v204, 16, v157
	v_and_b32_e32 v205, 0xffff0000, v157
	v_pk_add_f32 v[104:105], v[104:105], v[202:203]
	v_pk_add_f32 v[106:107], v[106:107], v[204:205]
	v_cvt_pk_bf16_f32 v154, v108, v109
	v_cvt_pk_bf16_f32 v155, v110, v111
	v_cvt_pk_bf16_f32 v156, v104, v105
	v_cvt_pk_bf16_f32 v157, v106, v107
	v_pk_mul_f32 v[138:139], v[108:109], v[108:109]
	global_store_dwordx4 v207, v[154:157], s[8:9]
	v_pk_fma_f32 v[138:139], v[110:111], v[110:111], v[138:139]
	v_pk_fma_f32 v[138:139], v[104:105], v[104:105], v[138:139]
	v_pk_fma_f32 v[138:139], v[106:107], v[106:107], v[138:139]
	v_lshlrev_b32_e32 v202, 16, v158
	v_and_b32_e32 v203, 0xffff0000, v158
	v_lshlrev_b32_e32 v204, 16, v159
	v_and_b32_e32 v205, 0xffff0000, v159
	v_pk_add_f32 v[100:101], v[100:101], v[202:203]
	v_pk_add_f32 v[102:103], v[102:103], v[204:205]
	v_lshlrev_b32_e32 v202, 16, v160
	v_and_b32_e32 v203, 0xffff0000, v160
	v_lshlrev_b32_e32 v204, 16, v161
	v_and_b32_e32 v205, 0xffff0000, v161
	v_pk_add_f32 v[96:97], v[96:97], v[202:203]
	v_pk_add_f32 v[98:99], v[98:99], v[204:205]
	v_cvt_pk_bf16_f32 v158, v100, v101
	v_cvt_pk_bf16_f32 v159, v102, v103
	v_cvt_pk_bf16_f32 v160, v96, v97
	v_cvt_pk_bf16_f32 v161, v98, v99
	v_pk_fma_f32 v[138:139], v[100:101], v[100:101], v[138:139]
	global_store_dwordx4 v207, v[158:161], s[8:9] offset:256
	v_pk_fma_f32 v[138:139], v[102:103], v[102:103], v[138:139]
	v_pk_fma_f32 v[138:139], v[96:97], v[96:97], v[138:139]
	v_pk_fma_f32 v[138:139], v[98:99], v[98:99], v[138:139]
	v_add_f32_e32 v214, v138, v139
	v_add_u32_e32 v207, 0x8000, v207
	v_mov_b32_e32 v215, v214
	s_nop 1
	v_permlane16_swap_b32_e32 v214, v215
	s_nop 0
	v_add_f32_e32 v214, v214, v215
	v_mov_b32_e32 v215, v214
	s_nop 1
	v_permlane32_swap_b32_e32 v214, v215
	s_nop 0
	v_add_f32_e32 v214, v214, v215
	s_and_saveexec_b64 s[26:27], s[4:5]
	global_store_dword v210, v214, s[14:15] offset:1024
	s_mov_b64 exec, s[26:27]
	s_waitcnt vmcnt(16)
	v_lshlrev_b32_e32 v202, 16, v162
	v_and_b32_e32 v203, 0xffff0000, v162
	v_lshlrev_b32_e32 v204, 16, v163
	v_and_b32_e32 v205, 0xffff0000, v163
	v_pk_add_f32 v[92:93], v[92:93], v[202:203]
	v_pk_add_f32 v[94:95], v[94:95], v[204:205]
	v_lshlrev_b32_e32 v202, 16, v164
	v_and_b32_e32 v203, 0xffff0000, v164
	v_lshlrev_b32_e32 v204, 16, v165
	v_and_b32_e32 v205, 0xffff0000, v165
	v_pk_add_f32 v[88:89], v[88:89], v[202:203]
	v_pk_add_f32 v[90:91], v[90:91], v[204:205]
	v_cvt_pk_bf16_f32 v162, v92, v93
	v_cvt_pk_bf16_f32 v163, v94, v95
	v_cvt_pk_bf16_f32 v164, v88, v89
	v_cvt_pk_bf16_f32 v165, v90, v91
	v_pk_mul_f32 v[138:139], v[92:93], v[92:93]
	global_store_dwordx4 v207, v[162:165], s[8:9]
	v_pk_fma_f32 v[138:139], v[94:95], v[94:95], v[138:139]
	v_pk_fma_f32 v[138:139], v[88:89], v[88:89], v[138:139]
	v_pk_fma_f32 v[138:139], v[90:91], v[90:91], v[138:139]
	v_lshlrev_b32_e32 v202, 16, v166
	v_and_b32_e32 v203, 0xffff0000, v166
	v_lshlrev_b32_e32 v204, 16, v167
	v_and_b32_e32 v205, 0xffff0000, v167
	v_pk_add_f32 v[84:85], v[84:85], v[202:203]
	v_pk_add_f32 v[86:87], v[86:87], v[204:205]
	v_lshlrev_b32_e32 v202, 16, v168
	v_and_b32_e32 v203, 0xffff0000, v168
	v_lshlrev_b32_e32 v204, 16, v169
	v_and_b32_e32 v205, 0xffff0000, v169
	v_pk_add_f32 v[80:81], v[80:81], v[202:203]
	v_pk_add_f32 v[82:83], v[82:83], v[204:205]
	v_cvt_pk_bf16_f32 v166, v84, v85
	v_cvt_pk_bf16_f32 v167, v86, v87
	v_cvt_pk_bf16_f32 v168, v80, v81
	v_cvt_pk_bf16_f32 v169, v82, v83
	v_pk_fma_f32 v[138:139], v[84:85], v[84:85], v[138:139]
	global_store_dwordx4 v207, v[166:169], s[8:9] offset:256
	v_pk_fma_f32 v[138:139], v[86:87], v[86:87], v[138:139]
	v_pk_fma_f32 v[138:139], v[80:81], v[80:81], v[138:139]
	v_pk_fma_f32 v[138:139], v[82:83], v[82:83], v[138:139]
	v_add_f32_e32 v214, v138, v139
	v_add_u32_e32 v207, 0x8000, v207
	v_mov_b32_e32 v215, v214
	s_nop 1
	v_permlane16_swap_b32_e32 v214, v215
	s_nop 0
	v_add_f32_e32 v214, v214, v215
	v_mov_b32_e32 v215, v214
	s_nop 1
	v_permlane32_swap_b32_e32 v214, v215
	s_nop 0
	v_add_f32_e32 v214, v214, v215
	s_and_saveexec_b64 s[26:27], s[4:5]
	global_store_dword v210, v214, s[14:15] offset:2048
	s_mov_b64 exec, s[26:27]
	s_waitcnt vmcnt(17)
	v_lshlrev_b32_e32 v202, 16, v170
	v_and_b32_e32 v203, 0xffff0000, v170
	v_lshlrev_b32_e32 v204, 16, v171
	v_and_b32_e32 v205, 0xffff0000, v171
	v_pk_add_f32 v[76:77], v[76:77], v[202:203]
	v_pk_add_f32 v[78:79], v[78:79], v[204:205]
	v_lshlrev_b32_e32 v202, 16, v172
	v_and_b32_e32 v203, 0xffff0000, v172
	v_lshlrev_b32_e32 v204, 16, v173
	v_and_b32_e32 v205, 0xffff0000, v173
	v_pk_add_f32 v[72:73], v[72:73], v[202:203]
	v_pk_add_f32 v[74:75], v[74:75], v[204:205]
	v_cvt_pk_bf16_f32 v170, v76, v77
	v_cvt_pk_bf16_f32 v171, v78, v79
	v_cvt_pk_bf16_f32 v172, v72, v73
	v_cvt_pk_bf16_f32 v173, v74, v75
	v_pk_mul_f32 v[138:139], v[76:77], v[76:77]
	global_store_dwordx4 v207, v[170:173], s[8:9]
	v_pk_fma_f32 v[138:139], v[78:79], v[78:79], v[138:139]
	v_pk_fma_f32 v[138:139], v[72:73], v[72:73], v[138:139]
	v_pk_fma_f32 v[138:139], v[74:75], v[74:75], v[138:139]
	v_lshlrev_b32_e32 v202, 16, v174
	v_and_b32_e32 v203, 0xffff0000, v174
	v_lshlrev_b32_e32 v204, 16, v175
	v_and_b32_e32 v205, 0xffff0000, v175
	v_pk_add_f32 v[68:69], v[68:69], v[202:203]
	v_pk_add_f32 v[70:71], v[70:71], v[204:205]
	v_lshlrev_b32_e32 v202, 16, v176
	v_and_b32_e32 v203, 0xffff0000, v176
	v_lshlrev_b32_e32 v204, 16, v177
	v_and_b32_e32 v205, 0xffff0000, v177
	v_pk_add_f32 v[64:65], v[64:65], v[202:203]
	v_pk_add_f32 v[66:67], v[66:67], v[204:205]
	v_cvt_pk_bf16_f32 v174, v68, v69
	v_cvt_pk_bf16_f32 v175, v70, v71
	v_cvt_pk_bf16_f32 v176, v64, v65
	v_cvt_pk_bf16_f32 v177, v66, v67
	v_pk_fma_f32 v[138:139], v[68:69], v[68:69], v[138:139]
	global_store_dwordx4 v207, v[174:177], s[8:9] offset:256
	v_pk_fma_f32 v[138:139], v[70:71], v[70:71], v[138:139]
	v_pk_fma_f32 v[138:139], v[64:65], v[64:65], v[138:139]
	v_pk_fma_f32 v[138:139], v[66:67], v[66:67], v[138:139]
	v_add_f32_e32 v214, v138, v139
	v_add_u32_e32 v207, 0x28000, v207
	v_mov_b32_e32 v215, v214
	s_nop 1
	v_permlane16_swap_b32_e32 v214, v215
	s_nop 0
	v_add_f32_e32 v214, v214, v215
	v_mov_b32_e32 v215, v214
	s_nop 1
	v_permlane32_swap_b32_e32 v214, v215
	s_nop 0
	v_add_f32_e32 v214, v214, v215
	s_and_saveexec_b64 s[26:27], s[4:5]
	global_store_dword v210, v214, s[14:15] offset:3072
	s_mov_b64 exec, s[26:27]
	v_add_u32_e32 v210, 0x2000, v210
	s_waitcnt vmcnt(18)
	v_lshlrev_b32_e32 v202, 16, v178
	v_and_b32_e32 v203, 0xffff0000, v178
	v_lshlrev_b32_e32 v204, 16, v179
	v_and_b32_e32 v205, 0xffff0000, v179
	v_pk_add_f32 v[60:61], v[60:61], v[202:203]
	v_pk_add_f32 v[62:63], v[62:63], v[204:205]
	v_lshlrev_b32_e32 v202, 16, v180
	v_and_b32_e32 v203, 0xffff0000, v180
	v_lshlrev_b32_e32 v204, 16, v181
	v_and_b32_e32 v205, 0xffff0000, v181
	v_pk_add_f32 v[56:57], v[56:57], v[202:203]
	v_pk_add_f32 v[58:59], v[58:59], v[204:205]
	v_cvt_pk_bf16_f32 v178, v60, v61
	v_cvt_pk_bf16_f32 v179, v62, v63
	v_cvt_pk_bf16_f32 v180, v56, v57
	v_cvt_pk_bf16_f32 v181, v58, v59
	v_pk_mul_f32 v[138:139], v[60:61], v[60:61]
	global_store_dwordx4 v207, v[178:181], s[8:9]
	v_pk_fma_f32 v[138:139], v[62:63], v[62:63], v[138:139]
	v_pk_fma_f32 v[138:139], v[56:57], v[56:57], v[138:139]
	v_pk_fma_f32 v[138:139], v[58:59], v[58:59], v[138:139]
	v_lshlrev_b32_e32 v202, 16, v182
	v_and_b32_e32 v203, 0xffff0000, v182
	v_lshlrev_b32_e32 v204, 16, v183
	v_and_b32_e32 v205, 0xffff0000, v183
	v_pk_add_f32 v[52:53], v[52:53], v[202:203]
	v_pk_add_f32 v[54:55], v[54:55], v[204:205]
	v_lshlrev_b32_e32 v202, 16, v184
	v_and_b32_e32 v203, 0xffff0000, v184
	v_lshlrev_b32_e32 v204, 16, v185
	v_and_b32_e32 v205, 0xffff0000, v185
	v_pk_add_f32 v[48:49], v[48:49], v[202:203]
	v_pk_add_f32 v[50:51], v[50:51], v[204:205]
	v_cvt_pk_bf16_f32 v182, v52, v53
	v_cvt_pk_bf16_f32 v183, v54, v55
	v_cvt_pk_bf16_f32 v184, v48, v49
	v_cvt_pk_bf16_f32 v185, v50, v51
	v_pk_fma_f32 v[138:139], v[52:53], v[52:53], v[138:139]
	global_store_dwordx4 v207, v[182:185], s[8:9] offset:256
	v_pk_fma_f32 v[138:139], v[54:55], v[54:55], v[138:139]
	v_pk_fma_f32 v[138:139], v[48:49], v[48:49], v[138:139]
	v_pk_fma_f32 v[138:139], v[50:51], v[50:51], v[138:139]
	v_add_f32_e32 v214, v138, v139
	v_add_u32_e32 v207, 0x8000, v207
	v_mov_b32_e32 v215, v214
	s_nop 1
	v_permlane16_swap_b32_e32 v214, v215
	s_nop 0
	v_add_f32_e32 v214, v214, v215
	v_mov_b32_e32 v215, v214
	s_nop 1
	v_permlane32_swap_b32_e32 v214, v215
	s_nop 0
	v_add_f32_e32 v214, v214, v215
	s_and_saveexec_b64 s[26:27], s[4:5]
	global_store_dword v210, v214, s[14:15]
	s_mov_b64 exec, s[26:27]
	s_waitcnt vmcnt(19)
	v_lshlrev_b32_e32 v202, 16, v186
	v_and_b32_e32 v203, 0xffff0000, v186
	v_lshlrev_b32_e32 v204, 16, v187
	v_and_b32_e32 v205, 0xffff0000, v187
	v_pk_add_f32 v[44:45], v[44:45], v[202:203]
	v_pk_add_f32 v[46:47], v[46:47], v[204:205]
	v_lshlrev_b32_e32 v202, 16, v188
	v_and_b32_e32 v203, 0xffff0000, v188
	v_lshlrev_b32_e32 v204, 16, v189
	v_and_b32_e32 v205, 0xffff0000, v189
	v_pk_add_f32 v[40:41], v[40:41], v[202:203]
	v_pk_add_f32 v[42:43], v[42:43], v[204:205]
	v_cvt_pk_bf16_f32 v186, v44, v45
	v_cvt_pk_bf16_f32 v187, v46, v47
	v_cvt_pk_bf16_f32 v188, v40, v41
	v_cvt_pk_bf16_f32 v189, v42, v43
	v_pk_mul_f32 v[138:139], v[44:45], v[44:45]
	global_store_dwordx4 v207, v[186:189], s[8:9]
	v_pk_fma_f32 v[138:139], v[46:47], v[46:47], v[138:139]
	v_pk_fma_f32 v[138:139], v[40:41], v[40:41], v[138:139]
	v_pk_fma_f32 v[138:139], v[42:43], v[42:43], v[138:139]
	v_lshlrev_b32_e32 v202, 16, v190
	v_and_b32_e32 v203, 0xffff0000, v190
	v_lshlrev_b32_e32 v204, 16, v191
	v_and_b32_e32 v205, 0xffff0000, v191
	v_pk_add_f32 v[36:37], v[36:37], v[202:203]
	v_pk_add_f32 v[38:39], v[38:39], v[204:205]
	v_lshlrev_b32_e32 v202, 16, v192
	v_and_b32_e32 v203, 0xffff0000, v192
	v_lshlrev_b32_e32 v204, 16, v193
	v_and_b32_e32 v205, 0xffff0000, v193
	v_pk_add_f32 v[32:33], v[32:33], v[202:203]
	v_pk_add_f32 v[34:35], v[34:35], v[204:205]
	v_cvt_pk_bf16_f32 v190, v36, v37
	v_cvt_pk_bf16_f32 v191, v38, v39
	v_cvt_pk_bf16_f32 v192, v32, v33
	v_cvt_pk_bf16_f32 v193, v34, v35
	v_pk_fma_f32 v[138:139], v[36:37], v[36:37], v[138:139]
	global_store_dwordx4 v207, v[190:193], s[8:9] offset:256
	v_pk_fma_f32 v[138:139], v[38:39], v[38:39], v[138:139]
	v_pk_fma_f32 v[138:139], v[32:33], v[32:33], v[138:139]
	v_pk_fma_f32 v[138:139], v[34:35], v[34:35], v[138:139]
	v_add_f32_e32 v214, v138, v139
	v_add_u32_e32 v207, 0x8000, v207
	v_mov_b32_e32 v215, v214
	s_nop 1
	v_permlane16_swap_b32_e32 v214, v215
	s_nop 0
	v_add_f32_e32 v214, v214, v215
	v_mov_b32_e32 v215, v214
	s_nop 1
	v_permlane32_swap_b32_e32 v214, v215
	s_nop 0
	v_add_f32_e32 v214, v214, v215
	s_and_saveexec_b64 s[26:27], s[4:5]
	global_store_dword v210, v214, s[14:15] offset:1024
	s_mov_b64 exec, s[26:27]
	s_waitcnt vmcnt(20)
	v_lshlrev_b32_e32 v202, 16, v194
	v_and_b32_e32 v203, 0xffff0000, v194
	v_lshlrev_b32_e32 v204, 16, v195
	v_and_b32_e32 v205, 0xffff0000, v195
	v_pk_add_f32 v[28:29], v[28:29], v[202:203]
	v_pk_add_f32 v[30:31], v[30:31], v[204:205]
	v_lshlrev_b32_e32 v202, 16, v196
	v_and_b32_e32 v203, 0xffff0000, v196
	v_lshlrev_b32_e32 v204, 16, v197
	v_and_b32_e32 v205, 0xffff0000, v197
	v_pk_add_f32 v[24:25], v[24:25], v[202:203]
	v_pk_add_f32 v[26:27], v[26:27], v[204:205]
	v_cvt_pk_bf16_f32 v194, v28, v29
	v_cvt_pk_bf16_f32 v195, v30, v31
	v_cvt_pk_bf16_f32 v196, v24, v25
	v_cvt_pk_bf16_f32 v197, v26, v27
	v_pk_mul_f32 v[138:139], v[28:29], v[28:29]
	global_store_dwordx4 v207, v[194:197], s[8:9]
	v_pk_fma_f32 v[138:139], v[30:31], v[30:31], v[138:139]
	v_pk_fma_f32 v[138:139], v[24:25], v[24:25], v[138:139]
	v_pk_fma_f32 v[138:139], v[26:27], v[26:27], v[138:139]
	v_lshlrev_b32_e32 v202, 16, v198
	v_and_b32_e32 v203, 0xffff0000, v198
	v_lshlrev_b32_e32 v204, 16, v199
	v_and_b32_e32 v205, 0xffff0000, v199
	v_pk_add_f32 v[20:21], v[20:21], v[202:203]
	v_pk_add_f32 v[22:23], v[22:23], v[204:205]
	v_lshlrev_b32_e32 v202, 16, v200
	v_and_b32_e32 v203, 0xffff0000, v200
	v_lshlrev_b32_e32 v204, 16, v201
	v_and_b32_e32 v205, 0xffff0000, v201
	v_pk_add_f32 v[16:17], v[16:17], v[202:203]
	v_pk_add_f32 v[18:19], v[18:19], v[204:205]
	v_cvt_pk_bf16_f32 v198, v20, v21
	v_cvt_pk_bf16_f32 v199, v22, v23
	v_cvt_pk_bf16_f32 v200, v16, v17
	v_cvt_pk_bf16_f32 v201, v18, v19
	v_pk_fma_f32 v[138:139], v[20:21], v[20:21], v[138:139]
	global_store_dwordx4 v207, v[198:201], s[8:9] offset:256
	v_pk_fma_f32 v[138:139], v[22:23], v[22:23], v[138:139]
	v_pk_fma_f32 v[138:139], v[16:17], v[16:17], v[138:139]
	v_pk_fma_f32 v[138:139], v[18:19], v[18:19], v[138:139]
	v_add_f32_e32 v214, v138, v139
	v_add_u32_e32 v207, 0x8000, v207
	v_mov_b32_e32 v215, v214
	s_nop 1
	v_permlane16_swap_b32_e32 v214, v215
	s_nop 0
	v_add_f32_e32 v214, v214, v215
	v_mov_b32_e32 v215, v214
	s_nop 1
	v_permlane32_swap_b32_e32 v214, v215
	s_nop 0
	v_add_f32_e32 v214, v214, v215
	s_and_saveexec_b64 s[26:27], s[4:5]
	global_store_dword v210, v214, s[14:15] offset:2048
	s_mov_b64 exec, s[26:27]
	s_waitcnt vmcnt(18)
	v_lshlrev_b32_e32 v202, 16, v146
	v_and_b32_e32 v203, 0xffff0000, v146
	v_lshlrev_b32_e32 v204, 16, v147
	v_and_b32_e32 v205, 0xffff0000, v147
	v_pk_add_f32 v[12:13], v[12:13], v[202:203]
	v_pk_add_f32 v[14:15], v[14:15], v[204:205]
	v_lshlrev_b32_e32 v202, 16, v148
	v_and_b32_e32 v203, 0xffff0000, v148
	v_lshlrev_b32_e32 v204, 16, v149
	v_and_b32_e32 v205, 0xffff0000, v149
	v_pk_add_f32 v[8:9], v[8:9], v[202:203]
	v_pk_add_f32 v[10:11], v[10:11], v[204:205]
	v_cvt_pk_bf16_f32 v146, v12, v13
	v_cvt_pk_bf16_f32 v147, v14, v15
	v_cvt_pk_bf16_f32 v148, v8, v9
	v_cvt_pk_bf16_f32 v149, v10, v11
	v_pk_mul_f32 v[138:139], v[12:13], v[12:13]
	global_store_dwordx4 v207, v[146:149], s[8:9]
	v_pk_fma_f32 v[138:139], v[14:15], v[14:15], v[138:139]
	v_pk_fma_f32 v[138:139], v[8:9], v[8:9], v[138:139]
	v_pk_fma_f32 v[138:139], v[10:11], v[10:11], v[138:139]
	v_lshlrev_b32_e32 v202, 16, v150
	v_and_b32_e32 v203, 0xffff0000, v150
	v_lshlrev_b32_e32 v204, 16, v151
	v_and_b32_e32 v205, 0xffff0000, v151
	v_pk_add_f32 v[4:5], v[4:5], v[202:203]
	v_pk_add_f32 v[6:7], v[6:7], v[204:205]
	v_lshlrev_b32_e32 v202, 16, v152
	v_and_b32_e32 v203, 0xffff0000, v152
	v_lshlrev_b32_e32 v204, 16, v153
	v_and_b32_e32 v205, 0xffff0000, v153
	v_pk_add_f32 v[0:1], v[0:1], v[202:203]
	v_pk_add_f32 v[2:3], v[2:3], v[204:205]
	v_cvt_pk_bf16_f32 v150, v4, v5
	v_cvt_pk_bf16_f32 v151, v6, v7
	v_cvt_pk_bf16_f32 v152, v0, v1
	v_cvt_pk_bf16_f32 v153, v2, v3
	v_pk_fma_f32 v[138:139], v[4:5], v[4:5], v[138:139]
	global_store_dwordx4 v207, v[150:153], s[8:9] offset:256
	v_pk_fma_f32 v[138:139], v[6:7], v[6:7], v[138:139]
	v_pk_fma_f32 v[138:139], v[0:1], v[0:1], v[138:139]
	v_pk_fma_f32 v[138:139], v[2:3], v[2:3], v[138:139]
	v_add_f32_e32 v214, v138, v139
	v_add_u32_e32 v207, 0x8000, v207
	v_mov_b32_e32 v215, v214
	s_nop 1
	v_permlane16_swap_b32_e32 v214, v215
	s_nop 0
	v_add_f32_e32 v214, v214, v215
	v_mov_b32_e32 v215, v214
	s_nop 1
	v_permlane32_swap_b32_e32 v214, v215
	s_nop 0
	v_add_f32_e32 v214, v214, v215
	s_and_saveexec_b64 s[26:27], s[4:5]
	global_store_dword v210, v214, s[14:15] offset:3072
	s_mov_b64 exec, s[26:27]
	s_branch .LBB0_870

.LBB0_921:
	s_add_u32 s8, s6, 0xfffe0080
	s_addc_u32 s9, s7, -1
	s_add_i32 s84, 0, 0x10000
	v_add_u32_e32 v140, s84, v253
	ds_read_b128 v[128:131], v140
	ds_read_b128 v[132:135], v140 offset:1024
	ds_read_b128 v[136:139], v140 offset:2048
	ds_read_b128 v[140:143], v140 offset:3072
	s_cmp_eq_u32 s73, 12
	s_cselect_b32 s11, s15, s9
	s_cselect_b32 s10, s39, s8
	s_cselect_b32 s9, s65, vcc_hi
	s_cselect_b32 s8, s67, vcc_lo
	s_add_i32 m0, s46, 0xc000
	ds_read_b128 v[144:147], v251
	ds_read_b128 v[148:151], v251 offset:1024
	ds_read_b128 v[152:155], v251 offset:2048
	ds_read_b128 v[156:159], v251 offset:3072
	ds_read_b128 v[160:163], v251 offset:4096
	ds_read_b128 v[164:167], v251 offset:5120
	ds_read_b128 v[168:171], v251 offset:6144
	global_load_lds_dwordx4 v220, s[6:7]
	s_add_i32 m0, s46, 0xe000
	ds_read_b128 v[172:175], v251 offset:7168
	global_load_lds_dwordx4 v222, s[6:7]
	s_waitcnt lgkmcnt(8)
	s_barrier
	s_waitcnt lgkmcnt(0)
	v_mfma_f32_16x16x32_bf16 v[124:127], v[128:131], v[144:147], v[124:127]
	v_mfma_f32_16x16x32_bf16 v[120:123], v[136:139], v[144:147], v[120:123]
	v_mfma_f32_16x16x32_bf16 v[92:95], v[128:131], v[152:155], v[92:95]
	v_mfma_f32_16x16x32_bf16 v[44:47], v[136:139], v[152:155], v[44:47]
	v_mfma_f32_16x16x32_bf16 v[84:87], v[128:131], v[160:163], v[84:87]
	v_mfma_f32_16x16x32_bf16 v[40:43], v[136:139], v[160:163], v[40:43]
	v_mfma_f32_16x16x32_bf16 v[76:79], v[128:131], v[168:171], v[76:79]
	v_mfma_f32_16x16x32_bf16 v[36:39], v[136:139], v[168:171], v[36:39]
	v_mfma_f32_16x16x32_bf16 v[124:127], v[132:135], v[148:151], v[124:127]
	v_mfma_f32_16x16x32_bf16 v[120:123], v[140:143], v[148:151], v[120:123]
	v_mfma_f32_16x16x32_bf16 v[92:95], v[132:135], v[156:159], v[92:95]
	v_mfma_f32_16x16x32_bf16 v[44:47], v[140:143], v[156:159], v[44:47]
	v_mfma_f32_16x16x32_bf16 v[84:87], v[132:135], v[164:167], v[84:87]
	v_mfma_f32_16x16x32_bf16 v[40:43], v[140:143], v[164:167], v[40:43]
	v_mfma_f32_16x16x32_bf16 v[76:79], v[132:135], v[172:175], v[76:79]
	v_mfma_f32_16x16x32_bf16 v[36:39], v[140:143], v[172:175], v[36:39]
	s_barrier
	s_add_i32 s86, 0, 0x14000
	s_add_i32 s84, s84, s88
	v_add_u32_e32 v188, s86, v253
	s_add_u32 s98, s8, s40
	s_addc_u32 s99, s9, s41
	s_mov_b32 m0, s84
	ds_read_b128 v[176:179], v188
	ds_read_b128 v[180:183], v188 offset:1024
	ds_read_b128 v[184:187], v188 offset:2048
	global_load_lds_dwordx4 v208, s[8:9]
	s_add_i32 m0, s84, 0x2000
	ds_read_b128 v[188:191], v188 offset:3072
	global_load_lds_dwordx4 v214, s[8:9]
	s_barrier
	s_waitcnt lgkmcnt(0)
	v_mfma_f32_16x16x32_bf16 v[116:119], v[176:179], v[144:147], v[116:119]
	v_mfma_f32_16x16x32_bf16 v[112:115], v[184:187], v[144:147], v[112:115]
	v_mfma_f32_16x16x32_bf16 v[88:91], v[176:179], v[152:155], v[88:91]
	v_mfma_f32_16x16x32_bf16 v[32:35], v[184:187], v[152:155], v[32:35]
	v_mfma_f32_16x16x32_bf16 v[80:83], v[176:179], v[160:163], v[80:83]
	v_mfma_f32_16x16x32_bf16 v[28:31], v[184:187], v[160:163], v[28:31]
	v_mfma_f32_16x16x32_bf16 v[72:75], v[176:179], v[168:171], v[72:75]
	v_mfma_f32_16x16x32_bf16 v[24:27], v[184:187], v[168:171], v[24:27]
	v_mfma_f32_16x16x32_bf16 v[116:119], v[180:183], v[148:151], v[116:119]
	v_mfma_f32_16x16x32_bf16 v[112:115], v[188:191], v[148:151], v[112:115]
	v_mfma_f32_16x16x32_bf16 v[88:91], v[180:183], v[156:159], v[88:91]
	v_mfma_f32_16x16x32_bf16 v[32:35], v[188:191], v[156:159], v[32:35]
	v_mfma_f32_16x16x32_bf16 v[80:83], v[180:183], v[164:167], v[80:83]
	v_mfma_f32_16x16x32_bf16 v[28:31], v[188:191], v[164:167], v[28:31]
	v_mfma_f32_16x16x32_bf16 v[72:75], v[180:183], v[172:175], v[72:75]
	v_mfma_f32_16x16x32_bf16 v[24:27], v[188:191], v[172:175], v[24:27]
	s_mov_b32 m0, s46
	s_add_u32 s100, s10, s40
	s_addc_u32 s101, s11, s41
	s_barrier
	ds_read_b128 v[144:147], v251 offset:16384
	ds_read_b128 v[148:151], v251 offset:17408
	ds_read_b128 v[152:155], v251 offset:18432
	ds_read_b128 v[156:159], v251 offset:19456
	ds_read_b128 v[160:163], v251 offset:20480
	ds_read_b128 v[164:167], v251 offset:21504
	ds_read_b128 v[168:171], v251 offset:22528
	global_load_lds_dwordx4 v218, s[10:11]
	s_mov_b32 m0, s50
	ds_read_b128 v[172:175], v251 offset:23552
	global_load_lds_dwordx4 v216, s[10:11]
	s_barrier
	s_waitcnt lgkmcnt(0)
	v_mfma_f32_16x16x32_bf16 v[68:71], v[128:131], v[144:147], v[68:71]
	v_mfma_f32_16x16x32_bf16 v[20:23], v[136:139], v[144:147], v[20:23]
	v_mfma_f32_16x16x32_bf16 v[64:67], v[128:131], v[152:155], v[64:67]
	v_mfma_f32_16x16x32_bf16 v[16:19], v[136:139], v[152:155], v[16:19]
	v_mfma_f32_16x16x32_bf16 v[60:63], v[128:131], v[160:163], v[60:63]
	v_mfma_f32_16x16x32_bf16 v[12:15], v[136:139], v[160:163], v[12:15]
	v_mfma_f32_16x16x32_bf16 v[108:111], v[128:131], v[168:171], v[108:111]
	v_mfma_f32_16x16x32_bf16 v[104:107], v[136:139], v[168:171], v[104:107]
	v_mfma_f32_16x16x32_bf16 v[68:71], v[132:135], v[148:151], v[68:71]
	v_mfma_f32_16x16x32_bf16 v[20:23], v[140:143], v[148:151], v[20:23]
	v_mfma_f32_16x16x32_bf16 v[64:67], v[132:135], v[156:159], v[64:67]
	v_mfma_f32_16x16x32_bf16 v[16:19], v[140:143], v[156:159], v[16:19]
	v_mfma_f32_16x16x32_bf16 v[60:63], v[132:135], v[164:167], v[60:63]
	v_mfma_f32_16x16x32_bf16 v[12:15], v[140:143], v[164:167], v[12:15]
	v_mfma_f32_16x16x32_bf16 v[108:111], v[132:135], v[172:175], v[108:111]
	v_mfma_f32_16x16x32_bf16 v[104:107], v[140:143], v[172:175], v[104:107]
	s_barrier
	s_add_u32 s84, s8, 0x40000
	s_addc_u32 s85, s9, 0
	s_add_i32 s86, s86, s88
	s_mov_b32 m0, s86
	s_nop 0
	global_load_lds_dwordx4 v208, s[84:85]
	s_add_i32 m0, s86, 0x2000
	s_nop 0
	global_load_lds_dwordx4 v214, s[84:85]
	s_waitcnt vmcnt(6)
	s_barrier
	v_mfma_f32_16x16x32_bf16 v[56:59], v[176:179], v[144:147], v[56:59]
	v_mfma_f32_16x16x32_bf16 v[8:11], v[184:187], v[144:147], v[8:11]
	v_mfma_f32_16x16x32_bf16 v[52:55], v[176:179], v[152:155], v[52:55]
	v_mfma_f32_16x16x32_bf16 v[4:7], v[184:187], v[152:155], v[4:7]
	v_mfma_f32_16x16x32_bf16 v[48:51], v[176:179], v[160:163], v[48:51]
	v_mfma_f32_16x16x32_bf16 v[0:3], v[184:187], v[160:163], v[0:3]
	v_mfma_f32_16x16x32_bf16 v[100:103], v[176:179], v[168:171], v[100:103]
	v_mfma_f32_16x16x32_bf16 v[96:99], v[184:187], v[168:171], v[96:99]
	v_mfma_f32_16x16x32_bf16 v[56:59], v[180:183], v[148:151], v[56:59]
	v_mfma_f32_16x16x32_bf16 v[8:11], v[188:191], v[148:151], v[8:11]
	v_mfma_f32_16x16x32_bf16 v[52:55], v[180:183], v[156:159], v[52:55]
	v_mfma_f32_16x16x32_bf16 v[4:7], v[188:191], v[156:159], v[4:7]
	v_mfma_f32_16x16x32_bf16 v[48:51], v[180:183], v[164:167], v[48:51]
	v_mfma_f32_16x16x32_bf16 v[0:3], v[188:191], v[164:167], v[0:3]
	v_mfma_f32_16x16x32_bf16 v[100:103], v[180:183], v[172:175], v[100:103]
	v_mfma_f32_16x16x32_bf16 v[96:99], v[188:191], v[172:175], v[96:99]
	s_add_i32 s84, 0, 0x18000
	v_add_u32_e32 v140, s84, v253
	s_barrier
	ds_read_b128 v[128:131], v140
	ds_read_b128 v[132:135], v140 offset:1024
	ds_read_b128 v[136:139], v140 offset:2048
	ds_read_b128 v[140:143], v140 offset:3072
	s_add_u32 s10, s10, 0x20000
	s_addc_u32 s11, s11, 0
	s_mov_b32 m0, s51
	ds_read_b128 v[144:147], v251 offset:32768
	ds_read_b128 v[148:151], v251 offset:33792
	ds_read_b128 v[152:155], v251 offset:34816
	ds_read_b128 v[156:159], v251 offset:35840
	ds_read_b128 v[160:163], v251 offset:36864
	ds_read_b128 v[164:167], v251 offset:37888
	ds_read_b128 v[168:171], v251 offset:38912
	global_load_lds_dwordx4 v218, s[10:11]
	s_mov_b32 m0, s34
	ds_read_b128 v[172:175], v251 offset:39936
	global_load_lds_dwordx4 v216, s[10:11]
	s_waitcnt lgkmcnt(8)
	s_barrier
	s_waitcnt lgkmcnt(0)
	v_mfma_f32_16x16x32_bf16 v[124:127], v[128:131], v[144:147], v[124:127]
	v_mfma_f32_16x16x32_bf16 v[120:123], v[136:139], v[144:147], v[120:123]
	v_mfma_f32_16x16x32_bf16 v[92:95], v[128:131], v[152:155], v[92:95]
	v_mfma_f32_16x16x32_bf16 v[44:47], v[136:139], v[152:155], v[44:47]
	v_mfma_f32_16x16x32_bf16 v[84:87], v[128:131], v[160:163], v[84:87]
	v_mfma_f32_16x16x32_bf16 v[40:43], v[136:139], v[160:163], v[40:43]
	v_mfma_f32_16x16x32_bf16 v[76:79], v[128:131], v[168:171], v[76:79]
	v_mfma_f32_16x16x32_bf16 v[36:39], v[136:139], v[168:171], v[36:39]
	v_mfma_f32_16x16x32_bf16 v[124:127], v[132:135], v[148:151], v[124:127]
	v_mfma_f32_16x16x32_bf16 v[120:123], v[140:143], v[148:151], v[120:123]
	v_mfma_f32_16x16x32_bf16 v[92:95], v[132:135], v[156:159], v[92:95]
	v_mfma_f32_16x16x32_bf16 v[44:47], v[140:143], v[156:159], v[44:47]
	v_mfma_f32_16x16x32_bf16 v[84:87], v[132:135], v[164:167], v[84:87]
	v_mfma_f32_16x16x32_bf16 v[40:43], v[140:143], v[164:167], v[40:43]
	v_mfma_f32_16x16x32_bf16 v[76:79], v[132:135], v[172:175], v[76:79]
	v_mfma_f32_16x16x32_bf16 v[36:39], v[140:143], v[172:175], v[36:39]
	s_barrier
	s_add_i32 s10, 0, 0x1c000
	s_add_i32 s11, s84, s88
	v_add_u32_e32 v188, s10, v253
	s_mov_b32 m0, s11
	ds_read_b128 v[176:179], v188
	ds_read_b128 v[180:183], v188 offset:1024
	ds_read_b128 v[184:187], v188 offset:2048
	global_load_lds_dwordx4 v208, s[98:99]
	s_add_i32 m0, s11, 0x2000
	ds_read_b128 v[188:191], v188 offset:3072
	global_load_lds_dwordx4 v214, s[98:99]
	s_barrier
	s_waitcnt lgkmcnt(0)
	v_mfma_f32_16x16x32_bf16 v[116:119], v[176:179], v[144:147], v[116:119]
	v_mfma_f32_16x16x32_bf16 v[112:115], v[184:187], v[144:147], v[112:115]
	v_mfma_f32_16x16x32_bf16 v[88:91], v[176:179], v[152:155], v[88:91]
	v_mfma_f32_16x16x32_bf16 v[32:35], v[184:187], v[152:155], v[32:35]
	v_mfma_f32_16x16x32_bf16 v[80:83], v[176:179], v[160:163], v[80:83]
	v_mfma_f32_16x16x32_bf16 v[28:31], v[184:187], v[160:163], v[28:31]
	v_mfma_f32_16x16x32_bf16 v[72:75], v[176:179], v[168:171], v[72:75]
	v_mfma_f32_16x16x32_bf16 v[24:27], v[184:187], v[168:171], v[24:27]
	v_mfma_f32_16x16x32_bf16 v[116:119], v[180:183], v[148:151], v[116:119]
	v_mfma_f32_16x16x32_bf16 v[112:115], v[188:191], v[148:151], v[112:115]
	v_mfma_f32_16x16x32_bf16 v[88:91], v[180:183], v[156:159], v[88:91]
	v_mfma_f32_16x16x32_bf16 v[32:35], v[188:191], v[156:159], v[32:35]
	v_mfma_f32_16x16x32_bf16 v[80:83], v[180:183], v[164:167], v[80:83]
	v_mfma_f32_16x16x32_bf16 v[28:31], v[188:191], v[164:167], v[28:31]
	v_mfma_f32_16x16x32_bf16 v[72:75], v[180:183], v[172:175], v[72:75]
	v_mfma_f32_16x16x32_bf16 v[24:27], v[188:191], v[172:175], v[24:27]
	s_mov_b32 m0, s92
	s_barrier
	ds_read_b128 v[144:147], v251 offset:49152
	ds_read_b128 v[148:151], v251 offset:50176
	ds_read_b128 v[152:155], v251 offset:51200
	ds_read_b128 v[156:159], v251 offset:52224
	ds_read_b128 v[160:163], v251 offset:53248
	ds_read_b128 v[164:167], v251 offset:54272
	ds_read_b128 v[168:171], v251 offset:55296
	global_load_lds_dwordx4 v218, s[100:101]
	s_mov_b32 m0, s93
	ds_read_b128 v[172:175], v251 offset:56320
	global_load_lds_dwordx4 v216, s[100:101]
	s_barrier
	s_waitcnt lgkmcnt(0)
	v_mfma_f32_16x16x32_bf16 v[68:71], v[128:131], v[144:147], v[68:71]
	v_mfma_f32_16x16x32_bf16 v[20:23], v[136:139], v[144:147], v[20:23]
	v_mfma_f32_16x16x32_bf16 v[64:67], v[128:131], v[152:155], v[64:67]
	v_mfma_f32_16x16x32_bf16 v[16:19], v[136:139], v[152:155], v[16:19]
	v_mfma_f32_16x16x32_bf16 v[60:63], v[128:131], v[160:163], v[60:63]
	v_mfma_f32_16x16x32_bf16 v[12:15], v[136:139], v[160:163], v[12:15]
	v_mfma_f32_16x16x32_bf16 v[108:111], v[128:131], v[168:171], v[108:111]
	v_mfma_f32_16x16x32_bf16 v[104:107], v[136:139], v[168:171], v[104:107]
	v_mfma_f32_16x16x32_bf16 v[68:71], v[132:135], v[148:151], v[68:71]
	v_mfma_f32_16x16x32_bf16 v[20:23], v[140:143], v[148:151], v[20:23]
	v_mfma_f32_16x16x32_bf16 v[64:67], v[132:135], v[156:159], v[64:67]
	v_mfma_f32_16x16x32_bf16 v[16:19], v[140:143], v[156:159], v[16:19]
	v_mfma_f32_16x16x32_bf16 v[60:63], v[132:135], v[164:167], v[60:63]
	v_mfma_f32_16x16x32_bf16 v[12:15], v[140:143], v[164:167], v[12:15]
	v_mfma_f32_16x16x32_bf16 v[108:111], v[132:135], v[172:175], v[108:111]
	v_mfma_f32_16x16x32_bf16 v[104:107], v[140:143], v[172:175], v[104:107]
	s_barrier
	s_add_u32 s8, s8, 0x40080
	s_addc_u32 s9, s9, 0
	s_add_i32 s10, s10, s88
	s_mov_b32 m0, s10
	s_add_i32 s73, s73, 2
	global_load_lds_dwordx4 v208, s[8:9]
	s_add_i32 m0, s10, 0x2000
	s_add_u32 s6, s6, 0x100
	s_addc_u32 s7, s7, 0
	global_load_lds_dwordx4 v214, s[8:9]
	s_add_u32 vcc_lo, vcc_lo, 0x100
	s_addc_u32 vcc_hi, vcc_hi, 0
	s_waitcnt vmcnt(6)
	s_barrier
	v_mfma_f32_16x16x32_bf16 v[56:59], v[176:179], v[144:147], v[56:59]
	v_mfma_f32_16x16x32_bf16 v[8:11], v[184:187], v[144:147], v[8:11]
	v_mfma_f32_16x16x32_bf16 v[52:55], v[176:179], v[152:155], v[52:55]
	v_mfma_f32_16x16x32_bf16 v[4:7], v[184:187], v[152:155], v[4:7]
	v_mfma_f32_16x16x32_bf16 v[48:51], v[176:179], v[160:163], v[48:51]
	v_mfma_f32_16x16x32_bf16 v[0:3], v[184:187], v[160:163], v[0:3]
	v_mfma_f32_16x16x32_bf16 v[100:103], v[176:179], v[168:171], v[100:103]
	v_mfma_f32_16x16x32_bf16 v[96:99], v[184:187], v[168:171], v[96:99]
	v_mfma_f32_16x16x32_bf16 v[56:59], v[180:183], v[148:151], v[56:59]
	v_mfma_f32_16x16x32_bf16 v[8:11], v[188:191], v[148:151], v[8:11]
	v_mfma_f32_16x16x32_bf16 v[52:55], v[180:183], v[156:159], v[52:55]
	v_mfma_f32_16x16x32_bf16 v[4:7], v[188:191], v[156:159], v[4:7]
	v_mfma_f32_16x16x32_bf16 v[48:51], v[180:183], v[164:167], v[48:51]
	v_mfma_f32_16x16x32_bf16 v[0:3], v[188:191], v[164:167], v[0:3]
	v_mfma_f32_16x16x32_bf16 v[100:103], v[180:183], v[172:175], v[100:103]
	v_mfma_f32_16x16x32_bf16 v[96:99], v[188:191], v[172:175], v[96:99]
	s_cmp_gt_u32 s73, 13
	s_barrier
	s_cbranch_scc0 .LBB0_921
	s_lshl_b32 s6, s38, 8
	v_mov_b32_e32 v250, v210
	v_mov_b32_e32 v254, v249
	s_add_i32 s6, s6, s90
	v_mov_b64_e32 v[242:243], s[44:45]
	v_add_u32_e32 v234, s6, v254
	v_ashrrev_i32_e32 v235, 31, v234
	v_mbcnt_lo_u32_b32 v212, -1, 0
	v_mbcnt_hi_u32_b32 v212, -1, v212
	v_lshlrev_b32_e32 v244, 6, v234
	v_and_b32_e32 v212, 48, v212
	v_add_u32_e32 v212, v244, v212
	v_add_u32_e32 v213, 0x1000, v212
	v_add_u32_e32 v245, 0x1000, v244
	global_load_dwordx4 v[192:195], v212, s[20:21]
	global_load_dwordx4 v[196:199], v212, s[20:21] offset:1024
	global_load_dwordx4 v[200:203], v213, s[20:21] offset:2048
	global_load_dwordx4 v[204:207], v213, s[20:21] offset:3072
	global_load_dwordx4 v[160:163], v244, s[20:21] offset:2096
	global_load_dwordx4 v[164:167], v244, s[20:21] offset:2080
	global_load_dwordx4 v[176:179], v244, s[20:21] offset:2064
	global_load_dwordx4 v[180:183], v244, s[20:21] offset:2048
	global_load_dwordx4 v[168:171], v244, s[20:21] offset:3120
	global_load_dwordx4 v[172:175], v244, s[20:21] offset:3104
	global_load_dwordx4 v[184:187], v244, s[20:21] offset:3088
	global_load_dwordx4 v[188:191], v244, s[20:21] offset:3072
	global_load_dwordx4 v[144:147], v245, s[20:21] offset:48
	global_load_dwordx4 v[148:151], v245, s[20:21] offset:32
	global_load_dwordx4 v[152:155], v245, s[20:21] offset:16
	global_load_dwordx4 v[156:159], v245, s[20:21]
	global_load_dwordx4 v[128:131], v245, s[20:21] offset:1072
	global_load_dwordx4 v[132:135], v245, s[20:21] offset:1056
	global_load_dwordx4 v[136:139], v245, s[20:21] offset:1040
	global_load_dwordx4 v[140:143], v245, s[20:21] offset:1024
	v_add_u32_e32 v236, 16, v234
	v_ashrrev_i32_e32 v237, 31, v236
	v_add_u32_e32 v238, 32, v234
	v_ashrrev_i32_e32 v239, 31, v238
	v_add_u32_e32 v232, 48, v234
	v_ashrrev_i32_e32 v233, 31, v232
	v_add_u32_e32 v230, 64, v234
	v_ashrrev_i32_e32 v231, 31, v230
	v_add_u32_e32 v228, 0x50, v234
	v_ashrrev_i32_e32 v229, 31, v228
	v_add_u32_e32 v224, 0x60, v234
	v_ashrrev_i32_e32 v225, 31, v224
	v_add_u32_e32 v226, 0x70, v234
	v_ashrrev_i32_e32 v227, 31, v226
	s_lshl_b32 s14, s14, 7
	s_or_b32 s14, s14, s35
	s_waitcnt vmcnt(16)
	v_pk_add_f32 v[192:193], v[192:193], v[194:195]
	s_nop 0
	v_add_f32_e32 v246, v192, v193
	v_mov_b32_e32 v247, v246
	s_nop 1
	v_permlane16_swap_b32_e32 v246, v247
	s_nop 0
	v_add_f32_e32 v246, v246, v247
	v_mov_b32_e32 v247, v246
	s_nop 1
	v_permlane32_swap_b32_e32 v246, v247
	s_nop 0
	v_add_f32_e32 v193, v246, v247
	v_pk_add_f32 v[196:197], v[196:197], v[198:199]
	s_nop 0
	v_add_f32_e32 v246, v196, v197
	v_mov_b32_e32 v247, v246
	s_nop 1
	v_permlane16_swap_b32_e32 v246, v247
	s_nop 0
	v_add_f32_e32 v246, v246, v247
	v_mov_b32_e32 v247, v246
	s_nop 1
	v_permlane32_swap_b32_e32 v246, v247
	s_nop 0
	v_add_f32_e32 v192, v246, v247
	v_pk_add_f32 v[200:201], v[200:201], v[202:203]
	s_nop 0
	v_add_f32_e32 v246, v200, v201
	v_mov_b32_e32 v247, v246
	s_nop 1
	v_permlane16_swap_b32_e32 v246, v247
	s_nop 0
	v_add_f32_e32 v246, v246, v247
	v_mov_b32_e32 v247, v246
	s_nop 1
	v_permlane32_swap_b32_e32 v246, v247
	s_nop 0
	v_add_f32_e32 v197, v246, v247
	v_pk_add_f32 v[204:205], v[204:205], v[206:207]
	s_nop 0
	v_add_f32_e32 v246, v204, v205
	v_mov_b32_e32 v247, v246
	s_nop 1
	v_permlane16_swap_b32_e32 v246, v247
	s_nop 0
	v_add_f32_e32 v246, v246, v247
	v_mov_b32_e32 v247, v246
	s_nop 1
	v_permlane32_swap_b32_e32 v246, v247
	s_nop 0
	v_add_f32_e32 v196, v246, v247
	s_nop 0
	v_pk_fma_f32 v[240:241], v[192:193], s[42:43], v[242:243] op_sel_hi:[1,0,0]
	v_pk_fma_f32 v[202:203], v[196:197], s[42:43], v[242:243] op_sel_hi:[1,0,0]
	v_cmp_gt_f32_e64 s[6:7], s97, v240
	v_cmp_gt_f32_e32 vcc, s97, v241
	s_waitcnt vmcnt(0)
	v_lshl_add_u32 v192, v250, 3, s14
	v_add_u32_e32 v193, -14, v254
	v_cmp_gt_f32_e64 s[8:9], s97, v203
	v_cmp_gt_f32_e64 s[10:11], s97, v202
	v_cmp_lt_u32_e64 s[14:15], -13, v193
	v_ashrrev_i32_e32 v193, 31, v192
	s_and_saveexec_b64 s[86:87], s[14:15]
	s_xor_b64 s[14:15], exec, s[86:87]
	s_or_saveexec_b64 s[14:15], s[14:15]
	v_mul_f32_e32 v194, 0x4b800000, v241
	v_cndmask_b32_e32 v194, v241, v194, vcc
	v_rsq_f32_e32 v194, v194
	s_nop 0
	v_mul_f32_e32 v195, 0x45800000, v194
	v_cndmask_b32_e32 v204, v194, v195, vcc
	v_pk_mul_f32 v[196:197], v[118:119], v[204:205] op_sel_hi:[1,0]
	v_mul_f32_e32 v118, 0x4b800000, v202
	v_cndmask_b32_e64 v118, v202, v118, s[10:11]
	v_rsq_f32_e32 v118, v118
	v_pk_mul_f32 v[200:201], v[116:117], v[204:205] op_sel_hi:[1,0]
	v_pk_mul_f32 v[194:195], v[126:127], v[204:205] op_sel_hi:[1,0]
	v_pk_mul_f32 v[198:199], v[124:125], v[204:205] op_sel_hi:[1,0]
	v_mul_f32_e32 v116, 0x45800000, v118
	v_cndmask_b32_e64 v116, v118, v116, s[10:11]
	v_pk_mul_f32 v[122:123], v[122:123], v[204:205] op_sel_hi:[1,0]
	v_pk_mul_f32 v[120:121], v[120:121], v[204:205] op_sel_hi:[1,0]
	v_pk_mul_f32 v[114:115], v[114:115], v[204:205] op_sel_hi:[1,0]
	v_pk_mul_f32 v[112:113], v[112:113], v[204:205] op_sel_hi:[1,0]
	v_pk_mul_f32 v[110:111], v[110:111], v[116:117] op_sel_hi:[1,0]
	v_pk_mul_f32 v[108:109], v[108:109], v[116:117] op_sel_hi:[1,0]
	v_pk_mul_f32 v[106:107], v[106:107], v[116:117] op_sel_hi:[1,0]
	v_pk_mul_f32 v[104:105], v[104:105], v[116:117] op_sel_hi:[1,0]
	v_pk_mul_f32 v[102:103], v[102:103], v[116:117] op_sel_hi:[1,0]
	v_pk_mul_f32 v[100:101], v[100:101], v[116:117] op_sel_hi:[1,0]
	v_pk_mul_f32 v[98:99], v[98:99], v[116:117] op_sel_hi:[1,0]
	v_pk_mul_f32 v[96:97], v[96:97], v[116:117] op_sel_hi:[1,0]
	s_xor_b64 exec, exec, s[14:15]
	s_cbranch_execz .LBB0_917
	v_add_u32_e32 v116, -12, v254
	v_cmp_gt_i32_e64 s[10:11], 2, v254
	s_lshl_b32 s38, s38, 3
	s_add_i32 s38, s38, s91
	v_cndmask_b32_e64 v116, v116, v254, s[10:11]
	v_add_u32_e32 v126, s38, v116
	v_mov_b64_e32 v[124:125], s[22:23]
	s_movk_i32 s38, 0x5800
	v_mad_i64_i32 v[124:125], s[38:39], v126, s38, v[124:125]
	v_cndmask_b32_e64 v119, v111, v195, s[10:11]
	v_cndmask_b32_e64 v118, v110, v194, s[10:11]
	v_cndmask_b32_e64 v117, v109, v199, s[10:11]
	v_cndmask_b32_e64 v116, v108, v198, s[10:11]
	v_lshl_add_u64 v[124:125], v[192:193], 2, v[124:125]
	s_mov_b64 s[38:39], 0x2c00
	global_store_dwordx4 v[124:125], v[116:119], off
	v_lshl_add_u64 v[126:127], v[124:125], 0, s[38:39]
	s_movk_i32 s38, 0x2000
	v_cndmask_b32_e64 v119, v107, v123, s[10:11]
	v_cndmask_b32_e64 v118, v106, v122, s[10:11]
	v_cndmask_b32_e64 v117, v105, v121, s[10:11]
	v_cndmask_b32_e64 v116, v104, v120, s[10:11]
	global_store_dwordx4 v[124:125], v[116:119], off offset:16
	v_add_co_u32_e32 v124, vcc, s38, v124
	s_nop 0
	v_cndmask_b32_e64 v119, v103, v197, s[10:11]
	v_cndmask_b32_e64 v118, v102, v196, s[10:11]
	v_cndmask_b32_e64 v117, v101, v201, s[10:11]
	v_cndmask_b32_e64 v116, v100, v200, s[10:11]
	v_addc_co_u32_e32 v125, vcc, 0, v125, vcc
	global_store_dwordx4 v[124:125], v[116:119], off offset:3072
	s_nop 1
	v_cndmask_b32_e64 v119, v99, v115, s[10:11]
	v_cndmask_b32_e64 v118, v98, v114, s[10:11]
	v_cndmask_b32_e64 v117, v97, v113, s[10:11]
	v_cndmask_b32_e64 v116, v96, v112, s[10:11]
	global_store_dwordx4 v[126:127], v[116:119], off offset:16
	s_branch .LBB0_917

.LBB0_998:
	s_add_u32 s20, s10, 0x100
	s_addc_u32 s21, s11, 0
	s_add_i32 s60, 0, 0x10000
	v_add_u32_e32 v142, s60, v145
	ds_read_b128 v[138:141], v142
	ds_read_b128 v[148:151], v142 offset:1024
	ds_read_b128 v[152:155], v142 offset:2048
	ds_read_b128 v[156:159], v142 offset:3072
	s_cmp_eq_u32 s59, 40
	s_cselect_b32 s25, s7, s21
	s_cselect_b32 s24, s6, s20
	s_cselect_b32 s23, s9, s58
	s_cselect_b32 s22, s8, s57
	s_add_i32 m0, s34, 0xc000
	ds_read_b128 v[160:163], v147
	ds_read_b128 v[164:167], v147 offset:1024
	ds_read_b128 v[168:171], v147 offset:2048
	ds_read_b128 v[172:175], v147 offset:3072
	ds_read_b128 v[176:179], v147 offset:4096
	ds_read_b128 v[180:183], v147 offset:5120
	ds_read_b128 v[184:187], v147 offset:6144
	global_load_lds_dwordx4 v134, s[10:11]
	s_add_i32 m0, s34, 0xe000
	ds_read_b128 v[188:191], v147 offset:7168
	global_load_lds_dwordx4 v136, s[10:11]
	s_waitcnt lgkmcnt(8)
	s_barrier
	s_waitcnt lgkmcnt(0)
	v_mfma_f32_16x16x32_bf16 v[124:127], v[138:141], v[160:163], v[124:127]
	v_mfma_f32_16x16x32_bf16 v[120:123], v[152:155], v[160:163], v[120:123]
	v_mfma_f32_16x16x32_bf16 v[108:111], v[138:141], v[168:171], v[108:111]
	v_mfma_f32_16x16x32_bf16 v[104:107], v[152:155], v[168:171], v[104:107]
	v_mfma_f32_16x16x32_bf16 v[92:95], v[138:141], v[176:179], v[92:95]
	v_mfma_f32_16x16x32_bf16 v[88:91], v[152:155], v[176:179], v[88:91]
	v_mfma_f32_16x16x32_bf16 v[76:79], v[138:141], v[184:187], v[76:79]
	v_mfma_f32_16x16x32_bf16 v[72:75], v[152:155], v[184:187], v[72:75]
	v_mfma_f32_16x16x32_bf16 v[124:127], v[148:151], v[164:167], v[124:127]
	v_mfma_f32_16x16x32_bf16 v[120:123], v[156:159], v[164:167], v[120:123]
	v_mfma_f32_16x16x32_bf16 v[108:111], v[148:151], v[172:175], v[108:111]
	v_mfma_f32_16x16x32_bf16 v[104:107], v[156:159], v[172:175], v[104:107]
	v_mfma_f32_16x16x32_bf16 v[92:95], v[148:151], v[180:183], v[92:95]
	v_mfma_f32_16x16x32_bf16 v[88:91], v[156:159], v[180:183], v[88:91]
	v_mfma_f32_16x16x32_bf16 v[76:79], v[148:151], v[188:191], v[76:79]
	v_mfma_f32_16x16x32_bf16 v[72:75], v[156:159], v[188:191], v[72:75]
	s_barrier
	s_add_i32 s61, 0, 0x14000
	v_add_u32_e32 v142, s61, v145
	s_add_i32 s10, s60, s27
	ds_read_b128 v[192:195], v142
	ds_read_b128 v[196:199], v142 offset:1024
	ds_read_b128 v[200:203], v142 offset:2048
	ds_read_b128 v[204:207], v142 offset:3072
	s_add_u32 s98, s22, s40
	s_addc_u32 s99, s23, s41
	s_mov_b32 m0, s10
	s_nop 0
	global_load_lds_dwordx4 v208, s[22:23]
	s_add_i32 m0, s10, 0x2000
	s_nop 0
	global_load_lds_dwordx4 v128, s[22:23]
	s_barrier
	s_waitcnt lgkmcnt(0)
	v_mfma_f32_16x16x32_bf16 v[116:119], v[192:195], v[160:163], v[116:119]
	v_mfma_f32_16x16x32_bf16 v[112:115], v[200:203], v[160:163], v[112:115]
	v_mfma_f32_16x16x32_bf16 v[100:103], v[192:195], v[168:171], v[100:103]
	v_mfma_f32_16x16x32_bf16 v[96:99], v[200:203], v[168:171], v[96:99]
	v_mfma_f32_16x16x32_bf16 v[84:87], v[192:195], v[176:179], v[84:87]
	v_mfma_f32_16x16x32_bf16 v[80:83], v[200:203], v[176:179], v[80:83]
	v_mfma_f32_16x16x32_bf16 v[68:71], v[192:195], v[184:187], v[68:71]
	v_mfma_f32_16x16x32_bf16 v[64:67], v[200:203], v[184:187], v[64:67]
	v_mfma_f32_16x16x32_bf16 v[116:119], v[196:199], v[164:167], v[116:119]
	v_mfma_f32_16x16x32_bf16 v[112:115], v[204:207], v[164:167], v[112:115]
	v_mfma_f32_16x16x32_bf16 v[100:103], v[196:199], v[172:175], v[100:103]
	v_mfma_f32_16x16x32_bf16 v[96:99], v[204:207], v[172:175], v[96:99]
	v_mfma_f32_16x16x32_bf16 v[84:87], v[196:199], v[180:183], v[84:87]
	v_mfma_f32_16x16x32_bf16 v[80:83], v[204:207], v[180:183], v[80:83]
	v_mfma_f32_16x16x32_bf16 v[68:71], v[196:199], v[188:191], v[68:71]
	v_mfma_f32_16x16x32_bf16 v[64:67], v[204:207], v[188:191], v[64:67]
	s_mov_b32 m0, s34
	s_add_u32 s100, s24, s40
	s_addc_u32 s101, s25, s41
	s_barrier
	ds_read_b128 v[160:163], v147 offset:16384
	ds_read_b128 v[164:167], v147 offset:17408
	ds_read_b128 v[168:171], v147 offset:18432
	ds_read_b128 v[172:175], v147 offset:19456
	ds_read_b128 v[176:179], v147 offset:20480
	ds_read_b128 v[180:183], v147 offset:21504
	ds_read_b128 v[184:187], v147 offset:22528
	global_load_lds_dwordx4 v132, s[24:25]
	s_mov_b32 m0, s35
	ds_read_b128 v[188:191], v147 offset:23552
	global_load_lds_dwordx4 v130, s[24:25]
	s_barrier
	s_waitcnt lgkmcnt(0)
	v_mfma_f32_16x16x32_bf16 v[60:63], v[138:141], v[160:163], v[60:63]
	v_mfma_f32_16x16x32_bf16 v[56:59], v[152:155], v[160:163], v[56:59]
	v_mfma_f32_16x16x32_bf16 v[44:47], v[138:141], v[168:171], v[44:47]
	v_mfma_f32_16x16x32_bf16 v[40:43], v[152:155], v[168:171], v[40:43]
	v_mfma_f32_16x16x32_bf16 v[28:31], v[138:141], v[176:179], v[28:31]
	v_mfma_f32_16x16x32_bf16 v[24:27], v[152:155], v[176:179], v[24:27]
	v_mfma_f32_16x16x32_bf16 v[12:15], v[138:141], v[184:187], v[12:15]
	v_mfma_f32_16x16x32_bf16 v[8:11], v[152:155], v[184:187], v[8:11]
	v_mfma_f32_16x16x32_bf16 v[60:63], v[148:151], v[164:167], v[60:63]
	v_mfma_f32_16x16x32_bf16 v[56:59], v[156:159], v[164:167], v[56:59]
	v_mfma_f32_16x16x32_bf16 v[44:47], v[148:151], v[172:175], v[44:47]
	v_mfma_f32_16x16x32_bf16 v[40:43], v[156:159], v[172:175], v[40:43]
	v_mfma_f32_16x16x32_bf16 v[28:31], v[148:151], v[180:183], v[28:31]
	v_mfma_f32_16x16x32_bf16 v[24:27], v[156:159], v[180:183], v[24:27]
	v_mfma_f32_16x16x32_bf16 v[12:15], v[148:151], v[188:191], v[12:15]
	v_mfma_f32_16x16x32_bf16 v[8:11], v[156:159], v[188:191], v[8:11]
	s_barrier
	s_add_u32 s10, s22, 0xb0000
	s_addc_u32 s11, s23, 0
	s_add_i32 s60, s61, s27
	s_mov_b32 m0, s60
	s_nop 0
	global_load_lds_dwordx4 v208, s[10:11]
	s_add_i32 m0, s60, 0x2000
	s_nop 0
	global_load_lds_dwordx4 v128, s[10:11]
	s_waitcnt vmcnt(6)
	s_barrier
	v_mfma_f32_16x16x32_bf16 v[52:55], v[192:195], v[160:163], v[52:55]
	v_mfma_f32_16x16x32_bf16 v[48:51], v[200:203], v[160:163], v[48:51]
	v_mfma_f32_16x16x32_bf16 v[36:39], v[192:195], v[168:171], v[36:39]
	v_mfma_f32_16x16x32_bf16 v[32:35], v[200:203], v[168:171], v[32:35]
	v_mfma_f32_16x16x32_bf16 v[20:23], v[192:195], v[176:179], v[20:23]
	v_mfma_f32_16x16x32_bf16 v[16:19], v[200:203], v[176:179], v[16:19]
	v_mfma_f32_16x16x32_bf16 v[4:7], v[192:195], v[184:187], v[4:7]
	v_mfma_f32_16x16x32_bf16 v[0:3], v[200:203], v[184:187], v[0:3]
	v_mfma_f32_16x16x32_bf16 v[52:55], v[196:199], v[164:167], v[52:55]
	v_mfma_f32_16x16x32_bf16 v[48:51], v[204:207], v[164:167], v[48:51]
	v_mfma_f32_16x16x32_bf16 v[36:39], v[196:199], v[172:175], v[36:39]
	v_mfma_f32_16x16x32_bf16 v[32:35], v[204:207], v[172:175], v[32:35]
	v_mfma_f32_16x16x32_bf16 v[20:23], v[196:199], v[180:183], v[20:23]
	v_mfma_f32_16x16x32_bf16 v[16:19], v[204:207], v[180:183], v[16:19]
	v_mfma_f32_16x16x32_bf16 v[4:7], v[196:199], v[188:191], v[4:7]
	v_mfma_f32_16x16x32_bf16 v[0:3], v[204:207], v[188:191], v[0:3]
	s_add_i32 s60, 0, 0x18000
	v_add_u32_e32 v156, s60, v145
	s_barrier
	ds_read_b128 v[138:141], v156
	ds_read_b128 v[148:151], v156 offset:1024
	ds_read_b128 v[152:155], v156 offset:2048
	ds_read_b128 v[156:159], v156 offset:3072
	s_add_u32 s10, s24, 0xb0000
	s_addc_u32 s11, s25, 0
	s_mov_b32 m0, s36
	ds_read_b128 v[160:163], v147 offset:32768
	ds_read_b128 v[164:167], v147 offset:33792
	ds_read_b128 v[168:171], v147 offset:34816
	ds_read_b128 v[172:175], v147 offset:35840
	ds_read_b128 v[176:179], v147 offset:36864
	ds_read_b128 v[180:183], v147 offset:37888
	ds_read_b128 v[184:187], v147 offset:38912
	global_load_lds_dwordx4 v132, s[10:11]
	s_mov_b32 m0, s46
	ds_read_b128 v[188:191], v147 offset:39936
	global_load_lds_dwordx4 v130, s[10:11]
	s_waitcnt lgkmcnt(8)
	s_barrier
	s_waitcnt lgkmcnt(0)
	v_mfma_f32_16x16x32_bf16 v[124:127], v[138:141], v[160:163], v[124:127]
	v_mfma_f32_16x16x32_bf16 v[120:123], v[152:155], v[160:163], v[120:123]
	v_mfma_f32_16x16x32_bf16 v[108:111], v[138:141], v[168:171], v[108:111]
	v_mfma_f32_16x16x32_bf16 v[104:107], v[152:155], v[168:171], v[104:107]
	v_mfma_f32_16x16x32_bf16 v[92:95], v[138:141], v[176:179], v[92:95]
	v_mfma_f32_16x16x32_bf16 v[88:91], v[152:155], v[176:179], v[88:91]
	v_mfma_f32_16x16x32_bf16 v[76:79], v[138:141], v[184:187], v[76:79]
	v_mfma_f32_16x16x32_bf16 v[72:75], v[152:155], v[184:187], v[72:75]
	v_mfma_f32_16x16x32_bf16 v[124:127], v[148:151], v[164:167], v[124:127]
	v_mfma_f32_16x16x32_bf16 v[120:123], v[156:159], v[164:167], v[120:123]
	v_mfma_f32_16x16x32_bf16 v[108:111], v[148:151], v[172:175], v[108:111]
	v_mfma_f32_16x16x32_bf16 v[104:107], v[156:159], v[172:175], v[104:107]
	v_mfma_f32_16x16x32_bf16 v[92:95], v[148:151], v[180:183], v[92:95]
	v_mfma_f32_16x16x32_bf16 v[88:91], v[156:159], v[180:183], v[88:91]
	v_mfma_f32_16x16x32_bf16 v[76:79], v[148:151], v[188:191], v[76:79]
	v_mfma_f32_16x16x32_bf16 v[72:75], v[156:159], v[188:191], v[72:75]
	s_barrier
	s_add_i32 s24, 0, 0x1c000
	s_add_i32 s10, s60, s27
	v_add_u32_e32 v204, s24, v145
	s_mov_b32 m0, s10
	ds_read_b128 v[192:195], v204
	ds_read_b128 v[196:199], v204 offset:1024
	ds_read_b128 v[200:203], v204 offset:2048
	global_load_lds_dwordx4 v208, s[98:99]
	s_add_i32 m0, s10, 0x2000
	ds_read_b128 v[204:207], v204 offset:3072
	global_load_lds_dwordx4 v128, s[98:99]
	s_barrier
	s_waitcnt lgkmcnt(0)
	v_mfma_f32_16x16x32_bf16 v[116:119], v[192:195], v[160:163], v[116:119]
	v_mfma_f32_16x16x32_bf16 v[112:115], v[200:203], v[160:163], v[112:115]
	v_mfma_f32_16x16x32_bf16 v[100:103], v[192:195], v[168:171], v[100:103]
	v_mfma_f32_16x16x32_bf16 v[96:99], v[200:203], v[168:171], v[96:99]
	v_mfma_f32_16x16x32_bf16 v[84:87], v[192:195], v[176:179], v[84:87]
	v_mfma_f32_16x16x32_bf16 v[80:83], v[200:203], v[176:179], v[80:83]
	v_mfma_f32_16x16x32_bf16 v[68:71], v[192:195], v[184:187], v[68:71]
	v_mfma_f32_16x16x32_bf16 v[64:67], v[200:203], v[184:187], v[64:67]
	v_mfma_f32_16x16x32_bf16 v[116:119], v[196:199], v[164:167], v[116:119]
	v_mfma_f32_16x16x32_bf16 v[112:115], v[204:207], v[164:167], v[112:115]
	v_mfma_f32_16x16x32_bf16 v[100:103], v[196:199], v[172:175], v[100:103]
	v_mfma_f32_16x16x32_bf16 v[96:99], v[204:207], v[172:175], v[96:99]
	v_mfma_f32_16x16x32_bf16 v[84:87], v[196:199], v[180:183], v[84:87]
	v_mfma_f32_16x16x32_bf16 v[80:83], v[204:207], v[180:183], v[80:83]
	v_mfma_f32_16x16x32_bf16 v[68:71], v[196:199], v[188:191], v[68:71]
	v_mfma_f32_16x16x32_bf16 v[64:67], v[204:207], v[188:191], v[64:67]
	s_mov_b32 m0, s50
	s_barrier
	ds_read_b128 v[160:163], v147 offset:49152
	ds_read_b128 v[164:167], v147 offset:50176
	ds_read_b128 v[168:171], v147 offset:51200
	ds_read_b128 v[172:175], v147 offset:52224
	ds_read_b128 v[176:179], v147 offset:53248
	ds_read_b128 v[180:183], v147 offset:54272
	ds_read_b128 v[184:187], v147 offset:55296
	global_load_lds_dwordx4 v132, s[100:101]
	s_mov_b32 m0, s51
	ds_read_b128 v[188:191], v147 offset:56320
	global_load_lds_dwordx4 v130, s[100:101]
	s_barrier
	s_waitcnt lgkmcnt(0)
	v_mfma_f32_16x16x32_bf16 v[60:63], v[138:141], v[160:163], v[60:63]
	v_mfma_f32_16x16x32_bf16 v[56:59], v[152:155], v[160:163], v[56:59]
	v_mfma_f32_16x16x32_bf16 v[44:47], v[138:141], v[168:171], v[44:47]
	v_mfma_f32_16x16x32_bf16 v[40:43], v[152:155], v[168:171], v[40:43]
	v_mfma_f32_16x16x32_bf16 v[28:31], v[138:141], v[176:179], v[28:31]
	v_mfma_f32_16x16x32_bf16 v[24:27], v[152:155], v[176:179], v[24:27]
	v_mfma_f32_16x16x32_bf16 v[12:15], v[138:141], v[184:187], v[12:15]
	v_mfma_f32_16x16x32_bf16 v[8:11], v[152:155], v[184:187], v[8:11]
	v_mfma_f32_16x16x32_bf16 v[60:63], v[148:151], v[164:167], v[60:63]
	v_mfma_f32_16x16x32_bf16 v[56:59], v[156:159], v[164:167], v[56:59]
	v_mfma_f32_16x16x32_bf16 v[44:47], v[148:151], v[172:175], v[44:47]
	v_mfma_f32_16x16x32_bf16 v[40:43], v[156:159], v[172:175], v[40:43]
	v_mfma_f32_16x16x32_bf16 v[28:31], v[148:151], v[180:183], v[28:31]
	v_mfma_f32_16x16x32_bf16 v[24:27], v[156:159], v[180:183], v[24:27]
	v_mfma_f32_16x16x32_bf16 v[12:15], v[148:151], v[188:191], v[12:15]
	v_mfma_f32_16x16x32_bf16 v[8:11], v[156:159], v[188:191], v[8:11]
	s_barrier
	s_add_u32 s10, s22, 0xb0080
	s_addc_u32 s11, s23, 0
	s_add_i32 s22, s24, s27
	s_mov_b32 m0, s22
	s_add_i32 s59, s59, 2
	global_load_lds_dwordx4 v208, s[10:11]
	s_add_i32 m0, s22, 0x2000
	s_add_u32 s57, s57, 0x100
	s_addc_u32 s58, s58, 0
	global_load_lds_dwordx4 v128, s[10:11]
	s_mov_b64 s[10:11], s[20:21]
	s_waitcnt vmcnt(6)
	s_barrier
	v_mfma_f32_16x16x32_bf16 v[52:55], v[192:195], v[160:163], v[52:55]
	v_mfma_f32_16x16x32_bf16 v[48:51], v[200:203], v[160:163], v[48:51]
	v_mfma_f32_16x16x32_bf16 v[36:39], v[192:195], v[168:171], v[36:39]
	v_mfma_f32_16x16x32_bf16 v[32:35], v[200:203], v[168:171], v[32:35]
	v_mfma_f32_16x16x32_bf16 v[20:23], v[192:195], v[176:179], v[20:23]
	v_mfma_f32_16x16x32_bf16 v[16:19], v[200:203], v[176:179], v[16:19]
	v_mfma_f32_16x16x32_bf16 v[4:7], v[192:195], v[184:187], v[4:7]
	v_mfma_f32_16x16x32_bf16 v[0:3], v[200:203], v[184:187], v[0:3]
	v_mfma_f32_16x16x32_bf16 v[52:55], v[196:199], v[164:167], v[52:55]
	v_mfma_f32_16x16x32_bf16 v[48:51], v[204:207], v[164:167], v[48:51]
	v_mfma_f32_16x16x32_bf16 v[36:39], v[196:199], v[172:175], v[36:39]
	v_mfma_f32_16x16x32_bf16 v[32:35], v[204:207], v[172:175], v[32:35]
	v_mfma_f32_16x16x32_bf16 v[20:23], v[196:199], v[180:183], v[20:23]
	v_mfma_f32_16x16x32_bf16 v[16:19], v[204:207], v[180:183], v[16:19]
	v_mfma_f32_16x16x32_bf16 v[4:7], v[196:199], v[188:191], v[4:7]
	v_mfma_f32_16x16x32_bf16 v[0:3], v[204:207], v[188:191], v[0:3]
	s_cmp_gt_u32 s59, 41
	s_barrier
	s_cbranch_scc0 .LBB0_998
	v_lshl_add_u32 v142, s39, 8, v144
	v_lshl_or_b32 v143, s38, 8, v146
	s_and_b64 vcc, exec, s[4:5]
	s_mov_b32 s38, s53
	s_mov_b32 s39, s56
	s_mov_b64 s[20:21], s[8:9]
	s_mov_b64 s[10:11], s[6:7]
	v_lshl_add_u32 v210, v142, 10, v143
	v_lshlrev_b32_e32 v211, 2, v210
	v_lshlrev_b32_e32 v210, 1, v210
	global_load_dwordx4 v[148:151], v210, s[14:15]
	global_load_dwordx4 v[152:155], v210, s[14:15] offset:256
	v_add_u32_e32 v210, 0x8000, v210
	global_load_dwordx4 v[156:159], v210, s[14:15]
	global_load_dwordx4 v[160:163], v210, s[14:15] offset:256
	v_add_u32_e32 v210, 0x8000, v210
	global_load_dwordx4 v[164:167], v210, s[14:15]
	global_load_dwordx4 v[168:171], v210, s[14:15] offset:256
	v_add_u32_e32 v210, 0x8000, v210
	global_load_dwordx4 v[172:175], v210, s[14:15]
	global_load_dwordx4 v[176:179], v210, s[14:15] offset:256
	v_add_u32_e32 v210, 0x28000, v210
	global_load_dwordx4 v[180:183], v210, s[14:15]
	global_load_dwordx4 v[184:187], v210, s[14:15] offset:256
	v_add_u32_e32 v210, 0x8000, v210
	global_load_dwordx4 v[188:191], v210, s[14:15]
	global_load_dwordx4 v[192:195], v210, s[14:15] offset:256
	v_add_u32_e32 v210, 0x8000, v210
	global_load_dwordx4 v[196:199], v210, s[14:15]
	global_load_dwordx4 v[200:203], v210, s[14:15] offset:256
	v_add_u32_e32 v210, 0x8000, v210
	s_waitcnt vmcnt(12)
	v_lshlrev_b32_e32 v204, 16, v148
	v_and_b32_e32 v205, 0xffff0000, v148
	v_lshlrev_b32_e32 v206, 16, v149
	v_and_b32_e32 v207, 0xffff0000, v149
	v_pk_add_f32 v[124:125], v[124:125], v[204:205]
	v_pk_add_f32 v[126:127], v[126:127], v[206:207]
	v_lshlrev_b32_e32 v204, 16, v150
	v_and_b32_e32 v205, 0xffff0000, v150
	v_lshlrev_b32_e32 v206, 16, v151
	v_and_b32_e32 v207, 0xffff0000, v151
	v_pk_add_f32 v[120:121], v[120:121], v[204:205]
	v_pk_add_f32 v[122:123], v[122:123], v[206:207]
	global_store_dwordx4 v211, v[124:127], s[16:17]
	global_store_dwordx4 v211, v[120:123], s[16:17] offset:16
	v_lshlrev_b32_e32 v204, 16, v152
	v_and_b32_e32 v205, 0xffff0000, v152
	v_lshlrev_b32_e32 v206, 16, v153
	v_and_b32_e32 v207, 0xffff0000, v153
	v_pk_add_f32 v[116:117], v[116:117], v[204:205]
	v_pk_add_f32 v[118:119], v[118:119], v[206:207]
	v_lshlrev_b32_e32 v204, 16, v154
	v_and_b32_e32 v205, 0xffff0000, v154
	v_lshlrev_b32_e32 v206, 16, v155
	v_and_b32_e32 v207, 0xffff0000, v155
	v_pk_add_f32 v[112:113], v[112:113], v[204:205]
	v_pk_add_f32 v[114:115], v[114:115], v[206:207]
	global_store_dwordx4 v211, v[116:119], s[16:17] offset:512
	global_store_dwordx4 v211, v[112:115], s[16:17] offset:528
	v_add_u32_e32 v211, 0x10000, v211
	global_load_dwordx4 v[148:151], v210, s[14:15]
	global_load_dwordx4 v[152:155], v210, s[14:15] offset:256
	s_waitcnt vmcnt(16)
	v_lshlrev_b32_e32 v204, 16, v156
	v_and_b32_e32 v205, 0xffff0000, v156
	v_lshlrev_b32_e32 v206, 16, v157
	v_and_b32_e32 v207, 0xffff0000, v157
	v_pk_add_f32 v[108:109], v[108:109], v[204:205]
	v_pk_add_f32 v[110:111], v[110:111], v[206:207]
	v_lshlrev_b32_e32 v204, 16, v158
	v_and_b32_e32 v205, 0xffff0000, v158
	v_lshlrev_b32_e32 v206, 16, v159
	v_and_b32_e32 v207, 0xffff0000, v159
	v_pk_add_f32 v[104:105], v[104:105], v[204:205]
	v_pk_add_f32 v[106:107], v[106:107], v[206:207]
	global_store_dwordx4 v211, v[108:111], s[16:17]
	global_store_dwordx4 v211, v[104:107], s[16:17] offset:16
	v_lshlrev_b32_e32 v204, 16, v160
	v_and_b32_e32 v205, 0xffff0000, v160
	v_lshlrev_b32_e32 v206, 16, v161
	v_and_b32_e32 v207, 0xffff0000, v161
	v_pk_add_f32 v[100:101], v[100:101], v[204:205]
	v_pk_add_f32 v[102:103], v[102:103], v[206:207]
	v_lshlrev_b32_e32 v204, 16, v162
	v_and_b32_e32 v205, 0xffff0000, v162
	v_lshlrev_b32_e32 v206, 16, v163
	v_and_b32_e32 v207, 0xffff0000, v163
	v_pk_add_f32 v[96:97], v[96:97], v[204:205]
	v_pk_add_f32 v[98:99], v[98:99], v[206:207]
	global_store_dwordx4 v211, v[100:103], s[16:17] offset:512
	global_store_dwordx4 v211, v[96:99], s[16:17] offset:528
	v_add_u32_e32 v211, 0x10000, v211
	s_waitcnt vmcnt(18)
	v_lshlrev_b32_e32 v204, 16, v164
	v_and_b32_e32 v205, 0xffff0000, v164
	v_lshlrev_b32_e32 v206, 16, v165
	v_and_b32_e32 v207, 0xffff0000, v165
	v_pk_add_f32 v[92:93], v[92:93], v[204:205]
	v_pk_add_f32 v[94:95], v[94:95], v[206:207]
	v_lshlrev_b32_e32 v204, 16, v166
	v_and_b32_e32 v205, 0xffff0000, v166
	v_lshlrev_b32_e32 v206, 16, v167
	v_and_b32_e32 v207, 0xffff0000, v167
	v_pk_add_f32 v[88:89], v[88:89], v[204:205]
	v_pk_add_f32 v[90:91], v[90:91], v[206:207]
	global_store_dwordx4 v211, v[92:95], s[16:17]
	global_store_dwordx4 v211, v[88:91], s[16:17] offset:16
	v_lshlrev_b32_e32 v204, 16, v168
	v_and_b32_e32 v205, 0xffff0000, v168
	v_lshlrev_b32_e32 v206, 16, v169
	v_and_b32_e32 v207, 0xffff0000, v169
	v_pk_add_f32 v[84:85], v[84:85], v[204:205]
	v_pk_add_f32 v[86:87], v[86:87], v[206:207]
	v_lshlrev_b32_e32 v204, 16, v170
	v_and_b32_e32 v205, 0xffff0000, v170
	v_lshlrev_b32_e32 v206, 16, v171
	v_and_b32_e32 v207, 0xffff0000, v171
	v_pk_add_f32 v[80:81], v[80:81], v[204:205]
	v_pk_add_f32 v[82:83], v[82:83], v[206:207]
	global_store_dwordx4 v211, v[84:87], s[16:17] offset:512
	global_store_dwordx4 v211, v[80:83], s[16:17] offset:528
	v_add_u32_e32 v211, 0x10000, v211
	s_waitcnt vmcnt(20)
	v_lshlrev_b32_e32 v204, 16, v172
	v_and_b32_e32 v205, 0xffff0000, v172
	v_lshlrev_b32_e32 v206, 16, v173
	v_and_b32_e32 v207, 0xffff0000, v173
	v_pk_add_f32 v[76:77], v[76:77], v[204:205]
	v_pk_add_f32 v[78:79], v[78:79], v[206:207]
	v_lshlrev_b32_e32 v204, 16, v174
	v_and_b32_e32 v205, 0xffff0000, v174
	v_lshlrev_b32_e32 v206, 16, v175
	v_and_b32_e32 v207, 0xffff0000, v175
	v_pk_add_f32 v[72:73], v[72:73], v[204:205]
	v_pk_add_f32 v[74:75], v[74:75], v[206:207]
	global_store_dwordx4 v211, v[76:79], s[16:17]
	global_store_dwordx4 v211, v[72:75], s[16:17] offset:16
	v_lshlrev_b32_e32 v204, 16, v176
	v_and_b32_e32 v205, 0xffff0000, v176
	v_lshlrev_b32_e32 v206, 16, v177
	v_and_b32_e32 v207, 0xffff0000, v177
	v_pk_add_f32 v[68:69], v[68:69], v[204:205]
	v_pk_add_f32 v[70:71], v[70:71], v[206:207]
	v_lshlrev_b32_e32 v204, 16, v178
	v_and_b32_e32 v205, 0xffff0000, v178
	v_lshlrev_b32_e32 v206, 16, v179
	v_and_b32_e32 v207, 0xffff0000, v179
	v_pk_add_f32 v[64:65], v[64:65], v[204:205]
	v_pk_add_f32 v[66:67], v[66:67], v[206:207]
	global_store_dwordx4 v211, v[68:71], s[16:17] offset:512
	global_store_dwordx4 v211, v[64:67], s[16:17] offset:528
	v_add_u32_e32 v211, 0x50000, v211
	s_waitcnt vmcnt(22)
	v_lshlrev_b32_e32 v204, 16, v180
	v_and_b32_e32 v205, 0xffff0000, v180
	v_lshlrev_b32_e32 v206, 16, v181
	v_and_b32_e32 v207, 0xffff0000, v181
	v_pk_add_f32 v[60:61], v[60:61], v[204:205]
	v_pk_add_f32 v[62:63], v[62:63], v[206:207]
	v_lshlrev_b32_e32 v204, 16, v182
	v_and_b32_e32 v205, 0xffff0000, v182
	v_lshlrev_b32_e32 v206, 16, v183
	v_and_b32_e32 v207, 0xffff0000, v183
	v_pk_add_f32 v[56:57], v[56:57], v[204:205]
	v_pk_add_f32 v[58:59], v[58:59], v[206:207]
	global_store_dwordx4 v211, v[60:63], s[16:17]
	global_store_dwordx4 v211, v[56:59], s[16:17] offset:16
	v_lshlrev_b32_e32 v204, 16, v184
	v_and_b32_e32 v205, 0xffff0000, v184
	v_lshlrev_b32_e32 v206, 16, v185
	v_and_b32_e32 v207, 0xffff0000, v185
	v_pk_add_f32 v[52:53], v[52:53], v[204:205]
	v_pk_add_f32 v[54:55], v[54:55], v[206:207]
	v_lshlrev_b32_e32 v204, 16, v186
	v_and_b32_e32 v205, 0xffff0000, v186
	v_lshlrev_b32_e32 v206, 16, v187
	v_and_b32_e32 v207, 0xffff0000, v187
	v_pk_add_f32 v[48:49], v[48:49], v[204:205]
	v_pk_add_f32 v[50:51], v[50:51], v[206:207]
	global_store_dwordx4 v211, v[52:55], s[16:17] offset:512
	global_store_dwordx4 v211, v[48:51], s[16:17] offset:528
	v_add_u32_e32 v211, 0x10000, v211
	s_waitcnt vmcnt(24)
	v_lshlrev_b32_e32 v204, 16, v188
	v_and_b32_e32 v205, 0xffff0000, v188
	v_lshlrev_b32_e32 v206, 16, v189
	v_and_b32_e32 v207, 0xffff0000, v189
	v_pk_add_f32 v[44:45], v[44:45], v[204:205]
	v_pk_add_f32 v[46:47], v[46:47], v[206:207]
	v_lshlrev_b32_e32 v204, 16, v190
	v_and_b32_e32 v205, 0xffff0000, v190
	v_lshlrev_b32_e32 v206, 16, v191
	v_and_b32_e32 v207, 0xffff0000, v191
	v_pk_add_f32 v[40:41], v[40:41], v[204:205]
	v_pk_add_f32 v[42:43], v[42:43], v[206:207]
	global_store_dwordx4 v211, v[44:47], s[16:17]
	global_store_dwordx4 v211, v[40:43], s[16:17] offset:16
	v_lshlrev_b32_e32 v204, 16, v192
	v_and_b32_e32 v205, 0xffff0000, v192
	v_lshlrev_b32_e32 v206, 16, v193
	v_and_b32_e32 v207, 0xffff0000, v193
	v_pk_add_f32 v[36:37], v[36:37], v[204:205]
	v_pk_add_f32 v[38:39], v[38:39], v[206:207]
	v_lshlrev_b32_e32 v204, 16, v194
	v_and_b32_e32 v205, 0xffff0000, v194
	v_lshlrev_b32_e32 v206, 16, v195
	v_and_b32_e32 v207, 0xffff0000, v195
	v_pk_add_f32 v[32:33], v[32:33], v[204:205]
	v_pk_add_f32 v[34:35], v[34:35], v[206:207]
	global_store_dwordx4 v211, v[36:39], s[16:17] offset:512
	global_store_dwordx4 v211, v[32:35], s[16:17] offset:528
	v_add_u32_e32 v211, 0x10000, v211
	s_waitcnt vmcnt(26)
	v_lshlrev_b32_e32 v204, 16, v196
	v_and_b32_e32 v205, 0xffff0000, v196
	v_lshlrev_b32_e32 v206, 16, v197
	v_and_b32_e32 v207, 0xffff0000, v197
	v_pk_add_f32 v[28:29], v[28:29], v[204:205]
	v_pk_add_f32 v[30:31], v[30:31], v[206:207]
	v_lshlrev_b32_e32 v204, 16, v198
	v_and_b32_e32 v205, 0xffff0000, v198
	v_lshlrev_b32_e32 v206, 16, v199
	v_and_b32_e32 v207, 0xffff0000, v199
	v_pk_add_f32 v[24:25], v[24:25], v[204:205]
	v_pk_add_f32 v[26:27], v[26:27], v[206:207]
	global_store_dwordx4 v211, v[28:31], s[16:17]
	global_store_dwordx4 v211, v[24:27], s[16:17] offset:16
	v_lshlrev_b32_e32 v204, 16, v200
	v_and_b32_e32 v205, 0xffff0000, v200
	v_lshlrev_b32_e32 v206, 16, v201
	v_and_b32_e32 v207, 0xffff0000, v201
	v_pk_add_f32 v[20:21], v[20:21], v[204:205]
	v_pk_add_f32 v[22:23], v[22:23], v[206:207]
	v_lshlrev_b32_e32 v204, 16, v202
	v_and_b32_e32 v205, 0xffff0000, v202
	v_lshlrev_b32_e32 v206, 16, v203
	v_and_b32_e32 v207, 0xffff0000, v203
	v_pk_add_f32 v[16:17], v[16:17], v[204:205]
	v_pk_add_f32 v[18:19], v[18:19], v[206:207]
	global_store_dwordx4 v211, v[20:23], s[16:17] offset:512
	global_store_dwordx4 v211, v[16:19], s[16:17] offset:528
	v_add_u32_e32 v211, 0x10000, v211
	s_waitcnt vmcnt(24)
	v_lshlrev_b32_e32 v204, 16, v148
	v_and_b32_e32 v205, 0xffff0000, v148
	v_lshlrev_b32_e32 v206, 16, v149
	v_and_b32_e32 v207, 0xffff0000, v149
	v_pk_add_f32 v[12:13], v[12:13], v[204:205]
	v_pk_add_f32 v[14:15], v[14:15], v[206:207]
	v_lshlrev_b32_e32 v204, 16, v150
	v_and_b32_e32 v205, 0xffff0000, v150
	v_lshlrev_b32_e32 v206, 16, v151
	v_and_b32_e32 v207, 0xffff0000, v151
	v_pk_add_f32 v[8:9], v[8:9], v[204:205]
	v_pk_add_f32 v[10:11], v[10:11], v[206:207]
	global_store_dwordx4 v211, v[12:15], s[16:17]
	global_store_dwordx4 v211, v[8:11], s[16:17] offset:16
	v_lshlrev_b32_e32 v204, 16, v152
	v_and_b32_e32 v205, 0xffff0000, v152
	v_lshlrev_b32_e32 v206, 16, v153
	v_and_b32_e32 v207, 0xffff0000, v153
	v_pk_add_f32 v[4:5], v[4:5], v[204:205]
	v_pk_add_f32 v[6:7], v[6:7], v[206:207]
	v_lshlrev_b32_e32 v204, 16, v154
	v_and_b32_e32 v205, 0xffff0000, v154
	v_lshlrev_b32_e32 v206, 16, v155
	v_and_b32_e32 v207, 0xffff0000, v155
	v_pk_add_f32 v[0:1], v[0:1], v[204:205]
	v_pk_add_f32 v[2:3], v[2:3], v[206:207]
	global_store_dwordx4 v211, v[4:7], s[16:17] offset:512
	global_store_dwordx4 v211, v[0:3], s[16:17] offset:528
	v_add_u32_e32 v211, 0x10000, v211
	s_cbranch_vccz .LBB0_987
	s_waitcnt vmcnt(0)
	s_cmpk_gt_u32 s26, 0xff
	s_cbranch_scc1 .LBB0_1002
	s_barrier

.LBB0_1021:
	s_add_u32 s22, s20, 0x100
	s_addc_u32 s23, s21, 0
	s_add_i32 s62, 0, 0x10000
	v_add_u32_e32 v154, s62, v143
	ds_read_b128 v[138:141], v154
	ds_read_b128 v[146:149], v154 offset:1024
	ds_read_b128 v[150:153], v154 offset:2048
	ds_read_b128 v[154:157], v154 offset:3072
	s_cmp_eq_u32 s61, 40
	s_cselect_b32 s27, s9, s23
	s_cselect_b32 s26, s8, s22
	s_cselect_b32 s25, s11, s60
	s_cselect_b32 s24, s10, s39
	s_add_i32 m0, s46, 0xc000
	ds_read_b128 v[158:161], v145
	ds_read_b128 v[162:165], v145 offset:1024
	ds_read_b128 v[166:169], v145 offset:2048
	ds_read_b128 v[170:173], v145 offset:3072
	ds_read_b128 v[174:177], v145 offset:4096
	ds_read_b128 v[178:181], v145 offset:5120
	ds_read_b128 v[182:185], v145 offset:6144
	global_load_lds_dwordx4 v134, s[20:21]
	s_add_i32 m0, s46, 0xe000
	ds_read_b128 v[186:189], v145 offset:7168
	global_load_lds_dwordx4 v136, s[20:21]
	s_waitcnt lgkmcnt(8)
	s_barrier
	s_waitcnt lgkmcnt(0)
	v_mfma_f32_16x16x32_bf16 v[124:127], v[138:141], v[158:161], v[124:127]
	v_mfma_f32_16x16x32_bf16 v[120:123], v[150:153], v[158:161], v[120:123]
	v_mfma_f32_16x16x32_bf16 v[108:111], v[138:141], v[166:169], v[108:111]
	v_mfma_f32_16x16x32_bf16 v[104:107], v[150:153], v[166:169], v[104:107]
	v_mfma_f32_16x16x32_bf16 v[92:95], v[138:141], v[174:177], v[92:95]
	v_mfma_f32_16x16x32_bf16 v[88:91], v[150:153], v[174:177], v[88:91]
	v_mfma_f32_16x16x32_bf16 v[76:79], v[138:141], v[182:185], v[76:79]
	v_mfma_f32_16x16x32_bf16 v[72:75], v[150:153], v[182:185], v[72:75]
	v_mfma_f32_16x16x32_bf16 v[124:127], v[146:149], v[162:165], v[124:127]
	v_mfma_f32_16x16x32_bf16 v[120:123], v[154:157], v[162:165], v[120:123]
	v_mfma_f32_16x16x32_bf16 v[108:111], v[146:149], v[170:173], v[108:111]
	v_mfma_f32_16x16x32_bf16 v[104:107], v[154:157], v[170:173], v[104:107]
	v_mfma_f32_16x16x32_bf16 v[92:95], v[146:149], v[178:181], v[92:95]
	v_mfma_f32_16x16x32_bf16 v[88:91], v[154:157], v[178:181], v[88:91]
	v_mfma_f32_16x16x32_bf16 v[76:79], v[146:149], v[186:189], v[76:79]
	v_mfma_f32_16x16x32_bf16 v[72:75], v[154:157], v[186:189], v[72:75]
	s_barrier
	s_add_i32 s63, 0, 0x14000
	s_add_i32 s20, s62, s35
	v_add_u32_e32 v202, s63, v143
	s_add_u32 s98, s24, s40
	s_addc_u32 s99, s25, s41
	s_mov_b32 m0, s20
	ds_read_b128 v[190:193], v202
	ds_read_b128 v[194:197], v202 offset:1024
	ds_read_b128 v[198:201], v202 offset:2048
	global_load_lds_dwordx4 v208, s[24:25]
	s_add_i32 m0, s20, 0x2000
	ds_read_b128 v[202:205], v202 offset:3072
	global_load_lds_dwordx4 v128, s[24:25]
	s_barrier
	s_waitcnt lgkmcnt(0)
	v_mfma_f32_16x16x32_bf16 v[116:119], v[190:193], v[158:161], v[116:119]
	v_mfma_f32_16x16x32_bf16 v[112:115], v[198:201], v[158:161], v[112:115]
	v_mfma_f32_16x16x32_bf16 v[100:103], v[190:193], v[166:169], v[100:103]
	v_mfma_f32_16x16x32_bf16 v[96:99], v[198:201], v[166:169], v[96:99]
	v_mfma_f32_16x16x32_bf16 v[84:87], v[190:193], v[174:177], v[84:87]
	v_mfma_f32_16x16x32_bf16 v[80:83], v[198:201], v[174:177], v[80:83]
	v_mfma_f32_16x16x32_bf16 v[68:71], v[190:193], v[182:185], v[68:71]
	v_mfma_f32_16x16x32_bf16 v[64:67], v[198:201], v[182:185], v[64:67]
	v_mfma_f32_16x16x32_bf16 v[116:119], v[194:197], v[162:165], v[116:119]
	v_mfma_f32_16x16x32_bf16 v[112:115], v[202:205], v[162:165], v[112:115]
	v_mfma_f32_16x16x32_bf16 v[100:103], v[194:197], v[170:173], v[100:103]
	v_mfma_f32_16x16x32_bf16 v[96:99], v[202:205], v[170:173], v[96:99]
	v_mfma_f32_16x16x32_bf16 v[84:87], v[194:197], v[178:181], v[84:87]
	v_mfma_f32_16x16x32_bf16 v[80:83], v[202:205], v[178:181], v[80:83]
	v_mfma_f32_16x16x32_bf16 v[68:71], v[194:197], v[186:189], v[68:71]
	v_mfma_f32_16x16x32_bf16 v[64:67], v[202:205], v[186:189], v[64:67]
	s_mov_b32 m0, s46
	s_add_u32 s100, s26, s40
	s_addc_u32 s101, s27, s41
	s_barrier
	ds_read_b128 v[158:161], v145 offset:16384
	ds_read_b128 v[162:165], v145 offset:17408
	ds_read_b128 v[166:169], v145 offset:18432
	ds_read_b128 v[170:173], v145 offset:19456
	ds_read_b128 v[174:177], v145 offset:20480
	ds_read_b128 v[178:181], v145 offset:21504
	ds_read_b128 v[182:185], v145 offset:22528
	global_load_lds_dwordx4 v132, s[26:27]
	s_mov_b32 m0, s47
	ds_read_b128 v[186:189], v145 offset:23552
	global_load_lds_dwordx4 v130, s[26:27]
	s_barrier
	s_waitcnt lgkmcnt(0)
	v_mfma_f32_16x16x32_bf16 v[60:63], v[138:141], v[158:161], v[60:63]
	v_mfma_f32_16x16x32_bf16 v[56:59], v[150:153], v[158:161], v[56:59]
	v_mfma_f32_16x16x32_bf16 v[44:47], v[138:141], v[166:169], v[44:47]
	v_mfma_f32_16x16x32_bf16 v[40:43], v[150:153], v[166:169], v[40:43]
	v_mfma_f32_16x16x32_bf16 v[28:31], v[138:141], v[174:177], v[28:31]
	v_mfma_f32_16x16x32_bf16 v[24:27], v[150:153], v[174:177], v[24:27]
	v_mfma_f32_16x16x32_bf16 v[12:15], v[138:141], v[182:185], v[12:15]
	v_mfma_f32_16x16x32_bf16 v[8:11], v[150:153], v[182:185], v[8:11]
	v_mfma_f32_16x16x32_bf16 v[60:63], v[146:149], v[162:165], v[60:63]
	v_mfma_f32_16x16x32_bf16 v[56:59], v[154:157], v[162:165], v[56:59]
	v_mfma_f32_16x16x32_bf16 v[44:47], v[146:149], v[170:173], v[44:47]
	v_mfma_f32_16x16x32_bf16 v[40:43], v[154:157], v[170:173], v[40:43]
	v_mfma_f32_16x16x32_bf16 v[28:31], v[146:149], v[178:181], v[28:31]
	v_mfma_f32_16x16x32_bf16 v[24:27], v[154:157], v[178:181], v[24:27]
	v_mfma_f32_16x16x32_bf16 v[12:15], v[146:149], v[186:189], v[12:15]
	v_mfma_f32_16x16x32_bf16 v[8:11], v[154:157], v[186:189], v[8:11]
	s_barrier
	s_add_u32 s20, s24, 0xb0000
	s_addc_u32 s21, s25, 0
	s_add_i32 s62, s63, s35
	s_mov_b32 m0, s62
	s_nop 0
	global_load_lds_dwordx4 v208, s[20:21]
	s_add_i32 m0, s62, 0x2000
	s_nop 0
	global_load_lds_dwordx4 v128, s[20:21]
	s_waitcnt vmcnt(6)
	s_barrier
	v_mfma_f32_16x16x32_bf16 v[52:55], v[190:193], v[158:161], v[52:55]
	v_mfma_f32_16x16x32_bf16 v[48:51], v[198:201], v[158:161], v[48:51]
	v_mfma_f32_16x16x32_bf16 v[36:39], v[190:193], v[166:169], v[36:39]
	v_mfma_f32_16x16x32_bf16 v[32:35], v[198:201], v[166:169], v[32:35]
	v_mfma_f32_16x16x32_bf16 v[20:23], v[190:193], v[174:177], v[20:23]
	v_mfma_f32_16x16x32_bf16 v[16:19], v[198:201], v[174:177], v[16:19]
	v_mfma_f32_16x16x32_bf16 v[4:7], v[190:193], v[182:185], v[4:7]
	v_mfma_f32_16x16x32_bf16 v[0:3], v[198:201], v[182:185], v[0:3]
	v_mfma_f32_16x16x32_bf16 v[52:55], v[194:197], v[162:165], v[52:55]
	v_mfma_f32_16x16x32_bf16 v[48:51], v[202:205], v[162:165], v[48:51]
	v_mfma_f32_16x16x32_bf16 v[36:39], v[194:197], v[170:173], v[36:39]
	v_mfma_f32_16x16x32_bf16 v[32:35], v[202:205], v[170:173], v[32:35]
	v_mfma_f32_16x16x32_bf16 v[20:23], v[194:197], v[178:181], v[20:23]
	v_mfma_f32_16x16x32_bf16 v[16:19], v[202:205], v[178:181], v[16:19]
	v_mfma_f32_16x16x32_bf16 v[4:7], v[194:197], v[186:189], v[4:7]
	v_mfma_f32_16x16x32_bf16 v[0:3], v[202:205], v[186:189], v[0:3]
	s_add_i32 s62, 0, 0x18000
	v_add_u32_e32 v154, s62, v143
	s_barrier
	ds_read_b128 v[138:141], v154
	ds_read_b128 v[146:149], v154 offset:1024
	ds_read_b128 v[150:153], v154 offset:2048
	ds_read_b128 v[154:157], v154 offset:3072
	s_add_u32 s20, s26, 0xb0000
	s_addc_u32 s21, s27, 0
	s_mov_b32 m0, s50
	ds_read_b128 v[158:161], v145 offset:32768
	ds_read_b128 v[162:165], v145 offset:33792
	ds_read_b128 v[166:169], v145 offset:34816
	ds_read_b128 v[170:173], v145 offset:35840
	ds_read_b128 v[174:177], v145 offset:36864
	ds_read_b128 v[178:181], v145 offset:37888
	ds_read_b128 v[182:185], v145 offset:38912
	global_load_lds_dwordx4 v132, s[20:21]
	s_mov_b32 m0, s51
	ds_read_b128 v[186:189], v145 offset:39936
	global_load_lds_dwordx4 v130, s[20:21]
	s_waitcnt lgkmcnt(8)
	s_barrier
	s_waitcnt lgkmcnt(0)
	v_mfma_f32_16x16x32_bf16 v[124:127], v[138:141], v[158:161], v[124:127]
	v_mfma_f32_16x16x32_bf16 v[120:123], v[150:153], v[158:161], v[120:123]
	v_mfma_f32_16x16x32_bf16 v[108:111], v[138:141], v[166:169], v[108:111]
	v_mfma_f32_16x16x32_bf16 v[104:107], v[150:153], v[166:169], v[104:107]
	v_mfma_f32_16x16x32_bf16 v[92:95], v[138:141], v[174:177], v[92:95]
	v_mfma_f32_16x16x32_bf16 v[88:91], v[150:153], v[174:177], v[88:91]
	v_mfma_f32_16x16x32_bf16 v[76:79], v[138:141], v[182:185], v[76:79]
	v_mfma_f32_16x16x32_bf16 v[72:75], v[150:153], v[182:185], v[72:75]
	v_mfma_f32_16x16x32_bf16 v[124:127], v[146:149], v[162:165], v[124:127]
	v_mfma_f32_16x16x32_bf16 v[120:123], v[154:157], v[162:165], v[120:123]
	v_mfma_f32_16x16x32_bf16 v[108:111], v[146:149], v[170:173], v[108:111]
	v_mfma_f32_16x16x32_bf16 v[104:107], v[154:157], v[170:173], v[104:107]
	v_mfma_f32_16x16x32_bf16 v[92:95], v[146:149], v[178:181], v[92:95]
	v_mfma_f32_16x16x32_bf16 v[88:91], v[154:157], v[178:181], v[88:91]
	v_mfma_f32_16x16x32_bf16 v[76:79], v[146:149], v[186:189], v[76:79]
	v_mfma_f32_16x16x32_bf16 v[72:75], v[154:157], v[186:189], v[72:75]
	s_barrier
	s_add_i32 s26, 0, 0x1c000
	s_add_i32 s20, s62, s35
	v_add_u32_e32 v202, s26, v143
	s_mov_b32 m0, s20
	ds_read_b128 v[190:193], v202
	ds_read_b128 v[194:197], v202 offset:1024
	ds_read_b128 v[198:201], v202 offset:2048
	global_load_lds_dwordx4 v208, s[98:99]
	s_add_i32 m0, s20, 0x2000
	ds_read_b128 v[202:205], v202 offset:3072
	global_load_lds_dwordx4 v128, s[98:99]
	s_barrier
	s_waitcnt lgkmcnt(0)
	v_mfma_f32_16x16x32_bf16 v[116:119], v[190:193], v[158:161], v[116:119]
	v_mfma_f32_16x16x32_bf16 v[112:115], v[198:201], v[158:161], v[112:115]
	v_mfma_f32_16x16x32_bf16 v[100:103], v[190:193], v[166:169], v[100:103]
	v_mfma_f32_16x16x32_bf16 v[96:99], v[198:201], v[166:169], v[96:99]
	v_mfma_f32_16x16x32_bf16 v[84:87], v[190:193], v[174:177], v[84:87]
	v_mfma_f32_16x16x32_bf16 v[80:83], v[198:201], v[174:177], v[80:83]
	v_mfma_f32_16x16x32_bf16 v[68:71], v[190:193], v[182:185], v[68:71]
	v_mfma_f32_16x16x32_bf16 v[64:67], v[198:201], v[182:185], v[64:67]
	v_mfma_f32_16x16x32_bf16 v[116:119], v[194:197], v[162:165], v[116:119]
	v_mfma_f32_16x16x32_bf16 v[112:115], v[202:205], v[162:165], v[112:115]
	v_mfma_f32_16x16x32_bf16 v[100:103], v[194:197], v[170:173], v[100:103]
	v_mfma_f32_16x16x32_bf16 v[96:99], v[202:205], v[170:173], v[96:99]
	v_mfma_f32_16x16x32_bf16 v[84:87], v[194:197], v[178:181], v[84:87]
	v_mfma_f32_16x16x32_bf16 v[80:83], v[202:205], v[178:181], v[80:83]
	v_mfma_f32_16x16x32_bf16 v[68:71], v[194:197], v[186:189], v[68:71]
	v_mfma_f32_16x16x32_bf16 v[64:67], v[202:205], v[186:189], v[64:67]
	s_mov_b32 m0, s53
	s_barrier
	ds_read_b128 v[158:161], v145 offset:49152
	ds_read_b128 v[162:165], v145 offset:50176
	ds_read_b128 v[166:169], v145 offset:51200
	ds_read_b128 v[170:173], v145 offset:52224
	ds_read_b128 v[174:177], v145 offset:53248
	ds_read_b128 v[178:181], v145 offset:54272
	ds_read_b128 v[182:185], v145 offset:55296
	global_load_lds_dwordx4 v132, s[100:101]
	s_mov_b32 m0, s56
	ds_read_b128 v[186:189], v145 offset:56320
	global_load_lds_dwordx4 v130, s[100:101]
	s_barrier
	s_waitcnt lgkmcnt(0)
	v_mfma_f32_16x16x32_bf16 v[60:63], v[138:141], v[158:161], v[60:63]
	v_mfma_f32_16x16x32_bf16 v[56:59], v[150:153], v[158:161], v[56:59]
	v_mfma_f32_16x16x32_bf16 v[44:47], v[138:141], v[166:169], v[44:47]
	v_mfma_f32_16x16x32_bf16 v[40:43], v[150:153], v[166:169], v[40:43]
	v_mfma_f32_16x16x32_bf16 v[28:31], v[138:141], v[174:177], v[28:31]
	v_mfma_f32_16x16x32_bf16 v[24:27], v[150:153], v[174:177], v[24:27]
	v_mfma_f32_16x16x32_bf16 v[12:15], v[138:141], v[182:185], v[12:15]
	v_mfma_f32_16x16x32_bf16 v[8:11], v[150:153], v[182:185], v[8:11]
	v_mfma_f32_16x16x32_bf16 v[60:63], v[146:149], v[162:165], v[60:63]
	v_mfma_f32_16x16x32_bf16 v[56:59], v[154:157], v[162:165], v[56:59]
	v_mfma_f32_16x16x32_bf16 v[44:47], v[146:149], v[170:173], v[44:47]
	v_mfma_f32_16x16x32_bf16 v[40:43], v[154:157], v[170:173], v[40:43]
	v_mfma_f32_16x16x32_bf16 v[28:31], v[146:149], v[178:181], v[28:31]
	v_mfma_f32_16x16x32_bf16 v[24:27], v[154:157], v[178:181], v[24:27]
	v_mfma_f32_16x16x32_bf16 v[12:15], v[146:149], v[186:189], v[12:15]
	v_mfma_f32_16x16x32_bf16 v[8:11], v[154:157], v[186:189], v[8:11]
	s_barrier
	s_add_u32 s20, s24, 0xb0080
	s_addc_u32 s21, s25, 0
	s_add_i32 s24, s26, s35
	s_mov_b32 m0, s24
	s_add_i32 s61, s61, 2
	global_load_lds_dwordx4 v208, s[20:21]
	s_add_i32 m0, s24, 0x2000
	s_add_u32 s39, s39, 0x100
	s_addc_u32 s60, s60, 0
	global_load_lds_dwordx4 v128, s[20:21]
	s_mov_b64 s[20:21], s[22:23]
	s_waitcnt vmcnt(6)
	s_barrier
	v_mfma_f32_16x16x32_bf16 v[52:55], v[190:193], v[158:161], v[52:55]
	v_mfma_f32_16x16x32_bf16 v[48:51], v[198:201], v[158:161], v[48:51]
	v_mfma_f32_16x16x32_bf16 v[36:39], v[190:193], v[166:169], v[36:39]
	v_mfma_f32_16x16x32_bf16 v[32:35], v[198:201], v[166:169], v[32:35]
	v_mfma_f32_16x16x32_bf16 v[20:23], v[190:193], v[174:177], v[20:23]
	v_mfma_f32_16x16x32_bf16 v[16:19], v[198:201], v[174:177], v[16:19]
	v_mfma_f32_16x16x32_bf16 v[4:7], v[190:193], v[182:185], v[4:7]
	v_mfma_f32_16x16x32_bf16 v[0:3], v[198:201], v[182:185], v[0:3]
	v_mfma_f32_16x16x32_bf16 v[52:55], v[194:197], v[162:165], v[52:55]
	v_mfma_f32_16x16x32_bf16 v[48:51], v[202:205], v[162:165], v[48:51]
	v_mfma_f32_16x16x32_bf16 v[36:39], v[194:197], v[170:173], v[36:39]
	v_mfma_f32_16x16x32_bf16 v[32:35], v[202:205], v[170:173], v[32:35]
	v_mfma_f32_16x16x32_bf16 v[20:23], v[194:197], v[178:181], v[20:23]
	v_mfma_f32_16x16x32_bf16 v[16:19], v[202:205], v[178:181], v[16:19]
	v_mfma_f32_16x16x32_bf16 v[4:7], v[194:197], v[186:189], v[4:7]
	v_mfma_f32_16x16x32_bf16 v[0:3], v[202:205], v[186:189], v[0:3]
	s_cmp_gt_u32 s61, 41
	s_barrier
	s_cbranch_scc0 .LBB0_1021
	v_lshl_add_u32 v140, s38, 8, v142
	v_lshl_or_b32 v141, s36, 8, v144
	s_lshl_b32 s20, s36, 2
	s_ashr_i32 s21, s20, 31
	s_lshl_b32 s36, s52, 2
	v_lshlrev_b32_e32 v206, 11, v140
	v_lshl_add_u32 v206, v141, 1, v206
	v_lshl_add_u32 v210, v140, 6, s36
	v_lshl_add_u32 v210, s20, 2, v210
	v_mov_b32_e32 v207, v206
	global_load_dwordx4 v[146:149], v206, s[14:15]
	global_load_dwordx4 v[150:153], v206, s[14:15] offset:256
	v_add_u32_e32 v206, 0x8000, v206
	global_load_dwordx4 v[154:157], v206, s[14:15]
	global_load_dwordx4 v[158:161], v206, s[14:15] offset:256
	v_add_u32_e32 v206, 0x8000, v206
	global_load_dwordx4 v[162:165], v206, s[14:15]
	global_load_dwordx4 v[166:169], v206, s[14:15] offset:256
	v_add_u32_e32 v206, 0x8000, v206
	global_load_dwordx4 v[170:173], v206, s[14:15]
	global_load_dwordx4 v[174:177], v206, s[14:15] offset:256
	v_add_u32_e32 v206, 0x28000, v206
	global_load_dwordx4 v[178:181], v206, s[14:15]
	global_load_dwordx4 v[182:185], v206, s[14:15] offset:256
	v_add_u32_e32 v206, 0x8000, v206
	global_load_dwordx4 v[186:189], v206, s[14:15]
	global_load_dwordx4 v[190:193], v206, s[14:15] offset:256
	v_add_u32_e32 v206, 0x8000, v206
	global_load_dwordx4 v[194:197], v206, s[14:15]
	global_load_dwordx4 v[198:201], v206, s[14:15] offset:256
	v_add_u32_e32 v206, 0x8000, v206
	s_waitcnt vmcnt(12)
	v_lshlrev_b32_e32 v202, 16, v146
	v_and_b32_e32 v203, 0xffff0000, v146
	v_lshlrev_b32_e32 v204, 16, v147
	v_and_b32_e32 v205, 0xffff0000, v147
	v_pk_add_f32 v[124:125], v[124:125], v[202:203]
	v_pk_add_f32 v[126:127], v[126:127], v[204:205]
	v_lshlrev_b32_e32 v202, 16, v148
	v_and_b32_e32 v203, 0xffff0000, v148
	v_lshlrev_b32_e32 v204, 16, v149
	v_and_b32_e32 v205, 0xffff0000, v149
	v_pk_add_f32 v[120:121], v[120:121], v[202:203]
	v_pk_add_f32 v[122:123], v[122:123], v[204:205]
	v_cvt_pk_bf16_f32 v146, v124, v125
	v_cvt_pk_bf16_f32 v147, v126, v127
	v_cvt_pk_bf16_f32 v148, v120, v121
	v_cvt_pk_bf16_f32 v149, v122, v123
	v_pk_mul_f32 v[138:139], v[124:125], v[124:125]
	global_store_dwordx4 v207, v[146:149], s[14:15]
	v_pk_fma_f32 v[138:139], v[126:127], v[126:127], v[138:139]
	v_pk_fma_f32 v[138:139], v[120:121], v[120:121], v[138:139]
	v_pk_fma_f32 v[138:139], v[122:123], v[122:123], v[138:139]
	v_lshlrev_b32_e32 v202, 16, v150
	v_and_b32_e32 v203, 0xffff0000, v150
	v_lshlrev_b32_e32 v204, 16, v151
	v_and_b32_e32 v205, 0xffff0000, v151
	v_pk_add_f32 v[116:117], v[116:117], v[202:203]
	v_pk_add_f32 v[118:119], v[118:119], v[204:205]
	v_lshlrev_b32_e32 v202, 16, v152
	v_and_b32_e32 v203, 0xffff0000, v152
	v_lshlrev_b32_e32 v204, 16, v153
	v_and_b32_e32 v205, 0xffff0000, v153
	v_pk_add_f32 v[112:113], v[112:113], v[202:203]
	v_pk_add_f32 v[114:115], v[114:115], v[204:205]
	v_cvt_pk_bf16_f32 v150, v116, v117
	v_cvt_pk_bf16_f32 v151, v118, v119
	v_cvt_pk_bf16_f32 v152, v112, v113
	v_cvt_pk_bf16_f32 v153, v114, v115
	v_pk_fma_f32 v[138:139], v[116:117], v[116:117], v[138:139]
	global_store_dwordx4 v207, v[150:153], s[14:15] offset:256
	v_pk_fma_f32 v[138:139], v[118:119], v[118:119], v[138:139]
	v_pk_fma_f32 v[138:139], v[112:113], v[112:113], v[138:139]
	v_pk_fma_f32 v[138:139], v[114:115], v[114:115], v[138:139]
	v_add_f32_e32 v214, v138, v139
	v_add_u32_e32 v207, 0x8000, v207
	v_mov_b32_e32 v215, v214
	s_nop 1
	v_permlane16_swap_b32_e32 v214, v215
	s_nop 0
	v_add_f32_e32 v214, v214, v215
	v_mov_b32_e32 v215, v214
	s_nop 1
	v_permlane32_swap_b32_e32 v214, v215
	s_nop 0
	v_add_f32_e32 v214, v214, v215
	s_and_saveexec_b64 s[22:23], s[4:5]
	global_store_dword v210, v214, s[16:17]
	s_mov_b64 exec, s[22:23]
	global_load_dwordx4 v[146:149], v206, s[14:15]
	global_load_dwordx4 v[150:153], v206, s[14:15] offset:256
	s_waitcnt vmcnt(15)
	v_lshlrev_b32_e32 v202, 16, v154
	v_and_b32_e32 v203, 0xffff0000, v154
	v_lshlrev_b32_e32 v204, 16, v155
	v_and_b32_e32 v205, 0xffff0000, v155
	v_pk_add_f32 v[108:109], v[108:109], v[202:203]
	v_pk_add_f32 v[110:111], v[110:111], v[204:205]
	v_lshlrev_b32_e32 v202, 16, v156
	v_and_b32_e32 v203, 0xffff0000, v156
	v_lshlrev_b32_e32 v204, 16, v157
	v_and_b32_e32 v205, 0xffff0000, v157
	v_pk_add_f32 v[104:105], v[104:105], v[202:203]
	v_pk_add_f32 v[106:107], v[106:107], v[204:205]
	v_cvt_pk_bf16_f32 v154, v108, v109
	v_cvt_pk_bf16_f32 v155, v110, v111
	v_cvt_pk_bf16_f32 v156, v104, v105
	v_cvt_pk_bf16_f32 v157, v106, v107
	v_pk_mul_f32 v[138:139], v[108:109], v[108:109]
	global_store_dwordx4 v207, v[154:157], s[14:15]
	v_pk_fma_f32 v[138:139], v[110:111], v[110:111], v[138:139]
	v_pk_fma_f32 v[138:139], v[104:105], v[104:105], v[138:139]
	v_pk_fma_f32 v[138:139], v[106:107], v[106:107], v[138:139]
	v_lshlrev_b32_e32 v202, 16, v158
	v_and_b32_e32 v203, 0xffff0000, v158
	v_lshlrev_b32_e32 v204, 16, v159
	v_and_b32_e32 v205, 0xffff0000, v159
	v_pk_add_f32 v[100:101], v[100:101], v[202:203]
	v_pk_add_f32 v[102:103], v[102:103], v[204:205]
	v_lshlrev_b32_e32 v202, 16, v160
	v_and_b32_e32 v203, 0xffff0000, v160
	v_lshlrev_b32_e32 v204, 16, v161
	v_and_b32_e32 v205, 0xffff0000, v161
	v_pk_add_f32 v[96:97], v[96:97], v[202:203]
	v_pk_add_f32 v[98:99], v[98:99], v[204:205]
	v_cvt_pk_bf16_f32 v158, v100, v101
	v_cvt_pk_bf16_f32 v159, v102, v103
	v_cvt_pk_bf16_f32 v160, v96, v97
	v_cvt_pk_bf16_f32 v161, v98, v99
	v_pk_fma_f32 v[138:139], v[100:101], v[100:101], v[138:139]
	global_store_dwordx4 v207, v[158:161], s[14:15] offset:256
	v_pk_fma_f32 v[138:139], v[102:103], v[102:103], v[138:139]
	v_pk_fma_f32 v[138:139], v[96:97], v[96:97], v[138:139]
	v_pk_fma_f32 v[138:139], v[98:99], v[98:99], v[138:139]
	v_add_f32_e32 v214, v138, v139
	v_add_u32_e32 v207, 0x8000, v207
	v_mov_b32_e32 v215, v214
	s_nop 1
	v_permlane16_swap_b32_e32 v214, v215
	s_nop 0
	v_add_f32_e32 v214, v214, v215
	v_mov_b32_e32 v215, v214
	s_nop 1
	v_permlane32_swap_b32_e32 v214, v215
	s_nop 0
	v_add_f32_e32 v214, v214, v215
	s_and_saveexec_b64 s[22:23], s[4:5]
	global_store_dword v210, v214, s[16:17] offset:1024
	s_mov_b64 exec, s[22:23]
	s_waitcnt vmcnt(16)
	v_lshlrev_b32_e32 v202, 16, v162
	v_and_b32_e32 v203, 0xffff0000, v162
	v_lshlrev_b32_e32 v204, 16, v163
	v_and_b32_e32 v205, 0xffff0000, v163
	v_pk_add_f32 v[92:93], v[92:93], v[202:203]
	v_pk_add_f32 v[94:95], v[94:95], v[204:205]
	v_lshlrev_b32_e32 v202, 16, v164
	v_and_b32_e32 v203, 0xffff0000, v164
	v_lshlrev_b32_e32 v204, 16, v165
	v_and_b32_e32 v205, 0xffff0000, v165
	v_pk_add_f32 v[88:89], v[88:89], v[202:203]
	v_pk_add_f32 v[90:91], v[90:91], v[204:205]
	v_cvt_pk_bf16_f32 v162, v92, v93
	v_cvt_pk_bf16_f32 v163, v94, v95
	v_cvt_pk_bf16_f32 v164, v88, v89
	v_cvt_pk_bf16_f32 v165, v90, v91
	v_pk_mul_f32 v[138:139], v[92:93], v[92:93]
	global_store_dwordx4 v207, v[162:165], s[14:15]
	v_pk_fma_f32 v[138:139], v[94:95], v[94:95], v[138:139]
	v_pk_fma_f32 v[138:139], v[88:89], v[88:89], v[138:139]
	v_pk_fma_f32 v[138:139], v[90:91], v[90:91], v[138:139]
	v_lshlrev_b32_e32 v202, 16, v166
	v_and_b32_e32 v203, 0xffff0000, v166
	v_lshlrev_b32_e32 v204, 16, v167
	v_and_b32_e32 v205, 0xffff0000, v167
	v_pk_add_f32 v[84:85], v[84:85], v[202:203]
	v_pk_add_f32 v[86:87], v[86:87], v[204:205]
	v_lshlrev_b32_e32 v202, 16, v168
	v_and_b32_e32 v203, 0xffff0000, v168
	v_lshlrev_b32_e32 v204, 16, v169
	v_and_b32_e32 v205, 0xffff0000, v169
	v_pk_add_f32 v[80:81], v[80:81], v[202:203]
	v_pk_add_f32 v[82:83], v[82:83], v[204:205]
	v_cvt_pk_bf16_f32 v166, v84, v85
	v_cvt_pk_bf16_f32 v167, v86, v87
	v_cvt_pk_bf16_f32 v168, v80, v81
	v_cvt_pk_bf16_f32 v169, v82, v83
	v_pk_fma_f32 v[138:139], v[84:85], v[84:85], v[138:139]
	global_store_dwordx4 v207, v[166:169], s[14:15] offset:256
	v_pk_fma_f32 v[138:139], v[86:87], v[86:87], v[138:139]
	v_pk_fma_f32 v[138:139], v[80:81], v[80:81], v[138:139]
	v_pk_fma_f32 v[138:139], v[82:83], v[82:83], v[138:139]
	v_add_f32_e32 v214, v138, v139
	v_add_u32_e32 v207, 0x8000, v207
	v_mov_b32_e32 v215, v214
	s_nop 1
	v_permlane16_swap_b32_e32 v214, v215
	s_nop 0
	v_add_f32_e32 v214, v214, v215
	v_mov_b32_e32 v215, v214
	s_nop 1
	v_permlane32_swap_b32_e32 v214, v215
	s_nop 0
	v_add_f32_e32 v214, v214, v215
	s_and_saveexec_b64 s[22:23], s[4:5]
	global_store_dword v210, v214, s[16:17] offset:2048
	s_mov_b64 exec, s[22:23]
	s_waitcnt vmcnt(17)
	v_lshlrev_b32_e32 v202, 16, v170
	v_and_b32_e32 v203, 0xffff0000, v170
	v_lshlrev_b32_e32 v204, 16, v171
	v_and_b32_e32 v205, 0xffff0000, v171
	v_pk_add_f32 v[76:77], v[76:77], v[202:203]
	v_pk_add_f32 v[78:79], v[78:79], v[204:205]
	v_lshlrev_b32_e32 v202, 16, v172
	v_and_b32_e32 v203, 0xffff0000, v172
	v_lshlrev_b32_e32 v204, 16, v173
	v_and_b32_e32 v205, 0xffff0000, v173
	v_pk_add_f32 v[72:73], v[72:73], v[202:203]
	v_pk_add_f32 v[74:75], v[74:75], v[204:205]
	v_cvt_pk_bf16_f32 v170, v76, v77
	v_cvt_pk_bf16_f32 v171, v78, v79
	v_cvt_pk_bf16_f32 v172, v72, v73
	v_cvt_pk_bf16_f32 v173, v74, v75
	v_pk_mul_f32 v[138:139], v[76:77], v[76:77]
	global_store_dwordx4 v207, v[170:173], s[14:15]
	v_pk_fma_f32 v[138:139], v[78:79], v[78:79], v[138:139]
	v_pk_fma_f32 v[138:139], v[72:73], v[72:73], v[138:139]
	v_pk_fma_f32 v[138:139], v[74:75], v[74:75], v[138:139]
	v_lshlrev_b32_e32 v202, 16, v174
	v_and_b32_e32 v203, 0xffff0000, v174
	v_lshlrev_b32_e32 v204, 16, v175
	v_and_b32_e32 v205, 0xffff0000, v175
	v_pk_add_f32 v[68:69], v[68:69], v[202:203]
	v_pk_add_f32 v[70:71], v[70:71], v[204:205]
	v_lshlrev_b32_e32 v202, 16, v176
	v_and_b32_e32 v203, 0xffff0000, v176
	v_lshlrev_b32_e32 v204, 16, v177
	v_and_b32_e32 v205, 0xffff0000, v177
	v_pk_add_f32 v[64:65], v[64:65], v[202:203]
	v_pk_add_f32 v[66:67], v[66:67], v[204:205]
	v_cvt_pk_bf16_f32 v174, v68, v69
	v_cvt_pk_bf16_f32 v175, v70, v71
	v_cvt_pk_bf16_f32 v176, v64, v65
	v_cvt_pk_bf16_f32 v177, v66, v67
	v_pk_fma_f32 v[138:139], v[68:69], v[68:69], v[138:139]
	global_store_dwordx4 v207, v[174:177], s[14:15] offset:256
	v_pk_fma_f32 v[138:139], v[70:71], v[70:71], v[138:139]
	v_pk_fma_f32 v[138:139], v[64:65], v[64:65], v[138:139]
	v_pk_fma_f32 v[138:139], v[66:67], v[66:67], v[138:139]
	v_add_f32_e32 v214, v138, v139
	v_add_u32_e32 v207, 0x28000, v207
	v_mov_b32_e32 v215, v214
	s_nop 1
	v_permlane16_swap_b32_e32 v214, v215
	s_nop 0
	v_add_f32_e32 v214, v214, v215
	v_mov_b32_e32 v215, v214
	s_nop 1
	v_permlane32_swap_b32_e32 v214, v215
	s_nop 0
	v_add_f32_e32 v214, v214, v215
	s_and_saveexec_b64 s[22:23], s[4:5]
	global_store_dword v210, v214, s[16:17] offset:3072
	s_mov_b64 exec, s[22:23]
	v_add_u32_e32 v210, 0x2000, v210
	s_waitcnt vmcnt(18)
	v_lshlrev_b32_e32 v202, 16, v178
	v_and_b32_e32 v203, 0xffff0000, v178
	v_lshlrev_b32_e32 v204, 16, v179
	v_and_b32_e32 v205, 0xffff0000, v179
	v_pk_add_f32 v[60:61], v[60:61], v[202:203]
	v_pk_add_f32 v[62:63], v[62:63], v[204:205]
	v_lshlrev_b32_e32 v202, 16, v180
	v_and_b32_e32 v203, 0xffff0000, v180
	v_lshlrev_b32_e32 v204, 16, v181
	v_and_b32_e32 v205, 0xffff0000, v181
	v_pk_add_f32 v[56:57], v[56:57], v[202:203]
	v_pk_add_f32 v[58:59], v[58:59], v[204:205]
	v_cvt_pk_bf16_f32 v178, v60, v61
	v_cvt_pk_bf16_f32 v179, v62, v63
	v_cvt_pk_bf16_f32 v180, v56, v57
	v_cvt_pk_bf16_f32 v181, v58, v59
	v_pk_mul_f32 v[138:139], v[60:61], v[60:61]
	global_store_dwordx4 v207, v[178:181], s[14:15]
	v_pk_fma_f32 v[138:139], v[62:63], v[62:63], v[138:139]
	v_pk_fma_f32 v[138:139], v[56:57], v[56:57], v[138:139]
	v_pk_fma_f32 v[138:139], v[58:59], v[58:59], v[138:139]
	v_lshlrev_b32_e32 v202, 16, v182
	v_and_b32_e32 v203, 0xffff0000, v182
	v_lshlrev_b32_e32 v204, 16, v183
	v_and_b32_e32 v205, 0xffff0000, v183
	v_pk_add_f32 v[52:53], v[52:53], v[202:203]
	v_pk_add_f32 v[54:55], v[54:55], v[204:205]
	v_lshlrev_b32_e32 v202, 16, v184
	v_and_b32_e32 v203, 0xffff0000, v184
	v_lshlrev_b32_e32 v204, 16, v185
	v_and_b32_e32 v205, 0xffff0000, v185
	v_pk_add_f32 v[48:49], v[48:49], v[202:203]
	v_pk_add_f32 v[50:51], v[50:51], v[204:205]
	v_cvt_pk_bf16_f32 v182, v52, v53
	v_cvt_pk_bf16_f32 v183, v54, v55
	v_cvt_pk_bf16_f32 v184, v48, v49
	v_cvt_pk_bf16_f32 v185, v50, v51
	v_pk_fma_f32 v[138:139], v[52:53], v[52:53], v[138:139]
	global_store_dwordx4 v207, v[182:185], s[14:15] offset:256
	v_pk_fma_f32 v[138:139], v[54:55], v[54:55], v[138:139]
	v_pk_fma_f32 v[138:139], v[48:49], v[48:49], v[138:139]
	v_pk_fma_f32 v[138:139], v[50:51], v[50:51], v[138:139]
	v_add_f32_e32 v214, v138, v139
	v_add_u32_e32 v207, 0x8000, v207
	v_mov_b32_e32 v215, v214
	s_nop 1
	v_permlane16_swap_b32_e32 v214, v215
	s_nop 0
	v_add_f32_e32 v214, v214, v215
	v_mov_b32_e32 v215, v214
	s_nop 1
	v_permlane32_swap_b32_e32 v214, v215
	s_nop 0
	v_add_f32_e32 v214, v214, v215
	s_and_saveexec_b64 s[22:23], s[4:5]
	global_store_dword v210, v214, s[16:17]
	s_mov_b64 exec, s[22:23]
	s_waitcnt vmcnt(19)
	v_lshlrev_b32_e32 v202, 16, v186
	v_and_b32_e32 v203, 0xffff0000, v186
	v_lshlrev_b32_e32 v204, 16, v187
	v_and_b32_e32 v205, 0xffff0000, v187
	v_pk_add_f32 v[44:45], v[44:45], v[202:203]
	v_pk_add_f32 v[46:47], v[46:47], v[204:205]
	v_lshlrev_b32_e32 v202, 16, v188
	v_and_b32_e32 v203, 0xffff0000, v188
	v_lshlrev_b32_e32 v204, 16, v189
	v_and_b32_e32 v205, 0xffff0000, v189
	v_pk_add_f32 v[40:41], v[40:41], v[202:203]
	v_pk_add_f32 v[42:43], v[42:43], v[204:205]
	v_cvt_pk_bf16_f32 v186, v44, v45
	v_cvt_pk_bf16_f32 v187, v46, v47
	v_cvt_pk_bf16_f32 v188, v40, v41
	v_cvt_pk_bf16_f32 v189, v42, v43
	v_pk_mul_f32 v[138:139], v[44:45], v[44:45]
	global_store_dwordx4 v207, v[186:189], s[14:15]
	v_pk_fma_f32 v[138:139], v[46:47], v[46:47], v[138:139]
	v_pk_fma_f32 v[138:139], v[40:41], v[40:41], v[138:139]
	v_pk_fma_f32 v[138:139], v[42:43], v[42:43], v[138:139]
	v_lshlrev_b32_e32 v202, 16, v190
	v_and_b32_e32 v203, 0xffff0000, v190
	v_lshlrev_b32_e32 v204, 16, v191
	v_and_b32_e32 v205, 0xffff0000, v191
	v_pk_add_f32 v[36:37], v[36:37], v[202:203]
	v_pk_add_f32 v[38:39], v[38:39], v[204:205]
	v_lshlrev_b32_e32 v202, 16, v192
	v_and_b32_e32 v203, 0xffff0000, v192
	v_lshlrev_b32_e32 v204, 16, v193
	v_and_b32_e32 v205, 0xffff0000, v193
	v_pk_add_f32 v[32:33], v[32:33], v[202:203]
	v_pk_add_f32 v[34:35], v[34:35], v[204:205]
	v_cvt_pk_bf16_f32 v190, v36, v37
	v_cvt_pk_bf16_f32 v191, v38, v39
	v_cvt_pk_bf16_f32 v192, v32, v33
	v_cvt_pk_bf16_f32 v193, v34, v35
	v_pk_fma_f32 v[138:139], v[36:37], v[36:37], v[138:139]
	global_store_dwordx4 v207, v[190:193], s[14:15] offset:256
	v_pk_fma_f32 v[138:139], v[38:39], v[38:39], v[138:139]
	v_pk_fma_f32 v[138:139], v[32:33], v[32:33], v[138:139]
	v_pk_fma_f32 v[138:139], v[34:35], v[34:35], v[138:139]
	v_add_f32_e32 v214, v138, v139
	v_add_u32_e32 v207, 0x8000, v207
	v_mov_b32_e32 v215, v214
	s_nop 1
	v_permlane16_swap_b32_e32 v214, v215
	s_nop 0
	v_add_f32_e32 v214, v214, v215
	v_mov_b32_e32 v215, v214
	s_nop 1
	v_permlane32_swap_b32_e32 v214, v215
	s_nop 0
	v_add_f32_e32 v214, v214, v215
	s_and_saveexec_b64 s[22:23], s[4:5]
	global_store_dword v210, v214, s[16:17] offset:1024
	s_mov_b64 exec, s[22:23]
	s_waitcnt vmcnt(20)
	v_lshlrev_b32_e32 v202, 16, v194
	v_and_b32_e32 v203, 0xffff0000, v194
	v_lshlrev_b32_e32 v204, 16, v195
	v_and_b32_e32 v205, 0xffff0000, v195
	v_pk_add_f32 v[28:29], v[28:29], v[202:203]
	v_pk_add_f32 v[30:31], v[30:31], v[204:205]
	v_lshlrev_b32_e32 v202, 16, v196
	v_and_b32_e32 v203, 0xffff0000, v196
	v_lshlrev_b32_e32 v204, 16, v197
	v_and_b32_e32 v205, 0xffff0000, v197
	v_pk_add_f32 v[24:25], v[24:25], v[202:203]
	v_pk_add_f32 v[26:27], v[26:27], v[204:205]
	v_cvt_pk_bf16_f32 v194, v28, v29
	v_cvt_pk_bf16_f32 v195, v30, v31
	v_cvt_pk_bf16_f32 v196, v24, v25
	v_cvt_pk_bf16_f32 v197, v26, v27
	v_pk_mul_f32 v[138:139], v[28:29], v[28:29]
	global_store_dwordx4 v207, v[194:197], s[14:15]
	v_pk_fma_f32 v[138:139], v[30:31], v[30:31], v[138:139]
	v_pk_fma_f32 v[138:139], v[24:25], v[24:25], v[138:139]
	v_pk_fma_f32 v[138:139], v[26:27], v[26:27], v[138:139]
	v_lshlrev_b32_e32 v202, 16, v198
	v_and_b32_e32 v203, 0xffff0000, v198
	v_lshlrev_b32_e32 v204, 16, v199
	v_and_b32_e32 v205, 0xffff0000, v199
	v_pk_add_f32 v[20:21], v[20:21], v[202:203]
	v_pk_add_f32 v[22:23], v[22:23], v[204:205]
	v_lshlrev_b32_e32 v202, 16, v200
	v_and_b32_e32 v203, 0xffff0000, v200
	v_lshlrev_b32_e32 v204, 16, v201
	v_and_b32_e32 v205, 0xffff0000, v201
	v_pk_add_f32 v[16:17], v[16:17], v[202:203]
	v_pk_add_f32 v[18:19], v[18:19], v[204:205]
	v_cvt_pk_bf16_f32 v198, v20, v21
	v_cvt_pk_bf16_f32 v199, v22, v23
	v_cvt_pk_bf16_f32 v200, v16, v17
	v_cvt_pk_bf16_f32 v201, v18, v19
	v_pk_fma_f32 v[138:139], v[20:21], v[20:21], v[138:139]
	global_store_dwordx4 v207, v[198:201], s[14:15] offset:256
	v_pk_fma_f32 v[138:139], v[22:23], v[22:23], v[138:139]
	v_pk_fma_f32 v[138:139], v[16:17], v[16:17], v[138:139]
	v_pk_fma_f32 v[138:139], v[18:19], v[18:19], v[138:139]
	v_add_f32_e32 v214, v138, v139
	v_add_u32_e32 v207, 0x8000, v207
	v_mov_b32_e32 v215, v214
	s_nop 1
	v_permlane16_swap_b32_e32 v214, v215
	s_nop 0
	v_add_f32_e32 v214, v214, v215
	v_mov_b32_e32 v215, v214
	s_nop 1
	v_permlane32_swap_b32_e32 v214, v215
	s_nop 0
	v_add_f32_e32 v214, v214, v215
	s_and_saveexec_b64 s[22:23], s[4:5]
	global_store_dword v210, v214, s[16:17] offset:2048
	s_mov_b64 exec, s[22:23]
	s_waitcnt vmcnt(18)
	v_lshlrev_b32_e32 v202, 16, v146
	v_and_b32_e32 v203, 0xffff0000, v146
	v_lshlrev_b32_e32 v204, 16, v147
	v_and_b32_e32 v205, 0xffff0000, v147
	v_pk_add_f32 v[12:13], v[12:13], v[202:203]
	v_pk_add_f32 v[14:15], v[14:15], v[204:205]
	v_lshlrev_b32_e32 v202, 16, v148
	v_and_b32_e32 v203, 0xffff0000, v148
	v_lshlrev_b32_e32 v204, 16, v149
	v_and_b32_e32 v205, 0xffff0000, v149
	v_pk_add_f32 v[8:9], v[8:9], v[202:203]
	v_pk_add_f32 v[10:11], v[10:11], v[204:205]
	v_cvt_pk_bf16_f32 v146, v12, v13
	v_cvt_pk_bf16_f32 v147, v14, v15
	v_cvt_pk_bf16_f32 v148, v8, v9
	v_cvt_pk_bf16_f32 v149, v10, v11
	v_pk_mul_f32 v[138:139], v[12:13], v[12:13]
	global_store_dwordx4 v207, v[146:149], s[14:15]
	v_pk_fma_f32 v[138:139], v[14:15], v[14:15], v[138:139]
	v_pk_fma_f32 v[138:139], v[8:9], v[8:9], v[138:139]
	v_pk_fma_f32 v[138:139], v[10:11], v[10:11], v[138:139]
	v_lshlrev_b32_e32 v202, 16, v150
	v_and_b32_e32 v203, 0xffff0000, v150
	v_lshlrev_b32_e32 v204, 16, v151
	v_and_b32_e32 v205, 0xffff0000, v151
	v_pk_add_f32 v[4:5], v[4:5], v[202:203]
	v_pk_add_f32 v[6:7], v[6:7], v[204:205]
	v_lshlrev_b32_e32 v202, 16, v152
	v_and_b32_e32 v203, 0xffff0000, v152
	v_lshlrev_b32_e32 v204, 16, v153
	v_and_b32_e32 v205, 0xffff0000, v153
	v_pk_add_f32 v[0:1], v[0:1], v[202:203]
	v_pk_add_f32 v[2:3], v[2:3], v[204:205]
	v_cvt_pk_bf16_f32 v150, v4, v5
	v_cvt_pk_bf16_f32 v151, v6, v7
	v_cvt_pk_bf16_f32 v152, v0, v1
	v_cvt_pk_bf16_f32 v153, v2, v3
	v_pk_fma_f32 v[138:139], v[4:5], v[4:5], v[138:139]
	global_store_dwordx4 v207, v[150:153], s[14:15] offset:256
	v_pk_fma_f32 v[138:139], v[6:7], v[6:7], v[138:139]
	v_pk_fma_f32 v[138:139], v[0:1], v[0:1], v[138:139]
	v_pk_fma_f32 v[138:139], v[2:3], v[2:3], v[138:139]
	v_add_f32_e32 v214, v138, v139
	v_add_u32_e32 v207, 0x8000, v207
	v_mov_b32_e32 v215, v214
	s_nop 1
	v_permlane16_swap_b32_e32 v214, v215
	s_nop 0
	v_add_f32_e32 v214, v214, v215
	v_mov_b32_e32 v215, v214
	s_nop 1
	v_permlane32_swap_b32_e32 v214, v215
	s_nop 0
	v_add_f32_e32 v214, v214, v215
	s_and_saveexec_b64 s[22:23], s[4:5]
	global_store_dword v210, v214, s[16:17] offset:3072
	s_mov_b64 exec, s[22:23]
	s_branch .LBB0_1009
